# FFN-up epilogue: the 16 per-lane conv-weight/bias loads per unit replaced by two coalesced wave loads staged through a wave-private LDS slot (ds_read_b128 readback)
# speedup vs baseline: 1.0009x; 1.0009x over previous
;     __device__ __forceinline__ void operator()(const f32x4 (&acc)[2][2][4][2], const Unit& u, int wr, int wc, int fr, int fq) const {
;     ...
;             for (int m = 0; m < 4; ++m) rs8[ai][m] = rsqrtf(SS[u.rb + (u.half ? 0 : ai * HALF) + wr * 64 + fr + 16 * m] * (1.f / 1024.f) + 1e-6f);
;         if (u.pm < 128) {
; #pragma unroll
;           for (int bj = 0; bj < 2; ++bj) {
;             const int col8 = u.pn * BM + bj * HALF + wc * 32 + 8 * fq;
;             float w0[2][4], w1[2][4], w2[2][4], bb[2][4];
; #pragma unroll
;             for (int hv = 0; hv < 2; ++hv) { ld4f(cw + col8 + 4 * hv, w0[hv]); ld4f(cw + 2816 + col8 + 4 * hv, w1[hv]); ld4f(cw + 2 * 2816 + col8 + 4 * hv, w2[hv]); ld4f(cb + col8 + 4 * hv, bb[hv]); }
; #pragma unroll
;             for (int ai = 0; ai < 2; ++ai) { const int R0 = u.rb + ai * HALF + wr * 64; const bf16_t* gp = G + (size_t)(R0 + fr) * 2816 + col8;
;                 u32x4 gq[4], prv = (u32x4){0u, 0u, 0u, 0u};
; #pragma unroll
;                 for (int m = 0; m < 4; ++m) gq[m] = *(const u32x4*)(gp + (size_t)m * 16 * 2816);
;                 if ((R0 & 8191) != 0) prv = *(const u32x4*)(gp - (size_t)16 * 2816);
.LBB0_1009:
	s_andn2_b64 vcc, exec, s[0:1]
	s_cbranch_vccnz .LBB0_1021
	s_and_b64 s[0:1], s[84:85], exec
	s_cselect_b32 s0, 0x80, 0
	v_add_u32_e32 v132, s0, v210
	v_add_u32_e32 v134, 16, v132
	v_ashrrev_i32_e32 v133, 31, v132
	v_ashrrev_i32_e32 v135, 31, v134
	v_lshl_add_u64 v[164:165], v[132:133], 2, s[12:13]
	v_lshl_add_u64 v[166:167], v[134:135], 2, s[12:13]
	v_add_u32_e32 v134, 32, v132
	v_add_u32_e32 v132, 48, v132
	s_lshl_b32 s0, s70, 8
	v_ashrrev_i32_e32 v133, 31, v132
	v_add_u32_e32 v212, s0, v3
	v_lshl_add_u64 v[132:133], v[132:133], 2, s[12:13]
	v_ashrrev_i32_e32 v213, 31, v212
	v_readlane_b32 s0, v240, 19
	global_load_dword v185, v[132:133], off
	v_lshlrev_b64 v[132:133], 2, v[212:213]
	v_readlane_b32 s1, v240, 20
	s_mov_b64 s[68:69], s[54:55]
	v_readlane_b32 s52, v240, 62
	v_lshl_add_u64 v[140:141], s[0:1], 0, v[132:133]
	v_readlane_b32 s0, v240, 21
	v_readlane_b32 s1, v240, 22
	v_readlane_b32 s66, v239, 12
	v_readlane_b32 s67, v239, 13
	v_lshl_add_u64 v[144:145], s[0:1], 0, v[132:133]
	v_readlane_b32 s0, v240, 12
	v_readlane_b32 s1, v240, 13
	v_ashrrev_i32_e32 v135, 31, v134
	v_lshl_add_u64 v[136:137], s[66:67], 0, v[132:133]
	v_mov_b64_e32 v[170:171], s[0:1]
	v_mad_i64_i32 v[214:215], s[0:1], v210, s91, v[170:171]
	v_lshl_add_u64 v[160:161], s[88:89], 0, v[132:133]
	v_lshl_add_u64 v[180:181], v[212:213], 1, v[214:215]
	s_mov_b32 s10, 0x16000
	v_lshl_add_u64 v[168:169], v[134:135], 2, s[12:13]
	v_and_b32_e32 v241, 63, v216
	v_lshrrev_b32_e32 v242, 4, v241
	v_and_b32_e32 v243, 15, v241
	v_cmp_eq_u32_e64 s[98:99], 1, v242
	v_lshlrev_b32_e32 v246, 3, v243
	v_lshlrev_b32_e32 v247, 5, v242
	v_cndmask_b32_e64 v244, v136, v140, s[98:99]
	v_cndmask_b32_e64 v245, v137, v141, s[98:99]
	v_cmp_eq_u32_e64 s[98:99], 2, v242
	v_sub_u32_e32 v246, v246, v247
	v_ashrrev_i32_e32 v247, 31, v246
	v_cndmask_b32_e64 v244, v244, v144, s[98:99]
	v_cndmask_b32_e64 v245, v245, v145, s[98:99]
	v_cmp_eq_u32_e64 s[98:99], 3, v242
	s_nop 1
	v_cndmask_b32_e64 v244, v244, v160, s[98:99]
	v_cndmask_b32_e64 v245, v245, v161, s[98:99]
	v_lshl_add_u64 v[244:245], v[244:245], 0, v[246:247]
	global_load_dwordx2 v[248:249], v[244:245], off
	s_nop 0
	s_nop 0
	s_nop 0
	s_nop 0
	s_nop 0
	global_load_dword v189, v[164:165], off
	global_load_dword v187, v[166:167], off
	global_load_dword v3, v[168:169], off
	global_load_dwordx4 v[176:179], v[180:181], off
	v_add_co_u32_e32 v164, vcc, s10, v180
	s_and_b32 s3, s2, 0x1fff
	s_nop 0
	v_addc_co_u32_e32 v165, vcc, 0, v181, vcc
	v_add_co_u32_e32 v166, vcc, 0x2c000, v180
	s_cmp_lg_u32 s3, 0
	s_nop 0
	v_addc_co_u32_e32 v167, vcc, 0, v181, vcc
	global_load_dwordx4 v[172:175], v[164:165], off
	global_load_dwordx4 v[168:171], v[166:167], off
	v_add_co_u32_e32 v164, vcc, 0x42000, v180
	s_cselect_b64 s[0:1], -1, 0
	s_nop 0
	v_addc_co_u32_e32 v165, vcc, 0, v181, vcc
	global_load_dwordx4 v[164:167], v[164:165], off
	s_cmp_eq_u32 s3, 0
	v_readlane_b32 s53, v240, 63
	v_readlane_b32 s54, v239, 0
	v_readlane_b32 s55, v239, 1
	v_readlane_b32 s56, v239, 2
	v_readlane_b32 s57, v239, 3
	v_readlane_b32 s58, v239, 4
	v_readlane_b32 s59, v239, 5
	v_readlane_b32 s60, v239, 6
	v_readlane_b32 s61, v239, 7
	v_readlane_b32 s62, v239, 8
	v_readlane_b32 s63, v239, 9
	v_readlane_b32 s64, v239, 10
	v_readlane_b32 s65, v239, 11
	s_cbranch_scc1 .LBB0_1012
	v_add_co_u32_e32 v180, vcc, 0xfffea000, v180
	s_nop 1
	v_addc_co_u32_e32 v181, vcc, -1, v181, vcc
	global_load_dwordx4 v[180:183], v[180:181], off
	s_branch .LBB0_1013

;     static __device__ __forceinline__ void unpk4(const u32x2 w, float (&o)[4]) { o[0] = bf_lo(w.x); o[1] = bf_hi(w.x); o[2] = bf_lo(w.y); o[3] = bf_hi(w.y); }
;     template <int N> static __device__ __forceinline__ u32x2 dpp_prev(const u32x2 pv, const u32x2 cur) { u32x2 r; r.x = dpp_prev1<N>(pv.x, cur.x); r.y = dpp_prev1<N>(pv.y, cur.y); return r; }
;     __device__ __forceinline__ void operator()(const f32x4 (&acc)[2][2][4][2], const Unit& u, int wr, int wc, int fr, int fq) const {
;     ...
;             for (int hv = 0; hv < 2; ++hv) { ld4f(cw + col8 + 4 * hv, w0[hv]); ld4f(cw + 2816 + col8 + 4 * hv, w1[hv]); ld4f(cw + 2 * 2816 + col8 + 4 * hv, w2[hv]); ld4f(cb + col8 + 4 * hv, bb[hv]); }
;     ...
;                 for (int m = 0; m < 4; ++m) { const u32x4 cur = gq[m]; u32x4 hw;
; #pragma unroll
;                     for (int hv = 0; hv < 2; ++hv) { const u32x2 c2 = half2(cur, hv), p2 = half2(pv, hv);
;                         const u32x2 q1 = dpp_prev<1>(p2, c2), q2 = dpp_prev<2>(p2, c2);
;                         float g0[4], g1[4], g2[4]; unpk4(c2, g0); unpk4(q1, g1); unpk4(q2, g2);
;                         const u32x2 r = finish2(g0, g1, g2, w0[hv], w1[hv], w2[hv], bb[hv], acc[ai][bj][m][hv], rs8[ai][m]);
;                         if (hv == 0) { hw.x = r.x; hw.y = r.y; } else { hw.z = r.x; hw.w = r.y; } }
;                     *(u32x4*)(H + (size_t)(R0 + fr + 16 * m) * 2816 + col8) = hw;
.LBB0_1013:
	s_waitcnt vmcnt(0)
	v_lshrrev_b32_e32 v252, 6, v216
	v_lshlrev_b32_e32 v252, 10, v252
	v_add_u32_e32 v252, 0x20000, v252
	v_lshl_add_u32 v253, v241, 3, v252
	v_lshl_add_u32 v254, v242, 5, v252
	ds_write_b64 v253, v[248:249]
	s_waitcnt lgkmcnt(0)
	ds_read_b128 v[132:135], v254 offset:16
	ds_read_b128 v[148:151], v254
	ds_read_b128 v[136:139], v254 offset:144
	ds_read_b128 v[152:155], v254 offset:128
	ds_read_b128 v[140:143], v254 offset:272
	ds_read_b128 v[156:159], v254 offset:256
	ds_read_b128 v[144:147], v254 offset:400
	ds_read_b128 v[160:163], v254 offset:384
	s_waitcnt lgkmcnt(0)
	s_nop 0
	s_nop 0
	s_nop 0
	s_nop 0
	s_nop 0
	s_nop 0
	v_mov_b32_dpp v195, v180 row_ror:2 row_mask:0xf bank_mask:0xf bound_ctrl:1
	v_mov_b32_dpp v191, v180 row_ror:1 row_mask:0xf bank_mask:0xf bound_ctrl:1
	v_mad_i64_i32 v[230:231], s[8:9], v210, s91, 0
	v_mov_b32_dpp v195, v176 row_shr:2 row_mask:0xf bank_mask:0xf
	v_mov_b32_dpp v191, v176 row_shr:1 row_mask:0xf bank_mask:0xf
	v_lshlrev_b32_e32 v210, 16, v195
	v_and_b32_e32 v211, 0xffff0000, v195
	v_mov_b32_dpp v193, v181 row_ror:1 row_mask:0xf bank_mask:0xf bound_ctrl:1
	v_mov_b32_dpp v229, v181 row_ror:2 row_mask:0xf bank_mask:0xf bound_ctrl:1
	v_lshlrev_b32_e32 v180, 16, v191
	v_and_b32_e32 v181, 0xffff0000, v191
	v_pk_fma_f32 v[210:211], v[148:149], v[210:211], v[160:161]
	v_lshlrev_b32_e32 v232, 16, v176
	v_and_b32_e32 v233, 0xffff0000, v176
	v_pk_fma_f32 v[180:181], v[152:153], v[180:181], v[210:211]
	v_mov_b32_dpp v229, v177 row_shr:2 row_mask:0xf bank_mask:0xf
	v_pk_fma_f32 v[180:181], v[156:157], v[232:233], v[180:181]
	v_mov_b32_dpp v193, v177 row_shr:1 row_mask:0xf bank_mask:0xf
	v_pk_mul_f32 v[210:211], v[180:181], s[30:31] op_sel_hi:[1,0]
	v_lshlrev_b32_e32 v228, 16, v229
	v_med3_f32 v232, v210, s47, v225
	v_med3_f32 v233, v211, s47, v225
	v_pk_mul_f32 v[234:235], v[232:233], v[232:233]
	v_mov_b64_e32 v[210:211], s[36:37]
	v_pk_fma_f32 v[236:237], v[234:235], s[34:35], v[210:211] op_sel_hi:[1,0,0] neg_lo:[1,0,0] neg_hi:[1,0,0]
	v_and_b32_e32 v229, 0xffff0000, v229
	v_pk_fma_f32 v[236:237], v[234:235], v[236:237], s[38:39] op_sel_hi:[1,1,0]
	v_pk_mul_f32 v[180:181], v[180:181], 0.5 op_sel_hi:[1,0]
	v_pk_fma_f32 v[236:237], v[234:235], v[236:237], s[40:41] op_sel_hi:[1,1,0]
	v_lshlrev_b32_e32 v226, 16, v193
	v_pk_fma_f32 v[236:237], v[234:235], v[236:237], s[42:43] op_sel_hi:[1,1,0]
	v_and_b32_e32 v227, 0xffff0000, v193
	v_pk_fma_f32 v[236:237], v[234:235], v[236:237], s[44:45] op_sel_hi:[1,1,0]
	v_pk_mul_f32 v[128:129], v[128:129], v[188:189] op_sel_hi:[1,0]
	v_pk_fma_f32 v[236:237], v[234:235], v[236:237], s[46:47] op_sel_hi:[1,1,0]
	v_pk_fma_f32 v[228:229], v[150:151], v[228:229], v[162:163]
	v_pk_fma_f32 v[234:235], v[234:235], v[236:237], s[48:49] op_sel_hi:[1,1,0]
	v_pk_fma_f32 v[226:227], v[154:155], v[226:227], v[228:229]
	v_pk_mul_f32 v[232:233], v[232:233], v[234:235]
	v_pk_mul_f32 v[130:131], v[130:131], v[188:189] op_sel_hi:[1,0]
	v_pk_fma_f32 v[180:181], v[180:181], v[232:233], v[180:181]
	v_pk_mul_f32 v[124:125], v[124:125], v[188:189] op_sel_hi:[1,0]
	v_pk_mul_f32 v[128:129], v[128:129], v[180:181]
	v_lshlrev_b32_e32 v180, 16, v177
	v_and_b32_e32 v181, 0xffff0000, v177
	v_pk_fma_f32 v[180:181], v[158:159], v[180:181], v[226:227]
	v_readlane_b32 s8, v240, 58
	v_pk_mul_f32 v[226:227], v[180:181], s[30:31] op_sel_hi:[1,0]
	v_pk_mul_f32 v[180:181], v[180:181], 0.5 op_sel_hi:[1,0]
	v_med3_f32 v226, v226, s47, v225
	v_med3_f32 v227, v227, s47, v225
	v_pk_mul_f32 v[228:229], v[226:227], v[226:227]
	v_readlane_b32 s9, v240, 59
	v_pk_fma_f32 v[232:233], v[228:229], s[34:35], v[210:211] op_sel_hi:[1,0,0] neg_lo:[1,0,0] neg_hi:[1,0,0]
	v_pk_mul_f32 v[126:127], v[126:127], v[188:189] op_sel_hi:[1,0]
	v_pk_fma_f32 v[232:233], v[228:229], v[232:233], s[38:39] op_sel_hi:[1,1,0]
	v_pk_mul_f32 v[120:121], v[120:121], v[186:187] op_sel_hi:[1,0]
	v_pk_fma_f32 v[232:233], v[228:229], v[232:233], s[40:41] op_sel_hi:[1,1,0]
	v_pk_mul_f32 v[122:123], v[122:123], v[186:187] op_sel_hi:[1,0]
	v_pk_fma_f32 v[232:233], v[228:229], v[232:233], s[42:43] op_sel_hi:[1,1,0]
	v_pk_mul_f32 v[116:117], v[116:117], v[186:187] op_sel_hi:[1,0]
	v_pk_fma_f32 v[232:233], v[228:229], v[232:233], s[44:45] op_sel_hi:[1,1,0]
	v_pk_mul_f32 v[118:119], v[118:119], v[186:187] op_sel_hi:[1,0]
	v_pk_fma_f32 v[232:233], v[228:229], v[232:233], s[46:47] op_sel_hi:[1,1,0]
	v_pk_mul_f32 v[112:113], v[112:113], v[184:185] op_sel_hi:[1,0]
	v_pk_fma_f32 v[228:229], v[228:229], v[232:233], s[48:49] op_sel_hi:[1,1,0]
	v_pk_mul_f32 v[114:115], v[114:115], v[184:185] op_sel_hi:[1,0]
	v_pk_mul_f32 v[226:227], v[226:227], v[228:229]
	v_lshlrev_b32_e32 v228, 16, v178
	v_pk_fma_f32 v[180:181], v[180:181], v[226:227], v[180:181]
	v_cvt_pk_bf16_f32 v226, v128, v129
	v_mov_b32_dpp v129, v182 row_ror:1 row_mask:0xf bank_mask:0xf bound_ctrl:1
	v_pk_mul_f32 v[130:131], v[130:131], v[180:181]
	v_mov_b32_dpp v181, v182 row_ror:2 row_mask:0xf bank_mask:0xf bound_ctrl:1
	v_mov_b32_dpp v129, v178 row_shr:1 row_mask:0xf bank_mask:0xf
	v_lshlrev_b32_e32 v128, 16, v129
	v_mov_b32_dpp v181, v178 row_shr:2 row_mask:0xf bank_mask:0xf
	v_lshlrev_b32_e32 v180, 16, v181
	v_and_b32_e32 v181, 0xffff0000, v181
	v_and_b32_e32 v129, 0xffff0000, v129
	v_pk_fma_f32 v[180:181], v[132:133], v[180:181], v[144:145]
	v_and_b32_e32 v229, 0xffff0000, v178
	v_pk_fma_f32 v[128:129], v[136:137], v[128:129], v[180:181]
	v_cvt_pk_bf16_f32 v227, v130, v131
	v_mov_b32_dpp v131, v183 row_ror:1 row_mask:0xf bank_mask:0xf bound_ctrl:1
	v_pk_fma_f32 v[128:129], v[140:141], v[228:229], v[128:129]
	v_mov_b32_dpp v183, v183 row_ror:2 row_mask:0xf bank_mask:0xf bound_ctrl:1
;     static __device__ __forceinline__ u32x2 finish2(const float (&g0)[4], const float (&g1)[4], const float (&g2)[4], const float (&w0)[4], const float (&w1)[4], const float (&w2)[4], const float (&bb)[4],
;                                                     const f32x4 v, float rs) {
;         float h[4];
; #pragma unroll
;         for (int j = 0; j < 4; j += 2) {
;             const f32x2 gc = (f32x2){bb[j] + w0[j] * g2[j] + w1[j] * g1[j] + w2[j] * g0[j], bb[j + 1] + w0[j + 1] * g2[j + 1] + w1[j + 1] * g1[j + 1] + w2[j + 1] * g0[j + 1]};
;             const f32x2 ge = gelu_pk(gc) * ((f32x2){v[j], v[j + 1]} * rs); h[j] = ge.x; h[j + 1] = ge.y; }
;         u32x2 w; w.x = cvt_pk_bf16(h[0], h[1]); w.y = cvt_pk_bf16(h[2], h[3]); return w;
;     }
;     __device__ __forceinline__ void operator()(const f32x4 (&acc)[2][2][4][2], const Unit& u, int wr, int wc, int fr, int fq) const {
;         asm volatile("" : "+v"(fr), "+v"(fq));
;         const int row0 = u.rb + wr * 64 + fr;
;         const int lane = fq * 16 + fr;
;         const int s1 = fr >= 1 ? lane - 1 : lane + 15, s2 = fr >= 2 ? lane - 2 : lane + 14; (void)s1; (void)s2;
;         float rs8[2][4];
; #pragma unroll
;         for (int ai = 0; ai < 2; ++ai)
; #pragma unroll
;             for (int m = 0; m < 4; ++m) rs8[ai][m] = rsqrtf(SS[u.rb + (u.half ? 0 : ai * HALF) + wr * 64 + fr + 16 * m] * (1.f / 1024.f) + 1e-6f);
;         if (u.pm < 128) {
; #pragma unroll
;           for (int bj = 0; bj < 2; ++bj) {
;             const int col8 = u.pn * BM + bj * HALF + wc * 32 + 8 * fq;
;             float w0[2][4], w1[2][4], w2[2][4], bb[2][4];
; #pragma unroll
;             for (int hv = 0; hv < 2; ++hv) { ld4f(cw + col8 + 4 * hv, w0[hv]); ld4f(cw + 2816 + col8 + 4 * hv, w1[hv]); ld4f(cw + 2 * 2816 + col8 + 4 * hv, w2[hv]); ld4f(cb + col8 + 4 * hv, bb[hv]); }
; #pragma unroll
;             for (int ai = 0; ai < 2; ++ai) { const int R0 = u.rb + ai * HALF + wr * 64; const bf16_t* gp = G + (size_t)(R0 + fr) * 2816 + col8;
;                 u32x4 gq[4], prv = (u32x4){0u, 0u, 0u, 0u};
; #pragma unroll
;                 for (int m = 0; m < 4; ++m) gq[m] = *(const u32x4*)(gp + (size_t)m * 16 * 2816);
;                 if ((R0 & 8191) != 0) prv = *(const u32x4*)(gp - (size_t)16 * 2816);
;                 u32x4 pv = prv;
; #pragma unroll
	v_pk_mul_f32 v[180:181], v[128:129], s[30:31] op_sel_hi:[1,0]
	v_mov_b32_dpp v131, v179 row_shr:1 row_mask:0xf bank_mask:0xf
	v_med3_f32 v180, v180, s47, v225
	v_med3_f32 v181, v181, s47, v225
	v_pk_mul_f32 v[228:229], v[180:181], v[180:181]
	v_mov_b32_dpp v183, v179 row_shr:2 row_mask:0xf bank_mask:0xf
	v_pk_fma_f32 v[232:233], v[228:229], s[34:35], v[210:211] op_sel_hi:[1,0,0] neg_lo:[1,0,0] neg_hi:[1,0,0]
	v_lshlrev_b32_e32 v182, 16, v183
	v_pk_fma_f32 v[232:233], v[228:229], v[232:233], s[38:39] op_sel_hi:[1,1,0]
	v_and_b32_e32 v183, 0xffff0000, v183
	v_pk_fma_f32 v[232:233], v[228:229], v[232:233], s[40:41] op_sel_hi:[1,1,0]
	v_pk_mul_f32 v[128:129], v[128:129], 0.5 op_sel_hi:[1,0]
	v_pk_fma_f32 v[232:233], v[228:229], v[232:233], s[42:43] op_sel_hi:[1,1,0]
	v_lshlrev_b32_e32 v130, 16, v131
	v_pk_fma_f32 v[232:233], v[228:229], v[232:233], s[44:45] op_sel_hi:[1,1,0]
	v_and_b32_e32 v131, 0xffff0000, v131
	v_pk_fma_f32 v[232:233], v[228:229], v[232:233], s[46:47] op_sel_hi:[1,1,0]
	v_pk_mul_f32 v[108:109], v[108:109], v[184:185] op_sel_hi:[1,0]
	v_pk_fma_f32 v[228:229], v[228:229], v[232:233], s[48:49] op_sel_hi:[1,1,0]
	v_pk_mul_f32 v[110:111], v[110:111], v[184:185] op_sel_hi:[1,0]
	v_pk_mul_f32 v[180:181], v[180:181], v[228:229]
	v_pk_mul_f32 v[104:105], v[104:105], v[2:3] op_sel_hi:[1,0]
	v_pk_fma_f32 v[128:129], v[128:129], v[180:181], v[128:129]
	v_pk_fma_f32 v[180:181], v[134:135], v[182:183], v[146:147]
	v_pk_mul_f32 v[124:125], v[124:125], v[128:129]
	v_lshlrev_b32_e32 v128, 16, v179
	v_and_b32_e32 v129, 0xffff0000, v179
	v_pk_fma_f32 v[130:131], v[138:139], v[130:131], v[180:181]
	v_cvt_pk_bf16_f32 v228, v124, v125
	v_pk_mul_f32 v[106:107], v[106:107], v[2:3] op_sel_hi:[1,0]
	v_pk_fma_f32 v[128:129], v[142:143], v[128:129], v[130:131]
	v_pk_mul_f32 v[100:101], v[100:101], v[2:3] op_sel_hi:[1,0]
	v_pk_mul_f32 v[130:131], v[128:129], s[30:31] op_sel_hi:[1,0]
	v_pk_mul_f32 v[128:129], v[128:129], 0.5 op_sel_hi:[1,0]
	v_med3_f32 v130, v130, s47, v225
	v_med3_f32 v131, v131, s47, v225
	v_pk_mul_f32 v[180:181], v[130:131], v[130:131]
	s_add_i32 s7, s2, 0x80
	v_pk_fma_f32 v[182:183], v[180:181], s[34:35], v[210:211] op_sel_hi:[1,0,0] neg_lo:[1,0,0] neg_hi:[1,0,0]
	v_readlane_b32 s2, v240, 12
	v_pk_fma_f32 v[182:183], v[180:181], v[182:183], s[38:39] op_sel_hi:[1,1,0]
	v_readlane_b32 s3, v240, 13
	v_pk_fma_f32 v[182:183], v[180:181], v[182:183], s[40:41] op_sel_hi:[1,1,0]
	v_add_u32_e32 v1, s7, v1
	v_pk_fma_f32 v[182:183], v[180:181], v[182:183], s[42:43] op_sel_hi:[1,1,0]
	v_pk_mul_f32 v[102:103], v[102:103], v[2:3] op_sel_hi:[1,0]
	v_pk_fma_f32 v[182:183], v[180:181], v[182:183], s[44:45] op_sel_hi:[1,1,0]
	s_and_b32 s7, s7, 0x1fff
	v_pk_fma_f32 v[182:183], v[180:181], v[182:183], s[46:47] op_sel_hi:[1,1,0]
	s_cmp_lg_u32 s7, 0
	v_pk_fma_f32 v[180:181], v[180:181], v[182:183], s[48:49] op_sel_hi:[1,1,0]
	v_lshlrev_b32_e32 v182, 16, v172
	v_pk_mul_f32 v[130:131], v[130:131], v[180:181]
	v_lshlrev_b64 v[180:181], 1, v[212:213]
	v_pk_fma_f32 v[128:129], v[128:129], v[130:131], v[128:129]
	v_lshl_add_u64 v[130:131], s[8:9], 0, v[230:231]
	v_pk_mul_f32 v[126:127], v[126:127], v[128:129]
	v_lshl_add_u64 v[124:125], v[130:131], 0, v[180:181]
	v_mov_b32_dpp v129, v176 row_ror:2 row_mask:0xf bank_mask:0xf bound_ctrl:1
	v_cvt_pk_bf16_f32 v229, v126, v127
	global_store_dwordx4 v[124:125], v[226:229], off
	v_mov_b32_dpp v125, v176 row_ror:1 row_mask:0xf bank_mask:0xf bound_ctrl:1
	v_mov_b32_dpp v129, v172 row_shr:2 row_mask:0xf bank_mask:0xf
	v_lshlrev_b32_e32 v128, 16, v129
	v_mov_b32_dpp v125, v172 row_shr:1 row_mask:0xf bank_mask:0xf
	v_and_b32_e32 v129, 0xffff0000, v129
	v_lshlrev_b32_e32 v124, 16, v125
	v_and_b32_e32 v125, 0xffff0000, v125
	v_pk_fma_f32 v[128:129], v[148:149], v[128:129], v[160:161]
	v_and_b32_e32 v183, 0xffff0000, v172
	v_pk_fma_f32 v[124:125], v[152:153], v[124:125], v[128:129]
	v_mov_b32_dpp v127, v177 row_ror:1 row_mask:0xf bank_mask:0xf bound_ctrl:1
	v_pk_fma_f32 v[124:125], v[156:157], v[182:183], v[124:125]
	v_mov_b32_dpp v177, v177 row_ror:2 row_mask:0xf bank_mask:0xf bound_ctrl:1
	v_pk_mul_f32 v[128:129], v[124:125], s[30:31] op_sel_hi:[1,0]
	v_mov_b32_dpp v127, v173 row_shr:1 row_mask:0xf bank_mask:0xf
	v_med3_f32 v128, v128, s47, v225
	v_med3_f32 v129, v129, s47, v225
	v_pk_mul_f32 v[182:183], v[128:129], v[128:129]
	v_mov_b32_dpp v177, v173 row_shr:2 row_mask:0xf bank_mask:0xf
	v_pk_fma_f32 v[226:227], v[182:183], s[34:35], v[210:211] op_sel_hi:[1,0,0] neg_lo:[1,0,0] neg_hi:[1,0,0]
	v_lshlrev_b32_e32 v176, 16, v177
	v_pk_fma_f32 v[226:227], v[182:183], v[226:227], s[38:39] op_sel_hi:[1,1,0]
	v_and_b32_e32 v177, 0xffff0000, v177
	v_pk_fma_f32 v[226:227], v[182:183], v[226:227], s[40:41] op_sel_hi:[1,1,0]
	v_pk_mul_f32 v[124:125], v[124:125], 0.5 op_sel_hi:[1,0]
	v_pk_fma_f32 v[226:227], v[182:183], v[226:227], s[42:43] op_sel_hi:[1,1,0]
	v_lshlrev_b32_e32 v126, 16, v127
	v_pk_fma_f32 v[226:227], v[182:183], v[226:227], s[44:45] op_sel_hi:[1,1,0]
	v_and_b32_e32 v127, 0xffff0000, v127
	v_pk_fma_f32 v[226:227], v[182:183], v[226:227], s[46:47] op_sel_hi:[1,1,0]
	s_nop 0
	v_pk_fma_f32 v[182:183], v[182:183], v[226:227], s[48:49] op_sel_hi:[1,1,0]
	s_nop 0
	v_pk_mul_f32 v[128:129], v[128:129], v[182:183]
	s_nop 0
	v_pk_fma_f32 v[124:125], v[124:125], v[128:129], v[124:125]
	v_pk_fma_f32 v[128:129], v[150:151], v[176:177], v[162:163]
	v_pk_mul_f32 v[120:121], v[120:121], v[124:125]
	v_lshlrev_b32_e32 v124, 16, v173
	v_and_b32_e32 v125, 0xffff0000, v173
	v_pk_fma_f32 v[126:127], v[154:155], v[126:127], v[128:129]
	v_cvt_pk_bf16_f32 v120, v120, v121
	s_nop 0
	v_pk_fma_f32 v[124:125], v[158:159], v[124:125], v[126:127]
;     static __device__ __forceinline__ u32x2 finish2(const float (&g0)[4], const float (&g1)[4], const float (&g2)[4], const float (&w0)[4], const float (&w1)[4], const float (&w2)[4], const float (&bb)[4],
;                                                     const f32x4 v, float rs) {
;         float h[4];
; #pragma unroll
;         for (int j = 0; j < 4; j += 2) {
;             const f32x2 gc = (f32x2){bb[j] + w0[j] * g2[j] + w1[j] * g1[j] + w2[j] * g0[j], bb[j + 1] + w0[j + 1] * g2[j + 1] + w1[j + 1] * g1[j + 1] + w2[j + 1] * g0[j + 1]};
;             const f32x2 ge = gelu_pk(gc) * ((f32x2){v[j], v[j + 1]} * rs); h[j] = ge.x; h[j + 1] = ge.y; }
;         u32x2 w; w.x = cvt_pk_bf16(h[0], h[1]); w.y = cvt_pk_bf16(h[2], h[3]); return w;
;     }
;     __device__ __forceinline__ void operator()(const f32x4 (&acc)[2][2][4][2], const Unit& u, int wr, int wc, int fr, int fq) const {
;         asm volatile("" : "+v"(fr), "+v"(fq));
;         const int row0 = u.rb + wr * 64 + fr;
;         const int lane = fq * 16 + fr;
;         const int s1 = fr >= 1 ? lane - 1 : lane + 15, s2 = fr >= 2 ? lane - 2 : lane + 14; (void)s1; (void)s2;
;         float rs8[2][4];
; #pragma unroll
;         for (int ai = 0; ai < 2; ++ai)
; #pragma unroll
;             for (int m = 0; m < 4; ++m) rs8[ai][m] = rsqrtf(SS[u.rb + (u.half ? 0 : ai * HALF) + wr * 64 + fr + 16 * m] * (1.f / 1024.f) + 1e-6f);
;         if (u.pm < 128) {
; #pragma unroll
;           for (int bj = 0; bj < 2; ++bj) {
;             const int col8 = u.pn * BM + bj * HALF + wc * 32 + 8 * fq;
;             float w0[2][4], w1[2][4], w2[2][4], bb[2][4];
; #pragma unroll
;             for (int hv = 0; hv < 2; ++hv) { ld4f(cw + col8 + 4 * hv, w0[hv]); ld4f(cw + 2816 + col8 + 4 * hv, w1[hv]); ld4f(cw + 2 * 2816 + col8 + 4 * hv, w2[hv]); ld4f(cb + col8 + 4 * hv, bb[hv]); }
; #pragma unroll
;             for (int ai = 0; ai < 2; ++ai) { const int R0 = u.rb + ai * HALF + wr * 64; const bf16_t* gp = G + (size_t)(R0 + fr) * 2816 + col8;
;                 u32x4 gq[4], prv = (u32x4){0u, 0u, 0u, 0u};
; #pragma unroll
;                 for (int m = 0; m < 4; ++m) gq[m] = *(const u32x4*)(gp + (size_t)m * 16 * 2816);
;                 if ((R0 & 8191) != 0) prv = *(const u32x4*)(gp - (size_t)16 * 2816);
;                 u32x4 pv = prv;
; #pragma unroll
	s_nop 0
	v_pk_mul_f32 v[126:127], v[124:125], s[30:31] op_sel_hi:[1,0]
	v_pk_mul_f32 v[124:125], v[124:125], 0.5 op_sel_hi:[1,0]
	v_med3_f32 v126, v126, s47, v225
	v_med3_f32 v127, v127, s47, v225
	v_pk_mul_f32 v[128:129], v[126:127], v[126:127]
	s_nop 0
	v_pk_fma_f32 v[176:177], v[128:129], s[34:35], v[210:211] op_sel_hi:[1,0,0] neg_lo:[1,0,0] neg_hi:[1,0,0]
	s_nop 0
	v_pk_fma_f32 v[176:177], v[128:129], v[176:177], s[38:39] op_sel_hi:[1,1,0]
	s_nop 0
	v_pk_fma_f32 v[176:177], v[128:129], v[176:177], s[40:41] op_sel_hi:[1,1,0]
	s_nop 0
	v_pk_fma_f32 v[176:177], v[128:129], v[176:177], s[42:43] op_sel_hi:[1,1,0]
	s_nop 0
	v_pk_fma_f32 v[176:177], v[128:129], v[176:177], s[44:45] op_sel_hi:[1,1,0]
	s_nop 0
	v_pk_fma_f32 v[176:177], v[128:129], v[176:177], s[46:47] op_sel_hi:[1,1,0]
	s_nop 0
	v_pk_fma_f32 v[128:129], v[128:129], v[176:177], s[48:49] op_sel_hi:[1,1,0]
	v_lshlrev_b32_e32 v176, 16, v174
	v_pk_mul_f32 v[126:127], v[126:127], v[128:129]
	v_and_b32_e32 v177, 0xffff0000, v174
	v_pk_fma_f32 v[124:125], v[124:125], v[126:127], v[124:125]
	v_mov_b32_dpp v127, v178 row_ror:2 row_mask:0xf bank_mask:0xf bound_ctrl:1
	v_pk_mul_f32 v[122:123], v[122:123], v[124:125]
	v_mov_b32_dpp v125, v179 row_ror:1 row_mask:0xf bank_mask:0xf bound_ctrl:1
	v_cvt_pk_bf16_f32 v121, v122, v123
	v_mov_b32_dpp v127, v174 row_shr:2 row_mask:0xf bank_mask:0xf
	v_mov_b32_dpp v123, v178 row_ror:1 row_mask:0xf bank_mask:0xf bound_ctrl:1
	v_lshlrev_b32_e32 v126, 16, v127
	v_and_b32_e32 v127, 0xffff0000, v127
	v_mov_b32_dpp v123, v174 row_shr:1 row_mask:0xf bank_mask:0xf
	v_lshlrev_b32_e32 v122, 16, v123
	v_and_b32_e32 v123, 0xffff0000, v123
	v_pk_fma_f32 v[126:127], v[132:133], v[126:127], v[144:145]
	v_mov_b32_dpp v129, v179 row_ror:2 row_mask:0xf bank_mask:0xf bound_ctrl:1
	v_pk_fma_f32 v[122:123], v[136:137], v[122:123], v[126:127]
	v_mov_b32_dpp v125, v175 row_shr:1 row_mask:0xf bank_mask:0xf
	v_pk_fma_f32 v[122:123], v[140:141], v[176:177], v[122:123]
	v_mov_b32_dpp v129, v175 row_shr:2 row_mask:0xf bank_mask:0xf
	v_pk_mul_f32 v[126:127], v[122:123], s[30:31] op_sel_hi:[1,0]
	v_lshlrev_b32_e32 v128, 16, v129
	v_med3_f32 v126, v126, s47, v225
	v_med3_f32 v127, v127, s47, v225
	v_pk_mul_f32 v[176:177], v[126:127], v[126:127]
	v_and_b32_e32 v129, 0xffff0000, v129
	v_pk_fma_f32 v[178:179], v[176:177], s[34:35], v[210:211] op_sel_hi:[1,0,0] neg_lo:[1,0,0] neg_hi:[1,0,0]
	v_pk_mul_f32 v[122:123], v[122:123], 0.5 op_sel_hi:[1,0]
	v_pk_fma_f32 v[178:179], v[176:177], v[178:179], s[38:39] op_sel_hi:[1,1,0]
	v_lshlrev_b32_e32 v124, 16, v125
	v_pk_fma_f32 v[178:179], v[176:177], v[178:179], s[40:41] op_sel_hi:[1,1,0]
	v_and_b32_e32 v125, 0xffff0000, v125
	v_pk_fma_f32 v[178:179], v[176:177], v[178:179], s[42:43] op_sel_hi:[1,1,0]
	s_nop 0
	v_pk_fma_f32 v[178:179], v[176:177], v[178:179], s[44:45] op_sel_hi:[1,1,0]
	s_nop 0
	v_pk_fma_f32 v[178:179], v[176:177], v[178:179], s[46:47] op_sel_hi:[1,1,0]
	s_nop 0
	v_pk_fma_f32 v[176:177], v[176:177], v[178:179], s[48:49] op_sel_hi:[1,1,0]
	s_nop 0
	v_pk_mul_f32 v[126:127], v[126:127], v[176:177]
	s_nop 0
	v_pk_fma_f32 v[122:123], v[122:123], v[126:127], v[122:123]
	v_pk_fma_f32 v[126:127], v[134:135], v[128:129], v[146:147]
	v_pk_mul_f32 v[116:117], v[116:117], v[122:123]
	v_lshlrev_b32_e32 v122, 16, v175
	v_and_b32_e32 v123, 0xffff0000, v175
	v_pk_fma_f32 v[124:125], v[138:139], v[124:125], v[126:127]
	s_nop 0
	v_pk_fma_f32 v[122:123], v[142:143], v[122:123], v[124:125]
	s_nop 0
	v_pk_mul_f32 v[124:125], v[122:123], s[30:31] op_sel_hi:[1,0]
	v_pk_mul_f32 v[122:123], v[122:123], 0.5 op_sel_hi:[1,0]
	v_med3_f32 v124, v124, s47, v225
	v_med3_f32 v125, v125, s47, v225
	v_pk_mul_f32 v[126:127], v[124:125], v[124:125]
	s_nop 0
	v_pk_fma_f32 v[128:129], v[126:127], s[34:35], v[210:211] op_sel_hi:[1,0,0] neg_lo:[1,0,0] neg_hi:[1,0,0]
	s_nop 0
	v_pk_fma_f32 v[128:129], v[126:127], v[128:129], s[38:39] op_sel_hi:[1,1,0]
	s_nop 0
	v_pk_fma_f32 v[128:129], v[126:127], v[128:129], s[40:41] op_sel_hi:[1,1,0]
	s_nop 0
	v_pk_fma_f32 v[128:129], v[126:127], v[128:129], s[42:43] op_sel_hi:[1,1,0]
	s_nop 0
	v_pk_fma_f32 v[128:129], v[126:127], v[128:129], s[44:45] op_sel_hi:[1,1,0]
	s_nop 0
	v_pk_fma_f32 v[128:129], v[126:127], v[128:129], s[46:47] op_sel_hi:[1,1,0]
	s_nop 0
	v_pk_fma_f32 v[126:127], v[126:127], v[128:129], s[48:49] op_sel_hi:[1,1,0]
	s_nop 0
	v_pk_mul_f32 v[124:125], v[124:125], v[126:127]
	v_lshlrev_b32_e32 v126, 16, v168
	v_pk_fma_f32 v[122:123], v[122:123], v[124:125], v[122:123]
	v_and_b32_e32 v127, 0xffff0000, v168
	v_pk_mul_f32 v[118:119], v[118:119], v[122:123]
	v_cvt_pk_bf16_f32 v122, v116, v117
	v_mov_b64_e32 v[116:117], s[8:9]
	v_mad_i64_i32 v[176:177], s[8:9], v194, s91, v[116:117]
	v_cvt_pk_bf16_f32 v123, v118, v119
	v_lshl_add_u64 v[118:119], v[176:177], 0, v[180:181]
	global_store_dwordx4 v[118:119], v[120:123], off
	v_mov_b32_dpp v125, v173 row_ror:2 row_mask:0xf bank_mask:0xf bound_ctrl:1
	v_mov_b32_dpp v119, v172 row_ror:1 row_mask:0xf bank_mask:0xf bound_ctrl:1
	v_mov_b32_dpp v123, v172 row_ror:2 row_mask:0xf bank_mask:0xf bound_ctrl:1
	v_mov_b32_dpp v121, v173 row_ror:1 row_mask:0xf bank_mask:0xf bound_ctrl:1
	v_mov_b32_dpp v119, v168 row_shr:1 row_mask:0xf bank_mask:0xf
	v_mov_b32_dpp v123, v168 row_shr:2 row_mask:0xf bank_mask:0xf
	v_lshlrev_b32_e32 v122, 16, v123
	v_and_b32_e32 v123, 0xffff0000, v123
	v_lshlrev_b32_e32 v118, 16, v119
	v_and_b32_e32 v119, 0xffff0000, v119
	v_pk_fma_f32 v[122:123], v[148:149], v[122:123], v[160:161]
	v_mov_b32_dpp v125, v169 row_shr:2 row_mask:0xf bank_mask:0xf
	v_pk_fma_f32 v[118:119], v[152:153], v[118:119], v[122:123]
	v_mov_b32_dpp v121, v169 row_shr:1 row_mask:0xf bank_mask:0xf
;     static __device__ __forceinline__ u32x2 finish2(const float (&g0)[4], const float (&g1)[4], const float (&g2)[4], const float (&w0)[4], const float (&w1)[4], const float (&w2)[4], const float (&bb)[4],
;                                                     const f32x4 v, float rs) {
;         float h[4];
; #pragma unroll
;         for (int j = 0; j < 4; j += 2) {
;             const f32x2 gc = (f32x2){bb[j] + w0[j] * g2[j] + w1[j] * g1[j] + w2[j] * g0[j], bb[j + 1] + w0[j + 1] * g2[j + 1] + w1[j + 1] * g1[j + 1] + w2[j + 1] * g0[j + 1]};
;             const f32x2 ge = gelu_pk(gc) * ((f32x2){v[j], v[j + 1]} * rs); h[j] = ge.x; h[j + 1] = ge.y; }
;         u32x2 w; w.x = cvt_pk_bf16(h[0], h[1]); w.y = cvt_pk_bf16(h[2], h[3]); return w;
;     }
;     __device__ __forceinline__ void operator()(const f32x4 (&acc)[2][2][4][2], const Unit& u, int wr, int wc, int fr, int fq) const {
;         asm volatile("" : "+v"(fr), "+v"(fq));
;         const int row0 = u.rb + wr * 64 + fr;
;         const int lane = fq * 16 + fr;
;         const int s1 = fr >= 1 ? lane - 1 : lane + 15, s2 = fr >= 2 ? lane - 2 : lane + 14; (void)s1; (void)s2;
;         float rs8[2][4];
; #pragma unroll
;         for (int ai = 0; ai < 2; ++ai)
; #pragma unroll
;             for (int m = 0; m < 4; ++m) rs8[ai][m] = rsqrtf(SS[u.rb + (u.half ? 0 : ai * HALF) + wr * 64 + fr + 16 * m] * (1.f / 1024.f) + 1e-6f);
;         if (u.pm < 128) {
; #pragma unroll
;           for (int bj = 0; bj < 2; ++bj) {
;             const int col8 = u.pn * BM + bj * HALF + wc * 32 + 8 * fq;
;             float w0[2][4], w1[2][4], w2[2][4], bb[2][4];
; #pragma unroll
;             for (int hv = 0; hv < 2; ++hv) { ld4f(cw + col8 + 4 * hv, w0[hv]); ld4f(cw + 2816 + col8 + 4 * hv, w1[hv]); ld4f(cw + 2 * 2816 + col8 + 4 * hv, w2[hv]); ld4f(cb + col8 + 4 * hv, bb[hv]); }
; #pragma unroll
;             for (int ai = 0; ai < 2; ++ai) { const int R0 = u.rb + ai * HALF + wr * 64; const bf16_t* gp = G + (size_t)(R0 + fr) * 2816 + col8;
;                 u32x4 gq[4], prv = (u32x4){0u, 0u, 0u, 0u};
; #pragma unroll
;                 for (int m = 0; m < 4; ++m) gq[m] = *(const u32x4*)(gp + (size_t)m * 16 * 2816);
;                 if ((R0 & 8191) != 0) prv = *(const u32x4*)(gp - (size_t)16 * 2816);
;                 u32x4 pv = prv;
; #pragma unroll
	v_pk_fma_f32 v[118:119], v[156:157], v[126:127], v[118:119]
	v_lshlrev_b32_e32 v124, 16, v125
	v_pk_mul_f32 v[122:123], v[118:119], s[30:31] op_sel_hi:[1,0]
	v_and_b32_e32 v125, 0xffff0000, v125
	v_med3_f32 v122, v122, s47, v225
	v_med3_f32 v123, v123, s47, v225
	v_pk_mul_f32 v[126:127], v[122:123], v[122:123]
	v_pk_mul_f32 v[118:119], v[118:119], 0.5 op_sel_hi:[1,0]
	v_pk_fma_f32 v[128:129], v[126:127], s[34:35], v[210:211] op_sel_hi:[1,0,0] neg_lo:[1,0,0] neg_hi:[1,0,0]
	v_lshlrev_b32_e32 v120, 16, v121
	v_pk_fma_f32 v[128:129], v[126:127], v[128:129], s[38:39] op_sel_hi:[1,1,0]
	v_and_b32_e32 v121, 0xffff0000, v121
	v_pk_fma_f32 v[128:129], v[126:127], v[128:129], s[40:41] op_sel_hi:[1,1,0]
	v_mad_i64_i32 v[172:173], s[8:9], v192, s91, v[116:117]
	v_pk_fma_f32 v[128:129], v[126:127], v[128:129], s[42:43] op_sel_hi:[1,1,0]
	s_nop 0
	v_pk_fma_f32 v[128:129], v[126:127], v[128:129], s[44:45] op_sel_hi:[1,1,0]
	s_nop 0
	v_pk_fma_f32 v[128:129], v[126:127], v[128:129], s[46:47] op_sel_hi:[1,1,0]
	s_nop 0
	v_pk_fma_f32 v[126:127], v[126:127], v[128:129], s[48:49] op_sel_hi:[1,1,0]
	s_nop 0
	v_pk_mul_f32 v[122:123], v[122:123], v[126:127]
	s_nop 0
	v_pk_fma_f32 v[118:119], v[118:119], v[122:123], v[118:119]
	v_pk_fma_f32 v[122:123], v[150:151], v[124:125], v[162:163]
	v_pk_mul_f32 v[112:113], v[112:113], v[118:119]
	v_lshlrev_b32_e32 v118, 16, v169
	v_and_b32_e32 v119, 0xffff0000, v169
	v_pk_fma_f32 v[120:121], v[154:155], v[120:121], v[122:123]
	v_cvt_pk_bf16_f32 v112, v112, v113
	s_nop 0
	v_pk_fma_f32 v[118:119], v[158:159], v[118:119], v[120:121]
	s_nop 0
	v_pk_mul_f32 v[120:121], v[118:119], s[30:31] op_sel_hi:[1,0]
	v_pk_mul_f32 v[118:119], v[118:119], 0.5 op_sel_hi:[1,0]
	v_med3_f32 v120, v120, s47, v225
	v_med3_f32 v121, v121, s47, v225
	v_pk_mul_f32 v[122:123], v[120:121], v[120:121]
	s_nop 0
	v_pk_fma_f32 v[124:125], v[122:123], s[34:35], v[210:211] op_sel_hi:[1,0,0] neg_lo:[1,0,0] neg_hi:[1,0,0]
	s_nop 0
	v_pk_fma_f32 v[124:125], v[122:123], v[124:125], s[38:39] op_sel_hi:[1,1,0]
	s_nop 0
	v_pk_fma_f32 v[124:125], v[122:123], v[124:125], s[40:41] op_sel_hi:[1,1,0]
	s_nop 0
	v_pk_fma_f32 v[124:125], v[122:123], v[124:125], s[42:43] op_sel_hi:[1,1,0]
	s_nop 0
	v_pk_fma_f32 v[124:125], v[122:123], v[124:125], s[44:45] op_sel_hi:[1,1,0]
	s_nop 0
	v_pk_fma_f32 v[124:125], v[122:123], v[124:125], s[46:47] op_sel_hi:[1,1,0]
	s_nop 0
	v_pk_fma_f32 v[122:123], v[122:123], v[124:125], s[48:49] op_sel_hi:[1,1,0]
	v_lshlrev_b32_e32 v124, 16, v170
	v_pk_mul_f32 v[120:121], v[120:121], v[122:123]
	v_and_b32_e32 v125, 0xffff0000, v170
	v_pk_fma_f32 v[118:119], v[118:119], v[120:121], v[118:119]
	v_mov_b32_dpp v121, v174 row_ror:2 row_mask:0xf bank_mask:0xf bound_ctrl:1
	v_pk_mul_f32 v[114:115], v[114:115], v[118:119]
	v_mov_b32_dpp v123, v175 row_ror:2 row_mask:0xf bank_mask:0xf bound_ctrl:1
	v_cvt_pk_bf16_f32 v113, v114, v115
	v_mov_b32_dpp v121, v170 row_shr:2 row_mask:0xf bank_mask:0xf
	v_mov_b32_dpp v115, v174 row_ror:1 row_mask:0xf bank_mask:0xf bound_ctrl:1
	v_lshlrev_b32_e32 v120, 16, v121
	v_and_b32_e32 v121, 0xffff0000, v121
	v_mov_b32_dpp v115, v170 row_shr:1 row_mask:0xf bank_mask:0xf
	v_lshlrev_b32_e32 v114, 16, v115
	v_and_b32_e32 v115, 0xffff0000, v115
	v_pk_fma_f32 v[120:121], v[132:133], v[120:121], v[144:145]
	v_mov_b32_dpp v119, v175 row_ror:1 row_mask:0xf bank_mask:0xf bound_ctrl:1
	v_pk_fma_f32 v[114:115], v[136:137], v[114:115], v[120:121]
	v_mov_b32_dpp v123, v171 row_shr:2 row_mask:0xf bank_mask:0xf
	v_pk_fma_f32 v[114:115], v[140:141], v[124:125], v[114:115]
	v_mov_b32_dpp v119, v171 row_shr:1 row_mask:0xf bank_mask:0xf
	v_pk_mul_f32 v[120:121], v[114:115], s[30:31] op_sel_hi:[1,0]
	v_lshlrev_b32_e32 v122, 16, v123
	v_med3_f32 v120, v120, s47, v225
	v_med3_f32 v121, v121, s47, v225
	v_pk_mul_f32 v[124:125], v[120:121], v[120:121]
	v_and_b32_e32 v123, 0xffff0000, v123
	v_pk_fma_f32 v[126:127], v[124:125], s[34:35], v[210:211] op_sel_hi:[1,0,0] neg_lo:[1,0,0] neg_hi:[1,0,0]
	v_pk_mul_f32 v[114:115], v[114:115], 0.5 op_sel_hi:[1,0]
	v_pk_fma_f32 v[126:127], v[124:125], v[126:127], s[38:39] op_sel_hi:[1,1,0]
	v_lshlrev_b32_e32 v118, 16, v119
	v_pk_fma_f32 v[126:127], v[124:125], v[126:127], s[40:41] op_sel_hi:[1,1,0]
	v_and_b32_e32 v119, 0xffff0000, v119
	v_pk_fma_f32 v[126:127], v[124:125], v[126:127], s[42:43] op_sel_hi:[1,1,0]
	s_nop 0
	v_pk_fma_f32 v[126:127], v[124:125], v[126:127], s[44:45] op_sel_hi:[1,1,0]
	s_nop 0
	v_pk_fma_f32 v[126:127], v[124:125], v[126:127], s[46:47] op_sel_hi:[1,1,0]
	s_nop 0
	v_pk_fma_f32 v[124:125], v[124:125], v[126:127], s[48:49] op_sel_hi:[1,1,0]
	s_nop 0
	v_pk_mul_f32 v[120:121], v[120:121], v[124:125]
	s_nop 0
	v_pk_fma_f32 v[114:115], v[114:115], v[120:121], v[114:115]
	v_pk_fma_f32 v[120:121], v[134:135], v[122:123], v[146:147]
	v_pk_mul_f32 v[108:109], v[108:109], v[114:115]
	v_lshlrev_b32_e32 v114, 16, v171
	v_and_b32_e32 v115, 0xffff0000, v171
	v_pk_fma_f32 v[118:119], v[138:139], v[118:119], v[120:121]
	s_nop 0
	v_pk_fma_f32 v[114:115], v[142:143], v[114:115], v[118:119]
	s_nop 0
	v_pk_mul_f32 v[118:119], v[114:115], s[30:31] op_sel_hi:[1,0]
	v_pk_mul_f32 v[114:115], v[114:115], 0.5 op_sel_hi:[1,0]
	v_med3_f32 v118, v118, s47, v225
	v_med3_f32 v119, v119, s47, v225
	v_pk_mul_f32 v[120:121], v[118:119], v[118:119]
	s_nop 0
	v_pk_fma_f32 v[122:123], v[120:121], s[34:35], v[210:211] op_sel_hi:[1,0,0] neg_lo:[1,0,0] neg_hi:[1,0,0]
	s_nop 0
	v_pk_fma_f32 v[122:123], v[120:121], v[122:123], s[38:39] op_sel_hi:[1,1,0]
	s_nop 0
	v_pk_fma_f32 v[122:123], v[120:121], v[122:123], s[40:41] op_sel_hi:[1,1,0]
	s_nop 0
	v_pk_fma_f32 v[122:123], v[120:121], v[122:123], s[42:43] op_sel_hi:[1,1,0]
;     static __device__ __forceinline__ u32x2 finish2(const float (&g0)[4], const float (&g1)[4], const float (&g2)[4], const float (&w0)[4], const float (&w1)[4], const float (&w2)[4], const float (&bb)[4],
;                                                     const f32x4 v, float rs) {
;         float h[4];
; #pragma unroll
;         for (int j = 0; j < 4; j += 2) {
;             const f32x2 gc = (f32x2){bb[j] + w0[j] * g2[j] + w1[j] * g1[j] + w2[j] * g0[j], bb[j + 1] + w0[j + 1] * g2[j + 1] + w1[j + 1] * g1[j + 1] + w2[j + 1] * g0[j + 1]};
;             const f32x2 ge = gelu_pk(gc) * ((f32x2){v[j], v[j + 1]} * rs); h[j] = ge.x; h[j + 1] = ge.y; }
;         u32x2 w; w.x = cvt_pk_bf16(h[0], h[1]); w.y = cvt_pk_bf16(h[2], h[3]); return w;
;     }
;     __device__ __forceinline__ void operator()(const f32x4 (&acc)[2][2][4][2], const Unit& u, int wr, int wc, int fr, int fq) const {
;         asm volatile("" : "+v"(fr), "+v"(fq));
;         const int row0 = u.rb + wr * 64 + fr;
;         const int lane = fq * 16 + fr;
;         const int s1 = fr >= 1 ? lane - 1 : lane + 15, s2 = fr >= 2 ? lane - 2 : lane + 14; (void)s1; (void)s2;
;         float rs8[2][4];
; #pragma unroll
;         for (int ai = 0; ai < 2; ++ai)
; #pragma unroll
;             for (int m = 0; m < 4; ++m) rs8[ai][m] = rsqrtf(SS[u.rb + (u.half ? 0 : ai * HALF) + wr * 64 + fr + 16 * m] * (1.f / 1024.f) + 1e-6f);
;         if (u.pm < 128) {
; #pragma unroll
;           for (int bj = 0; bj < 2; ++bj) {
;             const int col8 = u.pn * BM + bj * HALF + wc * 32 + 8 * fq;
;             float w0[2][4], w1[2][4], w2[2][4], bb[2][4];
; #pragma unroll
;             for (int hv = 0; hv < 2; ++hv) { ld4f(cw + col8 + 4 * hv, w0[hv]); ld4f(cw + 2816 + col8 + 4 * hv, w1[hv]); ld4f(cw + 2 * 2816 + col8 + 4 * hv, w2[hv]); ld4f(cb + col8 + 4 * hv, bb[hv]); }
; #pragma unroll
;             for (int ai = 0; ai < 2; ++ai) { const int R0 = u.rb + ai * HALF + wr * 64; const bf16_t* gp = G + (size_t)(R0 + fr) * 2816 + col8;
;                 u32x4 gq[4], prv = (u32x4){0u, 0u, 0u, 0u};
; #pragma unroll
;                 for (int m = 0; m < 4; ++m) gq[m] = *(const u32x4*)(gp + (size_t)m * 16 * 2816);
;                 if ((R0 & 8191) != 0) prv = *(const u32x4*)(gp - (size_t)16 * 2816);
;                 u32x4 pv = prv;
; #pragma unroll
	s_nop 0
	v_pk_fma_f32 v[122:123], v[120:121], v[122:123], s[44:45] op_sel_hi:[1,1,0]
	s_nop 0
	v_pk_fma_f32 v[122:123], v[120:121], v[122:123], s[46:47] op_sel_hi:[1,1,0]
	s_nop 0
	v_pk_fma_f32 v[120:121], v[120:121], v[122:123], s[48:49] op_sel_hi:[1,1,0]
	s_nop 0
	v_pk_mul_f32 v[118:119], v[118:119], v[120:121]
	s_nop 0
	v_pk_fma_f32 v[114:115], v[114:115], v[118:119], v[114:115]
	v_lshlrev_b32_e32 v118, 16, v164
	v_pk_mul_f32 v[110:111], v[110:111], v[114:115]
	v_cvt_pk_bf16_f32 v114, v108, v109
	v_lshl_add_u64 v[108:109], v[172:173], 0, v[180:181]
	v_cvt_pk_bf16_f32 v115, v110, v111
	global_store_dwordx4 v[108:109], v[112:115], off
	v_and_b32_e32 v119, 0xffff0000, v164
	v_mov_b32_dpp v109, v168 row_ror:1 row_mask:0xf bank_mask:0xf bound_ctrl:1
	v_mov_b32_dpp v113, v168 row_ror:2 row_mask:0xf bank_mask:0xf bound_ctrl:1
	v_mov_b32_dpp v115, v169 row_ror:2 row_mask:0xf bank_mask:0xf bound_ctrl:1
	v_mov_b32_dpp v109, v164 row_shr:1 row_mask:0xf bank_mask:0xf
	v_mov_b32_dpp v113, v164 row_shr:2 row_mask:0xf bank_mask:0xf
	v_lshlrev_b32_e32 v112, 16, v113
	v_and_b32_e32 v113, 0xffff0000, v113
	v_lshlrev_b32_e32 v108, 16, v109
	v_and_b32_e32 v109, 0xffff0000, v109
	v_pk_fma_f32 v[112:113], v[148:149], v[112:113], v[160:161]
	v_mov_b32_dpp v111, v169 row_ror:1 row_mask:0xf bank_mask:0xf bound_ctrl:1
	v_pk_fma_f32 v[108:109], v[152:153], v[108:109], v[112:113]
	v_mov_b32_dpp v115, v165 row_shr:2 row_mask:0xf bank_mask:0xf
	v_pk_fma_f32 v[108:109], v[156:157], v[118:119], v[108:109]
	v_mov_b32_dpp v111, v165 row_shr:1 row_mask:0xf bank_mask:0xf
	v_pk_mul_f32 v[112:113], v[108:109], s[30:31] op_sel_hi:[1,0]
	v_lshlrev_b32_e32 v114, 16, v115
	v_med3_f32 v112, v112, s47, v225
	v_med3_f32 v113, v113, s47, v225
	v_pk_mul_f32 v[118:119], v[112:113], v[112:113]
	v_and_b32_e32 v115, 0xffff0000, v115
	v_pk_fma_f32 v[120:121], v[118:119], s[34:35], v[210:211] op_sel_hi:[1,0,0] neg_lo:[1,0,0] neg_hi:[1,0,0]
	v_pk_mul_f32 v[108:109], v[108:109], 0.5 op_sel_hi:[1,0]
	v_pk_fma_f32 v[120:121], v[118:119], v[120:121], s[38:39] op_sel_hi:[1,1,0]
	v_lshlrev_b32_e32 v110, 16, v111
	v_pk_fma_f32 v[120:121], v[118:119], v[120:121], s[40:41] op_sel_hi:[1,1,0]
	v_and_b32_e32 v111, 0xffff0000, v111
	v_pk_fma_f32 v[120:121], v[118:119], v[120:121], s[42:43] op_sel_hi:[1,1,0]
	s_nop 0
	v_pk_fma_f32 v[120:121], v[118:119], v[120:121], s[44:45] op_sel_hi:[1,1,0]
	s_nop 0
	v_pk_fma_f32 v[120:121], v[118:119], v[120:121], s[46:47] op_sel_hi:[1,1,0]
	s_nop 0
	v_pk_fma_f32 v[118:119], v[118:119], v[120:121], s[48:49] op_sel_hi:[1,1,0]
	s_nop 0
	v_pk_mul_f32 v[112:113], v[112:113], v[118:119]
	s_nop 0
	v_pk_fma_f32 v[108:109], v[108:109], v[112:113], v[108:109]
	v_pk_fma_f32 v[112:113], v[150:151], v[114:115], v[162:163]
	v_pk_mul_f32 v[104:105], v[104:105], v[108:109]
	v_lshlrev_b32_e32 v108, 16, v165
	v_and_b32_e32 v109, 0xffff0000, v165
	v_pk_fma_f32 v[110:111], v[154:155], v[110:111], v[112:113]
	v_cvt_pk_bf16_f32 v120, v104, v105
	v_mov_b32_dpp v105, v170 row_ror:1 row_mask:0xf bank_mask:0xf bound_ctrl:1
	v_pk_fma_f32 v[108:109], v[158:159], v[108:109], v[110:111]
	s_nop 0
	v_pk_mul_f32 v[110:111], v[108:109], s[30:31] op_sel_hi:[1,0]
	v_pk_mul_f32 v[108:109], v[108:109], 0.5 op_sel_hi:[1,0]
	v_med3_f32 v110, v110, s47, v225
	v_med3_f32 v111, v111, s47, v225
	v_pk_mul_f32 v[112:113], v[110:111], v[110:111]
	v_mov_b32_dpp v105, v166 row_shr:1 row_mask:0xf bank_mask:0xf
	v_pk_fma_f32 v[114:115], v[112:113], s[34:35], v[210:211] op_sel_hi:[1,0,0] neg_lo:[1,0,0] neg_hi:[1,0,0]
	v_lshlrev_b32_e32 v104, 16, v105
	v_pk_fma_f32 v[114:115], v[112:113], v[114:115], s[38:39] op_sel_hi:[1,1,0]
	v_and_b32_e32 v105, 0xffff0000, v105
	v_pk_fma_f32 v[114:115], v[112:113], v[114:115], s[40:41] op_sel_hi:[1,1,0]
	s_nop 0
	v_pk_fma_f32 v[114:115], v[112:113], v[114:115], s[42:43] op_sel_hi:[1,1,0]
	s_nop 0
	v_pk_fma_f32 v[114:115], v[112:113], v[114:115], s[44:45] op_sel_hi:[1,1,0]
	s_nop 0
	v_pk_fma_f32 v[114:115], v[112:113], v[114:115], s[46:47] op_sel_hi:[1,1,0]
	s_nop 0
	v_pk_fma_f32 v[112:113], v[112:113], v[114:115], s[48:49] op_sel_hi:[1,1,0]
	s_nop 0
	v_pk_mul_f32 v[110:111], v[110:111], v[112:113]
	v_lshlrev_b32_e32 v112, 16, v166
	v_pk_fma_f32 v[108:109], v[108:109], v[110:111], v[108:109]
	v_and_b32_e32 v113, 0xffff0000, v166
;     static __device__ __forceinline__ void unpk4(const u32x2 w, float (&o)[4]) { o[0] = bf_lo(w.x); o[1] = bf_hi(w.x); o[2] = bf_lo(w.y); o[3] = bf_hi(w.y); }
;     template <int N> static __device__ __forceinline__ u32x2 dpp_prev(const u32x2 pv, const u32x2 cur) { u32x2 r; r.x = dpp_prev1<N>(pv.x, cur.x); r.y = dpp_prev1<N>(pv.y, cur.y); return r; }
;     __device__ __forceinline__ void operator()(const f32x4 (&acc)[2][2][4][2], const Unit& u, int wr, int wc, int fr, int fq) const {
;     ...
;             for (int ai = 0; ai < 2; ++ai) { const int R0 = u.rb + ai * HALF + wr * 64; const bf16_t* gp = G + (size_t)(R0 + fr) * 2816 + col8;
;                 u32x4 gq[4], prv = (u32x4){0u, 0u, 0u, 0u};
; #pragma unroll
;                 for (int m = 0; m < 4; ++m) gq[m] = *(const u32x4*)(gp + (size_t)m * 16 * 2816);
;                 if ((R0 & 8191) != 0) prv = *(const u32x4*)(gp - (size_t)16 * 2816);
;                 u32x4 pv = prv;
; #pragma unroll
;                 for (int m = 0; m < 4; ++m) { const u32x4 cur = gq[m]; u32x4 hw;
; #pragma unroll
;                     for (int hv = 0; hv < 2; ++hv) { const u32x2 c2 = half2(cur, hv), p2 = half2(pv, hv);
;                         const u32x2 q1 = dpp_prev<1>(p2, c2), q2 = dpp_prev<2>(p2, c2);
;                         float g0[4], g1[4], g2[4]; unpk4(c2, g0); unpk4(q1, g1); unpk4(q2, g2);
;                         const u32x2 r = finish2(g0, g1, g2, w0[hv], w1[hv], w2[hv], bb[hv], acc[ai][bj][m][hv], rs8[ai][m]);
;                         if (hv == 0) { hw.x = r.x; hw.y = r.y; } else { hw.z = r.x; hw.w = r.y; } }
;                     *(u32x4*)(H + (size_t)(R0 + fr + 16 * m) * 2816 + col8) = hw;
;                     pv = cur; } }
	v_pk_mul_f32 v[106:107], v[106:107], v[108:109]
	v_mov_b32_dpp v109, v170 row_ror:2 row_mask:0xf bank_mask:0xf bound_ctrl:1
	v_mov_b32_dpp v111, v171 row_ror:2 row_mask:0xf bank_mask:0xf bound_ctrl:1
	v_cvt_pk_bf16_f32 v121, v106, v107
	v_mov_b32_dpp v107, v171 row_ror:1 row_mask:0xf bank_mask:0xf bound_ctrl:1
	v_mov_b32_dpp v109, v166 row_shr:2 row_mask:0xf bank_mask:0xf
	v_lshlrev_b32_e32 v108, 16, v109
	v_and_b32_e32 v109, 0xffff0000, v109
	v_pk_fma_f32 v[108:109], v[132:133], v[108:109], v[144:145]
	v_mov_b32_dpp v111, v167 row_shr:2 row_mask:0xf bank_mask:0xf
	v_pk_fma_f32 v[104:105], v[136:137], v[104:105], v[108:109]
	v_mov_b32_dpp v107, v167 row_shr:1 row_mask:0xf bank_mask:0xf
	v_pk_fma_f32 v[104:105], v[140:141], v[112:113], v[104:105]
	v_lshlrev_b32_e32 v110, 16, v111
	v_pk_mul_f32 v[108:109], v[104:105], s[30:31] op_sel_hi:[1,0]
	v_and_b32_e32 v111, 0xffff0000, v111
	v_med3_f32 v108, v108, s47, v225
	v_med3_f32 v109, v109, s47, v225
	v_pk_mul_f32 v[112:113], v[108:109], v[108:109]
	v_pk_mul_f32 v[104:105], v[104:105], 0.5 op_sel_hi:[1,0]
	v_pk_fma_f32 v[114:115], v[112:113], s[34:35], v[210:211] op_sel_hi:[1,0,0] neg_lo:[1,0,0] neg_hi:[1,0,0]
	v_lshlrev_b32_e32 v106, 16, v107
	v_pk_fma_f32 v[114:115], v[112:113], v[114:115], s[38:39] op_sel_hi:[1,1,0]
	v_and_b32_e32 v107, 0xffff0000, v107
	v_pk_fma_f32 v[114:115], v[112:113], v[114:115], s[40:41] op_sel_hi:[1,1,0]
	s_nop 0
	v_pk_fma_f32 v[114:115], v[112:113], v[114:115], s[42:43] op_sel_hi:[1,1,0]
	s_nop 0
	v_pk_fma_f32 v[114:115], v[112:113], v[114:115], s[44:45] op_sel_hi:[1,1,0]
	s_nop 0
	v_pk_fma_f32 v[114:115], v[112:113], v[114:115], s[46:47] op_sel_hi:[1,1,0]
	s_nop 0
	v_pk_fma_f32 v[112:113], v[112:113], v[114:115], s[48:49] op_sel_hi:[1,1,0]
	s_nop 0
	v_pk_mul_f32 v[108:109], v[108:109], v[112:113]
	s_nop 0
	v_pk_fma_f32 v[104:105], v[104:105], v[108:109], v[104:105]
	v_pk_fma_f32 v[108:109], v[134:135], v[110:111], v[146:147]
	v_pk_mul_f32 v[100:101], v[100:101], v[104:105]
	v_lshlrev_b32_e32 v104, 16, v167
	v_and_b32_e32 v105, 0xffff0000, v167
	v_pk_fma_f32 v[106:107], v[138:139], v[106:107], v[108:109]
	v_cvt_pk_bf16_f32 v122, v100, v101
	v_mov_b64_e32 v[100:101], s[2:3]
	v_pk_fma_f32 v[104:105], v[142:143], v[104:105], v[106:107]
	v_mad_i64_i32 v[164:165], s[2:3], v1, s91, v[100:101]
	v_pk_mul_f32 v[106:107], v[104:105], s[30:31] op_sel_hi:[1,0]
	v_lshl_add_u64 v[118:119], v[164:165], 0, v[180:181]
	v_med3_f32 v106, v106, s47, v225
	v_med3_f32 v107, v107, s47, v225
	v_pk_mul_f32 v[108:109], v[106:107], v[106:107]
	v_pk_mul_f32 v[104:105], v[104:105], 0.5 op_sel_hi:[1,0]
	v_pk_fma_f32 v[110:111], v[108:109], s[34:35], v[210:211] op_sel_hi:[1,0,0] neg_lo:[1,0,0] neg_hi:[1,0,0]
	v_add_co_u32_e32 v100, vcc, s10, v118
	v_pk_fma_f32 v[110:111], v[108:109], v[110:111], s[38:39] op_sel_hi:[1,1,0]
	s_nop 0
	v_addc_co_u32_e32 v101, vcc, 0, v119, vcc
	v_pk_fma_f32 v[110:111], v[108:109], v[110:111], s[40:41] op_sel_hi:[1,1,0]
	v_mad_i64_i32 v[166:167], s[2:3], v190, s91, v[116:117]
	v_pk_fma_f32 v[110:111], v[108:109], v[110:111], s[42:43] op_sel_hi:[1,1,0]
	v_lshl_add_u64 v[116:117], v[166:167], 0, v[180:181]
	v_pk_fma_f32 v[110:111], v[108:109], v[110:111], s[44:45] op_sel_hi:[1,1,0]
	s_cselect_b64 s[2:3], -1, 0
	v_pk_fma_f32 v[110:111], v[108:109], v[110:111], s[46:47] op_sel_hi:[1,1,0]
	s_cmp_eq_u32 s7, 0
	v_pk_fma_f32 v[108:109], v[108:109], v[110:111], s[48:49] op_sel_hi:[1,1,0]
	s_nop 0
	v_pk_mul_f32 v[106:107], v[106:107], v[108:109]
	s_nop 0
	v_pk_fma_f32 v[104:105], v[104:105], v[106:107], v[104:105]
	s_nop 0
	v_pk_mul_f32 v[102:103], v[102:103], v[104:105]
	s_nop 0
	v_cvt_pk_bf16_f32 v123, v102, v103
	global_load_dwordx4 v[112:115], v[118:119], off
	global_load_dwordx4 v[108:111], v[100:101], off
	v_add_co_u32_e32 v100, vcc, 0x2c000, v118
	s_nop 1
	v_addc_co_u32_e32 v101, vcc, 0, v119, vcc
	v_add_co_u32_e32 v102, vcc, 0x42000, v118
	s_nop 1
	v_addc_co_u32_e32 v103, vcc, 0, v119, vcc
	global_load_dwordx4 v[104:107], v[100:101], off
	s_nop 0
	global_load_dwordx4 v[100:103], v[102:103], off
	s_nop 0
	global_store_dwordx4 v[116:117], v[120:123], off
	s_cbranch_scc1 .LBB0_1015
	v_add_co_u32_e32 v116, vcc, 0xfffea000, v118
	s_nop 1
	v_addc_co_u32_e32 v117, vcc, -1, v119, vcc
	global_load_dwordx4 v[116:119], v[116:117], off
	s_branch .LBB0_1016

;     static __device__ __forceinline__ void unpk4(const u32x2 w, float (&o)[4]) { o[0] = bf_lo(w.x); o[1] = bf_hi(w.x); o[2] = bf_lo(w.y); o[3] = bf_hi(w.y); }
;     template <int N> static __device__ __forceinline__ u32x2 dpp_prev(const u32x2 pv, const u32x2 cur) { u32x2 r; r.x = dpp_prev1<N>(pv.x, cur.x); r.y = dpp_prev1<N>(pv.y, cur.y); return r; }
;     __device__ __forceinline__ void operator()(const f32x4 (&acc)[2][2][4][2], const Unit& u, int wr, int wc, int fr, int fq) const {
;     ...
;             for (int m = 0; m < 4; ++m) rs8[ai][m] = rsqrtf(SS[u.rb + (u.half ? 0 : ai * HALF) + wr * 64 + fr + 16 * m] * (1.f / 1024.f) + 1e-6f);
;     ...
;                 for (int m = 0; m < 4; ++m) { const u32x4 cur = gq[m]; u32x4 hw;
; #pragma unroll
;                     for (int hv = 0; hv < 2; ++hv) { const u32x2 c2 = half2(cur, hv), p2 = half2(pv, hv);
;                         const u32x2 q1 = dpp_prev<1>(p2, c2), q2 = dpp_prev<2>(p2, c2);
;                         float g0[4], g1[4], g2[4]; unpk4(c2, g0); unpk4(q1, g1); unpk4(q2, g2);
;                         const u32x2 r = finish2(g0, g1, g2, w0[hv], w1[hv], w2[hv], bb[hv], acc[ai][bj][m][hv], rs8[ai][m]);
;                         if (hv == 0) { hw.x = r.x; hw.y = r.y; } else { hw.z = r.x; hw.w = r.y; } }
;                     *(u32x4*)(H + (size_t)(R0 + fr + 16 * m) * 2816 + col8) = hw;
.LBB0_1016:
	v_fmamk_f32 v122, v189, 0x3a800000, v224
	v_cmp_gt_f32_e32 vcc, s5, v122
	v_mul_f32_e32 v123, 0x4b800000, v122
	v_fmamk_f32 v3, v3, 0x3a800000, v224
	v_cndmask_b32_e32 v122, v122, v123, vcc
	v_rsq_f32_e32 v122, v122
	s_waitcnt vmcnt(0)
	v_mov_b32_dpp v125, v116 row_ror:2 row_mask:0xf bank_mask:0xf bound_ctrl:1
	v_mov_b32_dpp v127, v117 row_ror:2 row_mask:0xf bank_mask:0xf bound_ctrl:1
	v_lshlrev_b32_e32 v178, 16, v112
	v_mul_f32_e32 v123, 0x45800000, v122
	v_cndmask_b32_e32 v128, v122, v123, vcc
	v_fmamk_f32 v122, v187, 0x3a800000, v224
	v_cmp_gt_f32_e32 vcc, s5, v122
	v_mul_f32_e32 v123, 0x4b800000, v122
	v_mov_b32_dpp v125, v112 row_shr:2 row_mask:0xf bank_mask:0xf
	v_cndmask_b32_e32 v122, v122, v123, vcc
	v_rsq_f32_e32 v122, v122
	v_lshlrev_b32_e32 v170, 16, v125
	v_and_b32_e32 v171, 0xffff0000, v125
	v_pk_fma_f32 v[170:171], v[148:149], v[170:171], v[160:161]
	v_mul_f32_e32 v123, 0x45800000, v122
	v_cndmask_b32_e32 v126, v122, v123, vcc
	v_cmp_gt_f32_e32 vcc, s5, v3
	v_mul_f32_e32 v122, 0x4b800000, v3
	v_mov_b32_dpp v123, v117 row_ror:1 row_mask:0xf bank_mask:0xf bound_ctrl:1
	v_cndmask_b32_e32 v3, v3, v122, vcc
	v_rsq_f32_e32 v3, v3
	v_and_b32_e32 v179, 0xffff0000, v112
	v_mov_b32_dpp v127, v113 row_shr:2 row_mask:0xf bank_mask:0xf
	v_mov_b32_dpp v123, v113 row_shr:1 row_mask:0xf bank_mask:0xf
	v_mul_f32_e32 v122, 0x45800000, v3
	v_cndmask_b32_e32 v124, v3, v122, vcc
	v_fmamk_f32 v3, v185, 0x3a800000, v224
	v_cmp_gt_f32_e32 vcc, s5, v3
	v_mul_f32_e32 v122, 0x4b800000, v3
	v_lshlrev_b32_e32 v174, 16, v127
	v_cndmask_b32_e32 v3, v3, v122, vcc
	v_rsq_f32_e32 v3, v3
	v_and_b32_e32 v175, 0xffff0000, v127
	v_lshlrev_b32_e32 v168, 16, v123
	v_and_b32_e32 v169, 0xffff0000, v123
	v_mul_f32_e32 v122, 0x45800000, v3
	v_cndmask_b32_e32 v122, v3, v122, vcc
	v_mov_b32_dpp v3, v116 row_ror:1 row_mask:0xf bank_mask:0xf bound_ctrl:1
	v_pk_mul_f32 v[96:97], v[96:97], v[128:129] op_sel_hi:[1,0]
	v_pk_fma_f32 v[174:175], v[150:151], v[174:175], v[162:163]
	v_mov_b32_dpp v3, v112 row_shr:1 row_mask:0xf bank_mask:0xf
	v_lshlrev_b32_e32 v116, 16, v3
	v_and_b32_e32 v117, 0xffff0000, v3
	v_pk_fma_f32 v[116:117], v[152:153], v[116:117], v[170:171]
	v_pk_fma_f32 v[168:169], v[154:155], v[168:169], v[174:175]
	v_pk_fma_f32 v[170:171], v[156:157], v[178:179], v[116:117]
	v_mov_b32_dpp v125, v118 row_ror:2 row_mask:0xf bank_mask:0xf bound_ctrl:1
	v_pk_mul_f32 v[116:117], v[170:171], s[30:31] op_sel_hi:[1,0]
	v_pk_mul_f32 v[170:171], v[170:171], 0.5 op_sel_hi:[1,0]
	v_med3_f32 v178, v116, s47, v225
	v_med3_f32 v179, v117, s47, v225
	v_pk_mul_f32 v[182:183], v[178:179], v[178:179]
	v_mov_b64_e32 v[116:117], s[36:37]
	v_pk_fma_f32 v[190:191], v[182:183], s[34:35], v[116:117] op_sel_hi:[1,0,0] neg_lo:[1,0,0] neg_hi:[1,0,0]
	v_pk_mul_f32 v[98:99], v[98:99], v[128:129] op_sel_hi:[1,0]
	v_pk_fma_f32 v[190:191], v[182:183], v[190:191], s[38:39] op_sel_hi:[1,1,0]
	v_mov_b32_dpp v3, v118 row_ror:1 row_mask:0xf bank_mask:0xf bound_ctrl:1
	v_pk_fma_f32 v[190:191], v[182:183], v[190:191], s[40:41] op_sel_hi:[1,1,0]
	v_mov_b32_dpp v125, v114 row_shr:2 row_mask:0xf bank_mask:0xf
	v_pk_fma_f32 v[190:191], v[182:183], v[190:191], s[42:43] op_sel_hi:[1,1,0]
	v_mov_b32_dpp v3, v114 row_shr:1 row_mask:0xf bank_mask:0xf
	v_pk_fma_f32 v[190:191], v[182:183], v[190:191], s[44:45] op_sel_hi:[1,1,0]
	v_mov_b32_dpp v127, v119 row_ror:2 row_mask:0xf bank_mask:0xf bound_ctrl:1
	v_pk_fma_f32 v[190:191], v[182:183], v[190:191], s[46:47] op_sel_hi:[1,1,0]
	v_mov_b32_dpp v123, v119 row_ror:1 row_mask:0xf bank_mask:0xf bound_ctrl:1
	v_pk_fma_f32 v[182:183], v[182:183], v[190:191], s[48:49] op_sel_hi:[1,1,0]
	v_mov_b32_dpp v127, v115 row_shr:2 row_mask:0xf bank_mask:0xf
	v_pk_mul_f32 v[178:179], v[178:179], v[182:183]
	v_mov_b32_dpp v123, v115 row_shr:1 row_mask:0xf bank_mask:0xf
	v_pk_fma_f32 v[170:171], v[170:171], v[178:179], v[170:171]
	v_lshlrev_b32_e32 v118, 16, v123
	v_pk_mul_f32 v[96:97], v[96:97], v[170:171]
	v_lshlrev_b32_e32 v170, 16, v113
	v_and_b32_e32 v171, 0xffff0000, v113
	v_pk_fma_f32 v[168:169], v[158:159], v[170:171], v[168:169]
	v_cvt_pk_bf16_f32 v96, v96, v97
	v_and_b32_e32 v119, 0xffff0000, v123
	v_pk_mul_f32 v[170:171], v[168:169], s[30:31] op_sel_hi:[1,0]
	v_pk_mul_f32 v[168:169], v[168:169], 0.5 op_sel_hi:[1,0]
	v_med3_f32 v170, v170, s47, v225
	v_med3_f32 v171, v171, s47, v225
	v_pk_mul_f32 v[174:175], v[170:171], v[170:171]
	v_pk_mul_f32 v[92:93], v[92:93], v[128:129] op_sel_hi:[1,0]
	v_pk_fma_f32 v[178:179], v[174:175], s[34:35], v[116:117] op_sel_hi:[1,0,0] neg_lo:[1,0,0] neg_hi:[1,0,0]
	v_mad_i64_i32 v[120:121], s[8:9], v1, s91, 0
	v_pk_fma_f32 v[178:179], v[174:175], v[178:179], s[38:39] op_sel_hi:[1,1,0]
	v_readlane_b32 s8, v240, 58
	v_pk_fma_f32 v[178:179], v[174:175], v[178:179], s[40:41] op_sel_hi:[1,1,0]
	v_readlane_b32 s9, v240, 59
	v_pk_fma_f32 v[178:179], v[174:175], v[178:179], s[42:43] op_sel_hi:[1,1,0]
	v_pk_mul_f32 v[94:95], v[94:95], v[128:129] op_sel_hi:[1,0]
	v_pk_fma_f32 v[178:179], v[174:175], v[178:179], s[44:45] op_sel_hi:[1,1,0]
	v_pk_mul_f32 v[88:89], v[88:89], v[126:127] op_sel_hi:[1,0]
	v_pk_fma_f32 v[178:179], v[174:175], v[178:179], s[46:47] op_sel_hi:[1,1,0]
	v_pk_mul_f32 v[90:91], v[90:91], v[126:127] op_sel_hi:[1,0]
	v_pk_fma_f32 v[174:175], v[174:175], v[178:179], s[48:49] op_sel_hi:[1,1,0]
	v_pk_mul_f32 v[84:85], v[84:85], v[126:127] op_sel_hi:[1,0]
	v_pk_mul_f32 v[170:171], v[170:171], v[174:175]
	v_lshlrev_b32_e32 v174, 16, v114
	v_pk_fma_f32 v[168:169], v[168:169], v[170:171], v[168:169]
	v_and_b32_e32 v175, 0xffff0000, v114
	v_pk_mul_f32 v[98:99], v[98:99], v[168:169]
	v_lshlrev_b32_e32 v168, 16, v125
;     static __device__ __forceinline__ u32x2 finish2(const float (&g0)[4], const float (&g1)[4], const float (&g2)[4], const float (&w0)[4], const float (&w1)[4], const float (&w2)[4], const float (&bb)[4],
;                                                     const f32x4 v, float rs) {
;         float h[4];
; #pragma unroll
;         for (int j = 0; j < 4; j += 2) {
;             const f32x2 gc = (f32x2){bb[j] + w0[j] * g2[j] + w1[j] * g1[j] + w2[j] * g0[j], bb[j + 1] + w0[j + 1] * g2[j + 1] + w1[j + 1] * g1[j + 1] + w2[j + 1] * g0[j + 1]};
;             const f32x2 ge = gelu_pk(gc) * ((f32x2){v[j], v[j + 1]} * rs); h[j] = ge.x; h[j + 1] = ge.y; }
;         u32x2 w; w.x = cvt_pk_bf16(h[0], h[1]); w.y = cvt_pk_bf16(h[2], h[3]); return w;
;     }
;     __device__ __forceinline__ void operator()(const f32x4 (&acc)[2][2][4][2], const Unit& u, int wr, int wc, int fr, int fq) const {
;         asm volatile("" : "+v"(fr), "+v"(fq));
;         const int row0 = u.rb + wr * 64 + fr;
;         const int lane = fq * 16 + fr;
;         const int s1 = fr >= 1 ? lane - 1 : lane + 15, s2 = fr >= 2 ? lane - 2 : lane + 14; (void)s1; (void)s2;
;         float rs8[2][4];
; #pragma unroll
;         for (int ai = 0; ai < 2; ++ai)
; #pragma unroll
;             for (int m = 0; m < 4; ++m) rs8[ai][m] = rsqrtf(SS[u.rb + (u.half ? 0 : ai * HALF) + wr * 64 + fr + 16 * m] * (1.f / 1024.f) + 1e-6f);
;         if (u.pm < 128) {
; #pragma unroll
;           for (int bj = 0; bj < 2; ++bj) {
;             const int col8 = u.pn * BM + bj * HALF + wc * 32 + 8 * fq;
;             float w0[2][4], w1[2][4], w2[2][4], bb[2][4];
; #pragma unroll
;             for (int hv = 0; hv < 2; ++hv) { ld4f(cw + col8 + 4 * hv, w0[hv]); ld4f(cw + 2816 + col8 + 4 * hv, w1[hv]); ld4f(cw + 2 * 2816 + col8 + 4 * hv, w2[hv]); ld4f(cb + col8 + 4 * hv, bb[hv]); }
; #pragma unroll
;             for (int ai = 0; ai < 2; ++ai) { const int R0 = u.rb + ai * HALF + wr * 64; const bf16_t* gp = G + (size_t)(R0 + fr) * 2816 + col8;
;                 u32x4 gq[4], prv = (u32x4){0u, 0u, 0u, 0u};
; #pragma unroll
;                 for (int m = 0; m < 4; ++m) gq[m] = *(const u32x4*)(gp + (size_t)m * 16 * 2816);
;                 if ((R0 & 8191) != 0) prv = *(const u32x4*)(gp - (size_t)16 * 2816);
;                 u32x4 pv = prv;
; #pragma unroll
	v_and_b32_e32 v169, 0xffff0000, v125
	v_cvt_pk_bf16_f32 v97, v98, v99
	v_lshlrev_b32_e32 v98, 16, v3
	v_and_b32_e32 v99, 0xffff0000, v3
	v_pk_fma_f32 v[168:169], v[132:133], v[168:169], v[144:145]
	v_lshlrev_b32_e32 v170, 16, v127
	v_pk_fma_f32 v[98:99], v[136:137], v[98:99], v[168:169]
	v_and_b32_e32 v171, 0xffff0000, v127
	v_pk_fma_f32 v[98:99], v[140:141], v[174:175], v[98:99]
	v_mov_b32_dpp v3, v112 row_ror:1 row_mask:0xf bank_mask:0xf bound_ctrl:1
	v_pk_mul_f32 v[168:169], v[98:99], s[30:31] op_sel_hi:[1,0]
	v_pk_mul_f32 v[98:99], v[98:99], 0.5 op_sel_hi:[1,0]
	v_med3_f32 v168, v168, s47, v225
	v_med3_f32 v169, v169, s47, v225
	v_pk_mul_f32 v[174:175], v[168:169], v[168:169]
	v_mov_b32_dpp v3, v108 row_shr:1 row_mask:0xf bank_mask:0xf
	v_pk_fma_f32 v[178:179], v[174:175], s[34:35], v[116:117] op_sel_hi:[1,0,0] neg_lo:[1,0,0] neg_hi:[1,0,0]
	v_pk_mul_f32 v[86:87], v[86:87], v[126:127] op_sel_hi:[1,0]
	v_pk_fma_f32 v[178:179], v[174:175], v[178:179], s[38:39] op_sel_hi:[1,1,0]
	v_pk_mul_f32 v[80:81], v[80:81], v[124:125] op_sel_hi:[1,0]
	v_pk_fma_f32 v[178:179], v[174:175], v[178:179], s[40:41] op_sel_hi:[1,1,0]
	v_pk_mul_f32 v[82:83], v[82:83], v[124:125] op_sel_hi:[1,0]
	v_pk_fma_f32 v[178:179], v[174:175], v[178:179], s[42:43] op_sel_hi:[1,1,0]
	v_pk_mul_f32 v[76:77], v[76:77], v[124:125] op_sel_hi:[1,0]
	v_pk_fma_f32 v[178:179], v[174:175], v[178:179], s[44:45] op_sel_hi:[1,1,0]
	v_pk_mul_f32 v[78:79], v[78:79], v[124:125] op_sel_hi:[1,0]
	v_pk_fma_f32 v[178:179], v[174:175], v[178:179], s[46:47] op_sel_hi:[1,1,0]
	v_pk_mul_f32 v[72:73], v[72:73], v[122:123] op_sel_hi:[1,0]
	v_pk_fma_f32 v[174:175], v[174:175], v[178:179], s[48:49] op_sel_hi:[1,1,0]
	v_pk_mul_f32 v[74:75], v[74:75], v[122:123] op_sel_hi:[1,0]
	v_pk_mul_f32 v[168:169], v[168:169], v[174:175]
	v_pk_mul_f32 v[64:65], v[64:65], v[122:123] op_sel_hi:[1,0]
	v_pk_fma_f32 v[98:99], v[98:99], v[168:169], v[98:99]
	v_pk_fma_f32 v[168:169], v[134:135], v[170:171], v[146:147]
	v_pk_mul_f32 v[92:93], v[92:93], v[98:99]
	v_lshlrev_b32_e32 v98, 16, v115
	v_and_b32_e32 v99, 0xffff0000, v115
	v_pk_fma_f32 v[118:119], v[138:139], v[118:119], v[168:169]
	v_pk_mul_f32 v[66:67], v[66:67], v[122:123] op_sel_hi:[1,0]
	v_pk_fma_f32 v[98:99], v[142:143], v[98:99], v[118:119]
	v_readlane_b32 s52, v240, 62
	v_pk_mul_f32 v[118:119], v[98:99], s[30:31] op_sel_hi:[1,0]
	v_pk_mul_f32 v[98:99], v[98:99], 0.5 op_sel_hi:[1,0]
	v_med3_f32 v118, v118, s47, v225
	v_med3_f32 v119, v119, s47, v225
	v_pk_mul_f32 v[168:169], v[118:119], v[118:119]
	v_readlane_b32 s66, v239, 12
	v_pk_fma_f32 v[170:171], v[168:169], s[34:35], v[116:117] op_sel_hi:[1,0,0] neg_lo:[1,0,0] neg_hi:[1,0,0]
	v_readlane_b32 s67, v239, 13
	v_pk_fma_f32 v[170:171], v[168:169], v[170:171], s[38:39] op_sel_hi:[1,1,0]
	v_readlane_b32 s53, v240, 63
	v_pk_fma_f32 v[170:171], v[168:169], v[170:171], s[40:41] op_sel_hi:[1,1,0]
	v_readlane_b32 s54, v239, 0
	v_pk_fma_f32 v[170:171], v[168:169], v[170:171], s[42:43] op_sel_hi:[1,1,0]
	v_readlane_b32 s55, v239, 1
	v_pk_fma_f32 v[170:171], v[168:169], v[170:171], s[44:45] op_sel_hi:[1,1,0]
	v_readlane_b32 s56, v239, 2
	v_pk_fma_f32 v[170:171], v[168:169], v[170:171], s[46:47] op_sel_hi:[1,1,0]
	v_readlane_b32 s57, v239, 3
	v_pk_fma_f32 v[168:169], v[168:169], v[170:171], s[48:49] op_sel_hi:[1,1,0]
	v_readlane_b32 s58, v239, 4
	v_pk_mul_f32 v[118:119], v[118:119], v[168:169]
	v_lshl_add_u64 v[168:169], s[8:9], 0, v[120:121]
	v_pk_fma_f32 v[98:99], v[98:99], v[118:119], v[98:99]
	v_mov_b32_e32 v120, 0
	v_pk_mul_f32 v[94:95], v[94:95], v[98:99]
	v_cvt_pk_bf16_f32 v98, v92, v93
	v_lshl_add_u64 v[92:93], v[168:169], 0, v[180:181]
	v_cvt_pk_bf16_f32 v99, v94, v95
	global_store_dwordx4 v[92:93], v[96:99], off
	v_lshlrev_b32_e32 v92, 16, v3
	v_and_b32_e32 v93, 0xffff0000, v3
	v_mov_b32_dpp v97, v112 row_ror:2 row_mask:0xf bank_mask:0xf bound_ctrl:1
	v_mov_b32_dpp v95, v113 row_ror:1 row_mask:0xf bank_mask:0xf bound_ctrl:1
	v_mov_b32_dpp v99, v113 row_ror:2 row_mask:0xf bank_mask:0xf bound_ctrl:1
	v_mov_b32_dpp v97, v108 row_shr:2 row_mask:0xf bank_mask:0xf
	v_lshlrev_b32_e32 v96, 16, v97
	v_and_b32_e32 v97, 0xffff0000, v97
	v_pk_fma_f32 v[96:97], v[148:149], v[96:97], v[160:161]
	v_lshlrev_b32_e32 v112, 16, v108
	v_and_b32_e32 v113, 0xffff0000, v108
	v_pk_fma_f32 v[92:93], v[152:153], v[92:93], v[96:97]
	v_mov_b32_dpp v99, v109 row_shr:2 row_mask:0xf bank_mask:0xf
	v_pk_fma_f32 v[92:93], v[156:157], v[112:113], v[92:93]
	v_mov_b32_dpp v95, v109 row_shr:1 row_mask:0xf bank_mask:0xf
	v_pk_mul_f32 v[96:97], v[92:93], s[30:31] op_sel_hi:[1,0]
	v_lshlrev_b32_e32 v98, 16, v99
	v_med3_f32 v96, v96, s47, v225
	v_med3_f32 v97, v97, s47, v225
	v_pk_mul_f32 v[112:113], v[96:97], v[96:97]
	v_and_b32_e32 v99, 0xffff0000, v99
	v_pk_fma_f32 v[118:119], v[112:113], s[34:35], v[116:117] op_sel_hi:[1,0,0] neg_lo:[1,0,0] neg_hi:[1,0,0]
	v_pk_mul_f32 v[92:93], v[92:93], 0.5 op_sel_hi:[1,0]
	v_pk_fma_f32 v[118:119], v[112:113], v[118:119], s[38:39] op_sel_hi:[1,1,0]
	v_lshlrev_b32_e32 v94, 16, v95
	v_pk_fma_f32 v[118:119], v[112:113], v[118:119], s[40:41] op_sel_hi:[1,1,0]
	v_and_b32_e32 v95, 0xffff0000, v95
	v_pk_fma_f32 v[118:119], v[112:113], v[118:119], s[42:43] op_sel_hi:[1,1,0]
	v_mov_b32_dpp v3, v114 row_ror:1 row_mask:0xf bank_mask:0xf bound_ctrl:1
	v_pk_fma_f32 v[118:119], v[112:113], v[118:119], s[44:45] op_sel_hi:[1,1,0]
	v_mov_b32_e32 v121, 0
	v_pk_fma_f32 v[118:119], v[112:113], v[118:119], s[46:47] op_sel_hi:[1,1,0]
	v_mov_b32_dpp v3, v110 row_shr:1 row_mask:0xf bank_mask:0xf
	v_pk_fma_f32 v[112:113], v[112:113], v[118:119], s[48:49] op_sel_hi:[1,1,0]
	v_mov_b32_e32 v118, 0
	v_pk_mul_f32 v[96:97], v[96:97], v[112:113]
;     static __device__ __forceinline__ u32x2 finish2(const float (&g0)[4], const float (&g1)[4], const float (&g2)[4], const float (&w0)[4], const float (&w1)[4], const float (&w2)[4], const float (&bb)[4],
;                                                     const f32x4 v, float rs) {
;         float h[4];
; #pragma unroll
;         for (int j = 0; j < 4; j += 2) {
;             const f32x2 gc = (f32x2){bb[j] + w0[j] * g2[j] + w1[j] * g1[j] + w2[j] * g0[j], bb[j + 1] + w0[j + 1] * g2[j + 1] + w1[j + 1] * g1[j + 1] + w2[j + 1] * g0[j + 1]};
;             const f32x2 ge = gelu_pk(gc) * ((f32x2){v[j], v[j + 1]} * rs); h[j] = ge.x; h[j + 1] = ge.y; }
;         u32x2 w; w.x = cvt_pk_bf16(h[0], h[1]); w.y = cvt_pk_bf16(h[2], h[3]); return w;
;     }
;     __device__ __forceinline__ void operator()(const f32x4 (&acc)[2][2][4][2], const Unit& u, int wr, int wc, int fr, int fq) const {
;         asm volatile("" : "+v"(fr), "+v"(fq));
;         const int row0 = u.rb + wr * 64 + fr;
;         const int lane = fq * 16 + fr;
;         const int s1 = fr >= 1 ? lane - 1 : lane + 15, s2 = fr >= 2 ? lane - 2 : lane + 14; (void)s1; (void)s2;
;         float rs8[2][4];
; #pragma unroll
;         for (int ai = 0; ai < 2; ++ai)
; #pragma unroll
;             for (int m = 0; m < 4; ++m) rs8[ai][m] = rsqrtf(SS[u.rb + (u.half ? 0 : ai * HALF) + wr * 64 + fr + 16 * m] * (1.f / 1024.f) + 1e-6f);
;         if (u.pm < 128) {
; #pragma unroll
;           for (int bj = 0; bj < 2; ++bj) {
;             const int col8 = u.pn * BM + bj * HALF + wc * 32 + 8 * fq;
;             float w0[2][4], w1[2][4], w2[2][4], bb[2][4];
; #pragma unroll
;             for (int hv = 0; hv < 2; ++hv) { ld4f(cw + col8 + 4 * hv, w0[hv]); ld4f(cw + 2816 + col8 + 4 * hv, w1[hv]); ld4f(cw + 2 * 2816 + col8 + 4 * hv, w2[hv]); ld4f(cb + col8 + 4 * hv, bb[hv]); }
; #pragma unroll
;             for (int ai = 0; ai < 2; ++ai) { const int R0 = u.rb + ai * HALF + wr * 64; const bf16_t* gp = G + (size_t)(R0 + fr) * 2816 + col8;
;                 u32x4 gq[4], prv = (u32x4){0u, 0u, 0u, 0u};
; #pragma unroll
;                 for (int m = 0; m < 4; ++m) gq[m] = *(const u32x4*)(gp + (size_t)m * 16 * 2816);
;                 if ((R0 & 8191) != 0) prv = *(const u32x4*)(gp - (size_t)16 * 2816);
;                 u32x4 pv = prv;
; #pragma unroll
	v_mov_b32_e32 v119, 0
	v_pk_fma_f32 v[92:93], v[92:93], v[96:97], v[92:93]
	v_pk_fma_f32 v[96:97], v[150:151], v[98:99], v[162:163]
	v_pk_mul_f32 v[88:89], v[88:89], v[92:93]
	v_lshlrev_b32_e32 v92, 16, v109
	v_and_b32_e32 v93, 0xffff0000, v109
	v_pk_fma_f32 v[94:95], v[154:155], v[94:95], v[96:97]
	v_cvt_pk_bf16_f32 v88, v88, v89
	v_readlane_b32 s59, v239, 5
	v_pk_fma_f32 v[92:93], v[158:159], v[92:93], v[94:95]
	v_readlane_b32 s60, v239, 6
	v_pk_mul_f32 v[94:95], v[92:93], s[30:31] op_sel_hi:[1,0]
	v_pk_mul_f32 v[92:93], v[92:93], 0.5 op_sel_hi:[1,0]
	v_med3_f32 v94, v94, s47, v225
	v_med3_f32 v95, v95, s47, v225
	v_pk_mul_f32 v[96:97], v[94:95], v[94:95]
	v_readlane_b32 s61, v239, 7
	v_pk_fma_f32 v[98:99], v[96:97], s[34:35], v[116:117] op_sel_hi:[1,0,0] neg_lo:[1,0,0] neg_hi:[1,0,0]
	v_readlane_b32 s62, v239, 8
	v_pk_fma_f32 v[98:99], v[96:97], v[98:99], s[38:39] op_sel_hi:[1,1,0]
	v_readlane_b32 s63, v239, 9
	v_pk_fma_f32 v[98:99], v[96:97], v[98:99], s[40:41] op_sel_hi:[1,1,0]
	v_readlane_b32 s64, v239, 10
	v_pk_fma_f32 v[98:99], v[96:97], v[98:99], s[42:43] op_sel_hi:[1,1,0]
	v_readlane_b32 s65, v239, 11
	v_pk_fma_f32 v[98:99], v[96:97], v[98:99], s[44:45] op_sel_hi:[1,1,0]
	s_nop 0
	v_pk_fma_f32 v[98:99], v[96:97], v[98:99], s[46:47] op_sel_hi:[1,1,0]
	s_nop 0
	v_pk_fma_f32 v[96:97], v[96:97], v[98:99], s[48:49] op_sel_hi:[1,1,0]
	v_lshlrev_b32_e32 v98, 16, v110
	v_pk_mul_f32 v[94:95], v[94:95], v[96:97]
	v_and_b32_e32 v99, 0xffff0000, v110
	v_pk_fma_f32 v[92:93], v[92:93], v[94:95], v[92:93]
	v_mov_b32_dpp v95, v114 row_ror:2 row_mask:0xf bank_mask:0xf bound_ctrl:1
	v_pk_mul_f32 v[90:91], v[90:91], v[92:93]
	v_mov_b32_dpp v97, v115 row_ror:2 row_mask:0xf bank_mask:0xf bound_ctrl:1
	v_mov_b32_dpp v95, v110 row_shr:2 row_mask:0xf bank_mask:0xf
	v_lshlrev_b32_e32 v94, 16, v95
	v_and_b32_e32 v95, 0xffff0000, v95
	v_cvt_pk_bf16_f32 v89, v90, v91
	v_lshlrev_b32_e32 v90, 16, v3
	v_and_b32_e32 v91, 0xffff0000, v3
	v_pk_fma_f32 v[94:95], v[132:133], v[94:95], v[144:145]
	v_mov_b32_dpp v93, v115 row_ror:1 row_mask:0xf bank_mask:0xf bound_ctrl:1
	v_pk_fma_f32 v[90:91], v[136:137], v[90:91], v[94:95]
	v_mov_b32_dpp v97, v111 row_shr:2 row_mask:0xf bank_mask:0xf
	v_pk_fma_f32 v[90:91], v[140:141], v[98:99], v[90:91]
	v_mov_b32_dpp v93, v111 row_shr:1 row_mask:0xf bank_mask:0xf
	v_pk_mul_f32 v[94:95], v[90:91], s[30:31] op_sel_hi:[1,0]
	v_lshlrev_b32_e32 v96, 16, v97
	v_med3_f32 v94, v94, s47, v225
	v_med3_f32 v95, v95, s47, v225
	v_pk_mul_f32 v[98:99], v[94:95], v[94:95]
	v_and_b32_e32 v97, 0xffff0000, v97
	v_pk_fma_f32 v[112:113], v[98:99], s[34:35], v[116:117] op_sel_hi:[1,0,0] neg_lo:[1,0,0] neg_hi:[1,0,0]
	v_pk_mul_f32 v[90:91], v[90:91], 0.5 op_sel_hi:[1,0]
	v_pk_fma_f32 v[112:113], v[98:99], v[112:113], s[38:39] op_sel_hi:[1,1,0]
	v_lshlrev_b32_e32 v92, 16, v93
	v_pk_fma_f32 v[112:113], v[98:99], v[112:113], s[40:41] op_sel_hi:[1,1,0]
	v_and_b32_e32 v93, 0xffff0000, v93
	v_pk_fma_f32 v[112:113], v[98:99], v[112:113], s[42:43] op_sel_hi:[1,1,0]
	v_add_u32_e32 v3, 16, v1
	v_pk_fma_f32 v[112:113], v[98:99], v[112:113], s[44:45] op_sel_hi:[1,1,0]
	s_nop 0
	v_pk_fma_f32 v[112:113], v[98:99], v[112:113], s[46:47] op_sel_hi:[1,1,0]
	s_nop 0
	v_pk_fma_f32 v[98:99], v[98:99], v[112:113], s[48:49] op_sel_hi:[1,1,0]
	s_nop 0
	v_pk_mul_f32 v[94:95], v[94:95], v[98:99]
	s_nop 0
	v_pk_fma_f32 v[90:91], v[90:91], v[94:95], v[90:91]
	v_pk_fma_f32 v[94:95], v[134:135], v[96:97], v[146:147]
	v_pk_mul_f32 v[84:85], v[84:85], v[90:91]
	v_lshlrev_b32_e32 v90, 16, v111
	v_and_b32_e32 v91, 0xffff0000, v111
	v_pk_fma_f32 v[92:93], v[138:139], v[92:93], v[94:95]
	s_nop 0
	v_pk_fma_f32 v[90:91], v[142:143], v[90:91], v[92:93]
	s_nop 0
	v_pk_mul_f32 v[92:93], v[90:91], s[30:31] op_sel_hi:[1,0]
	v_pk_mul_f32 v[90:91], v[90:91], 0.5 op_sel_hi:[1,0]
	v_med3_f32 v92, v92, s47, v225
	v_med3_f32 v93, v93, s47, v225
	v_pk_mul_f32 v[94:95], v[92:93], v[92:93]
	s_nop 0
	v_pk_fma_f32 v[96:97], v[94:95], s[34:35], v[116:117] op_sel_hi:[1,0,0] neg_lo:[1,0,0] neg_hi:[1,0,0]
	s_nop 0
	v_pk_fma_f32 v[96:97], v[94:95], v[96:97], s[38:39] op_sel_hi:[1,1,0]
	s_nop 0
	v_pk_fma_f32 v[96:97], v[94:95], v[96:97], s[40:41] op_sel_hi:[1,1,0]
	s_nop 0
	v_pk_fma_f32 v[96:97], v[94:95], v[96:97], s[42:43] op_sel_hi:[1,1,0]
	s_nop 0
	v_pk_fma_f32 v[96:97], v[94:95], v[96:97], s[44:45] op_sel_hi:[1,1,0]
	s_nop 0
	v_pk_fma_f32 v[96:97], v[94:95], v[96:97], s[46:47] op_sel_hi:[1,1,0]
	s_nop 0
	v_pk_fma_f32 v[94:95], v[94:95], v[96:97], s[48:49] op_sel_hi:[1,1,0]
	s_nop 0
	v_pk_mul_f32 v[92:93], v[92:93], v[94:95]
	v_lshlrev_b32_e32 v94, 16, v104
	v_pk_fma_f32 v[90:91], v[90:91], v[92:93], v[90:91]
	v_and_b32_e32 v95, 0xffff0000, v104
	v_pk_mul_f32 v[86:87], v[86:87], v[90:91]
	v_cvt_pk_bf16_f32 v90, v84, v85
	v_mov_b64_e32 v[84:85], s[8:9]
	v_mad_i64_i32 v[170:171], s[8:9], v3, s91, v[84:85]
	v_cvt_pk_bf16_f32 v91, v86, v87
	v_lshl_add_u64 v[86:87], v[170:171], 0, v[180:181]
	global_store_dwordx4 v[86:87], v[88:91], off
	v_mov_b32_dpp v3, v108 row_ror:1 row_mask:0xf bank_mask:0xf bound_ctrl:1
	v_mov_b32_dpp v93, v109 row_ror:2 row_mask:0xf bank_mask:0xf bound_ctrl:1
	v_mov_b32_dpp v91, v108 row_ror:2 row_mask:0xf bank_mask:0xf bound_ctrl:1
	v_mov_b32_dpp v3, v104 row_shr:1 row_mask:0xf bank_mask:0xf
	v_lshlrev_b32_e32 v86, 16, v3
	v_mov_b32_dpp v91, v104 row_shr:2 row_mask:0xf bank_mask:0xf
	v_lshlrev_b32_e32 v90, 16, v91
	v_and_b32_e32 v91, 0xffff0000, v91
	v_and_b32_e32 v87, 0xffff0000, v3
	v_pk_fma_f32 v[90:91], v[148:149], v[90:91], v[160:161]
	v_mov_b32_dpp v89, v109 row_ror:1 row_mask:0xf bank_mask:0xf bound_ctrl:1
	v_pk_fma_f32 v[86:87], v[152:153], v[86:87], v[90:91]
;     static __device__ __forceinline__ u32x2 finish2(const float (&g0)[4], const float (&g1)[4], const float (&g2)[4], const float (&w0)[4], const float (&w1)[4], const float (&w2)[4], const float (&bb)[4],
;                                                     const f32x4 v, float rs) {
;         float h[4];
; #pragma unroll
;         for (int j = 0; j < 4; j += 2) {
;             const f32x2 gc = (f32x2){bb[j] + w0[j] * g2[j] + w1[j] * g1[j] + w2[j] * g0[j], bb[j + 1] + w0[j + 1] * g2[j + 1] + w1[j + 1] * g1[j + 1] + w2[j + 1] * g0[j + 1]};
;             const f32x2 ge = gelu_pk(gc) * ((f32x2){v[j], v[j + 1]} * rs); h[j] = ge.x; h[j + 1] = ge.y; }
;         u32x2 w; w.x = cvt_pk_bf16(h[0], h[1]); w.y = cvt_pk_bf16(h[2], h[3]); return w;
;     }
;     __device__ __forceinline__ void operator()(const f32x4 (&acc)[2][2][4][2], const Unit& u, int wr, int wc, int fr, int fq) const {
;         asm volatile("" : "+v"(fr), "+v"(fq));
;         const int row0 = u.rb + wr * 64 + fr;
;         const int lane = fq * 16 + fr;
;         const int s1 = fr >= 1 ? lane - 1 : lane + 15, s2 = fr >= 2 ? lane - 2 : lane + 14; (void)s1; (void)s2;
;         float rs8[2][4];
; #pragma unroll
;         for (int ai = 0; ai < 2; ++ai)
; #pragma unroll
;             for (int m = 0; m < 4; ++m) rs8[ai][m] = rsqrtf(SS[u.rb + (u.half ? 0 : ai * HALF) + wr * 64 + fr + 16 * m] * (1.f / 1024.f) + 1e-6f);
;         if (u.pm < 128) {
; #pragma unroll
;           for (int bj = 0; bj < 2; ++bj) {
;             const int col8 = u.pn * BM + bj * HALF + wc * 32 + 8 * fq;
;             float w0[2][4], w1[2][4], w2[2][4], bb[2][4];
; #pragma unroll
;             for (int hv = 0; hv < 2; ++hv) { ld4f(cw + col8 + 4 * hv, w0[hv]); ld4f(cw + 2816 + col8 + 4 * hv, w1[hv]); ld4f(cw + 2 * 2816 + col8 + 4 * hv, w2[hv]); ld4f(cb + col8 + 4 * hv, bb[hv]); }
; #pragma unroll
;             for (int ai = 0; ai < 2; ++ai) { const int R0 = u.rb + ai * HALF + wr * 64; const bf16_t* gp = G + (size_t)(R0 + fr) * 2816 + col8;
;                 u32x4 gq[4], prv = (u32x4){0u, 0u, 0u, 0u};
; #pragma unroll
;                 for (int m = 0; m < 4; ++m) gq[m] = *(const u32x4*)(gp + (size_t)m * 16 * 2816);
;                 if ((R0 & 8191) != 0) prv = *(const u32x4*)(gp - (size_t)16 * 2816);
;                 u32x4 pv = prv;
; #pragma unroll
	v_mov_b32_dpp v93, v105 row_shr:2 row_mask:0xf bank_mask:0xf
	v_pk_fma_f32 v[86:87], v[156:157], v[94:95], v[86:87]
	v_mov_b32_dpp v89, v105 row_shr:1 row_mask:0xf bank_mask:0xf
	v_pk_mul_f32 v[90:91], v[86:87], s[30:31] op_sel_hi:[1,0]
	v_lshlrev_b32_e32 v92, 16, v93
	v_med3_f32 v90, v90, s47, v225
	v_med3_f32 v91, v91, s47, v225
	v_pk_mul_f32 v[94:95], v[90:91], v[90:91]
	v_and_b32_e32 v93, 0xffff0000, v93
	v_pk_fma_f32 v[96:97], v[94:95], s[34:35], v[116:117] op_sel_hi:[1,0,0] neg_lo:[1,0,0] neg_hi:[1,0,0]
	v_pk_mul_f32 v[86:87], v[86:87], 0.5 op_sel_hi:[1,0]
	v_pk_fma_f32 v[96:97], v[94:95], v[96:97], s[38:39] op_sel_hi:[1,1,0]
	v_lshlrev_b32_e32 v88, 16, v89
	v_pk_fma_f32 v[96:97], v[94:95], v[96:97], s[40:41] op_sel_hi:[1,1,0]
	v_and_b32_e32 v89, 0xffff0000, v89
	v_pk_fma_f32 v[96:97], v[94:95], v[96:97], s[42:43] op_sel_hi:[1,1,0]
	v_mov_b32_dpp v3, v110 row_ror:1 row_mask:0xf bank_mask:0xf bound_ctrl:1
	v_pk_fma_f32 v[96:97], v[94:95], v[96:97], s[44:45] op_sel_hi:[1,1,0]
	s_nop 0
	v_pk_fma_f32 v[96:97], v[94:95], v[96:97], s[46:47] op_sel_hi:[1,1,0]
	v_mov_b32_dpp v3, v106 row_shr:1 row_mask:0xf bank_mask:0xf
	v_pk_fma_f32 v[94:95], v[94:95], v[96:97], s[48:49] op_sel_hi:[1,1,0]
	s_nop 0
	v_pk_mul_f32 v[90:91], v[90:91], v[94:95]
	s_nop 0
	v_pk_fma_f32 v[86:87], v[86:87], v[90:91], v[86:87]
	v_pk_fma_f32 v[90:91], v[150:151], v[92:93], v[162:163]
	v_pk_mul_f32 v[80:81], v[80:81], v[86:87]
	v_lshlrev_b32_e32 v86, 16, v105
	v_and_b32_e32 v87, 0xffff0000, v105
	v_pk_fma_f32 v[88:89], v[154:155], v[88:89], v[90:91]
	v_cvt_pk_bf16_f32 v80, v80, v81
	s_nop 0
	v_pk_fma_f32 v[86:87], v[158:159], v[86:87], v[88:89]
	s_nop 0
	v_pk_mul_f32 v[88:89], v[86:87], s[30:31] op_sel_hi:[1,0]
	v_pk_mul_f32 v[86:87], v[86:87], 0.5 op_sel_hi:[1,0]
	v_med3_f32 v88, v88, s47, v225
	v_med3_f32 v89, v89, s47, v225
	v_pk_mul_f32 v[90:91], v[88:89], v[88:89]
	s_nop 0
	v_pk_fma_f32 v[92:93], v[90:91], s[34:35], v[116:117] op_sel_hi:[1,0,0] neg_lo:[1,0,0] neg_hi:[1,0,0]
	s_nop 0
	v_pk_fma_f32 v[92:93], v[90:91], v[92:93], s[38:39] op_sel_hi:[1,1,0]
	s_nop 0
	v_pk_fma_f32 v[92:93], v[90:91], v[92:93], s[40:41] op_sel_hi:[1,1,0]
	s_nop 0
	v_pk_fma_f32 v[92:93], v[90:91], v[92:93], s[42:43] op_sel_hi:[1,1,0]
	s_nop 0
	v_pk_fma_f32 v[92:93], v[90:91], v[92:93], s[44:45] op_sel_hi:[1,1,0]
	s_nop 0
	v_pk_fma_f32 v[92:93], v[90:91], v[92:93], s[46:47] op_sel_hi:[1,1,0]
	s_nop 0
	v_pk_fma_f32 v[90:91], v[90:91], v[92:93], s[48:49] op_sel_hi:[1,1,0]
	v_lshlrev_b32_e32 v92, 16, v106
	v_pk_mul_f32 v[88:89], v[88:89], v[90:91]
	v_and_b32_e32 v93, 0xffff0000, v106
	v_pk_fma_f32 v[86:87], v[86:87], v[88:89], v[86:87]
	v_mov_b32_dpp v89, v110 row_ror:2 row_mask:0xf bank_mask:0xf bound_ctrl:1
	v_pk_mul_f32 v[82:83], v[82:83], v[86:87]
	v_mov_b32_dpp v91, v111 row_ror:2 row_mask:0xf bank_mask:0xf bound_ctrl:1
	v_mov_b32_dpp v89, v106 row_shr:2 row_mask:0xf bank_mask:0xf
	v_lshlrev_b32_e32 v88, 16, v89
	v_and_b32_e32 v89, 0xffff0000, v89
	v_cvt_pk_bf16_f32 v81, v82, v83
	v_lshlrev_b32_e32 v82, 16, v3
	v_and_b32_e32 v83, 0xffff0000, v3
	v_pk_fma_f32 v[88:89], v[132:133], v[88:89], v[144:145]
	v_mov_b32_dpp v87, v111 row_ror:1 row_mask:0xf bank_mask:0xf bound_ctrl:1
	v_pk_fma_f32 v[82:83], v[136:137], v[82:83], v[88:89]
	v_mov_b32_dpp v91, v107 row_shr:2 row_mask:0xf bank_mask:0xf
	v_pk_fma_f32 v[82:83], v[140:141], v[92:93], v[82:83]
	v_mov_b32_dpp v87, v107 row_shr:1 row_mask:0xf bank_mask:0xf
	v_pk_mul_f32 v[88:89], v[82:83], s[30:31] op_sel_hi:[1,0]
	v_lshlrev_b32_e32 v90, 16, v91
	v_med3_f32 v88, v88, s47, v225
	v_med3_f32 v89, v89, s47, v225
	v_pk_mul_f32 v[92:93], v[88:89], v[88:89]
	v_and_b32_e32 v91, 0xffff0000, v91
	v_pk_fma_f32 v[94:95], v[92:93], s[34:35], v[116:117] op_sel_hi:[1,0,0] neg_lo:[1,0,0] neg_hi:[1,0,0]
	v_pk_mul_f32 v[82:83], v[82:83], 0.5 op_sel_hi:[1,0]
	v_pk_fma_f32 v[94:95], v[92:93], v[94:95], s[38:39] op_sel_hi:[1,1,0]
	v_lshlrev_b32_e32 v86, 16, v87
	v_pk_fma_f32 v[94:95], v[92:93], v[94:95], s[40:41] op_sel_hi:[1,1,0]
	v_and_b32_e32 v87, 0xffff0000, v87
	v_pk_fma_f32 v[94:95], v[92:93], v[94:95], s[42:43] op_sel_hi:[1,1,0]
	v_add_u32_e32 v3, 32, v1
	v_pk_fma_f32 v[94:95], v[92:93], v[94:95], s[44:45] op_sel_hi:[1,1,0]
	v_mad_i64_i32 v[174:175], s[8:9], v3, s91, v[84:85]
	v_pk_fma_f32 v[94:95], v[92:93], v[94:95], s[46:47] op_sel_hi:[1,1,0]
	v_mov_b32_dpp v3, v104 row_ror:1 row_mask:0xf bank_mask:0xf bound_ctrl:1
	v_pk_fma_f32 v[92:93], v[92:93], v[94:95], s[48:49] op_sel_hi:[1,1,0]
	v_add_u32_e32 v1, 48, v1
	v_pk_mul_f32 v[88:89], v[88:89], v[92:93]
	v_mov_b32_dpp v3, v100 row_shr:1 row_mask:0xf bank_mask:0xf
	v_pk_fma_f32 v[82:83], v[82:83], v[88:89], v[82:83]
	v_pk_fma_f32 v[88:89], v[134:135], v[90:91], v[146:147]
	v_pk_mul_f32 v[76:77], v[76:77], v[82:83]
	v_lshlrev_b32_e32 v82, 16, v107
	v_and_b32_e32 v83, 0xffff0000, v107
	v_pk_fma_f32 v[86:87], v[138:139], v[86:87], v[88:89]
	s_nop 0
	v_pk_fma_f32 v[82:83], v[142:143], v[82:83], v[86:87]
	s_nop 0
	v_pk_mul_f32 v[86:87], v[82:83], s[30:31] op_sel_hi:[1,0]
	v_pk_mul_f32 v[82:83], v[82:83], 0.5 op_sel_hi:[1,0]
	v_med3_f32 v86, v86, s47, v225
	v_med3_f32 v87, v87, s47, v225
	v_pk_mul_f32 v[88:89], v[86:87], v[86:87]
	s_nop 0
	v_pk_fma_f32 v[90:91], v[88:89], s[34:35], v[116:117] op_sel_hi:[1,0,0] neg_lo:[1,0,0] neg_hi:[1,0,0]
	s_nop 0
	v_pk_fma_f32 v[90:91], v[88:89], v[90:91], s[38:39] op_sel_hi:[1,1,0]
	s_nop 0
	v_pk_fma_f32 v[90:91], v[88:89], v[90:91], s[40:41] op_sel_hi:[1,1,0]
	s_nop 0
	v_pk_fma_f32 v[90:91], v[88:89], v[90:91], s[42:43] op_sel_hi:[1,1,0]
	s_nop 0
	v_pk_fma_f32 v[90:91], v[88:89], v[90:91], s[44:45] op_sel_hi:[1,1,0]
	s_nop 0
	v_pk_fma_f32 v[90:91], v[88:89], v[90:91], s[46:47] op_sel_hi:[1,1,0]
;     static __device__ __forceinline__ u32x2 finish2(const float (&g0)[4], const float (&g1)[4], const float (&g2)[4], const float (&w0)[4], const float (&w1)[4], const float (&w2)[4], const float (&bb)[4],
;                                                     const f32x4 v, float rs) {
;         float h[4];
; #pragma unroll
;         for (int j = 0; j < 4; j += 2) {
;             const f32x2 gc = (f32x2){bb[j] + w0[j] * g2[j] + w1[j] * g1[j] + w2[j] * g0[j], bb[j + 1] + w0[j + 1] * g2[j + 1] + w1[j + 1] * g1[j + 1] + w2[j + 1] * g0[j + 1]};
;             const f32x2 ge = gelu_pk(gc) * ((f32x2){v[j], v[j + 1]} * rs); h[j] = ge.x; h[j + 1] = ge.y; }
;         u32x2 w; w.x = cvt_pk_bf16(h[0], h[1]); w.y = cvt_pk_bf16(h[2], h[3]); return w;
;     }
;     __device__ __forceinline__ void operator()(const f32x4 (&acc)[2][2][4][2], const Unit& u, int wr, int wc, int fr, int fq) const {
;         asm volatile("" : "+v"(fr), "+v"(fq));
;         const int row0 = u.rb + wr * 64 + fr;
;         const int lane = fq * 16 + fr;
;         const int s1 = fr >= 1 ? lane - 1 : lane + 15, s2 = fr >= 2 ? lane - 2 : lane + 14; (void)s1; (void)s2;
;         float rs8[2][4];
; #pragma unroll
;         for (int ai = 0; ai < 2; ++ai)
; #pragma unroll
;             for (int m = 0; m < 4; ++m) rs8[ai][m] = rsqrtf(SS[u.rb + (u.half ? 0 : ai * HALF) + wr * 64 + fr + 16 * m] * (1.f / 1024.f) + 1e-6f);
;         if (u.pm < 128) {
; #pragma unroll
;           for (int bj = 0; bj < 2; ++bj) {
;             const int col8 = u.pn * BM + bj * HALF + wc * 32 + 8 * fq;
;             float w0[2][4], w1[2][4], w2[2][4], bb[2][4];
; #pragma unroll
;             for (int hv = 0; hv < 2; ++hv) { ld4f(cw + col8 + 4 * hv, w0[hv]); ld4f(cw + 2816 + col8 + 4 * hv, w1[hv]); ld4f(cw + 2 * 2816 + col8 + 4 * hv, w2[hv]); ld4f(cb + col8 + 4 * hv, bb[hv]); }
; #pragma unroll
;             for (int ai = 0; ai < 2; ++ai) { const int R0 = u.rb + ai * HALF + wr * 64; const bf16_t* gp = G + (size_t)(R0 + fr) * 2816 + col8;
;                 u32x4 gq[4], prv = (u32x4){0u, 0u, 0u, 0u};
; #pragma unroll
;                 for (int m = 0; m < 4; ++m) gq[m] = *(const u32x4*)(gp + (size_t)m * 16 * 2816);
;                 if ((R0 & 8191) != 0) prv = *(const u32x4*)(gp - (size_t)16 * 2816);
;                 u32x4 pv = prv;
; #pragma unroll
	s_nop 0
	v_pk_fma_f32 v[88:89], v[88:89], v[90:91], s[48:49] op_sel_hi:[1,1,0]
	s_nop 0
	v_pk_mul_f32 v[86:87], v[86:87], v[88:89]
	s_nop 0
	v_pk_fma_f32 v[82:83], v[82:83], v[86:87], v[82:83]
	v_lshlrev_b32_e32 v86, 16, v100
	v_pk_mul_f32 v[78:79], v[78:79], v[82:83]
	v_cvt_pk_bf16_f32 v82, v76, v77
	v_lshl_add_u64 v[76:77], v[174:175], 0, v[180:181]
	v_cvt_pk_bf16_f32 v83, v78, v79
	global_store_dwordx4 v[76:77], v[80:83], off
	v_lshlrev_b32_e32 v76, 16, v3
	v_and_b32_e32 v77, 0xffff0000, v3
	v_mov_b32_dpp v81, v104 row_ror:2 row_mask:0xf bank_mask:0xf bound_ctrl:1
	v_and_b32_e32 v87, 0xffff0000, v100
	v_mov_b32_dpp v83, v105 row_ror:2 row_mask:0xf bank_mask:0xf bound_ctrl:1
	v_mov_b32_dpp v81, v100 row_shr:2 row_mask:0xf bank_mask:0xf
	v_lshlrev_b32_e32 v80, 16, v81
	v_and_b32_e32 v81, 0xffff0000, v81
	v_pk_fma_f32 v[80:81], v[148:149], v[80:81], v[160:161]
	v_mov_b32_dpp v79, v105 row_ror:1 row_mask:0xf bank_mask:0xf bound_ctrl:1
	v_pk_fma_f32 v[76:77], v[152:153], v[76:77], v[80:81]
	v_mov_b32_dpp v83, v101 row_shr:2 row_mask:0xf bank_mask:0xf
	v_pk_fma_f32 v[76:77], v[156:157], v[86:87], v[76:77]
	v_mov_b32_dpp v79, v101 row_shr:1 row_mask:0xf bank_mask:0xf
	v_pk_mul_f32 v[80:81], v[76:77], s[30:31] op_sel_hi:[1,0]
	v_lshlrev_b32_e32 v82, 16, v83
	v_med3_f32 v80, v80, s47, v225
	v_med3_f32 v81, v81, s47, v225
	v_pk_mul_f32 v[86:87], v[80:81], v[80:81]
	v_and_b32_e32 v83, 0xffff0000, v83
	v_pk_fma_f32 v[88:89], v[86:87], s[34:35], v[116:117] op_sel_hi:[1,0,0] neg_lo:[1,0,0] neg_hi:[1,0,0]
	v_pk_mul_f32 v[76:77], v[76:77], 0.5 op_sel_hi:[1,0]
	v_pk_fma_f32 v[88:89], v[86:87], v[88:89], s[38:39] op_sel_hi:[1,1,0]
	v_lshlrev_b32_e32 v78, 16, v79
	v_pk_fma_f32 v[88:89], v[86:87], v[88:89], s[40:41] op_sel_hi:[1,1,0]
	v_and_b32_e32 v79, 0xffff0000, v79
	v_pk_fma_f32 v[88:89], v[86:87], v[88:89], s[42:43] op_sel_hi:[1,1,0]
	v_mov_b32_dpp v3, v106 row_ror:1 row_mask:0xf bank_mask:0xf bound_ctrl:1
	v_pk_fma_f32 v[88:89], v[86:87], v[88:89], s[44:45] op_sel_hi:[1,1,0]
	s_nop 0
	v_pk_fma_f32 v[88:89], v[86:87], v[88:89], s[46:47] op_sel_hi:[1,1,0]
	v_mov_b32_dpp v3, v102 row_shr:1 row_mask:0xf bank_mask:0xf
	v_pk_fma_f32 v[86:87], v[86:87], v[88:89], s[48:49] op_sel_hi:[1,1,0]
	s_nop 0
	v_pk_mul_f32 v[80:81], v[80:81], v[86:87]
	s_nop 0
	v_pk_fma_f32 v[76:77], v[76:77], v[80:81], v[76:77]
	v_pk_fma_f32 v[80:81], v[150:151], v[82:83], v[162:163]
	v_pk_mul_f32 v[72:73], v[72:73], v[76:77]
	v_lshlrev_b32_e32 v76, 16, v101
	v_and_b32_e32 v77, 0xffff0000, v101
	v_pk_fma_f32 v[78:79], v[154:155], v[78:79], v[80:81]
	v_cvt_pk_bf16_f32 v72, v72, v73
	s_nop 0
	v_pk_fma_f32 v[76:77], v[158:159], v[76:77], v[78:79]
	s_nop 0
	v_pk_mul_f32 v[78:79], v[76:77], s[30:31] op_sel_hi:[1,0]
	v_pk_mul_f32 v[76:77], v[76:77], 0.5 op_sel_hi:[1,0]
	v_med3_f32 v78, v78, s47, v225
	v_med3_f32 v79, v79, s47, v225
	v_pk_mul_f32 v[80:81], v[78:79], v[78:79]
	s_nop 0
	v_pk_fma_f32 v[82:83], v[80:81], s[34:35], v[116:117] op_sel_hi:[1,0,0] neg_lo:[1,0,0] neg_hi:[1,0,0]
	s_nop 0
	v_pk_fma_f32 v[82:83], v[80:81], v[82:83], s[38:39] op_sel_hi:[1,1,0]
	s_nop 0
	v_pk_fma_f32 v[82:83], v[80:81], v[82:83], s[40:41] op_sel_hi:[1,1,0]
	s_nop 0
	v_pk_fma_f32 v[82:83], v[80:81], v[82:83], s[42:43] op_sel_hi:[1,1,0]
	s_nop 0
	v_pk_fma_f32 v[82:83], v[80:81], v[82:83], s[44:45] op_sel_hi:[1,1,0]
	s_nop 0
	v_pk_fma_f32 v[82:83], v[80:81], v[82:83], s[46:47] op_sel_hi:[1,1,0]
	s_nop 0
	v_pk_fma_f32 v[80:81], v[80:81], v[82:83], s[48:49] op_sel_hi:[1,1,0]
	v_lshlrev_b32_e32 v82, 16, v102
	v_pk_mul_f32 v[78:79], v[78:79], v[80:81]
	v_and_b32_e32 v83, 0xffff0000, v102
	v_pk_fma_f32 v[76:77], v[76:77], v[78:79], v[76:77]
	v_mov_b32_dpp v79, v106 row_ror:2 row_mask:0xf bank_mask:0xf bound_ctrl:1
	v_pk_mul_f32 v[74:75], v[74:75], v[76:77]
	v_mov_b32_dpp v81, v107 row_ror:2 row_mask:0xf bank_mask:0xf bound_ctrl:1
	v_mov_b32_dpp v79, v102 row_shr:2 row_mask:0xf bank_mask:0xf
	v_lshlrev_b32_e32 v78, 16, v79
	v_and_b32_e32 v79, 0xffff0000, v79
	v_cvt_pk_bf16_f32 v73, v74, v75
	v_lshlrev_b32_e32 v74, 16, v3
	v_and_b32_e32 v75, 0xffff0000, v3
	v_pk_fma_f32 v[78:79], v[132:133], v[78:79], v[144:145]
	v_mov_b32_dpp v77, v107 row_ror:1 row_mask:0xf bank_mask:0xf bound_ctrl:1
	v_pk_fma_f32 v[74:75], v[136:137], v[74:75], v[78:79]
	v_mov_b32_dpp v81, v103 row_shr:2 row_mask:0xf bank_mask:0xf
	v_pk_fma_f32 v[74:75], v[140:141], v[82:83], v[74:75]
	v_mov_b32_dpp v77, v103 row_shr:1 row_mask:0xf bank_mask:0xf
	v_pk_mul_f32 v[78:79], v[74:75], s[30:31] op_sel_hi:[1,0]
	v_lshlrev_b32_e32 v80, 16, v81
	v_med3_f32 v78, v78, s47, v225
	v_med3_f32 v79, v79, s47, v225
	v_pk_mul_f32 v[82:83], v[78:79], v[78:79]
	v_and_b32_e32 v81, 0xffff0000, v81
	v_pk_fma_f32 v[86:87], v[82:83], s[34:35], v[116:117] op_sel_hi:[1,0,0] neg_lo:[1,0,0] neg_hi:[1,0,0]
	v_pk_mul_f32 v[74:75], v[74:75], 0.5 op_sel_hi:[1,0]
	v_pk_fma_f32 v[86:87], v[82:83], v[86:87], s[38:39] op_sel_hi:[1,1,0]
	v_lshlrev_b32_e32 v76, 16, v77
	v_pk_fma_f32 v[86:87], v[82:83], v[86:87], s[40:41] op_sel_hi:[1,1,0]
	v_and_b32_e32 v77, 0xffff0000, v77
	v_pk_fma_f32 v[86:87], v[82:83], v[86:87], s[42:43] op_sel_hi:[1,1,0]
	v_mad_i64_i32 v[132:133], s[8:9], v1, s91, v[84:85]
	v_pk_fma_f32 v[86:87], v[82:83], v[86:87], s[44:45] op_sel_hi:[1,1,0]
	v_readlane_b32 s8, v240, 19
	v_pk_fma_f32 v[86:87], v[82:83], v[86:87], s[46:47] op_sel_hi:[1,1,0]
	v_readlane_b32 s9, v240, 20
	v_pk_fma_f32 v[82:83], v[82:83], v[86:87], s[48:49] op_sel_hi:[1,1,0]
	s_nop 0
	v_pk_mul_f32 v[78:79], v[78:79], v[82:83]
	s_nop 0
	v_pk_fma_f32 v[74:75], v[74:75], v[78:79], v[74:75]
	v_pk_fma_f32 v[78:79], v[134:135], v[80:81], v[146:147]
	v_pk_mul_f32 v[64:65], v[64:65], v[74:75]
;     static __device__ __forceinline__ void unpk4(const u32x2 w, float (&o)[4]) { o[0] = bf_lo(w.x); o[1] = bf_hi(w.x); o[2] = bf_lo(w.y); o[3] = bf_hi(w.y); }
;     template <int N> static __device__ __forceinline__ u32x2 dpp_prev(const u32x2 pv, const u32x2 cur) { u32x2 r; r.x = dpp_prev1<N>(pv.x, cur.x); r.y = dpp_prev1<N>(pv.y, cur.y); return r; }
;     __device__ __forceinline__ void operator()(const f32x4 (&acc)[2][2][4][2], const Unit& u, int wr, int wc, int fr, int fq) const {
;     ...
;           for (int bj = 0; bj < 2; ++bj) {
;             const int col8 = u.pn * BM + bj * HALF + wc * 32 + 8 * fq;
;             float w0[2][4], w1[2][4], w2[2][4], bb[2][4];
; #pragma unroll
;             for (int hv = 0; hv < 2; ++hv) { ld4f(cw + col8 + 4 * hv, w0[hv]); ld4f(cw + 2816 + col8 + 4 * hv, w1[hv]); ld4f(cw + 2 * 2816 + col8 + 4 * hv, w2[hv]); ld4f(cb + col8 + 4 * hv, bb[hv]); }
; #pragma unroll
;             for (int ai = 0; ai < 2; ++ai) { const int R0 = u.rb + ai * HALF + wr * 64; const bf16_t* gp = G + (size_t)(R0 + fr) * 2816 + col8;
;                 u32x4 gq[4], prv = (u32x4){0u, 0u, 0u, 0u};
; #pragma unroll
;                 for (int m = 0; m < 4; ++m) gq[m] = *(const u32x4*)(gp + (size_t)m * 16 * 2816);
;                 if ((R0 & 8191) != 0) prv = *(const u32x4*)(gp - (size_t)16 * 2816);
;                 u32x4 pv = prv;
; #pragma unroll
;                 for (int m = 0; m < 4; ++m) { const u32x4 cur = gq[m]; u32x4 hw;
; #pragma unroll
;                     for (int hv = 0; hv < 2; ++hv) { const u32x2 c2 = half2(cur, hv), p2 = half2(pv, hv);
;                         const u32x2 q1 = dpp_prev<1>(p2, c2), q2 = dpp_prev<2>(p2, c2);
;                         float g0[4], g1[4], g2[4]; unpk4(c2, g0); unpk4(q1, g1); unpk4(q2, g2);
;                         const u32x2 r = finish2(g0, g1, g2, w0[hv], w1[hv], w2[hv], bb[hv], acc[ai][bj][m][hv], rs8[ai][m]);
;                         if (hv == 0) { hw.x = r.x; hw.y = r.y; } else { hw.z = r.x; hw.w = r.y; } }
;                     *(u32x4*)(H + (size_t)(R0 + fr + 16 * m) * 2816 + col8) = hw;
	v_lshlrev_b32_e32 v74, 16, v103
	v_and_b32_e32 v75, 0xffff0000, v103
	v_pk_fma_f32 v[76:77], v[138:139], v[76:77], v[78:79]
	v_add_u32_e32 v134, 0x80, v212
	v_pk_fma_f32 v[74:75], v[142:143], v[74:75], v[76:77]
	v_ashrrev_i32_e32 v135, 31, v134
	v_pk_mul_f32 v[76:77], v[74:75], s[30:31] op_sel_hi:[1,0]
	v_pk_mul_f32 v[74:75], v[74:75], 0.5 op_sel_hi:[1,0]
	v_med3_f32 v76, v76, s47, v225
	v_med3_f32 v77, v77, s47, v225
	v_pk_mul_f32 v[78:79], v[76:77], v[76:77]
	v_lshl_add_u64 v[136:137], v[134:135], 1, v[214:215]
	v_pk_fma_f32 v[80:81], v[78:79], s[34:35], v[116:117] op_sel_hi:[1,0,0] neg_lo:[1,0,0] neg_hi:[1,0,0]
	v_add_co_u32_e32 v100, vcc, s10, v136
	v_pk_fma_f32 v[80:81], v[78:79], v[80:81], s[38:39] op_sel_hi:[1,1,0]
	s_nop 0
	v_addc_co_u32_e32 v101, vcc, 0, v137, vcc
	v_pk_fma_f32 v[80:81], v[78:79], v[80:81], s[40:41] op_sel_hi:[1,1,0]
	s_nop 0
	v_pk_fma_f32 v[80:81], v[78:79], v[80:81], s[42:43] op_sel_hi:[1,1,0]
	s_nop 0
	v_pk_fma_f32 v[80:81], v[78:79], v[80:81], s[44:45] op_sel_hi:[1,1,0]
	s_nop 0
	v_pk_fma_f32 v[80:81], v[78:79], v[80:81], s[46:47] op_sel_hi:[1,1,0]
	s_nop 0
	v_pk_fma_f32 v[78:79], v[78:79], v[80:81], s[48:49] op_sel_hi:[1,1,0]
	s_nop 0
	v_pk_mul_f32 v[76:77], v[76:77], v[78:79]
	s_nop 0
	v_pk_fma_f32 v[74:75], v[74:75], v[76:77], v[74:75]
	s_nop 0
	v_pk_mul_f32 v[66:67], v[66:67], v[74:75]
	v_cvt_pk_bf16_f32 v74, v64, v65
	v_lshl_add_u64 v[64:65], v[132:133], 0, v[180:181]
	v_cvt_pk_bf16_f32 v75, v66, v67
	global_store_dwordx4 v[64:65], v[72:75], off
	v_lshlrev_b64 v[64:65], 2, v[134:135]
	v_lshl_add_u64 v[76:77], s[8:9], 0, v[64:65]
	v_readlane_b32 s8, v240, 21
	v_readlane_b32 s9, v240, 22
	v_lshl_add_u64 v[72:73], s[66:67], 0, v[64:65]
	v_lshl_add_u64 v[96:97], s[88:89], 0, v[64:65]
	v_lshl_add_u64 v[80:81], s[8:9], 0, v[64:65]
	v_and_b32_e32 v241, 63, v216
	v_lshrrev_b32_e32 v242, 4, v241
	v_and_b32_e32 v243, 15, v241
	v_cmp_eq_u32_e64 s[98:99], 1, v242
	v_lshlrev_b32_e32 v246, 3, v243
	v_lshlrev_b32_e32 v247, 5, v242
	v_cndmask_b32_e64 v244, v72, v76, s[98:99]
	v_cndmask_b32_e64 v245, v73, v77, s[98:99]
	v_cmp_eq_u32_e64 s[98:99], 2, v242
	v_sub_u32_e32 v246, v246, v247
	v_ashrrev_i32_e32 v247, 31, v246
	v_cndmask_b32_e64 v244, v244, v80, s[98:99]
	v_cndmask_b32_e64 v245, v245, v81, s[98:99]
	v_cmp_eq_u32_e64 s[98:99], 3, v242
	s_nop 1
	v_cndmask_b32_e64 v244, v244, v96, s[98:99]
	v_cndmask_b32_e64 v245, v245, v97, s[98:99]
	v_lshl_add_u64 v[244:245], v[244:245], 0, v[246:247]
	global_load_dwordx2 v[250:251], v[244:245], off
	s_nop 0
	s_nop 0
	s_nop 0
	s_nop 0
	s_nop 0
	global_load_dwordx4 v[114:117], v[136:137], off
	global_load_dwordx4 v[110:113], v[100:101], off
	v_add_co_u32_e32 v100, vcc, 0x2c000, v136
	s_nop 1
	v_addc_co_u32_e32 v101, vcc, 0, v137, vcc
	global_load_dwordx4 v[106:109], v[100:101], off
	v_add_co_u32_e32 v100, vcc, 0x42000, v136
	s_nop 1
	v_addc_co_u32_e32 v101, vcc, 0, v137, vcc
	global_load_dwordx4 v[102:105], v[100:101], off
	v_mov_b32_e32 v100, 0
	s_andn2_b64 vcc, exec, s[0:1]
	s_cbranch_vccnz .LBB0_1018
	v_add_co_u32_e32 v118, vcc, 0xfffea000, v136
	s_nop 1
	v_addc_co_u32_e32 v119, vcc, -1, v137, vcc
	global_load_dwordx4 v[118:121], v[118:119], off
.LBB0_1018:
	s_waitcnt vmcnt(0)
	v_lshrrev_b32_e32 v252, 6, v216
	v_lshlrev_b32_e32 v252, 10, v252
	v_add_u32_e32 v252, 0x20200, v252
	v_lshl_add_u32 v253, v241, 3, v252
	v_lshl_add_u32 v254, v242, 5, v252
	ds_write_b64 v253, v[250:251]
	s_waitcnt lgkmcnt(0)
	ds_read_b128 v[64:67], v254 offset:16
	ds_read_b128 v[84:87], v254
	ds_read_b128 v[72:75], v254 offset:144
	ds_read_b128 v[88:91], v254 offset:128
	ds_read_b128 v[76:79], v254 offset:272
	ds_read_b128 v[92:95], v254 offset:256
	ds_read_b128 v[80:83], v254 offset:400
	ds_read_b128 v[96:99], v254 offset:384
	s_waitcnt lgkmcnt(0)
	s_nop 0
	s_nop 0
	s_nop 0
	s_nop 0
	s_nop 0
	s_nop 0
	s_nop 0
	v_mov_b32_dpp v123, v118 row_ror:2 row_mask:0xf bank_mask:0xf bound_ctrl:1
	v_mov_b32_dpp v1, v118 row_ror:1 row_mask:0xf bank_mask:0xf bound_ctrl:1
	v_mov_b32_dpp v101, v119 row_ror:1 row_mask:0xf bank_mask:0xf bound_ctrl:1
	v_mov_b32_dpp v123, v114 row_shr:2 row_mask:0xf bank_mask:0xf
	v_mov_b32_dpp v1, v114 row_shr:1 row_mask:0xf bank_mask:0xf
	v_lshlrev_b32_e32 v138, 16, v123
	v_and_b32_e32 v139, 0xffff0000, v123
	v_mov_b32_dpp v125, v119 row_ror:2 row_mask:0xf bank_mask:0xf bound_ctrl:1
	v_lshlrev_b32_e32 v118, 16, v1
	v_and_b32_e32 v119, 0xffff0000, v1
	v_pk_fma_f32 v[138:139], v[84:85], v[138:139], v[96:97]
	v_lshlrev_b32_e32 v142, 16, v114
	v_and_b32_e32 v143, 0xffff0000, v114
	v_pk_fma_f32 v[118:119], v[88:89], v[118:119], v[138:139]
	v_mov_b32_dpp v125, v115 row_shr:2 row_mask:0xf bank_mask:0xf
	v_pk_fma_f32 v[138:139], v[92:93], v[142:143], v[118:119]
	v_mov_b32_e32 v189, v188
	v_pk_mul_f32 v[118:119], v[138:139], s[30:31] op_sel_hi:[1,0]
	v_mov_b32_dpp v101, v115 row_shr:1 row_mask:0xf bank_mask:0xf
	v_med3_f32 v142, v118, s47, v225
	v_med3_f32 v143, v119, s47, v225
	v_pk_mul_f32 v[144:145], v[142:143], v[142:143]
	v_mov_b64_e32 v[118:119], s[36:37]
	v_pk_fma_f32 v[146:147], v[144:145], s[34:35], v[118:119] op_sel_hi:[1,0,0] neg_lo:[1,0,0] neg_hi:[1,0,0]
	v_lshlrev_b32_e32 v140, 16, v125
	v_pk_fma_f32 v[146:147], v[144:145], v[146:147], s[38:39] op_sel_hi:[1,1,0]
	v_and_b32_e32 v141, 0xffff0000, v125
	v_pk_fma_f32 v[146:147], v[144:145], v[146:147], s[40:41] op_sel_hi:[1,1,0]
	v_pk_mul_f32 v[138:139], v[138:139], 0.5 op_sel_hi:[1,0]
	v_pk_fma_f32 v[146:147], v[144:145], v[146:147], s[42:43] op_sel_hi:[1,1,0]
	v_lshlrev_b32_e32 v136, 16, v101
	v_pk_fma_f32 v[146:147], v[144:145], v[146:147], s[44:45] op_sel_hi:[1,1,0]
	v_and_b32_e32 v137, 0xffff0000, v101
;     static __device__ __forceinline__ u32x2 finish2(const float (&g0)[4], const float (&g1)[4], const float (&g2)[4], const float (&w0)[4], const float (&w1)[4], const float (&w2)[4], const float (&bb)[4],
;                                                     const f32x4 v, float rs) {
;         float h[4];
; #pragma unroll
;         for (int j = 0; j < 4; j += 2) {
;             const f32x2 gc = (f32x2){bb[j] + w0[j] * g2[j] + w1[j] * g1[j] + w2[j] * g0[j], bb[j + 1] + w0[j + 1] * g2[j + 1] + w1[j + 1] * g1[j + 1] + w2[j + 1] * g0[j + 1]};
;             const f32x2 ge = gelu_pk(gc) * ((f32x2){v[j], v[j + 1]} * rs); h[j] = ge.x; h[j + 1] = ge.y; }
;         u32x2 w; w.x = cvt_pk_bf16(h[0], h[1]); w.y = cvt_pk_bf16(h[2], h[3]); return w;
;     }
;     __device__ __forceinline__ void operator()(const f32x4 (&acc)[2][2][4][2], const Unit& u, int wr, int wc, int fr, int fq) const {
;         asm volatile("" : "+v"(fr), "+v"(fq));
;         const int row0 = u.rb + wr * 64 + fr;
;         const int lane = fq * 16 + fr;
;         const int s1 = fr >= 1 ? lane - 1 : lane + 15, s2 = fr >= 2 ? lane - 2 : lane + 14; (void)s1; (void)s2;
;         float rs8[2][4];
; #pragma unroll
;         for (int ai = 0; ai < 2; ++ai)
; #pragma unroll
;             for (int m = 0; m < 4; ++m) rs8[ai][m] = rsqrtf(SS[u.rb + (u.half ? 0 : ai * HALF) + wr * 64 + fr + 16 * m] * (1.f / 1024.f) + 1e-6f);
;         if (u.pm < 128) {
; #pragma unroll
;           for (int bj = 0; bj < 2; ++bj) {
;             const int col8 = u.pn * BM + bj * HALF + wc * 32 + 8 * fq;
;             float w0[2][4], w1[2][4], w2[2][4], bb[2][4];
; #pragma unroll
;             for (int hv = 0; hv < 2; ++hv) { ld4f(cw + col8 + 4 * hv, w0[hv]); ld4f(cw + 2816 + col8 + 4 * hv, w1[hv]); ld4f(cw + 2 * 2816 + col8 + 4 * hv, w2[hv]); ld4f(cb + col8 + 4 * hv, bb[hv]); }
; #pragma unroll
;             for (int ai = 0; ai < 2; ++ai) { const int R0 = u.rb + ai * HALF + wr * 64; const bf16_t* gp = G + (size_t)(R0 + fr) * 2816 + col8;
;                 u32x4 gq[4], prv = (u32x4){0u, 0u, 0u, 0u};
; #pragma unroll
;                 for (int m = 0; m < 4; ++m) gq[m] = *(const u32x4*)(gp + (size_t)m * 16 * 2816);
;                 if ((R0 & 8191) != 0) prv = *(const u32x4*)(gp - (size_t)16 * 2816);
;                 u32x4 pv = prv;
; #pragma unroll
	v_pk_fma_f32 v[146:147], v[144:145], v[146:147], s[46:47] op_sel_hi:[1,1,0]
	v_pk_mul_f32 v[68:69], v[68:69], v[188:189]
	v_pk_fma_f32 v[144:145], v[144:145], v[146:147], s[48:49] op_sel_hi:[1,1,0]
	v_pk_fma_f32 v[140:141], v[86:87], v[140:141], v[98:99]
	v_pk_mul_f32 v[142:143], v[142:143], v[144:145]
	v_pk_fma_f32 v[136:137], v[90:91], v[136:137], v[140:141]
	v_pk_fma_f32 v[138:139], v[138:139], v[142:143], v[138:139]
	v_mov_b32_dpp v123, v120 row_ror:2 row_mask:0xf bank_mask:0xf bound_ctrl:1
	v_pk_mul_f32 v[68:69], v[68:69], v[138:139]
	v_lshlrev_b32_e32 v138, 16, v115
	v_and_b32_e32 v139, 0xffff0000, v115
	v_pk_fma_f32 v[136:137], v[94:95], v[138:139], v[136:137]
	v_pk_mul_f32 v[70:71], v[70:71], v[188:189]
	v_pk_mul_f32 v[138:139], v[136:137], s[30:31] op_sel_hi:[1,0]
	v_pk_mul_f32 v[136:137], v[136:137], 0.5 op_sel_hi:[1,0]
	v_med3_f32 v138, v138, s47, v225
	v_med3_f32 v139, v139, s47, v225
	v_pk_mul_f32 v[140:141], v[138:139], v[138:139]
	v_mov_b32_dpp v1, v120 row_ror:1 row_mask:0xf bank_mask:0xf bound_ctrl:1
	v_pk_fma_f32 v[142:143], v[140:141], s[34:35], v[118:119] op_sel_hi:[1,0,0] neg_lo:[1,0,0] neg_hi:[1,0,0]
	v_mov_b32_dpp v123, v116 row_shr:2 row_mask:0xf bank_mask:0xf
	v_pk_fma_f32 v[142:143], v[140:141], v[142:143], s[38:39] op_sel_hi:[1,1,0]
	v_mov_b32_dpp v1, v116 row_shr:1 row_mask:0xf bank_mask:0xf
	v_pk_fma_f32 v[142:143], v[140:141], v[142:143], s[40:41] op_sel_hi:[1,1,0]
	v_cvt_pk_bf16_f32 v68, v68, v69
	v_mov_b32_dpp v125, v121 row_ror:2 row_mask:0xf bank_mask:0xf bound_ctrl:1
	v_pk_fma_f32 v[142:143], v[140:141], v[142:143], s[42:43] op_sel_hi:[1,1,0]
	v_mov_b32_dpp v101, v121 row_ror:1 row_mask:0xf bank_mask:0xf bound_ctrl:1
	v_pk_fma_f32 v[142:143], v[140:141], v[142:143], s[44:45] op_sel_hi:[1,1,0]
	v_mov_b32_dpp v125, v117 row_shr:2 row_mask:0xf bank_mask:0xf
	v_pk_fma_f32 v[142:143], v[140:141], v[142:143], s[46:47] op_sel_hi:[1,1,0]
	v_mov_b32_dpp v101, v117 row_shr:1 row_mask:0xf bank_mask:0xf
	v_pk_fma_f32 v[140:141], v[140:141], v[142:143], s[48:49] op_sel_hi:[1,1,0]
	v_lshlrev_b32_e32 v120, 16, v101
	v_pk_mul_f32 v[138:139], v[138:139], v[140:141]
	v_lshlrev_b32_e32 v140, 16, v116
	v_pk_fma_f32 v[136:137], v[136:137], v[138:139], v[136:137]
	v_and_b32_e32 v141, 0xffff0000, v116
	v_pk_mul_f32 v[70:71], v[70:71], v[136:137]
	v_lshlrev_b32_e32 v136, 16, v123
	v_and_b32_e32 v137, 0xffff0000, v123
	v_cvt_pk_bf16_f32 v69, v70, v71
	v_lshlrev_b32_e32 v70, 16, v1
	v_and_b32_e32 v71, 0xffff0000, v1
	v_pk_fma_f32 v[136:137], v[64:65], v[136:137], v[80:81]
	v_lshlrev_b32_e32 v138, 16, v125
	v_pk_fma_f32 v[70:71], v[72:73], v[70:71], v[136:137]
	v_and_b32_e32 v139, 0xffff0000, v125
	v_pk_fma_f32 v[70:71], v[76:77], v[140:141], v[70:71]
	v_and_b32_e32 v121, 0xffff0000, v101
	v_pk_mul_f32 v[136:137], v[70:71], s[30:31] op_sel_hi:[1,0]
	v_pk_mul_f32 v[70:71], v[70:71], 0.5 op_sel_hi:[1,0]
	v_med3_f32 v136, v136, s47, v225
	v_med3_f32 v137, v137, s47, v225
	v_pk_mul_f32 v[140:141], v[136:137], v[136:137]
	v_pk_mul_f32 v[60:61], v[60:61], v[188:189]
	v_pk_fma_f32 v[142:143], v[140:141], s[34:35], v[118:119] op_sel_hi:[1,0,0] neg_lo:[1,0,0] neg_hi:[1,0,0]
	v_pk_mul_f32 v[62:63], v[62:63], v[188:189]
	v_pk_fma_f32 v[142:143], v[140:141], v[142:143], s[38:39] op_sel_hi:[1,1,0]
	v_mov_b32_dpp v1, v114 row_ror:1 row_mask:0xf bank_mask:0xf bound_ctrl:1
	v_pk_fma_f32 v[142:143], v[140:141], v[142:143], s[40:41] op_sel_hi:[1,1,0]
	v_mov_b32_dpp v101, v115 row_ror:2 row_mask:0xf bank_mask:0xf bound_ctrl:1
	v_pk_fma_f32 v[142:143], v[140:141], v[142:143], s[42:43] op_sel_hi:[1,1,0]
	v_mov_b32_dpp v1, v110 row_shr:1 row_mask:0xf bank_mask:0xf
	v_pk_fma_f32 v[142:143], v[140:141], v[142:143], s[44:45] op_sel_hi:[1,1,0]
	v_mov_b32_dpp v101, v111 row_shr:2 row_mask:0xf bank_mask:0xf
	v_pk_fma_f32 v[142:143], v[140:141], v[142:143], s[46:47] op_sel_hi:[1,1,0]
	v_mov_b32_e32 v187, v186
	v_pk_fma_f32 v[140:141], v[140:141], v[142:143], s[48:49] op_sel_hi:[1,1,0]
	v_pk_mul_f32 v[56:57], v[56:57], v[186:187]
	v_pk_mul_f32 v[136:137], v[136:137], v[140:141]
	v_pk_mul_f32 v[58:59], v[58:59], v[186:187]
	v_pk_fma_f32 v[70:71], v[70:71], v[136:137], v[70:71]
	v_pk_fma_f32 v[136:137], v[66:67], v[138:139], v[82:83]
	v_pk_mul_f32 v[60:61], v[60:61], v[70:71]
	v_lshlrev_b32_e32 v70, 16, v117
	v_and_b32_e32 v71, 0xffff0000, v117
	v_pk_fma_f32 v[120:121], v[74:75], v[120:121], v[136:137]
	v_pk_mul_f32 v[52:53], v[52:53], v[186:187]
	v_pk_fma_f32 v[70:71], v[78:79], v[70:71], v[120:121]
	v_pk_mul_f32 v[54:55], v[54:55], v[186:187]
	v_pk_mul_f32 v[120:121], v[70:71], s[30:31] op_sel_hi:[1,0]
	v_pk_mul_f32 v[70:71], v[70:71], 0.5 op_sel_hi:[1,0]
	v_med3_f32 v120, v120, s47, v225
	v_med3_f32 v121, v121, s47, v225
	v_pk_mul_f32 v[136:137], v[120:121], v[120:121]
	v_mov_b32_e32 v185, v184
	v_pk_fma_f32 v[138:139], v[136:137], s[34:35], v[118:119] op_sel_hi:[1,0,0] neg_lo:[1,0,0] neg_hi:[1,0,0]
	v_pk_mul_f32 v[48:49], v[48:49], v[184:185]
	v_pk_fma_f32 v[138:139], v[136:137], v[138:139], s[38:39] op_sel_hi:[1,1,0]
	v_pk_mul_f32 v[50:51], v[50:51], v[184:185]
	v_pk_fma_f32 v[138:139], v[136:137], v[138:139], s[40:41] op_sel_hi:[1,1,0]
	v_pk_mul_f32 v[44:45], v[44:45], v[184:185]
	v_pk_fma_f32 v[138:139], v[136:137], v[138:139], s[42:43] op_sel_hi:[1,1,0]
	v_pk_mul_f32 v[46:47], v[46:47], v[184:185]
	v_pk_fma_f32 v[138:139], v[136:137], v[138:139], s[44:45] op_sel_hi:[1,1,0]
	v_mov_b32_e32 v3, v2
	v_pk_fma_f32 v[138:139], v[136:137], v[138:139], s[46:47] op_sel_hi:[1,1,0]
	v_pk_mul_f32 v[40:41], v[40:41], v[2:3]
	v_pk_fma_f32 v[136:137], v[136:137], v[138:139], s[48:49] op_sel_hi:[1,1,0]
	v_pk_mul_f32 v[42:43], v[42:43], v[2:3]
;     static __device__ __forceinline__ u32x2 finish2(const float (&g0)[4], const float (&g1)[4], const float (&g2)[4], const float (&w0)[4], const float (&w1)[4], const float (&w2)[4], const float (&bb)[4],
;                                                     const f32x4 v, float rs) {
;         float h[4];
; #pragma unroll
;         for (int j = 0; j < 4; j += 2) {
;             const f32x2 gc = (f32x2){bb[j] + w0[j] * g2[j] + w1[j] * g1[j] + w2[j] * g0[j], bb[j + 1] + w0[j + 1] * g2[j + 1] + w1[j + 1] * g1[j + 1] + w2[j + 1] * g0[j + 1]};
;             const f32x2 ge = gelu_pk(gc) * ((f32x2){v[j], v[j + 1]} * rs); h[j] = ge.x; h[j + 1] = ge.y; }
;         u32x2 w; w.x = cvt_pk_bf16(h[0], h[1]); w.y = cvt_pk_bf16(h[2], h[3]); return w;
;     }
;     __device__ __forceinline__ void operator()(const f32x4 (&acc)[2][2][4][2], const Unit& u, int wr, int wc, int fr, int fq) const {
;         asm volatile("" : "+v"(fr), "+v"(fq));
;         const int row0 = u.rb + wr * 64 + fr;
;         const int lane = fq * 16 + fr;
;         const int s1 = fr >= 1 ? lane - 1 : lane + 15, s2 = fr >= 2 ? lane - 2 : lane + 14; (void)s1; (void)s2;
;         float rs8[2][4];
; #pragma unroll
;         for (int ai = 0; ai < 2; ++ai)
; #pragma unroll
;             for (int m = 0; m < 4; ++m) rs8[ai][m] = rsqrtf(SS[u.rb + (u.half ? 0 : ai * HALF) + wr * 64 + fr + 16 * m] * (1.f / 1024.f) + 1e-6f);
;         if (u.pm < 128) {
; #pragma unroll
;           for (int bj = 0; bj < 2; ++bj) {
;             const int col8 = u.pn * BM + bj * HALF + wc * 32 + 8 * fq;
;             float w0[2][4], w1[2][4], w2[2][4], bb[2][4];
; #pragma unroll
;             for (int hv = 0; hv < 2; ++hv) { ld4f(cw + col8 + 4 * hv, w0[hv]); ld4f(cw + 2816 + col8 + 4 * hv, w1[hv]); ld4f(cw + 2 * 2816 + col8 + 4 * hv, w2[hv]); ld4f(cb + col8 + 4 * hv, bb[hv]); }
; #pragma unroll
;             for (int ai = 0; ai < 2; ++ai) { const int R0 = u.rb + ai * HALF + wr * 64; const bf16_t* gp = G + (size_t)(R0 + fr) * 2816 + col8;
;                 u32x4 gq[4], prv = (u32x4){0u, 0u, 0u, 0u};
; #pragma unroll
;                 for (int m = 0; m < 4; ++m) gq[m] = *(const u32x4*)(gp + (size_t)m * 16 * 2816);
;                 if ((R0 & 8191) != 0) prv = *(const u32x4*)(gp - (size_t)16 * 2816);
;                 u32x4 pv = prv;
; #pragma unroll
	v_pk_mul_f32 v[120:121], v[120:121], v[136:137]
	v_pk_mul_f32 v[36:37], v[36:37], v[2:3]
	v_pk_fma_f32 v[70:71], v[70:71], v[120:121], v[70:71]
	v_lshlrev_b32_e32 v120, 16, v110
	v_pk_mul_f32 v[62:63], v[62:63], v[70:71]
	v_cvt_pk_bf16_f32 v70, v60, v61
	v_lshlrev_b64 v[60:61], 1, v[134:135]
	v_cvt_pk_bf16_f32 v71, v62, v63
	v_lshl_add_u64 v[62:63], v[130:131], 0, v[60:61]
	global_store_dwordx4 v[62:63], v[68:71], off
	v_lshlrev_b32_e32 v62, 16, v1
	v_and_b32_e32 v63, 0xffff0000, v1
	v_mov_b32_dpp v71, v114 row_ror:2 row_mask:0xf bank_mask:0xf bound_ctrl:1
	v_and_b32_e32 v121, 0xffff0000, v110
	v_mov_b32_dpp v69, v115 row_ror:1 row_mask:0xf bank_mask:0xf bound_ctrl:1
	v_mov_b32_dpp v71, v110 row_shr:2 row_mask:0xf bank_mask:0xf
	v_lshlrev_b32_e32 v70, 16, v71
	v_and_b32_e32 v71, 0xffff0000, v71
	v_pk_fma_f32 v[70:71], v[84:85], v[70:71], v[96:97]
	v_mov_b32_dpp v69, v111 row_shr:1 row_mask:0xf bank_mask:0xf
	v_pk_fma_f32 v[62:63], v[88:89], v[62:63], v[70:71]
	v_lshlrev_b32_e32 v114, 16, v101
	v_pk_fma_f32 v[62:63], v[92:93], v[120:121], v[62:63]
	v_and_b32_e32 v115, 0xffff0000, v101
	v_pk_mul_f32 v[70:71], v[62:63], s[30:31] op_sel_hi:[1,0]
	v_pk_mul_f32 v[62:63], v[62:63], 0.5 op_sel_hi:[1,0]
	v_med3_f32 v70, v70, s47, v225
	v_med3_f32 v71, v71, s47, v225
	v_pk_mul_f32 v[120:121], v[70:71], v[70:71]
	v_lshlrev_b32_e32 v68, 16, v69
	v_pk_fma_f32 v[130:131], v[120:121], s[34:35], v[118:119] op_sel_hi:[1,0,0] neg_lo:[1,0,0] neg_hi:[1,0,0]
	v_and_b32_e32 v69, 0xffff0000, v69
	v_pk_fma_f32 v[130:131], v[120:121], v[130:131], s[38:39] op_sel_hi:[1,1,0]
	v_mov_b32_dpp v1, v116 row_ror:1 row_mask:0xf bank_mask:0xf bound_ctrl:1
	v_pk_fma_f32 v[130:131], v[120:121], v[130:131], s[40:41] op_sel_hi:[1,1,0]
	v_pk_mul_f32 v[2:3], v[38:39], v[2:3]
	v_pk_fma_f32 v[130:131], v[120:121], v[130:131], s[42:43] op_sel_hi:[1,1,0]
	v_mov_b32_dpp v1, v112 row_shr:1 row_mask:0xf bank_mask:0xf
	v_pk_fma_f32 v[130:131], v[120:121], v[130:131], s[44:45] op_sel_hi:[1,1,0]
	v_readlane_b32 s64, v240, 23
	v_pk_fma_f32 v[130:131], v[120:121], v[130:131], s[46:47] op_sel_hi:[1,1,0]
	v_mov_b32_e32 v101, 0
	v_pk_fma_f32 v[120:121], v[120:121], v[130:131], s[48:49] op_sel_hi:[1,1,0]
	v_readlane_b32 s65, v240, 24
	v_pk_mul_f32 v[70:71], v[70:71], v[120:121]
	s_mov_b64 s[54:55], s[68:69]
	v_pk_fma_f32 v[62:63], v[62:63], v[70:71], v[62:63]
	v_pk_fma_f32 v[70:71], v[86:87], v[114:115], v[98:99]
	v_pk_mul_f32 v[56:57], v[56:57], v[62:63]
	v_lshlrev_b32_e32 v62, 16, v111
	v_and_b32_e32 v63, 0xffff0000, v111
	v_pk_fma_f32 v[68:69], v[90:91], v[68:69], v[70:71]
	v_cvt_pk_bf16_f32 v56, v56, v57
	s_nop 0
	v_pk_fma_f32 v[62:63], v[94:95], v[62:63], v[68:69]
	s_nop 0
	v_pk_mul_f32 v[68:69], v[62:63], s[30:31] op_sel_hi:[1,0]
	v_pk_mul_f32 v[62:63], v[62:63], 0.5 op_sel_hi:[1,0]
	v_med3_f32 v68, v68, s47, v225
	v_med3_f32 v69, v69, s47, v225
	v_pk_mul_f32 v[70:71], v[68:69], v[68:69]
	s_nop 0
	v_pk_fma_f32 v[114:115], v[70:71], s[34:35], v[118:119] op_sel_hi:[1,0,0] neg_lo:[1,0,0] neg_hi:[1,0,0]
	s_nop 0
	v_pk_fma_f32 v[114:115], v[70:71], v[114:115], s[38:39] op_sel_hi:[1,1,0]
	s_nop 0
	v_pk_fma_f32 v[114:115], v[70:71], v[114:115], s[40:41] op_sel_hi:[1,1,0]
	s_nop 0
	v_pk_fma_f32 v[114:115], v[70:71], v[114:115], s[42:43] op_sel_hi:[1,1,0]
	s_nop 0
	v_pk_fma_f32 v[114:115], v[70:71], v[114:115], s[44:45] op_sel_hi:[1,1,0]
	s_nop 0
	v_pk_fma_f32 v[114:115], v[70:71], v[114:115], s[46:47] op_sel_hi:[1,1,0]
	s_nop 0
	v_pk_fma_f32 v[70:71], v[70:71], v[114:115], s[48:49] op_sel_hi:[1,1,0]
	v_lshlrev_b32_e32 v114, 16, v112
	v_pk_mul_f32 v[68:69], v[68:69], v[70:71]
	v_and_b32_e32 v115, 0xffff0000, v112
	v_pk_fma_f32 v[62:63], v[62:63], v[68:69], v[62:63]
	v_mov_b32_dpp v69, v116 row_ror:2 row_mask:0xf bank_mask:0xf bound_ctrl:1
	v_pk_mul_f32 v[58:59], v[58:59], v[62:63]
	v_mov_b32_dpp v63, v117 row_ror:1 row_mask:0xf bank_mask:0xf bound_ctrl:1
	v_mov_b32_dpp v69, v112 row_shr:2 row_mask:0xf bank_mask:0xf
	v_lshlrev_b32_e32 v68, 16, v69
	v_and_b32_e32 v69, 0xffff0000, v69
	v_cvt_pk_bf16_f32 v57, v58, v59
	v_lshlrev_b32_e32 v58, 16, v1
	v_and_b32_e32 v59, 0xffff0000, v1
	v_pk_fma_f32 v[68:69], v[64:65], v[68:69], v[80:81]
	v_mov_b32_dpp v71, v117 row_ror:2 row_mask:0xf bank_mask:0xf bound_ctrl:1
	v_pk_fma_f32 v[58:59], v[72:73], v[58:59], v[68:69]
	v_mov_b32_dpp v63, v113 row_shr:1 row_mask:0xf bank_mask:0xf
	v_pk_fma_f32 v[58:59], v[76:77], v[114:115], v[58:59]
	v_mov_b32_dpp v71, v113 row_shr:2 row_mask:0xf bank_mask:0xf
	v_pk_mul_f32 v[68:69], v[58:59], s[30:31] op_sel_hi:[1,0]
	v_lshlrev_b32_e32 v70, 16, v71
	v_med3_f32 v68, v68, s47, v225
	v_med3_f32 v69, v69, s47, v225
	v_pk_mul_f32 v[114:115], v[68:69], v[68:69]
	v_and_b32_e32 v71, 0xffff0000, v71
	v_pk_fma_f32 v[116:117], v[114:115], s[34:35], v[118:119] op_sel_hi:[1,0,0] neg_lo:[1,0,0] neg_hi:[1,0,0]
	v_pk_mul_f32 v[58:59], v[58:59], 0.5 op_sel_hi:[1,0]
	v_pk_fma_f32 v[116:117], v[114:115], v[116:117], s[38:39] op_sel_hi:[1,1,0]
	v_lshlrev_b32_e32 v62, 16, v63
	v_pk_fma_f32 v[116:117], v[114:115], v[116:117], s[40:41] op_sel_hi:[1,1,0]
	v_and_b32_e32 v63, 0xffff0000, v63
	v_pk_fma_f32 v[116:117], v[114:115], v[116:117], s[42:43] op_sel_hi:[1,1,0]
	v_mov_b32_dpp v1, v110 row_ror:1 row_mask:0xf bank_mask:0xf bound_ctrl:1
	v_pk_fma_f32 v[116:117], v[114:115], v[116:117], s[44:45] op_sel_hi:[1,1,0]
	s_nop 0
	v_pk_fma_f32 v[116:117], v[114:115], v[116:117], s[46:47] op_sel_hi:[1,1,0]
	v_mov_b32_dpp v1, v106 row_shr:1 row_mask:0xf bank_mask:0xf
	v_pk_fma_f32 v[114:115], v[114:115], v[116:117], s[48:49] op_sel_hi:[1,1,0]
	s_nop 0
	v_pk_mul_f32 v[68:69], v[68:69], v[114:115]
	s_nop 0
	v_pk_fma_f32 v[58:59], v[58:59], v[68:69], v[58:59]
;     static __device__ __forceinline__ u32x2 finish2(const float (&g0)[4], const float (&g1)[4], const float (&g2)[4], const float (&w0)[4], const float (&w1)[4], const float (&w2)[4], const float (&bb)[4],
;                                                     const f32x4 v, float rs) {
;         float h[4];
; #pragma unroll
;         for (int j = 0; j < 4; j += 2) {
;             const f32x2 gc = (f32x2){bb[j] + w0[j] * g2[j] + w1[j] * g1[j] + w2[j] * g0[j], bb[j + 1] + w0[j + 1] * g2[j + 1] + w1[j + 1] * g1[j + 1] + w2[j + 1] * g0[j + 1]};
;             const f32x2 ge = gelu_pk(gc) * ((f32x2){v[j], v[j + 1]} * rs); h[j] = ge.x; h[j + 1] = ge.y; }
;         u32x2 w; w.x = cvt_pk_bf16(h[0], h[1]); w.y = cvt_pk_bf16(h[2], h[3]); return w;
;     }
;     __device__ __forceinline__ void operator()(const f32x4 (&acc)[2][2][4][2], const Unit& u, int wr, int wc, int fr, int fq) const {
;         asm volatile("" : "+v"(fr), "+v"(fq));
;         const int row0 = u.rb + wr * 64 + fr;
;         const int lane = fq * 16 + fr;
;         const int s1 = fr >= 1 ? lane - 1 : lane + 15, s2 = fr >= 2 ? lane - 2 : lane + 14; (void)s1; (void)s2;
;         float rs8[2][4];
; #pragma unroll
;         for (int ai = 0; ai < 2; ++ai)
; #pragma unroll
;             for (int m = 0; m < 4; ++m) rs8[ai][m] = rsqrtf(SS[u.rb + (u.half ? 0 : ai * HALF) + wr * 64 + fr + 16 * m] * (1.f / 1024.f) + 1e-6f);
;         if (u.pm < 128) {
; #pragma unroll
;           for (int bj = 0; bj < 2; ++bj) {
;             const int col8 = u.pn * BM + bj * HALF + wc * 32 + 8 * fq;
;             float w0[2][4], w1[2][4], w2[2][4], bb[2][4];
; #pragma unroll
;             for (int hv = 0; hv < 2; ++hv) { ld4f(cw + col8 + 4 * hv, w0[hv]); ld4f(cw + 2816 + col8 + 4 * hv, w1[hv]); ld4f(cw + 2 * 2816 + col8 + 4 * hv, w2[hv]); ld4f(cb + col8 + 4 * hv, bb[hv]); }
; #pragma unroll
;             for (int ai = 0; ai < 2; ++ai) { const int R0 = u.rb + ai * HALF + wr * 64; const bf16_t* gp = G + (size_t)(R0 + fr) * 2816 + col8;
;                 u32x4 gq[4], prv = (u32x4){0u, 0u, 0u, 0u};
; #pragma unroll
;                 for (int m = 0; m < 4; ++m) gq[m] = *(const u32x4*)(gp + (size_t)m * 16 * 2816);
;                 if ((R0 & 8191) != 0) prv = *(const u32x4*)(gp - (size_t)16 * 2816);
;                 u32x4 pv = prv;
; #pragma unroll
	v_pk_fma_f32 v[68:69], v[66:67], v[70:71], v[82:83]
	v_pk_mul_f32 v[52:53], v[52:53], v[58:59]
	v_lshlrev_b32_e32 v58, 16, v113
	v_and_b32_e32 v59, 0xffff0000, v113
	v_pk_fma_f32 v[62:63], v[74:75], v[62:63], v[68:69]
	s_nop 0
	v_pk_fma_f32 v[58:59], v[78:79], v[58:59], v[62:63]
	s_nop 0
	v_pk_mul_f32 v[62:63], v[58:59], s[30:31] op_sel_hi:[1,0]
	v_pk_mul_f32 v[58:59], v[58:59], 0.5 op_sel_hi:[1,0]
	v_med3_f32 v62, v62, s47, v225
	v_med3_f32 v63, v63, s47, v225
	v_pk_mul_f32 v[68:69], v[62:63], v[62:63]
	s_nop 0
	v_pk_fma_f32 v[70:71], v[68:69], s[34:35], v[118:119] op_sel_hi:[1,0,0] neg_lo:[1,0,0] neg_hi:[1,0,0]
	s_nop 0
	v_pk_fma_f32 v[70:71], v[68:69], v[70:71], s[38:39] op_sel_hi:[1,1,0]
	s_nop 0
	v_pk_fma_f32 v[70:71], v[68:69], v[70:71], s[40:41] op_sel_hi:[1,1,0]
	s_nop 0
	v_pk_fma_f32 v[70:71], v[68:69], v[70:71], s[42:43] op_sel_hi:[1,1,0]
	s_nop 0
	v_pk_fma_f32 v[70:71], v[68:69], v[70:71], s[44:45] op_sel_hi:[1,1,0]
	s_nop 0
	v_pk_fma_f32 v[70:71], v[68:69], v[70:71], s[46:47] op_sel_hi:[1,1,0]
	s_nop 0
	v_pk_fma_f32 v[68:69], v[68:69], v[70:71], s[48:49] op_sel_hi:[1,1,0]
	s_nop 0
	v_pk_mul_f32 v[62:63], v[62:63], v[68:69]
	s_nop 0
	v_pk_fma_f32 v[58:59], v[58:59], v[62:63], v[58:59]
	v_lshlrev_b32_e32 v62, 16, v106
	v_pk_mul_f32 v[54:55], v[54:55], v[58:59]
	v_cvt_pk_bf16_f32 v58, v52, v53
	v_lshl_add_u64 v[52:53], v[176:177], 0, v[60:61]
	v_cvt_pk_bf16_f32 v59, v54, v55
	global_store_dwordx4 v[52:53], v[56:59], off
	v_lshlrev_b32_e32 v52, 16, v1
	v_and_b32_e32 v53, 0xffff0000, v1
	v_mov_b32_dpp v57, v110 row_ror:2 row_mask:0xf bank_mask:0xf bound_ctrl:1
	v_and_b32_e32 v63, 0xffff0000, v106
	v_mov_b32_dpp v59, v111 row_ror:2 row_mask:0xf bank_mask:0xf bound_ctrl:1
	v_mov_b32_dpp v57, v106 row_shr:2 row_mask:0xf bank_mask:0xf
	v_lshlrev_b32_e32 v56, 16, v57
	v_and_b32_e32 v57, 0xffff0000, v57
	v_pk_fma_f32 v[56:57], v[84:85], v[56:57], v[96:97]
	v_mov_b32_dpp v55, v111 row_ror:1 row_mask:0xf bank_mask:0xf bound_ctrl:1
	v_pk_fma_f32 v[52:53], v[88:89], v[52:53], v[56:57]
	v_mov_b32_dpp v59, v107 row_shr:2 row_mask:0xf bank_mask:0xf
	v_pk_fma_f32 v[52:53], v[92:93], v[62:63], v[52:53]
	v_mov_b32_dpp v55, v107 row_shr:1 row_mask:0xf bank_mask:0xf
	v_pk_mul_f32 v[56:57], v[52:53], s[30:31] op_sel_hi:[1,0]
	v_lshlrev_b32_e32 v58, 16, v59
	v_med3_f32 v56, v56, s47, v225
	v_med3_f32 v57, v57, s47, v225
	v_pk_mul_f32 v[62:63], v[56:57], v[56:57]
	v_and_b32_e32 v59, 0xffff0000, v59
	v_pk_fma_f32 v[68:69], v[62:63], s[34:35], v[118:119] op_sel_hi:[1,0,0] neg_lo:[1,0,0] neg_hi:[1,0,0]
	v_pk_mul_f32 v[52:53], v[52:53], 0.5 op_sel_hi:[1,0]
	v_pk_fma_f32 v[68:69], v[62:63], v[68:69], s[38:39] op_sel_hi:[1,1,0]
	v_lshlrev_b32_e32 v54, 16, v55
	v_pk_fma_f32 v[68:69], v[62:63], v[68:69], s[40:41] op_sel_hi:[1,1,0]
	v_and_b32_e32 v55, 0xffff0000, v55
	v_pk_fma_f32 v[68:69], v[62:63], v[68:69], s[42:43] op_sel_hi:[1,1,0]
	v_mov_b32_dpp v1, v112 row_ror:1 row_mask:0xf bank_mask:0xf bound_ctrl:1
	v_pk_fma_f32 v[68:69], v[62:63], v[68:69], s[44:45] op_sel_hi:[1,1,0]
	s_nop 0
	v_pk_fma_f32 v[68:69], v[62:63], v[68:69], s[46:47] op_sel_hi:[1,1,0]
	v_mov_b32_dpp v1, v108 row_shr:1 row_mask:0xf bank_mask:0xf
	v_pk_fma_f32 v[62:63], v[62:63], v[68:69], s[48:49] op_sel_hi:[1,1,0]
	s_nop 0
	v_pk_mul_f32 v[56:57], v[56:57], v[62:63]
	s_nop 0
	v_pk_fma_f32 v[52:53], v[52:53], v[56:57], v[52:53]
	v_pk_fma_f32 v[56:57], v[86:87], v[58:59], v[98:99]
	v_pk_mul_f32 v[48:49], v[48:49], v[52:53]
	v_lshlrev_b32_e32 v52, 16, v107
	v_and_b32_e32 v53, 0xffff0000, v107
	v_pk_fma_f32 v[54:55], v[90:91], v[54:55], v[56:57]
	v_cvt_pk_bf16_f32 v48, v48, v49
	s_nop 0
	v_pk_fma_f32 v[52:53], v[94:95], v[52:53], v[54:55]
	s_nop 0
	v_pk_mul_f32 v[54:55], v[52:53], s[30:31] op_sel_hi:[1,0]
	v_pk_mul_f32 v[52:53], v[52:53], 0.5 op_sel_hi:[1,0]
	v_med3_f32 v54, v54, s47, v225
	v_med3_f32 v55, v55, s47, v225
	v_pk_mul_f32 v[56:57], v[54:55], v[54:55]
	s_nop 0
	v_pk_fma_f32 v[58:59], v[56:57], s[34:35], v[118:119] op_sel_hi:[1,0,0] neg_lo:[1,0,0] neg_hi:[1,0,0]
	s_nop 0
	v_pk_fma_f32 v[58:59], v[56:57], v[58:59], s[38:39] op_sel_hi:[1,1,0]
	s_nop 0
	v_pk_fma_f32 v[58:59], v[56:57], v[58:59], s[40:41] op_sel_hi:[1,1,0]
	s_nop 0
	v_pk_fma_f32 v[58:59], v[56:57], v[58:59], s[42:43] op_sel_hi:[1,1,0]
	s_nop 0
	v_pk_fma_f32 v[58:59], v[56:57], v[58:59], s[44:45] op_sel_hi:[1,1,0]
	s_nop 0
	v_pk_fma_f32 v[58:59], v[56:57], v[58:59], s[46:47] op_sel_hi:[1,1,0]
	s_nop 0
	v_pk_fma_f32 v[56:57], v[56:57], v[58:59], s[48:49] op_sel_hi:[1,1,0]
	v_lshlrev_b32_e32 v58, 16, v108
	v_pk_mul_f32 v[54:55], v[54:55], v[56:57]
	v_and_b32_e32 v59, 0xffff0000, v108
	v_pk_fma_f32 v[52:53], v[52:53], v[54:55], v[52:53]
	v_mov_b32_dpp v55, v112 row_ror:2 row_mask:0xf bank_mask:0xf bound_ctrl:1
	v_pk_mul_f32 v[50:51], v[50:51], v[52:53]
	v_mov_b32_dpp v57, v113 row_ror:2 row_mask:0xf bank_mask:0xf bound_ctrl:1
	v_mov_b32_dpp v55, v108 row_shr:2 row_mask:0xf bank_mask:0xf
	v_lshlrev_b32_e32 v54, 16, v55
	v_and_b32_e32 v55, 0xffff0000, v55
	v_cvt_pk_bf16_f32 v49, v50, v51
	v_lshlrev_b32_e32 v50, 16, v1
	v_and_b32_e32 v51, 0xffff0000, v1
	v_pk_fma_f32 v[54:55], v[64:65], v[54:55], v[80:81]
	v_mov_b32_dpp v53, v113 row_ror:1 row_mask:0xf bank_mask:0xf bound_ctrl:1
	v_pk_fma_f32 v[50:51], v[72:73], v[50:51], v[54:55]
	v_mov_b32_dpp v57, v109 row_shr:2 row_mask:0xf bank_mask:0xf
	v_pk_fma_f32 v[50:51], v[76:77], v[58:59], v[50:51]
	v_mov_b32_dpp v53, v109 row_shr:1 row_mask:0xf bank_mask:0xf
	v_pk_mul_f32 v[54:55], v[50:51], s[30:31] op_sel_hi:[1,0]
	v_lshlrev_b32_e32 v56, 16, v57
	v_med3_f32 v54, v54, s47, v225
	v_med3_f32 v55, v55, s47, v225
	v_pk_mul_f32 v[58:59], v[54:55], v[54:55]
	v_and_b32_e32 v57, 0xffff0000, v57
;     static __device__ __forceinline__ u32x2 finish2(const float (&g0)[4], const float (&g1)[4], const float (&g2)[4], const float (&w0)[4], const float (&w1)[4], const float (&w2)[4], const float (&bb)[4],
;                                                     const f32x4 v, float rs) {
;         float h[4];
; #pragma unroll
;         for (int j = 0; j < 4; j += 2) {
;             const f32x2 gc = (f32x2){bb[j] + w0[j] * g2[j] + w1[j] * g1[j] + w2[j] * g0[j], bb[j + 1] + w0[j + 1] * g2[j + 1] + w1[j + 1] * g1[j + 1] + w2[j + 1] * g0[j + 1]};
;             const f32x2 ge = gelu_pk(gc) * ((f32x2){v[j], v[j + 1]} * rs); h[j] = ge.x; h[j + 1] = ge.y; }
;         u32x2 w; w.x = cvt_pk_bf16(h[0], h[1]); w.y = cvt_pk_bf16(h[2], h[3]); return w;
;     }
;     __device__ __forceinline__ void operator()(const f32x4 (&acc)[2][2][4][2], const Unit& u, int wr, int wc, int fr, int fq) const {
;         asm volatile("" : "+v"(fr), "+v"(fq));
;         const int row0 = u.rb + wr * 64 + fr;
;         const int lane = fq * 16 + fr;
;         const int s1 = fr >= 1 ? lane - 1 : lane + 15, s2 = fr >= 2 ? lane - 2 : lane + 14; (void)s1; (void)s2;
;         float rs8[2][4];
; #pragma unroll
;         for (int ai = 0; ai < 2; ++ai)
; #pragma unroll
;             for (int m = 0; m < 4; ++m) rs8[ai][m] = rsqrtf(SS[u.rb + (u.half ? 0 : ai * HALF) + wr * 64 + fr + 16 * m] * (1.f / 1024.f) + 1e-6f);
;         if (u.pm < 128) {
; #pragma unroll
;           for (int bj = 0; bj < 2; ++bj) {
;             const int col8 = u.pn * BM + bj * HALF + wc * 32 + 8 * fq;
;             float w0[2][4], w1[2][4], w2[2][4], bb[2][4];
; #pragma unroll
;             for (int hv = 0; hv < 2; ++hv) { ld4f(cw + col8 + 4 * hv, w0[hv]); ld4f(cw + 2816 + col8 + 4 * hv, w1[hv]); ld4f(cw + 2 * 2816 + col8 + 4 * hv, w2[hv]); ld4f(cb + col8 + 4 * hv, bb[hv]); }
; #pragma unroll
;             for (int ai = 0; ai < 2; ++ai) { const int R0 = u.rb + ai * HALF + wr * 64; const bf16_t* gp = G + (size_t)(R0 + fr) * 2816 + col8;
;                 u32x4 gq[4], prv = (u32x4){0u, 0u, 0u, 0u};
; #pragma unroll
;                 for (int m = 0; m < 4; ++m) gq[m] = *(const u32x4*)(gp + (size_t)m * 16 * 2816);
;                 if ((R0 & 8191) != 0) prv = *(const u32x4*)(gp - (size_t)16 * 2816);
;                 u32x4 pv = prv;
; #pragma unroll
	v_pk_fma_f32 v[62:63], v[58:59], s[34:35], v[118:119] op_sel_hi:[1,0,0] neg_lo:[1,0,0] neg_hi:[1,0,0]
	v_pk_mul_f32 v[50:51], v[50:51], 0.5 op_sel_hi:[1,0]
	v_pk_fma_f32 v[62:63], v[58:59], v[62:63], s[38:39] op_sel_hi:[1,1,0]
	v_lshlrev_b32_e32 v52, 16, v53
	v_pk_fma_f32 v[62:63], v[58:59], v[62:63], s[40:41] op_sel_hi:[1,1,0]
	v_and_b32_e32 v53, 0xffff0000, v53
	v_pk_fma_f32 v[62:63], v[58:59], v[62:63], s[42:43] op_sel_hi:[1,1,0]
	v_mov_b32_dpp v1, v106 row_ror:1 row_mask:0xf bank_mask:0xf bound_ctrl:1
	v_pk_fma_f32 v[62:63], v[58:59], v[62:63], s[44:45] op_sel_hi:[1,1,0]
	s_nop 0
	v_pk_fma_f32 v[62:63], v[58:59], v[62:63], s[46:47] op_sel_hi:[1,1,0]
	v_mov_b32_dpp v1, v102 row_shr:1 row_mask:0xf bank_mask:0xf
	v_pk_fma_f32 v[58:59], v[58:59], v[62:63], s[48:49] op_sel_hi:[1,1,0]
	s_nop 0
	v_pk_mul_f32 v[54:55], v[54:55], v[58:59]
	s_nop 0
	v_pk_fma_f32 v[50:51], v[50:51], v[54:55], v[50:51]
	v_pk_fma_f32 v[54:55], v[66:67], v[56:57], v[82:83]
	v_pk_mul_f32 v[44:45], v[44:45], v[50:51]
	v_lshlrev_b32_e32 v50, 16, v109
	v_and_b32_e32 v51, 0xffff0000, v109
	v_pk_fma_f32 v[52:53], v[74:75], v[52:53], v[54:55]
	s_nop 0
	v_pk_fma_f32 v[50:51], v[78:79], v[50:51], v[52:53]
	s_nop 0
	v_pk_mul_f32 v[52:53], v[50:51], s[30:31] op_sel_hi:[1,0]
	v_pk_mul_f32 v[50:51], v[50:51], 0.5 op_sel_hi:[1,0]
	v_med3_f32 v52, v52, s47, v225
	v_med3_f32 v53, v53, s47, v225
	v_pk_mul_f32 v[54:55], v[52:53], v[52:53]
	s_nop 0
	v_pk_fma_f32 v[56:57], v[54:55], s[34:35], v[118:119] op_sel_hi:[1,0,0] neg_lo:[1,0,0] neg_hi:[1,0,0]
	s_nop 0
	v_pk_fma_f32 v[56:57], v[54:55], v[56:57], s[38:39] op_sel_hi:[1,1,0]
	s_nop 0
	v_pk_fma_f32 v[56:57], v[54:55], v[56:57], s[40:41] op_sel_hi:[1,1,0]
	s_nop 0
	v_pk_fma_f32 v[56:57], v[54:55], v[56:57], s[42:43] op_sel_hi:[1,1,0]
	s_nop 0
	v_pk_fma_f32 v[56:57], v[54:55], v[56:57], s[44:45] op_sel_hi:[1,1,0]
	s_nop 0
	v_pk_fma_f32 v[56:57], v[54:55], v[56:57], s[46:47] op_sel_hi:[1,1,0]
	s_nop 0
	v_pk_fma_f32 v[54:55], v[54:55], v[56:57], s[48:49] op_sel_hi:[1,1,0]
	v_lshl_add_u64 v[56:57], v[166:167], 0, v[60:61]
	v_pk_mul_f32 v[52:53], v[52:53], v[54:55]
	s_nop 0
	v_pk_fma_f32 v[50:51], v[50:51], v[52:53], v[50:51]
	v_lshlrev_b32_e32 v52, 16, v102
	v_pk_mul_f32 v[46:47], v[46:47], v[50:51]
	v_cvt_pk_bf16_f32 v50, v44, v45
	v_lshl_add_u64 v[44:45], v[172:173], 0, v[60:61]
	v_cvt_pk_bf16_f32 v51, v46, v47
	global_store_dwordx4 v[44:45], v[48:51], off
	v_lshlrev_b32_e32 v44, 16, v1
	v_and_b32_e32 v45, 0xffff0000, v1
	v_mov_b32_dpp v49, v106 row_ror:2 row_mask:0xf bank_mask:0xf bound_ctrl:1
	v_and_b32_e32 v53, 0xffff0000, v102
	v_mov_b32_dpp v51, v107 row_ror:2 row_mask:0xf bank_mask:0xf bound_ctrl:1
	v_mov_b32_dpp v49, v102 row_shr:2 row_mask:0xf bank_mask:0xf
	v_lshlrev_b32_e32 v48, 16, v49
	v_and_b32_e32 v49, 0xffff0000, v49
	v_pk_fma_f32 v[48:49], v[84:85], v[48:49], v[96:97]
	v_mov_b32_dpp v47, v107 row_ror:1 row_mask:0xf bank_mask:0xf bound_ctrl:1
	v_pk_fma_f32 v[44:45], v[88:89], v[44:45], v[48:49]
	v_mov_b32_dpp v51, v103 row_shr:2 row_mask:0xf bank_mask:0xf
	v_pk_fma_f32 v[44:45], v[92:93], v[52:53], v[44:45]
	v_mov_b32_dpp v47, v103 row_shr:1 row_mask:0xf bank_mask:0xf
	v_pk_mul_f32 v[48:49], v[44:45], s[30:31] op_sel_hi:[1,0]
	v_lshlrev_b32_e32 v50, 16, v51
	v_med3_f32 v48, v48, s47, v225
	v_med3_f32 v49, v49, s47, v225
	v_pk_mul_f32 v[52:53], v[48:49], v[48:49]
	v_and_b32_e32 v51, 0xffff0000, v51
	v_pk_fma_f32 v[54:55], v[52:53], s[34:35], v[118:119] op_sel_hi:[1,0,0] neg_lo:[1,0,0] neg_hi:[1,0,0]
	v_pk_mul_f32 v[44:45], v[44:45], 0.5 op_sel_hi:[1,0]
	v_pk_fma_f32 v[54:55], v[52:53], v[54:55], s[38:39] op_sel_hi:[1,1,0]
	v_lshlrev_b32_e32 v46, 16, v47
	v_pk_fma_f32 v[54:55], v[52:53], v[54:55], s[40:41] op_sel_hi:[1,1,0]
	v_and_b32_e32 v47, 0xffff0000, v47
	v_pk_fma_f32 v[54:55], v[52:53], v[54:55], s[42:43] op_sel_hi:[1,1,0]
	v_mov_b32_dpp v1, v108 row_ror:1 row_mask:0xf bank_mask:0xf bound_ctrl:1
	v_pk_fma_f32 v[54:55], v[52:53], v[54:55], s[44:45] op_sel_hi:[1,1,0]
	v_mov_b32_e32 v102, 0
	v_pk_fma_f32 v[54:55], v[52:53], v[54:55], s[46:47] op_sel_hi:[1,1,0]
	v_mov_b32_dpp v1, v104 row_shr:1 row_mask:0xf bank_mask:0xf
	v_pk_fma_f32 v[52:53], v[52:53], v[54:55], s[48:49] op_sel_hi:[1,1,0]
	s_nop 0
	v_pk_mul_f32 v[48:49], v[48:49], v[52:53]
	s_nop 0
	v_pk_fma_f32 v[44:45], v[44:45], v[48:49], v[44:45]
	v_pk_fma_f32 v[48:49], v[86:87], v[50:51], v[98:99]
	v_pk_mul_f32 v[40:41], v[40:41], v[44:45]
	v_lshlrev_b32_e32 v44, 16, v103
	v_and_b32_e32 v45, 0xffff0000, v103
	v_pk_fma_f32 v[46:47], v[90:91], v[46:47], v[48:49]
	v_cvt_pk_bf16_f32 v52, v40, v41
	v_lshlrev_b32_e32 v40, 16, v1
	v_pk_fma_f32 v[44:45], v[94:95], v[44:45], v[46:47]
	v_and_b32_e32 v41, 0xffff0000, v1
	v_pk_mul_f32 v[46:47], v[44:45], s[30:31] op_sel_hi:[1,0]
;     static __device__ __forceinline__ void unpk4(const u32x2 w, float (&o)[4]) { o[0] = bf_lo(w.x); o[1] = bf_hi(w.x); o[2] = bf_lo(w.y); o[3] = bf_hi(w.y); }
;     template <int N> static __device__ __forceinline__ u32x2 dpp_prev(const u32x2 pv, const u32x2 cur) { u32x2 r; r.x = dpp_prev1<N>(pv.x, cur.x); r.y = dpp_prev1<N>(pv.y, cur.y); return r; }
;     __device__ __forceinline__ void operator()(const f32x4 (&acc)[2][2][4][2], const Unit& u, int wr, int wc, int fr, int fq) const {
;     ...
;             for (int ai = 0; ai < 2; ++ai) { const int R0 = u.rb + ai * HALF + wr * 64; const bf16_t* gp = G + (size_t)(R0 + fr) * 2816 + col8;
;                 u32x4 gq[4], prv = (u32x4){0u, 0u, 0u, 0u};
; #pragma unroll
;                 for (int m = 0; m < 4; ++m) gq[m] = *(const u32x4*)(gp + (size_t)m * 16 * 2816);
;                 if ((R0 & 8191) != 0) prv = *(const u32x4*)(gp - (size_t)16 * 2816);
;                 u32x4 pv = prv;
; #pragma unroll
;                 for (int m = 0; m < 4; ++m) { const u32x4 cur = gq[m]; u32x4 hw;
; #pragma unroll
;                     for (int hv = 0; hv < 2; ++hv) { const u32x2 c2 = half2(cur, hv), p2 = half2(pv, hv);
;                         const u32x2 q1 = dpp_prev<1>(p2, c2), q2 = dpp_prev<2>(p2, c2);
;                         float g0[4], g1[4], g2[4]; unpk4(c2, g0); unpk4(q1, g1); unpk4(q2, g2);
;                         const u32x2 r = finish2(g0, g1, g2, w0[hv], w1[hv], w2[hv], bb[hv], acc[ai][bj][m][hv], rs8[ai][m]);
;                         if (hv == 0) { hw.x = r.x; hw.y = r.y; } else { hw.z = r.x; hw.w = r.y; } }
;                     *(u32x4*)(H + (size_t)(R0 + fr + 16 * m) * 2816 + col8) = hw;
	v_pk_mul_f32 v[44:45], v[44:45], 0.5 op_sel_hi:[1,0]
	v_med3_f32 v46, v46, s47, v225
	v_med3_f32 v47, v47, s47, v225
	v_pk_mul_f32 v[48:49], v[46:47], v[46:47]
	v_mov_b32_e32 v103, 0
	v_pk_fma_f32 v[50:51], v[48:49], s[34:35], v[118:119] op_sel_hi:[1,0,0] neg_lo:[1,0,0] neg_hi:[1,0,0]
	s_nop 0
	v_pk_fma_f32 v[50:51], v[48:49], v[50:51], s[38:39] op_sel_hi:[1,1,0]
	s_nop 0
	v_pk_fma_f32 v[50:51], v[48:49], v[50:51], s[40:41] op_sel_hi:[1,1,0]
	s_nop 0
	v_pk_fma_f32 v[50:51], v[48:49], v[50:51], s[42:43] op_sel_hi:[1,1,0]
	s_nop 0
	v_pk_fma_f32 v[50:51], v[48:49], v[50:51], s[44:45] op_sel_hi:[1,1,0]
	s_nop 0
	v_pk_fma_f32 v[50:51], v[48:49], v[50:51], s[46:47] op_sel_hi:[1,1,0]
	s_nop 0
	v_pk_fma_f32 v[48:49], v[48:49], v[50:51], s[48:49] op_sel_hi:[1,1,0]
	s_nop 0
	v_pk_mul_f32 v[46:47], v[46:47], v[48:49]
	v_lshlrev_b32_e32 v48, 16, v104
	v_pk_fma_f32 v[44:45], v[44:45], v[46:47], v[44:45]
	v_and_b32_e32 v49, 0xffff0000, v104
	v_pk_mul_f32 v[42:43], v[42:43], v[44:45]
	v_mov_b32_dpp v45, v108 row_ror:2 row_mask:0xf bank_mask:0xf bound_ctrl:1
	v_mov_b32_dpp v47, v109 row_ror:2 row_mask:0xf bank_mask:0xf bound_ctrl:1
	v_cvt_pk_bf16_f32 v53, v42, v43
	v_mov_b32_dpp v43, v109 row_ror:1 row_mask:0xf bank_mask:0xf bound_ctrl:1
	v_mov_b32_dpp v45, v104 row_shr:2 row_mask:0xf bank_mask:0xf
	v_lshlrev_b32_e32 v44, 16, v45
	v_and_b32_e32 v45, 0xffff0000, v45
	v_pk_fma_f32 v[44:45], v[64:65], v[44:45], v[80:81]
	v_mov_b32_dpp v47, v105 row_shr:2 row_mask:0xf bank_mask:0xf
	v_pk_fma_f32 v[40:41], v[72:73], v[40:41], v[44:45]
	v_mov_b32_dpp v43, v105 row_shr:1 row_mask:0xf bank_mask:0xf
	v_pk_fma_f32 v[40:41], v[76:77], v[48:49], v[40:41]
	v_lshlrev_b32_e32 v46, 16, v47
	v_pk_mul_f32 v[44:45], v[40:41], s[30:31] op_sel_hi:[1,0]
	v_and_b32_e32 v47, 0xffff0000, v47
	v_med3_f32 v44, v44, s47, v225
	v_med3_f32 v45, v45, s47, v225
	v_pk_mul_f32 v[48:49], v[44:45], v[44:45]
	v_pk_mul_f32 v[40:41], v[40:41], 0.5 op_sel_hi:[1,0]
	v_pk_fma_f32 v[50:51], v[48:49], s[34:35], v[118:119] op_sel_hi:[1,0,0] neg_lo:[1,0,0] neg_hi:[1,0,0]
	v_lshlrev_b32_e32 v42, 16, v43
	v_pk_fma_f32 v[50:51], v[48:49], v[50:51], s[38:39] op_sel_hi:[1,1,0]
	v_and_b32_e32 v43, 0xffff0000, v43
	v_pk_fma_f32 v[50:51], v[48:49], v[50:51], s[40:41] op_sel_hi:[1,1,0]
	s_nop 0
	v_pk_fma_f32 v[50:51], v[48:49], v[50:51], s[42:43] op_sel_hi:[1,1,0]
	s_nop 0
	v_pk_fma_f32 v[50:51], v[48:49], v[50:51], s[44:45] op_sel_hi:[1,1,0]
	s_nop 0
	v_pk_fma_f32 v[50:51], v[48:49], v[50:51], s[46:47] op_sel_hi:[1,1,0]
	s_nop 0
	v_pk_fma_f32 v[48:49], v[48:49], v[50:51], s[48:49] op_sel_hi:[1,1,0]
	s_nop 0
	v_pk_mul_f32 v[44:45], v[44:45], v[48:49]
	s_nop 0
	v_pk_fma_f32 v[40:41], v[40:41], v[44:45], v[40:41]
	v_pk_fma_f32 v[44:45], v[66:67], v[46:47], v[82:83]
	v_pk_mul_f32 v[36:37], v[36:37], v[40:41]
	v_lshlrev_b32_e32 v40, 16, v105
	v_and_b32_e32 v41, 0xffff0000, v105
	v_pk_fma_f32 v[42:43], v[74:75], v[42:43], v[44:45]
	v_cvt_pk_bf16_f32 v54, v36, v37
	s_nop 0
	v_pk_fma_f32 v[40:41], v[78:79], v[40:41], v[42:43]
	s_nop 0
	v_pk_mul_f32 v[42:43], v[40:41], s[30:31] op_sel_hi:[1,0]
	v_pk_mul_f32 v[40:41], v[40:41], 0.5 op_sel_hi:[1,0]
	v_med3_f32 v42, v42, s47, v225
	v_med3_f32 v43, v43, s47, v225
	v_pk_mul_f32 v[44:45], v[42:43], v[42:43]
	s_nop 0
	v_pk_fma_f32 v[46:47], v[44:45], s[34:35], v[118:119] op_sel_hi:[1,0,0] neg_lo:[1,0,0] neg_hi:[1,0,0]
	s_nop 0
	v_pk_fma_f32 v[46:47], v[44:45], v[46:47], s[38:39] op_sel_hi:[1,1,0]
	s_nop 0
	v_pk_fma_f32 v[46:47], v[44:45], v[46:47], s[40:41] op_sel_hi:[1,1,0]
	s_nop 0
	v_pk_fma_f32 v[46:47], v[44:45], v[46:47], s[42:43] op_sel_hi:[1,1,0]
	s_nop 0
	v_pk_fma_f32 v[46:47], v[44:45], v[46:47], s[44:45] op_sel_hi:[1,1,0]
	s_nop 0
	v_pk_fma_f32 v[46:47], v[44:45], v[46:47], s[46:47] op_sel_hi:[1,1,0]
	s_nop 0
	v_pk_fma_f32 v[44:45], v[44:45], v[46:47], s[48:49] op_sel_hi:[1,1,0]
	s_nop 0
	v_pk_mul_f32 v[42:43], v[42:43], v[44:45]
	s_nop 0
	v_pk_fma_f32 v[40:41], v[40:41], v[42:43], v[40:41]
	s_nop 0
	v_pk_mul_f32 v[2:3], v[2:3], v[40:41]
	s_nop 0
	v_cvt_pk_bf16_f32 v55, v2, v3
	v_lshl_add_u64 v[2:3], v[164:165], 0, v[60:61]
	v_add_co_u32_e32 v36, vcc, s10, v2
	s_nop 1
	v_addc_co_u32_e32 v37, vcc, 0, v3, vcc
	global_load_dwordx4 v[48:51], v[2:3], off
	global_load_dwordx4 v[44:47], v[36:37], off
	v_add_co_u32_e32 v36, vcc, 0x2c000, v2
	s_nop 1
	v_addc_co_u32_e32 v37, vcc, 0, v3, vcc
	v_add_co_u32_e32 v38, vcc, 0x42000, v2
	s_nop 1
	v_addc_co_u32_e32 v39, vcc, 0, v3, vcc
	global_load_dwordx4 v[40:43], v[36:37], off
	s_nop 0
	global_load_dwordx4 v[36:39], v[38:39], off
	s_andn2_b64 vcc, exec, s[2:3]
	global_store_dwordx4 v[56:57], v[52:55], off
	s_cbranch_vccnz .LBB0_1020
	v_add_co_u32_e32 v2, vcc, 0xfffea000, v2
	s_nop 1
	v_addc_co_u32_e32 v3, vcc, -1, v3, vcc
	global_load_dwordx4 v[100:103], v[2:3], off

;     __device__ __forceinline__ void operator()(const f32x4 (&acc)[2][2][4][2], const Unit& u, int wr, int wc, int fr, int fq) const {
;     ...
;             for (int m = 0; m < 4; ++m) rs8[ai][m] = rsqrtf(SS[u.rb + (u.half ? 0 : ai * HALF) + wr * 64 + fr + 16 * m] * (1.f / 1024.f) + 1e-6f);
;         if (u.pm < 128) {
; #pragma unroll
;           for (int bj = 0; bj < 2; ++bj) {
;             const int col8 = u.pn * BM + bj * HALF + wc * 32 + 8 * fq;
;             float w0[2][4], w1[2][4], w2[2][4], bb[2][4];
; #pragma unroll
;             for (int hv = 0; hv < 2; ++hv) { ld4f(cw + col8 + 4 * hv, w0[hv]); ld4f(cw + 2816 + col8 + 4 * hv, w1[hv]); ld4f(cw + 2 * 2816 + col8 + 4 * hv, w2[hv]); ld4f(cb + col8 + 4 * hv, bb[hv]); }
; #pragma unroll
;             for (int ai = 0; ai < 2; ++ai) { const int R0 = u.rb + ai * HALF + wr * 64; const bf16_t* gp = G + (size_t)(R0 + fr) * 2816 + col8;
;                 u32x4 gq[4], prv = (u32x4){0u, 0u, 0u, 0u};
; #pragma unroll
;                 for (int m = 0; m < 4; ++m) gq[m] = *(const u32x4*)(gp + (size_t)m * 16 * 2816);
;                 if ((R0 & 8191) != 0) prv = *(const u32x4*)(gp - (size_t)16 * 2816);
.LBB0_3142:
	s_and_b64 s[0:1], s[2:3], exec
	s_cselect_b32 s0, 0x80, 0
	v_add_u32_e32 v132, s0, v210
	v_add_u32_e32 v134, 16, v132
	v_ashrrev_i32_e32 v133, 31, v132
	v_ashrrev_i32_e32 v135, 31, v134
	s_lshl_b32 s0, s80, 8
	v_lshl_add_u64 v[164:165], v[132:133], 2, s[10:11]
	v_lshl_add_u64 v[166:167], v[134:135], 2, s[10:11]
	v_add_u32_e32 v134, 32, v132
	v_add_u32_e32 v132, 48, v132
	v_add_u32_e32 v212, s0, v3
	v_readlane_b32 s0, v240, 12
	v_ashrrev_i32_e32 v133, 31, v132
	v_readlane_b32 s1, v240, 13
	v_lshl_add_u64 v[132:133], v[132:133], 2, s[10:11]
	v_ashrrev_i32_e32 v213, 31, v212
	v_mov_b64_e32 v[170:171], s[0:1]
	global_load_dword v185, v[132:133], off
	v_lshlrev_b64 v[132:133], 2, v[212:213]
	v_mad_i64_i32 v[214:215], s[0:1], v210, s67, v[170:171]
	v_ashrrev_i32_e32 v135, 31, v134
	v_lshl_add_u64 v[136:137], s[12:13], 0, v[132:133]
	v_lshl_add_u64 v[140:141], s[18:19], 0, v[132:133]
	v_lshl_add_u64 v[144:145], s[20:21], 0, v[132:133]
	v_lshl_add_u64 v[160:161], s[14:15], 0, v[132:133]
	v_lshl_add_u64 v[180:181], v[212:213], 1, v[214:215]
	v_lshl_add_u64 v[168:169], v[134:135], 2, s[10:11]
	v_and_b32_e32 v241, 63, v216
	v_lshrrev_b32_e32 v242, 4, v241
	v_and_b32_e32 v243, 15, v241
	v_cmp_eq_u32_e64 s[98:99], 1, v242
	v_lshlrev_b32_e32 v246, 3, v243
	v_lshlrev_b32_e32 v247, 5, v242
	v_cndmask_b32_e64 v244, v136, v140, s[98:99]
	v_cndmask_b32_e64 v245, v137, v141, s[98:99]
	v_cmp_eq_u32_e64 s[98:99], 2, v242
	v_sub_u32_e32 v246, v246, v247
	v_ashrrev_i32_e32 v247, 31, v246
	v_cndmask_b32_e64 v244, v244, v144, s[98:99]
	v_cndmask_b32_e64 v245, v245, v145, s[98:99]
	v_cmp_eq_u32_e64 s[98:99], 3, v242
	s_nop 1
	v_cndmask_b32_e64 v244, v244, v160, s[98:99]
	v_cndmask_b32_e64 v245, v245, v161, s[98:99]
	v_lshl_add_u64 v[244:245], v[244:245], 0, v[246:247]
	global_load_dwordx2 v[248:249], v[244:245], off
	s_nop 0
	s_nop 0
	s_nop 0
	s_nop 0
	s_nop 0
	global_load_dword v189, v[164:165], off
	global_load_dword v187, v[166:167], off
	global_load_dword v3, v[168:169], off
	global_load_dwordx4 v[176:179], v[180:181], off
	v_add_co_u32_e32 v164, vcc, s45, v180
	s_and_b32 s0, s47, 0x1fff
	s_nop 0
	v_addc_co_u32_e32 v165, vcc, 0, v181, vcc
	v_add_co_u32_e32 v166, vcc, 0x2c000, v180
	s_cmp_lg_u32 s0, 0
	s_nop 0
	v_addc_co_u32_e32 v167, vcc, 0, v181, vcc
	global_load_dwordx4 v[172:175], v[164:165], off
	global_load_dwordx4 v[168:171], v[166:167], off
	v_add_co_u32_e32 v164, vcc, 0x42000, v180
	s_cselect_b64 s[2:3], -1, 0
	s_nop 0
	v_addc_co_u32_e32 v165, vcc, 0, v181, vcc
	global_load_dwordx4 v[164:167], v[164:165], off
	s_cmp_eq_u32 s0, 0
	s_cbranch_scc1 .LBB0_3144
	v_add_co_u32_e32 v180, vcc, 0xfffea000, v180
	s_nop 1
	v_addc_co_u32_e32 v181, vcc, -1, v181, vcc
	global_load_dwordx4 v[180:183], v[180:181], off
	s_branch .LBB0_3145

;     static __device__ __forceinline__ void unpk4(const u32x2 w, float (&o)[4]) { o[0] = bf_lo(w.x); o[1] = bf_hi(w.x); o[2] = bf_lo(w.y); o[3] = bf_hi(w.y); }
;     template <int N> static __device__ __forceinline__ u32x2 dpp_prev(const u32x2 pv, const u32x2 cur) { u32x2 r; r.x = dpp_prev1<N>(pv.x, cur.x); r.y = dpp_prev1<N>(pv.y, cur.y); return r; }
;     __device__ __forceinline__ void operator()(const f32x4 (&acc)[2][2][4][2], const Unit& u, int wr, int wc, int fr, int fq) const {
;     ...
;             for (int hv = 0; hv < 2; ++hv) { ld4f(cw + col8 + 4 * hv, w0[hv]); ld4f(cw + 2816 + col8 + 4 * hv, w1[hv]); ld4f(cw + 2 * 2816 + col8 + 4 * hv, w2[hv]); ld4f(cb + col8 + 4 * hv, bb[hv]); }
;     ...
;                 for (int m = 0; m < 4; ++m) { const u32x4 cur = gq[m]; u32x4 hw;
; #pragma unroll
;                     for (int hv = 0; hv < 2; ++hv) { const u32x2 c2 = half2(cur, hv), p2 = half2(pv, hv);
;                         const u32x2 q1 = dpp_prev<1>(p2, c2), q2 = dpp_prev<2>(p2, c2);
;                         float g0[4], g1[4], g2[4]; unpk4(c2, g0); unpk4(q1, g1); unpk4(q2, g2);
;                         const u32x2 r = finish2(g0, g1, g2, w0[hv], w1[hv], w2[hv], bb[hv], acc[ai][bj][m][hv], rs8[ai][m]);
;                         if (hv == 0) { hw.x = r.x; hw.y = r.y; } else { hw.z = r.x; hw.w = r.y; } }
;                     *(u32x4*)(H + (size_t)(R0 + fr + 16 * m) * 2816 + col8) = hw;
.LBB0_3145:
	s_waitcnt vmcnt(0)
	v_lshrrev_b32_e32 v252, 6, v216
	v_lshlrev_b32_e32 v252, 10, v252
	v_add_u32_e32 v252, 0x20000, v252
	v_lshl_add_u32 v253, v241, 3, v252
	v_lshl_add_u32 v254, v242, 5, v252
	ds_write_b64 v253, v[248:249]
	s_waitcnt lgkmcnt(0)
	ds_read_b128 v[132:135], v254 offset:16
	ds_read_b128 v[148:151], v254
	ds_read_b128 v[136:139], v254 offset:144
	ds_read_b128 v[152:155], v254 offset:128
	ds_read_b128 v[140:143], v254 offset:272
	ds_read_b128 v[156:159], v254 offset:256
	ds_read_b128 v[144:147], v254 offset:400
	ds_read_b128 v[160:163], v254 offset:384
	s_waitcnt lgkmcnt(0)
	s_nop 0
	s_nop 0
	s_nop 0
	s_nop 0
	s_nop 0
	s_nop 0
	v_mov_b32_dpp v195, v180 row_ror:2 row_mask:0xf bank_mask:0xf bound_ctrl:1
	v_mov_b32_dpp v191, v180 row_ror:1 row_mask:0xf bank_mask:0xf bound_ctrl:1
	v_mad_i64_i32 v[230:231], s[0:1], v210, s67, 0
	v_mov_b32_dpp v195, v176 row_shr:2 row_mask:0xf bank_mask:0xf
	v_mov_b32_dpp v191, v176 row_shr:1 row_mask:0xf bank_mask:0xf
	v_lshlrev_b32_e32 v210, 16, v195
	v_and_b32_e32 v211, 0xffff0000, v195
	v_mov_b32_dpp v193, v181 row_ror:1 row_mask:0xf bank_mask:0xf bound_ctrl:1
	v_mov_b32_dpp v225, v181 row_ror:2 row_mask:0xf bank_mask:0xf bound_ctrl:1
	v_lshlrev_b32_e32 v180, 16, v191
	v_and_b32_e32 v181, 0xffff0000, v191
	v_pk_fma_f32 v[210:211], v[148:149], v[210:211], v[160:161]
	v_lshlrev_b32_e32 v232, 16, v176
	v_and_b32_e32 v233, 0xffff0000, v176
	v_pk_fma_f32 v[180:181], v[152:153], v[180:181], v[210:211]
	v_mov_b32_dpp v225, v177 row_shr:2 row_mask:0xf bank_mask:0xf
	v_pk_fma_f32 v[180:181], v[156:157], v[232:233], v[180:181]
	v_mov_b32_dpp v193, v177 row_shr:1 row_mask:0xf bank_mask:0xf
	v_pk_mul_f32 v[210:211], v[180:181], s[26:27] op_sel_hi:[1,0]
	v_lshlrev_b32_e32 v228, 16, v225
	v_med3_f32 v232, v210, s71, v224
	v_med3_f32 v233, v211, s71, v224
	v_pk_mul_f32 v[234:235], v[232:233], v[232:233]
	v_mov_b64_e32 v[210:211], s[30:31]
	v_pk_fma_f32 v[236:237], v[234:235], s[28:29], v[210:211] op_sel_hi:[1,0,0] neg_lo:[1,0,0] neg_hi:[1,0,0]
	v_and_b32_e32 v229, 0xffff0000, v225
	v_pk_fma_f32 v[236:237], v[234:235], v[236:237], s[34:35] op_sel_hi:[1,1,0]
	v_pk_mul_f32 v[180:181], v[180:181], 0.5 op_sel_hi:[1,0]
	v_pk_fma_f32 v[236:237], v[234:235], v[236:237], s[36:37] op_sel_hi:[1,1,0]
	v_lshlrev_b32_e32 v226, 16, v193
	v_pk_fma_f32 v[236:237], v[234:235], v[236:237], s[38:39] op_sel_hi:[1,1,0]
	v_and_b32_e32 v227, 0xffff0000, v193
	v_pk_fma_f32 v[236:237], v[234:235], v[236:237], s[40:41] op_sel_hi:[1,1,0]
	v_pk_mul_f32 v[128:129], v[128:129], v[188:189] op_sel_hi:[1,0]
	v_pk_fma_f32 v[236:237], v[234:235], v[236:237], s[42:43] op_sel_hi:[1,1,0]
	v_pk_fma_f32 v[228:229], v[150:151], v[228:229], v[162:163]
	v_pk_fma_f32 v[234:235], v[234:235], v[236:237], s[44:45] op_sel_hi:[1,1,0]
	v_pk_fma_f32 v[226:227], v[154:155], v[226:227], v[228:229]
	v_pk_mul_f32 v[232:233], v[232:233], v[234:235]
	v_pk_mul_f32 v[130:131], v[130:131], v[188:189] op_sel_hi:[1,0]
	v_pk_fma_f32 v[180:181], v[180:181], v[232:233], v[180:181]
	v_pk_mul_f32 v[124:125], v[124:125], v[188:189] op_sel_hi:[1,0]
	v_pk_mul_f32 v[128:129], v[128:129], v[180:181]
	v_lshlrev_b32_e32 v180, 16, v177
	v_and_b32_e32 v181, 0xffff0000, v177
	v_pk_fma_f32 v[180:181], v[158:159], v[180:181], v[226:227]
	v_readlane_b32 s0, v240, 58
	v_pk_mul_f32 v[226:227], v[180:181], s[26:27] op_sel_hi:[1,0]
	v_pk_mul_f32 v[180:181], v[180:181], 0.5 op_sel_hi:[1,0]
	v_med3_f32 v226, v226, s71, v224
	v_med3_f32 v227, v227, s71, v224
	v_pk_mul_f32 v[228:229], v[226:227], v[226:227]
	v_readlane_b32 s1, v240, 59
	v_pk_fma_f32 v[232:233], v[228:229], s[28:29], v[210:211] op_sel_hi:[1,0,0] neg_lo:[1,0,0] neg_hi:[1,0,0]
	v_pk_mul_f32 v[126:127], v[126:127], v[188:189] op_sel_hi:[1,0]
	v_pk_fma_f32 v[232:233], v[228:229], v[232:233], s[34:35] op_sel_hi:[1,1,0]
	v_pk_mul_f32 v[120:121], v[120:121], v[186:187] op_sel_hi:[1,0]
	v_pk_fma_f32 v[232:233], v[228:229], v[232:233], s[36:37] op_sel_hi:[1,1,0]
	v_pk_mul_f32 v[122:123], v[122:123], v[186:187] op_sel_hi:[1,0]
	v_pk_fma_f32 v[232:233], v[228:229], v[232:233], s[38:39] op_sel_hi:[1,1,0]
	v_pk_mul_f32 v[116:117], v[116:117], v[186:187] op_sel_hi:[1,0]
	v_pk_fma_f32 v[232:233], v[228:229], v[232:233], s[40:41] op_sel_hi:[1,1,0]
	v_pk_mul_f32 v[118:119], v[118:119], v[186:187] op_sel_hi:[1,0]
	v_pk_fma_f32 v[232:233], v[228:229], v[232:233], s[42:43] op_sel_hi:[1,1,0]
	v_pk_mul_f32 v[112:113], v[112:113], v[184:185] op_sel_hi:[1,0]
	v_pk_fma_f32 v[228:229], v[228:229], v[232:233], s[44:45] op_sel_hi:[1,1,0]
	v_pk_mul_f32 v[114:115], v[114:115], v[184:185] op_sel_hi:[1,0]
	v_pk_mul_f32 v[226:227], v[226:227], v[228:229]
	v_lshlrev_b32_e32 v228, 16, v178
	v_pk_fma_f32 v[180:181], v[180:181], v[226:227], v[180:181]
	v_cvt_pk_bf16_f32 v226, v128, v129
	v_mov_b32_dpp v129, v182 row_ror:1 row_mask:0xf bank_mask:0xf bound_ctrl:1
	v_pk_mul_f32 v[130:131], v[130:131], v[180:181]
	v_mov_b32_dpp v181, v182 row_ror:2 row_mask:0xf bank_mask:0xf bound_ctrl:1
	v_mov_b32_dpp v129, v178 row_shr:1 row_mask:0xf bank_mask:0xf
	v_lshlrev_b32_e32 v128, 16, v129
	v_mov_b32_dpp v181, v178 row_shr:2 row_mask:0xf bank_mask:0xf
	v_lshlrev_b32_e32 v180, 16, v181
	v_and_b32_e32 v181, 0xffff0000, v181
	v_and_b32_e32 v129, 0xffff0000, v129
	v_pk_fma_f32 v[180:181], v[132:133], v[180:181], v[144:145]
	v_and_b32_e32 v229, 0xffff0000, v178
	v_pk_fma_f32 v[128:129], v[136:137], v[128:129], v[180:181]
	v_cvt_pk_bf16_f32 v227, v130, v131
	v_mov_b32_dpp v131, v183 row_ror:1 row_mask:0xf bank_mask:0xf bound_ctrl:1
	v_pk_fma_f32 v[128:129], v[140:141], v[228:229], v[128:129]
	v_mov_b32_dpp v183, v183 row_ror:2 row_mask:0xf bank_mask:0xf bound_ctrl:1
;     static __device__ __forceinline__ void unpk4(const u32x2 w, float (&o)[4]) { o[0] = bf_lo(w.x); o[1] = bf_hi(w.x); o[2] = bf_lo(w.y); o[3] = bf_hi(w.y); }
;     template <int N> static __device__ __forceinline__ u32x2 dpp_prev(const u32x2 pv, const u32x2 cur) { u32x2 r; r.x = dpp_prev1<N>(pv.x, cur.x); r.y = dpp_prev1<N>(pv.y, cur.y); return r; }
; __device__ __forceinline__ f32x2 gelu_pk(f32x2 v) {
;     f32x2 x = v * 0.70710678118f;
;     x.x = __builtin_amdgcn_fmed3f(x.x, -2.9f, 2.9f); x.y = __builtin_amdgcn_fmed3f(x.y, -2.9f, 2.9f);
;     const f32x2 t = x * x;
;     f32x2 p = t * (-4.953124630e-07f) + 1.987094038e-05f;
;     p = p * t + (-3.472001117e-04f); p = p * t + 3.517547622e-03f; p = p * t + (-2.333305031e-02f); p = p * t + 1.087993085e-01f; p = p * t + (-3.740358949e-01f); p = p * t + 1.128076553e+00f;
;     const f32x2 hv = v * 0.5f;
;     return hv * (x * p) + hv;
; }
;     __device__ __forceinline__ void operator()(const f32x4 (&acc)[2][2][4][2], const Unit& u, int wr, int wc, int fr, int fq) const {
;     ...
;                 for (int m = 0; m < 4; ++m) { const u32x4 cur = gq[m]; u32x4 hw;
; #pragma unroll
;                     for (int hv = 0; hv < 2; ++hv) { const u32x2 c2 = half2(cur, hv), p2 = half2(pv, hv);
;                         const u32x2 q1 = dpp_prev<1>(p2, c2), q2 = dpp_prev<2>(p2, c2);
;                         float g0[4], g1[4], g2[4]; unpk4(c2, g0); unpk4(q1, g1); unpk4(q2, g2);
;                         const u32x2 r = finish2(g0, g1, g2, w0[hv], w1[hv], w2[hv], bb[hv], acc[ai][bj][m][hv], rs8[ai][m]);
;                         if (hv == 0) { hw.x = r.x; hw.y = r.y; } else { hw.z = r.x; hw.w = r.y; } }
;                     *(u32x4*)(H + (size_t)(R0 + fr + 16 * m) * 2816 + col8) = hw;
;                     pv = cur; } }
	v_pk_mul_f32 v[180:181], v[128:129], s[26:27] op_sel_hi:[1,0]
	v_mov_b32_dpp v131, v179 row_shr:1 row_mask:0xf bank_mask:0xf
	v_med3_f32 v180, v180, s71, v224
	v_med3_f32 v181, v181, s71, v224
	v_pk_mul_f32 v[228:229], v[180:181], v[180:181]
	v_mov_b32_dpp v183, v179 row_shr:2 row_mask:0xf bank_mask:0xf
	v_pk_fma_f32 v[232:233], v[228:229], s[28:29], v[210:211] op_sel_hi:[1,0,0] neg_lo:[1,0,0] neg_hi:[1,0,0]
	v_lshlrev_b32_e32 v182, 16, v183
	v_pk_fma_f32 v[232:233], v[228:229], v[232:233], s[34:35] op_sel_hi:[1,1,0]
	v_and_b32_e32 v183, 0xffff0000, v183
	v_pk_fma_f32 v[232:233], v[228:229], v[232:233], s[36:37] op_sel_hi:[1,1,0]
	v_pk_mul_f32 v[128:129], v[128:129], 0.5 op_sel_hi:[1,0]
	v_pk_fma_f32 v[232:233], v[228:229], v[232:233], s[38:39] op_sel_hi:[1,1,0]
	v_lshlrev_b32_e32 v130, 16, v131
	v_pk_fma_f32 v[232:233], v[228:229], v[232:233], s[40:41] op_sel_hi:[1,1,0]
	v_and_b32_e32 v131, 0xffff0000, v131
	v_pk_fma_f32 v[232:233], v[228:229], v[232:233], s[42:43] op_sel_hi:[1,1,0]
	v_pk_mul_f32 v[108:109], v[108:109], v[184:185] op_sel_hi:[1,0]
	v_pk_fma_f32 v[228:229], v[228:229], v[232:233], s[44:45] op_sel_hi:[1,1,0]
	v_pk_mul_f32 v[110:111], v[110:111], v[184:185] op_sel_hi:[1,0]
	v_pk_mul_f32 v[180:181], v[180:181], v[228:229]
	v_pk_mul_f32 v[104:105], v[104:105], v[2:3] op_sel_hi:[1,0]
	v_pk_fma_f32 v[128:129], v[128:129], v[180:181], v[128:129]
	v_pk_fma_f32 v[180:181], v[134:135], v[182:183], v[146:147]
	v_pk_mul_f32 v[124:125], v[124:125], v[128:129]
	v_lshlrev_b32_e32 v128, 16, v179
	v_and_b32_e32 v129, 0xffff0000, v179
	v_pk_fma_f32 v[130:131], v[138:139], v[130:131], v[180:181]
	v_cvt_pk_bf16_f32 v228, v124, v125
	v_pk_mul_f32 v[106:107], v[106:107], v[2:3] op_sel_hi:[1,0]
	v_pk_fma_f32 v[128:129], v[142:143], v[128:129], v[130:131]
	v_pk_mul_f32 v[100:101], v[100:101], v[2:3] op_sel_hi:[1,0]
	v_pk_mul_f32 v[130:131], v[128:129], s[26:27] op_sel_hi:[1,0]
	v_pk_mul_f32 v[128:129], v[128:129], 0.5 op_sel_hi:[1,0]
	v_med3_f32 v130, v130, s71, v224
	v_med3_f32 v131, v131, s71, v224
	v_pk_mul_f32 v[180:181], v[130:131], v[130:131]
	s_addk_i32 s47, 0x80
	v_pk_fma_f32 v[182:183], v[180:181], s[28:29], v[210:211] op_sel_hi:[1,0,0] neg_lo:[1,0,0] neg_hi:[1,0,0]
	v_add_u32_e32 v1, s47, v1
	v_pk_fma_f32 v[182:183], v[180:181], v[182:183], s[34:35] op_sel_hi:[1,1,0]
	v_pk_mul_f32 v[102:103], v[102:103], v[2:3] op_sel_hi:[1,0]
	v_pk_fma_f32 v[182:183], v[180:181], v[182:183], s[36:37] op_sel_hi:[1,1,0]
	s_nop 0
	v_pk_fma_f32 v[182:183], v[180:181], v[182:183], s[38:39] op_sel_hi:[1,1,0]
	s_nop 0
	v_pk_fma_f32 v[182:183], v[180:181], v[182:183], s[40:41] op_sel_hi:[1,1,0]
	s_nop 0
	v_pk_fma_f32 v[182:183], v[180:181], v[182:183], s[42:43] op_sel_hi:[1,1,0]
	s_nop 0
	v_pk_fma_f32 v[180:181], v[180:181], v[182:183], s[44:45] op_sel_hi:[1,1,0]
	v_lshlrev_b32_e32 v182, 16, v172
	v_pk_mul_f32 v[130:131], v[130:131], v[180:181]
	v_lshlrev_b64 v[180:181], 1, v[212:213]
	v_pk_fma_f32 v[128:129], v[128:129], v[130:131], v[128:129]
	v_lshl_add_u64 v[130:131], s[0:1], 0, v[230:231]
	v_pk_mul_f32 v[126:127], v[126:127], v[128:129]
	v_lshl_add_u64 v[124:125], v[130:131], 0, v[180:181]
	v_mov_b32_dpp v129, v176 row_ror:2 row_mask:0xf bank_mask:0xf bound_ctrl:1
	v_cvt_pk_bf16_f32 v229, v126, v127
	global_store_dwordx4 v[124:125], v[226:229], off
	v_mov_b32_dpp v125, v176 row_ror:1 row_mask:0xf bank_mask:0xf bound_ctrl:1
	v_mov_b32_dpp v129, v172 row_shr:2 row_mask:0xf bank_mask:0xf
	v_lshlrev_b32_e32 v128, 16, v129
	v_mov_b32_dpp v125, v172 row_shr:1 row_mask:0xf bank_mask:0xf
	v_and_b32_e32 v129, 0xffff0000, v129
	v_lshlrev_b32_e32 v124, 16, v125
	v_and_b32_e32 v125, 0xffff0000, v125
	v_pk_fma_f32 v[128:129], v[148:149], v[128:129], v[160:161]
	v_and_b32_e32 v183, 0xffff0000, v172
	v_pk_fma_f32 v[124:125], v[152:153], v[124:125], v[128:129]
	v_mov_b32_dpp v127, v177 row_ror:1 row_mask:0xf bank_mask:0xf bound_ctrl:1
	v_pk_fma_f32 v[124:125], v[156:157], v[182:183], v[124:125]
	v_mov_b32_dpp v177, v177 row_ror:2 row_mask:0xf bank_mask:0xf bound_ctrl:1
	v_pk_mul_f32 v[128:129], v[124:125], s[26:27] op_sel_hi:[1,0]
	v_mov_b32_dpp v127, v173 row_shr:1 row_mask:0xf bank_mask:0xf
	v_med3_f32 v128, v128, s71, v224
	v_med3_f32 v129, v129, s71, v224
	v_pk_mul_f32 v[182:183], v[128:129], v[128:129]
	v_mov_b32_dpp v177, v173 row_shr:2 row_mask:0xf bank_mask:0xf
	v_pk_fma_f32 v[226:227], v[182:183], s[28:29], v[210:211] op_sel_hi:[1,0,0] neg_lo:[1,0,0] neg_hi:[1,0,0]
	v_lshlrev_b32_e32 v176, 16, v177
	v_pk_fma_f32 v[226:227], v[182:183], v[226:227], s[34:35] op_sel_hi:[1,1,0]
	v_and_b32_e32 v177, 0xffff0000, v177
	v_pk_fma_f32 v[226:227], v[182:183], v[226:227], s[36:37] op_sel_hi:[1,1,0]
	v_pk_mul_f32 v[124:125], v[124:125], 0.5 op_sel_hi:[1,0]
	v_pk_fma_f32 v[226:227], v[182:183], v[226:227], s[38:39] op_sel_hi:[1,1,0]
	v_lshlrev_b32_e32 v126, 16, v127
	v_pk_fma_f32 v[226:227], v[182:183], v[226:227], s[40:41] op_sel_hi:[1,1,0]
	v_and_b32_e32 v127, 0xffff0000, v127
	v_pk_fma_f32 v[226:227], v[182:183], v[226:227], s[42:43] op_sel_hi:[1,1,0]
	s_nop 0
	v_pk_fma_f32 v[182:183], v[182:183], v[226:227], s[44:45] op_sel_hi:[1,1,0]
	s_nop 0
	v_pk_mul_f32 v[128:129], v[128:129], v[182:183]
	s_nop 0
	v_pk_fma_f32 v[124:125], v[124:125], v[128:129], v[124:125]
	v_pk_fma_f32 v[128:129], v[150:151], v[176:177], v[162:163]
	v_pk_mul_f32 v[120:121], v[120:121], v[124:125]
	v_lshlrev_b32_e32 v124, 16, v173
	v_and_b32_e32 v125, 0xffff0000, v173
	v_pk_fma_f32 v[126:127], v[154:155], v[126:127], v[128:129]
	v_cvt_pk_bf16_f32 v120, v120, v121
	s_nop 0
	v_pk_fma_f32 v[124:125], v[158:159], v[124:125], v[126:127]
	s_nop 0
	v_pk_mul_f32 v[126:127], v[124:125], s[26:27] op_sel_hi:[1,0]
;     static __device__ __forceinline__ void unpk4(const u32x2 w, float (&o)[4]) { o[0] = bf_lo(w.x); o[1] = bf_hi(w.x); o[2] = bf_lo(w.y); o[3] = bf_hi(w.y); }
;     template <int N> static __device__ __forceinline__ u32x2 dpp_prev(const u32x2 pv, const u32x2 cur) { u32x2 r; r.x = dpp_prev1<N>(pv.x, cur.x); r.y = dpp_prev1<N>(pv.y, cur.y); return r; }
; __device__ __forceinline__ f32x2 gelu_pk(f32x2 v) {
;     f32x2 x = v * 0.70710678118f;
;     x.x = __builtin_amdgcn_fmed3f(x.x, -2.9f, 2.9f); x.y = __builtin_amdgcn_fmed3f(x.y, -2.9f, 2.9f);
;     const f32x2 t = x * x;
;     f32x2 p = t * (-4.953124630e-07f) + 1.987094038e-05f;
;     p = p * t + (-3.472001117e-04f); p = p * t + 3.517547622e-03f; p = p * t + (-2.333305031e-02f); p = p * t + 1.087993085e-01f; p = p * t + (-3.740358949e-01f); p = p * t + 1.128076553e+00f;
;     const f32x2 hv = v * 0.5f;
;     return hv * (x * p) + hv;
; }
;     __device__ __forceinline__ void operator()(const f32x4 (&acc)[2][2][4][2], const Unit& u, int wr, int wc, int fr, int fq) const {
;     ...
;                 for (int m = 0; m < 4; ++m) { const u32x4 cur = gq[m]; u32x4 hw;
; #pragma unroll
;                     for (int hv = 0; hv < 2; ++hv) { const u32x2 c2 = half2(cur, hv), p2 = half2(pv, hv);
;                         const u32x2 q1 = dpp_prev<1>(p2, c2), q2 = dpp_prev<2>(p2, c2);
;                         float g0[4], g1[4], g2[4]; unpk4(c2, g0); unpk4(q1, g1); unpk4(q2, g2);
;                         const u32x2 r = finish2(g0, g1, g2, w0[hv], w1[hv], w2[hv], bb[hv], acc[ai][bj][m][hv], rs8[ai][m]);
;                         if (hv == 0) { hw.x = r.x; hw.y = r.y; } else { hw.z = r.x; hw.w = r.y; } }
;                     *(u32x4*)(H + (size_t)(R0 + fr + 16 * m) * 2816 + col8) = hw;
;                     pv = cur; } }
	v_pk_mul_f32 v[124:125], v[124:125], 0.5 op_sel_hi:[1,0]
	v_med3_f32 v126, v126, s71, v224
	v_med3_f32 v127, v127, s71, v224
	v_pk_mul_f32 v[128:129], v[126:127], v[126:127]
	s_nop 0
	v_pk_fma_f32 v[176:177], v[128:129], s[28:29], v[210:211] op_sel_hi:[1,0,0] neg_lo:[1,0,0] neg_hi:[1,0,0]
	s_nop 0
	v_pk_fma_f32 v[176:177], v[128:129], v[176:177], s[34:35] op_sel_hi:[1,1,0]
	s_nop 0
	v_pk_fma_f32 v[176:177], v[128:129], v[176:177], s[36:37] op_sel_hi:[1,1,0]
	s_nop 0
	v_pk_fma_f32 v[176:177], v[128:129], v[176:177], s[38:39] op_sel_hi:[1,1,0]
	s_nop 0
	v_pk_fma_f32 v[176:177], v[128:129], v[176:177], s[40:41] op_sel_hi:[1,1,0]
	s_nop 0
	v_pk_fma_f32 v[176:177], v[128:129], v[176:177], s[42:43] op_sel_hi:[1,1,0]
	s_nop 0
	v_pk_fma_f32 v[128:129], v[128:129], v[176:177], s[44:45] op_sel_hi:[1,1,0]
	v_lshlrev_b32_e32 v176, 16, v174
	v_pk_mul_f32 v[126:127], v[126:127], v[128:129]
	v_and_b32_e32 v177, 0xffff0000, v174
	v_pk_fma_f32 v[124:125], v[124:125], v[126:127], v[124:125]
	v_mov_b32_dpp v127, v178 row_ror:2 row_mask:0xf bank_mask:0xf bound_ctrl:1
	v_pk_mul_f32 v[122:123], v[122:123], v[124:125]
	v_mov_b32_dpp v125, v179 row_ror:1 row_mask:0xf bank_mask:0xf bound_ctrl:1
	v_cvt_pk_bf16_f32 v121, v122, v123
	v_mov_b32_dpp v127, v174 row_shr:2 row_mask:0xf bank_mask:0xf
	v_mov_b32_dpp v123, v178 row_ror:1 row_mask:0xf bank_mask:0xf bound_ctrl:1
	v_lshlrev_b32_e32 v126, 16, v127
	v_and_b32_e32 v127, 0xffff0000, v127
	v_mov_b32_dpp v123, v174 row_shr:1 row_mask:0xf bank_mask:0xf
	v_lshlrev_b32_e32 v122, 16, v123
	v_and_b32_e32 v123, 0xffff0000, v123
	v_pk_fma_f32 v[126:127], v[132:133], v[126:127], v[144:145]
	v_mov_b32_dpp v129, v179 row_ror:2 row_mask:0xf bank_mask:0xf bound_ctrl:1
	v_pk_fma_f32 v[122:123], v[136:137], v[122:123], v[126:127]
	v_mov_b32_dpp v125, v175 row_shr:1 row_mask:0xf bank_mask:0xf
	v_pk_fma_f32 v[122:123], v[140:141], v[176:177], v[122:123]
	v_mov_b32_dpp v129, v175 row_shr:2 row_mask:0xf bank_mask:0xf
	v_pk_mul_f32 v[126:127], v[122:123], s[26:27] op_sel_hi:[1,0]
	v_lshlrev_b32_e32 v128, 16, v129
	v_med3_f32 v126, v126, s71, v224
	v_med3_f32 v127, v127, s71, v224
	v_pk_mul_f32 v[176:177], v[126:127], v[126:127]
	v_and_b32_e32 v129, 0xffff0000, v129
	v_pk_fma_f32 v[178:179], v[176:177], s[28:29], v[210:211] op_sel_hi:[1,0,0] neg_lo:[1,0,0] neg_hi:[1,0,0]
	v_pk_mul_f32 v[122:123], v[122:123], 0.5 op_sel_hi:[1,0]
	v_pk_fma_f32 v[178:179], v[176:177], v[178:179], s[34:35] op_sel_hi:[1,1,0]
	v_lshlrev_b32_e32 v124, 16, v125
	v_pk_fma_f32 v[178:179], v[176:177], v[178:179], s[36:37] op_sel_hi:[1,1,0]
	v_and_b32_e32 v125, 0xffff0000, v125
	v_pk_fma_f32 v[178:179], v[176:177], v[178:179], s[38:39] op_sel_hi:[1,1,0]
	s_nop 0
	v_pk_fma_f32 v[178:179], v[176:177], v[178:179], s[40:41] op_sel_hi:[1,1,0]
	s_nop 0
	v_pk_fma_f32 v[178:179], v[176:177], v[178:179], s[42:43] op_sel_hi:[1,1,0]
	s_nop 0
	v_pk_fma_f32 v[176:177], v[176:177], v[178:179], s[44:45] op_sel_hi:[1,1,0]
	s_nop 0
	v_pk_mul_f32 v[126:127], v[126:127], v[176:177]
	s_nop 0
	v_pk_fma_f32 v[122:123], v[122:123], v[126:127], v[122:123]
	v_pk_fma_f32 v[126:127], v[134:135], v[128:129], v[146:147]
	v_pk_mul_f32 v[116:117], v[116:117], v[122:123]
	v_lshlrev_b32_e32 v122, 16, v175
	v_and_b32_e32 v123, 0xffff0000, v175
	v_pk_fma_f32 v[124:125], v[138:139], v[124:125], v[126:127]
	s_nop 0
	v_pk_fma_f32 v[122:123], v[142:143], v[122:123], v[124:125]
	s_nop 0
	v_pk_mul_f32 v[124:125], v[122:123], s[26:27] op_sel_hi:[1,0]
	v_pk_mul_f32 v[122:123], v[122:123], 0.5 op_sel_hi:[1,0]
	v_med3_f32 v124, v124, s71, v224
	v_med3_f32 v125, v125, s71, v224
	v_pk_mul_f32 v[126:127], v[124:125], v[124:125]
	s_nop 0
	v_pk_fma_f32 v[128:129], v[126:127], s[28:29], v[210:211] op_sel_hi:[1,0,0] neg_lo:[1,0,0] neg_hi:[1,0,0]
	s_nop 0
	v_pk_fma_f32 v[128:129], v[126:127], v[128:129], s[34:35] op_sel_hi:[1,1,0]
	s_nop 0
	v_pk_fma_f32 v[128:129], v[126:127], v[128:129], s[36:37] op_sel_hi:[1,1,0]
	s_nop 0
	v_pk_fma_f32 v[128:129], v[126:127], v[128:129], s[38:39] op_sel_hi:[1,1,0]
	s_nop 0
	v_pk_fma_f32 v[128:129], v[126:127], v[128:129], s[40:41] op_sel_hi:[1,1,0]
	s_nop 0
	v_pk_fma_f32 v[128:129], v[126:127], v[128:129], s[42:43] op_sel_hi:[1,1,0]
	s_nop 0
	v_pk_fma_f32 v[126:127], v[126:127], v[128:129], s[44:45] op_sel_hi:[1,1,0]
	s_nop 0
	v_pk_mul_f32 v[124:125], v[124:125], v[126:127]
	v_lshlrev_b32_e32 v126, 16, v168
	v_pk_fma_f32 v[122:123], v[122:123], v[124:125], v[122:123]
	v_and_b32_e32 v127, 0xffff0000, v168
	v_pk_mul_f32 v[118:119], v[118:119], v[122:123]
	v_cvt_pk_bf16_f32 v122, v116, v117
	v_mov_b64_e32 v[116:117], s[0:1]
	v_mad_i64_i32 v[176:177], s[0:1], v194, s67, v[116:117]
	v_cvt_pk_bf16_f32 v123, v118, v119
	v_lshl_add_u64 v[118:119], v[176:177], 0, v[180:181]
	global_store_dwordx4 v[118:119], v[120:123], off
	v_mov_b32_dpp v125, v173 row_ror:2 row_mask:0xf bank_mask:0xf bound_ctrl:1
	v_mov_b32_dpp v119, v172 row_ror:1 row_mask:0xf bank_mask:0xf bound_ctrl:1
	v_mov_b32_dpp v123, v172 row_ror:2 row_mask:0xf bank_mask:0xf bound_ctrl:1
	v_mov_b32_dpp v121, v173 row_ror:1 row_mask:0xf bank_mask:0xf bound_ctrl:1
	v_mov_b32_dpp v119, v168 row_shr:1 row_mask:0xf bank_mask:0xf
	v_mov_b32_dpp v123, v168 row_shr:2 row_mask:0xf bank_mask:0xf
	v_lshlrev_b32_e32 v122, 16, v123
	v_and_b32_e32 v123, 0xffff0000, v123
	v_lshlrev_b32_e32 v118, 16, v119
	v_and_b32_e32 v119, 0xffff0000, v119
	v_pk_fma_f32 v[122:123], v[148:149], v[122:123], v[160:161]
	v_mov_b32_dpp v125, v169 row_shr:2 row_mask:0xf bank_mask:0xf
	v_pk_fma_f32 v[118:119], v[152:153], v[118:119], v[122:123]
	v_mov_b32_dpp v121, v169 row_shr:1 row_mask:0xf bank_mask:0xf
	v_pk_fma_f32 v[118:119], v[156:157], v[126:127], v[118:119]
;     static __device__ __forceinline__ void unpk4(const u32x2 w, float (&o)[4]) { o[0] = bf_lo(w.x); o[1] = bf_hi(w.x); o[2] = bf_lo(w.y); o[3] = bf_hi(w.y); }
;     template <int N> static __device__ __forceinline__ u32x2 dpp_prev(const u32x2 pv, const u32x2 cur) { u32x2 r; r.x = dpp_prev1<N>(pv.x, cur.x); r.y = dpp_prev1<N>(pv.y, cur.y); return r; }
; __device__ __forceinline__ f32x2 gelu_pk(f32x2 v) {
;     f32x2 x = v * 0.70710678118f;
;     x.x = __builtin_amdgcn_fmed3f(x.x, -2.9f, 2.9f); x.y = __builtin_amdgcn_fmed3f(x.y, -2.9f, 2.9f);
;     const f32x2 t = x * x;
;     f32x2 p = t * (-4.953124630e-07f) + 1.987094038e-05f;
;     p = p * t + (-3.472001117e-04f); p = p * t + 3.517547622e-03f; p = p * t + (-2.333305031e-02f); p = p * t + 1.087993085e-01f; p = p * t + (-3.740358949e-01f); p = p * t + 1.128076553e+00f;
;     const f32x2 hv = v * 0.5f;
;     return hv * (x * p) + hv;
; }
;     __device__ __forceinline__ void operator()(const f32x4 (&acc)[2][2][4][2], const Unit& u, int wr, int wc, int fr, int fq) const {
;     ...
;                 for (int m = 0; m < 4; ++m) { const u32x4 cur = gq[m]; u32x4 hw;
; #pragma unroll
;                     for (int hv = 0; hv < 2; ++hv) { const u32x2 c2 = half2(cur, hv), p2 = half2(pv, hv);
;                         const u32x2 q1 = dpp_prev<1>(p2, c2), q2 = dpp_prev<2>(p2, c2);
;                         float g0[4], g1[4], g2[4]; unpk4(c2, g0); unpk4(q1, g1); unpk4(q2, g2);
;                         const u32x2 r = finish2(g0, g1, g2, w0[hv], w1[hv], w2[hv], bb[hv], acc[ai][bj][m][hv], rs8[ai][m]);
;                         if (hv == 0) { hw.x = r.x; hw.y = r.y; } else { hw.z = r.x; hw.w = r.y; } }
;                     *(u32x4*)(H + (size_t)(R0 + fr + 16 * m) * 2816 + col8) = hw;
;                     pv = cur; } }
	v_lshlrev_b32_e32 v124, 16, v125
	v_pk_mul_f32 v[122:123], v[118:119], s[26:27] op_sel_hi:[1,0]
	v_and_b32_e32 v125, 0xffff0000, v125
	v_med3_f32 v122, v122, s71, v224
	v_med3_f32 v123, v123, s71, v224
	v_pk_mul_f32 v[126:127], v[122:123], v[122:123]
	v_pk_mul_f32 v[118:119], v[118:119], 0.5 op_sel_hi:[1,0]
	v_pk_fma_f32 v[128:129], v[126:127], s[28:29], v[210:211] op_sel_hi:[1,0,0] neg_lo:[1,0,0] neg_hi:[1,0,0]
	v_lshlrev_b32_e32 v120, 16, v121
	v_pk_fma_f32 v[128:129], v[126:127], v[128:129], s[34:35] op_sel_hi:[1,1,0]
	v_and_b32_e32 v121, 0xffff0000, v121
	v_pk_fma_f32 v[128:129], v[126:127], v[128:129], s[36:37] op_sel_hi:[1,1,0]
	v_mad_i64_i32 v[172:173], s[0:1], v192, s67, v[116:117]
	v_pk_fma_f32 v[128:129], v[126:127], v[128:129], s[38:39] op_sel_hi:[1,1,0]
	v_readlane_b32 s0, v240, 12
	v_pk_fma_f32 v[128:129], v[126:127], v[128:129], s[40:41] op_sel_hi:[1,1,0]
	v_readlane_b32 s1, v240, 13
	v_pk_fma_f32 v[128:129], v[126:127], v[128:129], s[42:43] op_sel_hi:[1,1,0]
	s_nop 0
	v_pk_fma_f32 v[126:127], v[126:127], v[128:129], s[44:45] op_sel_hi:[1,1,0]
	s_nop 0
	v_pk_mul_f32 v[122:123], v[122:123], v[126:127]
	s_nop 0
	v_pk_fma_f32 v[118:119], v[118:119], v[122:123], v[118:119]
	v_pk_fma_f32 v[122:123], v[150:151], v[124:125], v[162:163]
	v_pk_mul_f32 v[112:113], v[112:113], v[118:119]
	v_lshlrev_b32_e32 v118, 16, v169
	v_and_b32_e32 v119, 0xffff0000, v169
	v_pk_fma_f32 v[120:121], v[154:155], v[120:121], v[122:123]
	v_cvt_pk_bf16_f32 v112, v112, v113
	s_nop 0
	v_pk_fma_f32 v[118:119], v[158:159], v[118:119], v[120:121]
	s_nop 0
	v_pk_mul_f32 v[120:121], v[118:119], s[26:27] op_sel_hi:[1,0]
	v_pk_mul_f32 v[118:119], v[118:119], 0.5 op_sel_hi:[1,0]
	v_med3_f32 v120, v120, s71, v224
	v_med3_f32 v121, v121, s71, v224
	v_pk_mul_f32 v[122:123], v[120:121], v[120:121]
	s_nop 0
	v_pk_fma_f32 v[124:125], v[122:123], s[28:29], v[210:211] op_sel_hi:[1,0,0] neg_lo:[1,0,0] neg_hi:[1,0,0]
	s_nop 0
	v_pk_fma_f32 v[124:125], v[122:123], v[124:125], s[34:35] op_sel_hi:[1,1,0]
	s_nop 0
	v_pk_fma_f32 v[124:125], v[122:123], v[124:125], s[36:37] op_sel_hi:[1,1,0]
	s_nop 0
	v_pk_fma_f32 v[124:125], v[122:123], v[124:125], s[38:39] op_sel_hi:[1,1,0]
	s_nop 0
	v_pk_fma_f32 v[124:125], v[122:123], v[124:125], s[40:41] op_sel_hi:[1,1,0]
	s_nop 0
	v_pk_fma_f32 v[124:125], v[122:123], v[124:125], s[42:43] op_sel_hi:[1,1,0]
	s_nop 0
	v_pk_fma_f32 v[122:123], v[122:123], v[124:125], s[44:45] op_sel_hi:[1,1,0]
	v_lshlrev_b32_e32 v124, 16, v170
	v_pk_mul_f32 v[120:121], v[120:121], v[122:123]
	v_and_b32_e32 v125, 0xffff0000, v170
	v_pk_fma_f32 v[118:119], v[118:119], v[120:121], v[118:119]
	v_mov_b32_dpp v121, v174 row_ror:2 row_mask:0xf bank_mask:0xf bound_ctrl:1
	v_pk_mul_f32 v[114:115], v[114:115], v[118:119]
	v_mov_b32_dpp v123, v175 row_ror:2 row_mask:0xf bank_mask:0xf bound_ctrl:1
	v_cvt_pk_bf16_f32 v113, v114, v115
	v_mov_b32_dpp v121, v170 row_shr:2 row_mask:0xf bank_mask:0xf
	v_mov_b32_dpp v115, v174 row_ror:1 row_mask:0xf bank_mask:0xf bound_ctrl:1
	v_lshlrev_b32_e32 v120, 16, v121
	v_and_b32_e32 v121, 0xffff0000, v121
	v_mov_b32_dpp v115, v170 row_shr:1 row_mask:0xf bank_mask:0xf
	v_lshlrev_b32_e32 v114, 16, v115
	v_and_b32_e32 v115, 0xffff0000, v115
	v_pk_fma_f32 v[120:121], v[132:133], v[120:121], v[144:145]
	v_mov_b32_dpp v119, v175 row_ror:1 row_mask:0xf bank_mask:0xf bound_ctrl:1
	v_pk_fma_f32 v[114:115], v[136:137], v[114:115], v[120:121]
	v_mov_b32_dpp v123, v171 row_shr:2 row_mask:0xf bank_mask:0xf
	v_pk_fma_f32 v[114:115], v[140:141], v[124:125], v[114:115]
	v_mov_b32_dpp v119, v171 row_shr:1 row_mask:0xf bank_mask:0xf
	v_pk_mul_f32 v[120:121], v[114:115], s[26:27] op_sel_hi:[1,0]
	v_lshlrev_b32_e32 v122, 16, v123
	v_med3_f32 v120, v120, s71, v224
	v_med3_f32 v121, v121, s71, v224
	v_pk_mul_f32 v[124:125], v[120:121], v[120:121]
	v_and_b32_e32 v123, 0xffff0000, v123
	v_pk_fma_f32 v[126:127], v[124:125], s[28:29], v[210:211] op_sel_hi:[1,0,0] neg_lo:[1,0,0] neg_hi:[1,0,0]
	v_pk_mul_f32 v[114:115], v[114:115], 0.5 op_sel_hi:[1,0]
	v_pk_fma_f32 v[126:127], v[124:125], v[126:127], s[34:35] op_sel_hi:[1,1,0]
	v_lshlrev_b32_e32 v118, 16, v119
	v_pk_fma_f32 v[126:127], v[124:125], v[126:127], s[36:37] op_sel_hi:[1,1,0]
	v_and_b32_e32 v119, 0xffff0000, v119
	v_pk_fma_f32 v[126:127], v[124:125], v[126:127], s[38:39] op_sel_hi:[1,1,0]
	s_nop 0
	v_pk_fma_f32 v[126:127], v[124:125], v[126:127], s[40:41] op_sel_hi:[1,1,0]
	s_nop 0
	v_pk_fma_f32 v[126:127], v[124:125], v[126:127], s[42:43] op_sel_hi:[1,1,0]
	s_nop 0
	v_pk_fma_f32 v[124:125], v[124:125], v[126:127], s[44:45] op_sel_hi:[1,1,0]
	s_nop 0
	v_pk_mul_f32 v[120:121], v[120:121], v[124:125]
	s_nop 0
	v_pk_fma_f32 v[114:115], v[114:115], v[120:121], v[114:115]
	v_pk_fma_f32 v[120:121], v[134:135], v[122:123], v[146:147]
	v_pk_mul_f32 v[108:109], v[108:109], v[114:115]
	v_lshlrev_b32_e32 v114, 16, v171
	v_and_b32_e32 v115, 0xffff0000, v171
	v_pk_fma_f32 v[118:119], v[138:139], v[118:119], v[120:121]
	s_nop 0
	v_pk_fma_f32 v[114:115], v[142:143], v[114:115], v[118:119]
	s_nop 0
	v_pk_mul_f32 v[118:119], v[114:115], s[26:27] op_sel_hi:[1,0]
	v_pk_mul_f32 v[114:115], v[114:115], 0.5 op_sel_hi:[1,0]
	v_med3_f32 v118, v118, s71, v224
	v_med3_f32 v119, v119, s71, v224
	v_pk_mul_f32 v[120:121], v[118:119], v[118:119]
	s_nop 0
	v_pk_fma_f32 v[122:123], v[120:121], s[28:29], v[210:211] op_sel_hi:[1,0,0] neg_lo:[1,0,0] neg_hi:[1,0,0]
	s_nop 0
	v_pk_fma_f32 v[122:123], v[120:121], v[122:123], s[34:35] op_sel_hi:[1,1,0]
	s_nop 0
	v_pk_fma_f32 v[122:123], v[120:121], v[122:123], s[36:37] op_sel_hi:[1,1,0]
	s_nop 0
	v_pk_fma_f32 v[122:123], v[120:121], v[122:123], s[38:39] op_sel_hi:[1,1,0]
	s_nop 0
;     static __device__ __forceinline__ void unpk4(const u32x2 w, float (&o)[4]) { o[0] = bf_lo(w.x); o[1] = bf_hi(w.x); o[2] = bf_lo(w.y); o[3] = bf_hi(w.y); }
;     template <int N> static __device__ __forceinline__ u32x2 dpp_prev(const u32x2 pv, const u32x2 cur) { u32x2 r; r.x = dpp_prev1<N>(pv.x, cur.x); r.y = dpp_prev1<N>(pv.y, cur.y); return r; }
; __device__ __forceinline__ f32x2 gelu_pk(f32x2 v) {
;     f32x2 x = v * 0.70710678118f;
;     x.x = __builtin_amdgcn_fmed3f(x.x, -2.9f, 2.9f); x.y = __builtin_amdgcn_fmed3f(x.y, -2.9f, 2.9f);
;     const f32x2 t = x * x;
;     f32x2 p = t * (-4.953124630e-07f) + 1.987094038e-05f;
;     p = p * t + (-3.472001117e-04f); p = p * t + 3.517547622e-03f; p = p * t + (-2.333305031e-02f); p = p * t + 1.087993085e-01f; p = p * t + (-3.740358949e-01f); p = p * t + 1.128076553e+00f;
;     const f32x2 hv = v * 0.5f;
;     return hv * (x * p) + hv;
; }
;     __device__ __forceinline__ void operator()(const f32x4 (&acc)[2][2][4][2], const Unit& u, int wr, int wc, int fr, int fq) const {
;     ...
;                 for (int m = 0; m < 4; ++m) { const u32x4 cur = gq[m]; u32x4 hw;
; #pragma unroll
;                     for (int hv = 0; hv < 2; ++hv) { const u32x2 c2 = half2(cur, hv), p2 = half2(pv, hv);
;                         const u32x2 q1 = dpp_prev<1>(p2, c2), q2 = dpp_prev<2>(p2, c2);
;                         float g0[4], g1[4], g2[4]; unpk4(c2, g0); unpk4(q1, g1); unpk4(q2, g2);
;                         const u32x2 r = finish2(g0, g1, g2, w0[hv], w1[hv], w2[hv], bb[hv], acc[ai][bj][m][hv], rs8[ai][m]);
;                         if (hv == 0) { hw.x = r.x; hw.y = r.y; } else { hw.z = r.x; hw.w = r.y; } }
;                     *(u32x4*)(H + (size_t)(R0 + fr + 16 * m) * 2816 + col8) = hw;
;                     pv = cur; } }
	v_pk_fma_f32 v[122:123], v[120:121], v[122:123], s[40:41] op_sel_hi:[1,1,0]
	s_nop 0
	v_pk_fma_f32 v[122:123], v[120:121], v[122:123], s[42:43] op_sel_hi:[1,1,0]
	s_nop 0
	v_pk_fma_f32 v[120:121], v[120:121], v[122:123], s[44:45] op_sel_hi:[1,1,0]
	s_nop 0
	v_pk_mul_f32 v[118:119], v[118:119], v[120:121]
	s_nop 0
	v_pk_fma_f32 v[114:115], v[114:115], v[118:119], v[114:115]
	v_lshlrev_b32_e32 v118, 16, v164
	v_pk_mul_f32 v[110:111], v[110:111], v[114:115]
	v_cvt_pk_bf16_f32 v114, v108, v109
	v_lshl_add_u64 v[108:109], v[172:173], 0, v[180:181]
	v_cvt_pk_bf16_f32 v115, v110, v111
	global_store_dwordx4 v[108:109], v[112:115], off
	v_and_b32_e32 v119, 0xffff0000, v164
	v_mov_b32_dpp v109, v168 row_ror:1 row_mask:0xf bank_mask:0xf bound_ctrl:1
	v_mov_b32_dpp v113, v168 row_ror:2 row_mask:0xf bank_mask:0xf bound_ctrl:1
	v_mov_b32_dpp v115, v169 row_ror:2 row_mask:0xf bank_mask:0xf bound_ctrl:1
	v_mov_b32_dpp v109, v164 row_shr:1 row_mask:0xf bank_mask:0xf
	v_mov_b32_dpp v113, v164 row_shr:2 row_mask:0xf bank_mask:0xf
	v_lshlrev_b32_e32 v112, 16, v113
	v_and_b32_e32 v113, 0xffff0000, v113
	v_lshlrev_b32_e32 v108, 16, v109
	v_and_b32_e32 v109, 0xffff0000, v109
	v_pk_fma_f32 v[112:113], v[148:149], v[112:113], v[160:161]
	v_mov_b32_dpp v111, v169 row_ror:1 row_mask:0xf bank_mask:0xf bound_ctrl:1
	v_pk_fma_f32 v[108:109], v[152:153], v[108:109], v[112:113]
	v_mov_b32_dpp v115, v165 row_shr:2 row_mask:0xf bank_mask:0xf
	v_pk_fma_f32 v[108:109], v[156:157], v[118:119], v[108:109]
	v_mov_b32_dpp v111, v165 row_shr:1 row_mask:0xf bank_mask:0xf
	v_pk_mul_f32 v[112:113], v[108:109], s[26:27] op_sel_hi:[1,0]
	v_lshlrev_b32_e32 v114, 16, v115
	v_med3_f32 v112, v112, s71, v224
	v_med3_f32 v113, v113, s71, v224
	v_pk_mul_f32 v[118:119], v[112:113], v[112:113]
	v_and_b32_e32 v115, 0xffff0000, v115
	v_pk_fma_f32 v[120:121], v[118:119], s[28:29], v[210:211] op_sel_hi:[1,0,0] neg_lo:[1,0,0] neg_hi:[1,0,0]
	v_pk_mul_f32 v[108:109], v[108:109], 0.5 op_sel_hi:[1,0]
	v_pk_fma_f32 v[120:121], v[118:119], v[120:121], s[34:35] op_sel_hi:[1,1,0]
	v_lshlrev_b32_e32 v110, 16, v111
	v_pk_fma_f32 v[120:121], v[118:119], v[120:121], s[36:37] op_sel_hi:[1,1,0]
	v_and_b32_e32 v111, 0xffff0000, v111
	v_pk_fma_f32 v[120:121], v[118:119], v[120:121], s[38:39] op_sel_hi:[1,1,0]
	s_nop 0
	v_pk_fma_f32 v[120:121], v[118:119], v[120:121], s[40:41] op_sel_hi:[1,1,0]
	s_nop 0
	v_pk_fma_f32 v[120:121], v[118:119], v[120:121], s[42:43] op_sel_hi:[1,1,0]
	s_nop 0
	v_pk_fma_f32 v[118:119], v[118:119], v[120:121], s[44:45] op_sel_hi:[1,1,0]
	s_nop 0
	v_pk_mul_f32 v[112:113], v[112:113], v[118:119]
	s_nop 0
	v_pk_fma_f32 v[108:109], v[108:109], v[112:113], v[108:109]
	v_pk_fma_f32 v[112:113], v[150:151], v[114:115], v[162:163]
	v_pk_mul_f32 v[104:105], v[104:105], v[108:109]
	v_lshlrev_b32_e32 v108, 16, v165
	v_and_b32_e32 v109, 0xffff0000, v165
	v_pk_fma_f32 v[110:111], v[154:155], v[110:111], v[112:113]
	v_cvt_pk_bf16_f32 v120, v104, v105
	v_mov_b32_dpp v105, v170 row_ror:1 row_mask:0xf bank_mask:0xf bound_ctrl:1
	v_pk_fma_f32 v[108:109], v[158:159], v[108:109], v[110:111]
	s_nop 0
	v_pk_mul_f32 v[110:111], v[108:109], s[26:27] op_sel_hi:[1,0]
	v_pk_mul_f32 v[108:109], v[108:109], 0.5 op_sel_hi:[1,0]
	v_med3_f32 v110, v110, s71, v224
	v_med3_f32 v111, v111, s71, v224
	v_pk_mul_f32 v[112:113], v[110:111], v[110:111]
	v_mov_b32_dpp v105, v166 row_shr:1 row_mask:0xf bank_mask:0xf
	v_pk_fma_f32 v[114:115], v[112:113], s[28:29], v[210:211] op_sel_hi:[1,0,0] neg_lo:[1,0,0] neg_hi:[1,0,0]
	v_lshlrev_b32_e32 v104, 16, v105
	v_pk_fma_f32 v[114:115], v[112:113], v[114:115], s[34:35] op_sel_hi:[1,1,0]
	v_and_b32_e32 v105, 0xffff0000, v105
	v_pk_fma_f32 v[114:115], v[112:113], v[114:115], s[36:37] op_sel_hi:[1,1,0]
	s_nop 0
	v_pk_fma_f32 v[114:115], v[112:113], v[114:115], s[38:39] op_sel_hi:[1,1,0]
	s_nop 0
	v_pk_fma_f32 v[114:115], v[112:113], v[114:115], s[40:41] op_sel_hi:[1,1,0]
	s_nop 0
	v_pk_fma_f32 v[114:115], v[112:113], v[114:115], s[42:43] op_sel_hi:[1,1,0]
	s_nop 0
	v_pk_fma_f32 v[112:113], v[112:113], v[114:115], s[44:45] op_sel_hi:[1,1,0]
	s_nop 0
	v_pk_mul_f32 v[110:111], v[110:111], v[112:113]
	v_lshlrev_b32_e32 v112, 16, v166
	v_pk_fma_f32 v[108:109], v[108:109], v[110:111], v[108:109]
	v_and_b32_e32 v113, 0xffff0000, v166
	v_pk_mul_f32 v[106:107], v[106:107], v[108:109]
;     static __device__ __forceinline__ void unpk4(const u32x2 w, float (&o)[4]) { o[0] = bf_lo(w.x); o[1] = bf_hi(w.x); o[2] = bf_lo(w.y); o[3] = bf_hi(w.y); }
;     template <int N> static __device__ __forceinline__ u32x2 dpp_prev(const u32x2 pv, const u32x2 cur) { u32x2 r; r.x = dpp_prev1<N>(pv.x, cur.x); r.y = dpp_prev1<N>(pv.y, cur.y); return r; }
; __device__ __forceinline__ f32x2 gelu_pk(f32x2 v) {
;     f32x2 x = v * 0.70710678118f;
;     x.x = __builtin_amdgcn_fmed3f(x.x, -2.9f, 2.9f); x.y = __builtin_amdgcn_fmed3f(x.y, -2.9f, 2.9f);
;     const f32x2 t = x * x;
;     f32x2 p = t * (-4.953124630e-07f) + 1.987094038e-05f;
;     p = p * t + (-3.472001117e-04f); p = p * t + 3.517547622e-03f; p = p * t + (-2.333305031e-02f); p = p * t + 1.087993085e-01f; p = p * t + (-3.740358949e-01f); p = p * t + 1.128076553e+00f;
;     const f32x2 hv = v * 0.5f;
;     return hv * (x * p) + hv;
; }
;     __device__ __forceinline__ void operator()(const f32x4 (&acc)[2][2][4][2], const Unit& u, int wr, int wc, int fr, int fq) const {
;     ...
;             for (int ai = 0; ai < 2; ++ai) { const int R0 = u.rb + ai * HALF + wr * 64; const bf16_t* gp = G + (size_t)(R0 + fr) * 2816 + col8;
;                 u32x4 gq[4], prv = (u32x4){0u, 0u, 0u, 0u};
; #pragma unroll
;                 for (int m = 0; m < 4; ++m) gq[m] = *(const u32x4*)(gp + (size_t)m * 16 * 2816);
;                 if ((R0 & 8191) != 0) prv = *(const u32x4*)(gp - (size_t)16 * 2816);
;                 u32x4 pv = prv;
; #pragma unroll
;                 for (int m = 0; m < 4; ++m) { const u32x4 cur = gq[m]; u32x4 hw;
; #pragma unroll
;                     for (int hv = 0; hv < 2; ++hv) { const u32x2 c2 = half2(cur, hv), p2 = half2(pv, hv);
;                         const u32x2 q1 = dpp_prev<1>(p2, c2), q2 = dpp_prev<2>(p2, c2);
;                         float g0[4], g1[4], g2[4]; unpk4(c2, g0); unpk4(q1, g1); unpk4(q2, g2);
;                         const u32x2 r = finish2(g0, g1, g2, w0[hv], w1[hv], w2[hv], bb[hv], acc[ai][bj][m][hv], rs8[ai][m]);
;                         if (hv == 0) { hw.x = r.x; hw.y = r.y; } else { hw.z = r.x; hw.w = r.y; } }
;                     *(u32x4*)(H + (size_t)(R0 + fr + 16 * m) * 2816 + col8) = hw;
;                     pv = cur; } }
	v_mov_b32_dpp v109, v170 row_ror:2 row_mask:0xf bank_mask:0xf bound_ctrl:1
	v_mov_b32_dpp v111, v171 row_ror:2 row_mask:0xf bank_mask:0xf bound_ctrl:1
	v_cvt_pk_bf16_f32 v121, v106, v107
	v_mov_b32_dpp v107, v171 row_ror:1 row_mask:0xf bank_mask:0xf bound_ctrl:1
	v_mov_b32_dpp v109, v166 row_shr:2 row_mask:0xf bank_mask:0xf
	v_lshlrev_b32_e32 v108, 16, v109
	v_and_b32_e32 v109, 0xffff0000, v109
	v_pk_fma_f32 v[108:109], v[132:133], v[108:109], v[144:145]
	v_mov_b32_dpp v111, v167 row_shr:2 row_mask:0xf bank_mask:0xf
	v_pk_fma_f32 v[104:105], v[136:137], v[104:105], v[108:109]
	v_mov_b32_dpp v107, v167 row_shr:1 row_mask:0xf bank_mask:0xf
	v_pk_fma_f32 v[104:105], v[140:141], v[112:113], v[104:105]
	v_lshlrev_b32_e32 v110, 16, v111
	v_pk_mul_f32 v[108:109], v[104:105], s[26:27] op_sel_hi:[1,0]
	v_and_b32_e32 v111, 0xffff0000, v111
	v_med3_f32 v108, v108, s71, v224
	v_med3_f32 v109, v109, s71, v224
	v_pk_mul_f32 v[112:113], v[108:109], v[108:109]
	v_pk_mul_f32 v[104:105], v[104:105], 0.5 op_sel_hi:[1,0]
	v_pk_fma_f32 v[114:115], v[112:113], s[28:29], v[210:211] op_sel_hi:[1,0,0] neg_lo:[1,0,0] neg_hi:[1,0,0]
	v_lshlrev_b32_e32 v106, 16, v107
	v_pk_fma_f32 v[114:115], v[112:113], v[114:115], s[34:35] op_sel_hi:[1,1,0]
	v_and_b32_e32 v107, 0xffff0000, v107
	v_pk_fma_f32 v[114:115], v[112:113], v[114:115], s[36:37] op_sel_hi:[1,1,0]
	s_nop 0
	v_pk_fma_f32 v[114:115], v[112:113], v[114:115], s[38:39] op_sel_hi:[1,1,0]
	s_nop 0
	v_pk_fma_f32 v[114:115], v[112:113], v[114:115], s[40:41] op_sel_hi:[1,1,0]
	s_nop 0
	v_pk_fma_f32 v[114:115], v[112:113], v[114:115], s[42:43] op_sel_hi:[1,1,0]
	s_nop 0
	v_pk_fma_f32 v[112:113], v[112:113], v[114:115], s[44:45] op_sel_hi:[1,1,0]
	s_nop 0
	v_pk_mul_f32 v[108:109], v[108:109], v[112:113]
	s_nop 0
	v_pk_fma_f32 v[104:105], v[104:105], v[108:109], v[104:105]
	v_pk_fma_f32 v[108:109], v[134:135], v[110:111], v[146:147]
	v_pk_mul_f32 v[100:101], v[100:101], v[104:105]
	v_lshlrev_b32_e32 v104, 16, v167
	v_and_b32_e32 v105, 0xffff0000, v167
	v_pk_fma_f32 v[106:107], v[138:139], v[106:107], v[108:109]
	v_cvt_pk_bf16_f32 v122, v100, v101
	v_mov_b64_e32 v[100:101], s[0:1]
	v_pk_fma_f32 v[104:105], v[142:143], v[104:105], v[106:107]
	v_mad_i64_i32 v[164:165], s[0:1], v1, s67, v[100:101]
	v_pk_mul_f32 v[106:107], v[104:105], s[26:27] op_sel_hi:[1,0]
	v_lshl_add_u64 v[118:119], v[164:165], 0, v[180:181]
	v_med3_f32 v106, v106, s71, v224
	v_med3_f32 v107, v107, s71, v224
	v_pk_mul_f32 v[108:109], v[106:107], v[106:107]
	v_pk_mul_f32 v[104:105], v[104:105], 0.5 op_sel_hi:[1,0]
	v_pk_fma_f32 v[110:111], v[108:109], s[28:29], v[210:211] op_sel_hi:[1,0,0] neg_lo:[1,0,0] neg_hi:[1,0,0]
	v_add_co_u32_e32 v100, vcc, s45, v118
	v_pk_fma_f32 v[110:111], v[108:109], v[110:111], s[34:35] op_sel_hi:[1,1,0]
	s_nop 0
	v_addc_co_u32_e32 v101, vcc, 0, v119, vcc
	v_pk_fma_f32 v[110:111], v[108:109], v[110:111], s[36:37] op_sel_hi:[1,1,0]
	v_mad_i64_i32 v[166:167], s[0:1], v190, s67, v[116:117]
	v_pk_fma_f32 v[110:111], v[108:109], v[110:111], s[38:39] op_sel_hi:[1,1,0]
	s_and_b32 s0, s47, 0x1fff
	v_pk_fma_f32 v[110:111], v[108:109], v[110:111], s[40:41] op_sel_hi:[1,1,0]
	s_cmp_lg_u32 s0, 0
	v_pk_fma_f32 v[110:111], v[108:109], v[110:111], s[42:43] op_sel_hi:[1,1,0]
	v_lshl_add_u64 v[116:117], v[166:167], 0, v[180:181]
	v_pk_fma_f32 v[108:109], v[108:109], v[110:111], s[44:45] op_sel_hi:[1,1,0]
	s_cselect_b64 s[8:9], -1, 0
	v_pk_mul_f32 v[106:107], v[106:107], v[108:109]
	s_cmp_eq_u32 s0, 0
	v_pk_fma_f32 v[104:105], v[104:105], v[106:107], v[104:105]
	s_nop 0
	v_pk_mul_f32 v[102:103], v[102:103], v[104:105]
	s_nop 0
	v_cvt_pk_bf16_f32 v123, v102, v103
	global_load_dwordx4 v[112:115], v[118:119], off
	global_load_dwordx4 v[108:111], v[100:101], off
	v_add_co_u32_e32 v100, vcc, 0x2c000, v118
	s_nop 1
	v_addc_co_u32_e32 v101, vcc, 0, v119, vcc
	v_add_co_u32_e32 v102, vcc, 0x42000, v118
	s_nop 1
	v_addc_co_u32_e32 v103, vcc, 0, v119, vcc
	global_load_dwordx4 v[104:107], v[100:101], off
	s_nop 0
	global_load_dwordx4 v[100:103], v[102:103], off
	s_nop 0
	global_store_dwordx4 v[116:117], v[120:123], off
	s_cbranch_scc1 .LBB0_3147
	v_add_co_u32_e32 v116, vcc, 0xfffea000, v118
	s_nop 1
	v_addc_co_u32_e32 v117, vcc, -1, v119, vcc
	global_load_dwordx4 v[116:119], v[116:117], off
	s_branch .LBB0_3148

; __device__ __forceinline__ f32x2 gelu_pk(f32x2 v) {
;     f32x2 x = v * 0.70710678118f;
;     x.x = __builtin_amdgcn_fmed3f(x.x, -2.9f, 2.9f); x.y = __builtin_amdgcn_fmed3f(x.y, -2.9f, 2.9f);
;     const f32x2 t = x * x;
;     f32x2 p = t * (-4.953124630e-07f) + 1.987094038e-05f;
;     p = p * t + (-3.472001117e-04f); p = p * t + 3.517547622e-03f; p = p * t + (-2.333305031e-02f); p = p * t + 1.087993085e-01f; p = p * t + (-3.740358949e-01f); p = p * t + 1.128076553e+00f;
;     const f32x2 hv = v * 0.5f;
;     return hv * (x * p) + hv;
; }
;     __device__ __forceinline__ void operator()(const f32x4 (&acc)[2][2][4][2], const Unit& u, int wr, int wc, int fr, int fq) const {
;     ...
;         float rs8[2][4];
; #pragma unroll
;         for (int ai = 0; ai < 2; ++ai)
; #pragma unroll
;             for (int m = 0; m < 4; ++m) rs8[ai][m] = rsqrtf(SS[u.rb + (u.half ? 0 : ai * HALF) + wr * 64 + fr + 16 * m] * (1.f / 1024.f) + 1e-6f);
;         if (u.pm < 128) {
; #pragma unroll
;           for (int bj = 0; bj < 2; ++bj) {
;             const int col8 = u.pn * BM + bj * HALF + wc * 32 + 8 * fq;
;             float w0[2][4], w1[2][4], w2[2][4], bb[2][4];
; #pragma unroll
;             for (int hv = 0; hv < 2; ++hv) { ld4f(cw + col8 + 4 * hv, w0[hv]); ld4f(cw + 2816 + col8 + 4 * hv, w1[hv]); ld4f(cw + 2 * 2816 + col8 + 4 * hv, w2[hv]); ld4f(cb + col8 + 4 * hv, bb[hv]); }
; #pragma unroll
;             for (int ai = 0; ai < 2; ++ai) { const int R0 = u.rb + ai * HALF + wr * 64; const bf16_t* gp = G + (size_t)(R0 + fr) * 2816 + col8;
;                 u32x4 gq[4], prv = (u32x4){0u, 0u, 0u, 0u};
; #pragma unroll
;                 for (int m = 0; m < 4; ++m) gq[m] = *(const u32x4*)(gp + (size_t)m * 16 * 2816);
;                 if ((R0 & 8191) != 0) prv = *(const u32x4*)(gp - (size_t)16 * 2816);
;                 u32x4 pv = prv;
; #pragma unroll
;                 for (int m = 0; m < 4; ++m) { const u32x4 cur = gq[m]; u32x4 hw;
; #pragma unroll
;                     for (int hv = 0; hv < 2; ++hv) { const u32x2 c2 = half2(cur, hv), p2 = half2(pv, hv);
;                         const u32x2 q1 = dpp_prev<1>(p2, c2), q2 = dpp_prev<2>(p2, c2);
;                         float g0[4], g1[4], g2[4]; unpk4(c2, g0); unpk4(q1, g1); unpk4(q2, g2);
;                         const u32x2 r = finish2(g0, g1, g2, w0[hv], w1[hv], w2[hv], bb[hv], acc[ai][bj][m][hv], rs8[ai][m]);
.LBB0_3148:
	v_fmamk_f32 v120, v189, 0x3a800000, v223
	v_mul_f32_e32 v121, 0x4b800000, v120
	v_cmp_gt_f32_e32 vcc, s66, v120
	v_fmamk_f32 v3, v3, 0x3a800000, v223
	s_waitcnt vmcnt(0)
	v_mov_b32_dpp v127, v117 row_ror:2 row_mask:0xf bank_mask:0xf bound_ctrl:1
	v_cndmask_b32_e32 v120, v120, v121, vcc
	v_rsq_f32_e32 v122, v120
	v_fmamk_f32 v120, v187, 0x3a800000, v223
	v_mul_f32_e32 v121, 0x4b800000, v120
	v_cmp_gt_f32_e64 s[0:1], s66, v120
	v_mul_f32_e32 v124, 0x45800000, v122
	v_cndmask_b32_e32 v128, v122, v124, vcc
	v_cndmask_b32_e64 v120, v120, v121, s[0:1]
	v_mul_f32_e32 v124, 0x4b800000, v3
	v_cmp_gt_f32_e32 vcc, s66, v3
	v_rsq_f32_e32 v123, v120
	v_mad_i64_i32 v[120:121], s[6:7], v1, s67, 0
	v_cndmask_b32_e32 v3, v3, v124, vcc
	v_fmamk_f32 v124, v185, 0x3a800000, v223
	v_mul_f32_e32 v125, 0x4b800000, v124
	v_cmp_gt_f32_e64 s[6:7], s66, v124
	v_rsq_f32_e32 v3, v3
	v_mul_f32_e32 v122, 0x45800000, v123
	v_cndmask_b32_e64 v124, v124, v125, s[6:7]
	v_rsq_f32_e32 v125, v124
	v_cndmask_b32_e64 v126, v123, v122, s[0:1]
	v_mul_f32_e32 v122, 0x45800000, v3
	v_cndmask_b32_e32 v124, v3, v122, vcc
	v_mul_f32_e32 v3, 0x45800000, v125
	v_cndmask_b32_e64 v122, v125, v3, s[6:7]
	v_mov_b32_dpp v125, v116 row_ror:2 row_mask:0xf bank_mask:0xf bound_ctrl:1
	v_mov_b32_dpp v3, v116 row_ror:1 row_mask:0xf bank_mask:0xf bound_ctrl:1
	v_mov_b32_dpp v123, v117 row_ror:1 row_mask:0xf bank_mask:0xf bound_ctrl:1
	v_mov_b32_dpp v125, v112 row_shr:2 row_mask:0xf bank_mask:0xf
	v_mov_b32_dpp v3, v112 row_shr:1 row_mask:0xf bank_mask:0xf
	v_lshlrev_b32_e32 v170, 16, v125
	v_and_b32_e32 v171, 0xffff0000, v125
	v_lshlrev_b32_e32 v116, 16, v3
	v_and_b32_e32 v117, 0xffff0000, v3
	v_pk_fma_f32 v[170:171], v[148:149], v[170:171], v[160:161]
	v_lshlrev_b32_e32 v178, 16, v112
	v_and_b32_e32 v179, 0xffff0000, v112
	v_pk_fma_f32 v[116:117], v[152:153], v[116:117], v[170:171]
	v_mov_b32_dpp v127, v113 row_shr:2 row_mask:0xf bank_mask:0xf
	v_pk_fma_f32 v[170:171], v[156:157], v[178:179], v[116:117]
	v_mov_b32_dpp v123, v113 row_shr:1 row_mask:0xf bank_mask:0xf
	v_pk_mul_f32 v[116:117], v[170:171], s[26:27] op_sel_hi:[1,0]
	v_lshlrev_b32_e32 v174, 16, v127
	v_med3_f32 v178, v116, s71, v224
	v_med3_f32 v179, v117, s71, v224
	v_pk_mul_f32 v[182:183], v[178:179], v[178:179]
	v_mov_b64_e32 v[116:117], s[30:31]
	v_pk_fma_f32 v[190:191], v[182:183], s[28:29], v[116:117] op_sel_hi:[1,0,0] neg_lo:[1,0,0] neg_hi:[1,0,0]
	v_and_b32_e32 v175, 0xffff0000, v127
	v_pk_fma_f32 v[190:191], v[182:183], v[190:191], s[34:35] op_sel_hi:[1,1,0]
	v_pk_mul_f32 v[170:171], v[170:171], 0.5 op_sel_hi:[1,0]
	v_pk_fma_f32 v[190:191], v[182:183], v[190:191], s[36:37] op_sel_hi:[1,1,0]
	v_lshlrev_b32_e32 v168, 16, v123
	v_pk_fma_f32 v[190:191], v[182:183], v[190:191], s[38:39] op_sel_hi:[1,1,0]
	v_and_b32_e32 v169, 0xffff0000, v123
	v_pk_fma_f32 v[190:191], v[182:183], v[190:191], s[40:41] op_sel_hi:[1,1,0]
	v_pk_mul_f32 v[96:97], v[96:97], v[128:129] op_sel_hi:[1,0]
	v_pk_fma_f32 v[190:191], v[182:183], v[190:191], s[42:43] op_sel_hi:[1,1,0]
	v_pk_fma_f32 v[174:175], v[150:151], v[174:175], v[162:163]
	v_pk_fma_f32 v[182:183], v[182:183], v[190:191], s[44:45] op_sel_hi:[1,1,0]
	v_pk_fma_f32 v[168:169], v[154:155], v[168:169], v[174:175]
	v_pk_mul_f32 v[178:179], v[178:179], v[182:183]
	v_mov_b32_dpp v125, v118 row_ror:2 row_mask:0xf bank_mask:0xf bound_ctrl:1
	v_pk_fma_f32 v[170:171], v[170:171], v[178:179], v[170:171]
	v_pk_mul_f32 v[98:99], v[98:99], v[128:129] op_sel_hi:[1,0]
	v_pk_mul_f32 v[96:97], v[96:97], v[170:171]
	v_lshlrev_b32_e32 v170, 16, v113
	v_and_b32_e32 v171, 0xffff0000, v113
	v_pk_fma_f32 v[168:169], v[158:159], v[170:171], v[168:169]
	v_mov_b32_dpp v3, v118 row_ror:1 row_mask:0xf bank_mask:0xf bound_ctrl:1
	v_pk_mul_f32 v[170:171], v[168:169], s[26:27] op_sel_hi:[1,0]
	v_pk_mul_f32 v[168:169], v[168:169], 0.5 op_sel_hi:[1,0]
	v_med3_f32 v170, v170, s71, v224
	v_med3_f32 v171, v171, s71, v224
	v_pk_mul_f32 v[174:175], v[170:171], v[170:171]
	v_mov_b32_dpp v125, v114 row_shr:2 row_mask:0xf bank_mask:0xf
	v_pk_fma_f32 v[178:179], v[174:175], s[28:29], v[116:117] op_sel_hi:[1,0,0] neg_lo:[1,0,0] neg_hi:[1,0,0]
	v_mov_b32_dpp v3, v114 row_shr:1 row_mask:0xf bank_mask:0xf
	v_pk_fma_f32 v[178:179], v[174:175], v[178:179], s[34:35] op_sel_hi:[1,1,0]
	v_cvt_pk_bf16_f32 v96, v96, v97
	v_mov_b32_dpp v127, v119 row_ror:2 row_mask:0xf bank_mask:0xf bound_ctrl:1
	v_pk_fma_f32 v[178:179], v[174:175], v[178:179], s[36:37] op_sel_hi:[1,1,0]
	v_mov_b32_dpp v123, v119 row_ror:1 row_mask:0xf bank_mask:0xf bound_ctrl:1
	v_pk_fma_f32 v[178:179], v[174:175], v[178:179], s[38:39] op_sel_hi:[1,1,0]
	v_mov_b32_dpp v127, v115 row_shr:2 row_mask:0xf bank_mask:0xf
	v_pk_fma_f32 v[178:179], v[174:175], v[178:179], s[40:41] op_sel_hi:[1,1,0]
	v_mov_b32_dpp v123, v115 row_shr:1 row_mask:0xf bank_mask:0xf
	v_pk_fma_f32 v[178:179], v[174:175], v[178:179], s[42:43] op_sel_hi:[1,1,0]
	v_lshlrev_b32_e32 v118, 16, v123
	v_pk_fma_f32 v[174:175], v[174:175], v[178:179], s[44:45] op_sel_hi:[1,1,0]
	v_and_b32_e32 v119, 0xffff0000, v123
	v_pk_mul_f32 v[170:171], v[170:171], v[174:175]
	v_lshlrev_b32_e32 v174, 16, v114
	v_pk_fma_f32 v[168:169], v[168:169], v[170:171], v[168:169]
	v_and_b32_e32 v175, 0xffff0000, v114
	v_pk_mul_f32 v[98:99], v[98:99], v[168:169]
	v_lshlrev_b32_e32 v168, 16, v125
	v_and_b32_e32 v169, 0xffff0000, v125
	v_cvt_pk_bf16_f32 v97, v98, v99
	v_lshlrev_b32_e32 v98, 16, v3
	v_and_b32_e32 v99, 0xffff0000, v3
	v_pk_fma_f32 v[168:169], v[132:133], v[168:169], v[144:145]
	v_lshlrev_b32_e32 v170, 16, v127
	v_pk_fma_f32 v[98:99], v[136:137], v[98:99], v[168:169]
	v_and_b32_e32 v171, 0xffff0000, v127
;     static __device__ __forceinline__ void unpk4(const u32x2 w, float (&o)[4]) { o[0] = bf_lo(w.x); o[1] = bf_hi(w.x); o[2] = bf_lo(w.y); o[3] = bf_hi(w.y); }
;     template <int N> static __device__ __forceinline__ u32x2 dpp_prev(const u32x2 pv, const u32x2 cur) { u32x2 r; r.x = dpp_prev1<N>(pv.x, cur.x); r.y = dpp_prev1<N>(pv.y, cur.y); return r; }
; __device__ __forceinline__ f32x2 gelu_pk(f32x2 v) {
;     f32x2 x = v * 0.70710678118f;
;     x.x = __builtin_amdgcn_fmed3f(x.x, -2.9f, 2.9f); x.y = __builtin_amdgcn_fmed3f(x.y, -2.9f, 2.9f);
;     const f32x2 t = x * x;
;     f32x2 p = t * (-4.953124630e-07f) + 1.987094038e-05f;
;     p = p * t + (-3.472001117e-04f); p = p * t + 3.517547622e-03f; p = p * t + (-2.333305031e-02f); p = p * t + 1.087993085e-01f; p = p * t + (-3.740358949e-01f); p = p * t + 1.128076553e+00f;
;     const f32x2 hv = v * 0.5f;
;     return hv * (x * p) + hv;
; }
;     __device__ __forceinline__ void operator()(const f32x4 (&acc)[2][2][4][2], const Unit& u, int wr, int wc, int fr, int fq) const {
;     ...
;                 for (int m = 0; m < 4; ++m) { const u32x4 cur = gq[m]; u32x4 hw;
; #pragma unroll
;                     for (int hv = 0; hv < 2; ++hv) { const u32x2 c2 = half2(cur, hv), p2 = half2(pv, hv);
;                         const u32x2 q1 = dpp_prev<1>(p2, c2), q2 = dpp_prev<2>(p2, c2);
;                         float g0[4], g1[4], g2[4]; unpk4(c2, g0); unpk4(q1, g1); unpk4(q2, g2);
;                         const u32x2 r = finish2(g0, g1, g2, w0[hv], w1[hv], w2[hv], bb[hv], acc[ai][bj][m][hv], rs8[ai][m]);
;                         if (hv == 0) { hw.x = r.x; hw.y = r.y; } else { hw.z = r.x; hw.w = r.y; } }
;                     *(u32x4*)(H + (size_t)(R0 + fr + 16 * m) * 2816 + col8) = hw;
;                     pv = cur; } }
	v_pk_fma_f32 v[98:99], v[140:141], v[174:175], v[98:99]
	v_pk_mul_f32 v[92:93], v[92:93], v[128:129] op_sel_hi:[1,0]
	v_pk_mul_f32 v[168:169], v[98:99], s[26:27] op_sel_hi:[1,0]
	v_pk_mul_f32 v[98:99], v[98:99], 0.5 op_sel_hi:[1,0]
	v_med3_f32 v168, v168, s71, v224
	v_med3_f32 v169, v169, s71, v224
	v_pk_mul_f32 v[174:175], v[168:169], v[168:169]
	v_readlane_b32 s0, v240, 58
	v_pk_fma_f32 v[178:179], v[174:175], s[28:29], v[116:117] op_sel_hi:[1,0,0] neg_lo:[1,0,0] neg_hi:[1,0,0]
	v_readlane_b32 s1, v240, 59
	v_pk_fma_f32 v[178:179], v[174:175], v[178:179], s[34:35] op_sel_hi:[1,1,0]
	v_pk_mul_f32 v[94:95], v[94:95], v[128:129] op_sel_hi:[1,0]
	v_pk_fma_f32 v[178:179], v[174:175], v[178:179], s[36:37] op_sel_hi:[1,1,0]
	v_mov_b32_dpp v3, v112 row_ror:1 row_mask:0xf bank_mask:0xf bound_ctrl:1
	v_pk_fma_f32 v[178:179], v[174:175], v[178:179], s[38:39] op_sel_hi:[1,1,0]
	v_pk_mul_f32 v[88:89], v[88:89], v[126:127] op_sel_hi:[1,0]
	v_pk_fma_f32 v[178:179], v[174:175], v[178:179], s[40:41] op_sel_hi:[1,1,0]
	v_mov_b32_dpp v3, v108 row_shr:1 row_mask:0xf bank_mask:0xf
	v_pk_fma_f32 v[178:179], v[174:175], v[178:179], s[42:43] op_sel_hi:[1,1,0]
	v_pk_mul_f32 v[90:91], v[90:91], v[126:127] op_sel_hi:[1,0]
	v_pk_fma_f32 v[174:175], v[174:175], v[178:179], s[44:45] op_sel_hi:[1,1,0]
	v_pk_mul_f32 v[84:85], v[84:85], v[126:127] op_sel_hi:[1,0]
	v_pk_mul_f32 v[168:169], v[168:169], v[174:175]
	v_pk_mul_f32 v[86:87], v[86:87], v[126:127] op_sel_hi:[1,0]
	v_pk_fma_f32 v[98:99], v[98:99], v[168:169], v[98:99]
	v_pk_fma_f32 v[168:169], v[134:135], v[170:171], v[146:147]
	v_pk_mul_f32 v[92:93], v[92:93], v[98:99]
	v_lshlrev_b32_e32 v98, 16, v115
	v_and_b32_e32 v99, 0xffff0000, v115
	v_pk_fma_f32 v[118:119], v[138:139], v[118:119], v[168:169]
	v_pk_mul_f32 v[80:81], v[80:81], v[124:125] op_sel_hi:[1,0]
	v_pk_fma_f32 v[98:99], v[142:143], v[98:99], v[118:119]
	v_pk_mul_f32 v[82:83], v[82:83], v[124:125] op_sel_hi:[1,0]
	v_pk_mul_f32 v[118:119], v[98:99], s[26:27] op_sel_hi:[1,0]
	v_pk_mul_f32 v[98:99], v[98:99], 0.5 op_sel_hi:[1,0]
	v_med3_f32 v118, v118, s71, v224
	v_med3_f32 v119, v119, s71, v224
	v_pk_mul_f32 v[168:169], v[118:119], v[118:119]
	v_pk_mul_f32 v[76:77], v[76:77], v[124:125] op_sel_hi:[1,0]
	v_pk_fma_f32 v[170:171], v[168:169], s[28:29], v[116:117] op_sel_hi:[1,0,0] neg_lo:[1,0,0] neg_hi:[1,0,0]
	v_pk_mul_f32 v[78:79], v[78:79], v[124:125] op_sel_hi:[1,0]
	v_pk_fma_f32 v[170:171], v[168:169], v[170:171], s[34:35] op_sel_hi:[1,1,0]
	v_pk_mul_f32 v[72:73], v[72:73], v[122:123] op_sel_hi:[1,0]
	v_pk_fma_f32 v[170:171], v[168:169], v[170:171], s[36:37] op_sel_hi:[1,1,0]
	v_pk_mul_f32 v[74:75], v[74:75], v[122:123] op_sel_hi:[1,0]
	v_pk_fma_f32 v[170:171], v[168:169], v[170:171], s[38:39] op_sel_hi:[1,1,0]
	v_pk_mul_f32 v[64:65], v[64:65], v[122:123] op_sel_hi:[1,0]
	v_pk_fma_f32 v[170:171], v[168:169], v[170:171], s[40:41] op_sel_hi:[1,1,0]
	v_pk_mul_f32 v[66:67], v[66:67], v[122:123] op_sel_hi:[1,0]
	v_pk_fma_f32 v[170:171], v[168:169], v[170:171], s[42:43] op_sel_hi:[1,1,0]
	s_nop 0
	v_pk_fma_f32 v[168:169], v[168:169], v[170:171], s[44:45] op_sel_hi:[1,1,0]
	s_nop 0
	v_pk_mul_f32 v[118:119], v[118:119], v[168:169]
	v_lshl_add_u64 v[168:169], s[0:1], 0, v[120:121]
	v_pk_fma_f32 v[98:99], v[98:99], v[118:119], v[98:99]
	v_mov_b32_e32 v120, 0
	v_pk_mul_f32 v[94:95], v[94:95], v[98:99]
	v_cvt_pk_bf16_f32 v98, v92, v93
	v_lshl_add_u64 v[92:93], v[168:169], 0, v[180:181]
	v_cvt_pk_bf16_f32 v99, v94, v95
	global_store_dwordx4 v[92:93], v[96:99], off
	v_lshlrev_b32_e32 v92, 16, v3
	v_and_b32_e32 v93, 0xffff0000, v3
	v_mov_b32_dpp v97, v112 row_ror:2 row_mask:0xf bank_mask:0xf bound_ctrl:1
	v_mov_b32_dpp v95, v113 row_ror:1 row_mask:0xf bank_mask:0xf bound_ctrl:1
	v_mov_b32_dpp v99, v113 row_ror:2 row_mask:0xf bank_mask:0xf bound_ctrl:1
	v_mov_b32_dpp v97, v108 row_shr:2 row_mask:0xf bank_mask:0xf
	v_lshlrev_b32_e32 v96, 16, v97
	v_and_b32_e32 v97, 0xffff0000, v97
	v_pk_fma_f32 v[96:97], v[148:149], v[96:97], v[160:161]
	v_lshlrev_b32_e32 v112, 16, v108
	v_and_b32_e32 v113, 0xffff0000, v108
	v_pk_fma_f32 v[92:93], v[152:153], v[92:93], v[96:97]
	v_mov_b32_dpp v99, v109 row_shr:2 row_mask:0xf bank_mask:0xf
	v_pk_fma_f32 v[92:93], v[156:157], v[112:113], v[92:93]
	v_mov_b32_dpp v95, v109 row_shr:1 row_mask:0xf bank_mask:0xf
	v_pk_mul_f32 v[96:97], v[92:93], s[26:27] op_sel_hi:[1,0]
	v_lshlrev_b32_e32 v98, 16, v99
	v_med3_f32 v96, v96, s71, v224
	v_med3_f32 v97, v97, s71, v224
	v_pk_mul_f32 v[112:113], v[96:97], v[96:97]
	v_and_b32_e32 v99, 0xffff0000, v99
	v_pk_fma_f32 v[118:119], v[112:113], s[28:29], v[116:117] op_sel_hi:[1,0,0] neg_lo:[1,0,0] neg_hi:[1,0,0]
	v_pk_mul_f32 v[92:93], v[92:93], 0.5 op_sel_hi:[1,0]
	v_pk_fma_f32 v[118:119], v[112:113], v[118:119], s[34:35] op_sel_hi:[1,1,0]
	v_lshlrev_b32_e32 v94, 16, v95
	v_pk_fma_f32 v[118:119], v[112:113], v[118:119], s[36:37] op_sel_hi:[1,1,0]
	v_and_b32_e32 v95, 0xffff0000, v95
	v_pk_fma_f32 v[118:119], v[112:113], v[118:119], s[38:39] op_sel_hi:[1,1,0]
	v_mov_b32_dpp v3, v114 row_ror:1 row_mask:0xf bank_mask:0xf bound_ctrl:1
	v_pk_fma_f32 v[118:119], v[112:113], v[118:119], s[40:41] op_sel_hi:[1,1,0]
	v_mov_b32_e32 v121, 0
	v_pk_fma_f32 v[118:119], v[112:113], v[118:119], s[42:43] op_sel_hi:[1,1,0]
	v_mov_b32_dpp v3, v110 row_shr:1 row_mask:0xf bank_mask:0xf
	v_pk_fma_f32 v[112:113], v[112:113], v[118:119], s[44:45] op_sel_hi:[1,1,0]
	v_mov_b32_e32 v118, 0
	v_pk_mul_f32 v[96:97], v[96:97], v[112:113]
	v_mov_b32_e32 v119, 0
	v_pk_fma_f32 v[92:93], v[92:93], v[96:97], v[92:93]
	v_pk_fma_f32 v[96:97], v[150:151], v[98:99], v[162:163]
	v_pk_mul_f32 v[88:89], v[88:89], v[92:93]
	v_lshlrev_b32_e32 v92, 16, v109
;     static __device__ __forceinline__ void unpk4(const u32x2 w, float (&o)[4]) { o[0] = bf_lo(w.x); o[1] = bf_hi(w.x); o[2] = bf_lo(w.y); o[3] = bf_hi(w.y); }
;     template <int N> static __device__ __forceinline__ u32x2 dpp_prev(const u32x2 pv, const u32x2 cur) { u32x2 r; r.x = dpp_prev1<N>(pv.x, cur.x); r.y = dpp_prev1<N>(pv.y, cur.y); return r; }
; __device__ __forceinline__ f32x2 gelu_pk(f32x2 v) {
;     f32x2 x = v * 0.70710678118f;
;     x.x = __builtin_amdgcn_fmed3f(x.x, -2.9f, 2.9f); x.y = __builtin_amdgcn_fmed3f(x.y, -2.9f, 2.9f);
;     const f32x2 t = x * x;
;     f32x2 p = t * (-4.953124630e-07f) + 1.987094038e-05f;
;     p = p * t + (-3.472001117e-04f); p = p * t + 3.517547622e-03f; p = p * t + (-2.333305031e-02f); p = p * t + 1.087993085e-01f; p = p * t + (-3.740358949e-01f); p = p * t + 1.128076553e+00f;
;     const f32x2 hv = v * 0.5f;
;     return hv * (x * p) + hv;
; }
;     __device__ __forceinline__ void operator()(const f32x4 (&acc)[2][2][4][2], const Unit& u, int wr, int wc, int fr, int fq) const {
;     ...
;                 for (int m = 0; m < 4; ++m) { const u32x4 cur = gq[m]; u32x4 hw;
; #pragma unroll
;                     for (int hv = 0; hv < 2; ++hv) { const u32x2 c2 = half2(cur, hv), p2 = half2(pv, hv);
;                         const u32x2 q1 = dpp_prev<1>(p2, c2), q2 = dpp_prev<2>(p2, c2);
;                         float g0[4], g1[4], g2[4]; unpk4(c2, g0); unpk4(q1, g1); unpk4(q2, g2);
;                         const u32x2 r = finish2(g0, g1, g2, w0[hv], w1[hv], w2[hv], bb[hv], acc[ai][bj][m][hv], rs8[ai][m]);
;                         if (hv == 0) { hw.x = r.x; hw.y = r.y; } else { hw.z = r.x; hw.w = r.y; } }
;                     *(u32x4*)(H + (size_t)(R0 + fr + 16 * m) * 2816 + col8) = hw;
;                     pv = cur; } }
	v_and_b32_e32 v93, 0xffff0000, v109
	v_pk_fma_f32 v[94:95], v[154:155], v[94:95], v[96:97]
	v_cvt_pk_bf16_f32 v88, v88, v89
	s_nop 0
	v_pk_fma_f32 v[92:93], v[158:159], v[92:93], v[94:95]
	s_nop 0
	v_pk_mul_f32 v[94:95], v[92:93], s[26:27] op_sel_hi:[1,0]
	v_pk_mul_f32 v[92:93], v[92:93], 0.5 op_sel_hi:[1,0]
	v_med3_f32 v94, v94, s71, v224
	v_med3_f32 v95, v95, s71, v224
	v_pk_mul_f32 v[96:97], v[94:95], v[94:95]
	s_nop 0
	v_pk_fma_f32 v[98:99], v[96:97], s[28:29], v[116:117] op_sel_hi:[1,0,0] neg_lo:[1,0,0] neg_hi:[1,0,0]
	s_nop 0
	v_pk_fma_f32 v[98:99], v[96:97], v[98:99], s[34:35] op_sel_hi:[1,1,0]
	s_nop 0
	v_pk_fma_f32 v[98:99], v[96:97], v[98:99], s[36:37] op_sel_hi:[1,1,0]
	s_nop 0
	v_pk_fma_f32 v[98:99], v[96:97], v[98:99], s[38:39] op_sel_hi:[1,1,0]
	s_nop 0
	v_pk_fma_f32 v[98:99], v[96:97], v[98:99], s[40:41] op_sel_hi:[1,1,0]
	s_nop 0
	v_pk_fma_f32 v[98:99], v[96:97], v[98:99], s[42:43] op_sel_hi:[1,1,0]
	s_nop 0
	v_pk_fma_f32 v[96:97], v[96:97], v[98:99], s[44:45] op_sel_hi:[1,1,0]
	v_lshlrev_b32_e32 v98, 16, v110
	v_pk_mul_f32 v[94:95], v[94:95], v[96:97]
	v_and_b32_e32 v99, 0xffff0000, v110
	v_pk_fma_f32 v[92:93], v[92:93], v[94:95], v[92:93]
	v_mov_b32_dpp v95, v114 row_ror:2 row_mask:0xf bank_mask:0xf bound_ctrl:1
	v_pk_mul_f32 v[90:91], v[90:91], v[92:93]
	v_mov_b32_dpp v97, v115 row_ror:2 row_mask:0xf bank_mask:0xf bound_ctrl:1
	v_mov_b32_dpp v95, v110 row_shr:2 row_mask:0xf bank_mask:0xf
	v_lshlrev_b32_e32 v94, 16, v95
	v_and_b32_e32 v95, 0xffff0000, v95
	v_cvt_pk_bf16_f32 v89, v90, v91
	v_lshlrev_b32_e32 v90, 16, v3
	v_and_b32_e32 v91, 0xffff0000, v3
	v_pk_fma_f32 v[94:95], v[132:133], v[94:95], v[144:145]
	v_mov_b32_dpp v93, v115 row_ror:1 row_mask:0xf bank_mask:0xf bound_ctrl:1
	v_pk_fma_f32 v[90:91], v[136:137], v[90:91], v[94:95]
	v_mov_b32_dpp v97, v111 row_shr:2 row_mask:0xf bank_mask:0xf
	v_pk_fma_f32 v[90:91], v[140:141], v[98:99], v[90:91]
	v_mov_b32_dpp v93, v111 row_shr:1 row_mask:0xf bank_mask:0xf
	v_pk_mul_f32 v[94:95], v[90:91], s[26:27] op_sel_hi:[1,0]
	v_lshlrev_b32_e32 v96, 16, v97
	v_med3_f32 v94, v94, s71, v224
	v_med3_f32 v95, v95, s71, v224
	v_pk_mul_f32 v[98:99], v[94:95], v[94:95]
	v_and_b32_e32 v97, 0xffff0000, v97
	v_pk_fma_f32 v[112:113], v[98:99], s[28:29], v[116:117] op_sel_hi:[1,0,0] neg_lo:[1,0,0] neg_hi:[1,0,0]
	v_pk_mul_f32 v[90:91], v[90:91], 0.5 op_sel_hi:[1,0]
	v_pk_fma_f32 v[112:113], v[98:99], v[112:113], s[34:35] op_sel_hi:[1,1,0]
	v_lshlrev_b32_e32 v92, 16, v93
	v_pk_fma_f32 v[112:113], v[98:99], v[112:113], s[36:37] op_sel_hi:[1,1,0]
	v_and_b32_e32 v93, 0xffff0000, v93
	v_pk_fma_f32 v[112:113], v[98:99], v[112:113], s[38:39] op_sel_hi:[1,1,0]
	v_add_u32_e32 v3, 16, v1
	v_pk_fma_f32 v[112:113], v[98:99], v[112:113], s[40:41] op_sel_hi:[1,1,0]
	s_nop 0
	v_pk_fma_f32 v[112:113], v[98:99], v[112:113], s[42:43] op_sel_hi:[1,1,0]
	s_nop 0
	v_pk_fma_f32 v[98:99], v[98:99], v[112:113], s[44:45] op_sel_hi:[1,1,0]
	s_nop 0
	v_pk_mul_f32 v[94:95], v[94:95], v[98:99]
	s_nop 0
	v_pk_fma_f32 v[90:91], v[90:91], v[94:95], v[90:91]
	v_pk_fma_f32 v[94:95], v[134:135], v[96:97], v[146:147]
	v_pk_mul_f32 v[84:85], v[84:85], v[90:91]
	v_lshlrev_b32_e32 v90, 16, v111
	v_and_b32_e32 v91, 0xffff0000, v111
	v_pk_fma_f32 v[92:93], v[138:139], v[92:93], v[94:95]
	s_nop 0
	v_pk_fma_f32 v[90:91], v[142:143], v[90:91], v[92:93]
	s_nop 0
	v_pk_mul_f32 v[92:93], v[90:91], s[26:27] op_sel_hi:[1,0]
	v_pk_mul_f32 v[90:91], v[90:91], 0.5 op_sel_hi:[1,0]
	v_med3_f32 v92, v92, s71, v224
	v_med3_f32 v93, v93, s71, v224
	v_pk_mul_f32 v[94:95], v[92:93], v[92:93]
	s_nop 0
	v_pk_fma_f32 v[96:97], v[94:95], s[28:29], v[116:117] op_sel_hi:[1,0,0] neg_lo:[1,0,0] neg_hi:[1,0,0]
	s_nop 0
	v_pk_fma_f32 v[96:97], v[94:95], v[96:97], s[34:35] op_sel_hi:[1,1,0]
	s_nop 0
	v_pk_fma_f32 v[96:97], v[94:95], v[96:97], s[36:37] op_sel_hi:[1,1,0]
	s_nop 0
	v_pk_fma_f32 v[96:97], v[94:95], v[96:97], s[38:39] op_sel_hi:[1,1,0]
	s_nop 0
	v_pk_fma_f32 v[96:97], v[94:95], v[96:97], s[40:41] op_sel_hi:[1,1,0]
	s_nop 0
	v_pk_fma_f32 v[96:97], v[94:95], v[96:97], s[42:43] op_sel_hi:[1,1,0]
	s_nop 0
	v_pk_fma_f32 v[94:95], v[94:95], v[96:97], s[44:45] op_sel_hi:[1,1,0]
	s_nop 0
	v_pk_mul_f32 v[92:93], v[92:93], v[94:95]
	v_lshlrev_b32_e32 v94, 16, v104
	v_pk_fma_f32 v[90:91], v[90:91], v[92:93], v[90:91]
	v_and_b32_e32 v95, 0xffff0000, v104
	v_pk_mul_f32 v[86:87], v[86:87], v[90:91]
	v_cvt_pk_bf16_f32 v90, v84, v85
	v_mov_b64_e32 v[84:85], s[0:1]
	v_mad_i64_i32 v[170:171], s[0:1], v3, s67, v[84:85]
	v_cvt_pk_bf16_f32 v91, v86, v87
	v_lshl_add_u64 v[86:87], v[170:171], 0, v[180:181]
	global_store_dwordx4 v[86:87], v[88:91], off
	v_mov_b32_dpp v3, v108 row_ror:1 row_mask:0xf bank_mask:0xf bound_ctrl:1
	v_mov_b32_dpp v93, v109 row_ror:2 row_mask:0xf bank_mask:0xf bound_ctrl:1
	v_mov_b32_dpp v91, v108 row_ror:2 row_mask:0xf bank_mask:0xf bound_ctrl:1
	v_mov_b32_dpp v3, v104 row_shr:1 row_mask:0xf bank_mask:0xf
	v_lshlrev_b32_e32 v86, 16, v3
	v_mov_b32_dpp v91, v104 row_shr:2 row_mask:0xf bank_mask:0xf
	v_lshlrev_b32_e32 v90, 16, v91
	v_and_b32_e32 v91, 0xffff0000, v91
	v_and_b32_e32 v87, 0xffff0000, v3
	v_pk_fma_f32 v[90:91], v[148:149], v[90:91], v[160:161]
	v_mov_b32_dpp v89, v109 row_ror:1 row_mask:0xf bank_mask:0xf bound_ctrl:1
	v_pk_fma_f32 v[86:87], v[152:153], v[86:87], v[90:91]
	v_mov_b32_dpp v93, v105 row_shr:2 row_mask:0xf bank_mask:0xf
	v_pk_fma_f32 v[86:87], v[156:157], v[94:95], v[86:87]
	v_mov_b32_dpp v89, v105 row_shr:1 row_mask:0xf bank_mask:0xf
	v_pk_mul_f32 v[90:91], v[86:87], s[26:27] op_sel_hi:[1,0]
	v_lshlrev_b32_e32 v92, 16, v93
	v_med3_f32 v90, v90, s71, v224
	v_med3_f32 v91, v91, s71, v224
	v_pk_mul_f32 v[94:95], v[90:91], v[90:91]
;     static __device__ __forceinline__ void unpk4(const u32x2 w, float (&o)[4]) { o[0] = bf_lo(w.x); o[1] = bf_hi(w.x); o[2] = bf_lo(w.y); o[3] = bf_hi(w.y); }
;     template <int N> static __device__ __forceinline__ u32x2 dpp_prev(const u32x2 pv, const u32x2 cur) { u32x2 r; r.x = dpp_prev1<N>(pv.x, cur.x); r.y = dpp_prev1<N>(pv.y, cur.y); return r; }
; __device__ __forceinline__ f32x2 gelu_pk(f32x2 v) {
;     f32x2 x = v * 0.70710678118f;
;     x.x = __builtin_amdgcn_fmed3f(x.x, -2.9f, 2.9f); x.y = __builtin_amdgcn_fmed3f(x.y, -2.9f, 2.9f);
;     const f32x2 t = x * x;
;     f32x2 p = t * (-4.953124630e-07f) + 1.987094038e-05f;
;     p = p * t + (-3.472001117e-04f); p = p * t + 3.517547622e-03f; p = p * t + (-2.333305031e-02f); p = p * t + 1.087993085e-01f; p = p * t + (-3.740358949e-01f); p = p * t + 1.128076553e+00f;
;     const f32x2 hv = v * 0.5f;
;     return hv * (x * p) + hv;
; }
;     __device__ __forceinline__ void operator()(const f32x4 (&acc)[2][2][4][2], const Unit& u, int wr, int wc, int fr, int fq) const {
;     ...
;                 for (int m = 0; m < 4; ++m) { const u32x4 cur = gq[m]; u32x4 hw;
; #pragma unroll
;                     for (int hv = 0; hv < 2; ++hv) { const u32x2 c2 = half2(cur, hv), p2 = half2(pv, hv);
;                         const u32x2 q1 = dpp_prev<1>(p2, c2), q2 = dpp_prev<2>(p2, c2);
;                         float g0[4], g1[4], g2[4]; unpk4(c2, g0); unpk4(q1, g1); unpk4(q2, g2);
;                         const u32x2 r = finish2(g0, g1, g2, w0[hv], w1[hv], w2[hv], bb[hv], acc[ai][bj][m][hv], rs8[ai][m]);
;                         if (hv == 0) { hw.x = r.x; hw.y = r.y; } else { hw.z = r.x; hw.w = r.y; } }
;                     *(u32x4*)(H + (size_t)(R0 + fr + 16 * m) * 2816 + col8) = hw;
;                     pv = cur; } }
	v_and_b32_e32 v93, 0xffff0000, v93
	v_pk_fma_f32 v[96:97], v[94:95], s[28:29], v[116:117] op_sel_hi:[1,0,0] neg_lo:[1,0,0] neg_hi:[1,0,0]
	v_pk_mul_f32 v[86:87], v[86:87], 0.5 op_sel_hi:[1,0]
	v_pk_fma_f32 v[96:97], v[94:95], v[96:97], s[34:35] op_sel_hi:[1,1,0]
	v_lshlrev_b32_e32 v88, 16, v89
	v_pk_fma_f32 v[96:97], v[94:95], v[96:97], s[36:37] op_sel_hi:[1,1,0]
	v_and_b32_e32 v89, 0xffff0000, v89
	v_pk_fma_f32 v[96:97], v[94:95], v[96:97], s[38:39] op_sel_hi:[1,1,0]
	v_mov_b32_dpp v3, v110 row_ror:1 row_mask:0xf bank_mask:0xf bound_ctrl:1
	v_pk_fma_f32 v[96:97], v[94:95], v[96:97], s[40:41] op_sel_hi:[1,1,0]
	s_nop 0
	v_pk_fma_f32 v[96:97], v[94:95], v[96:97], s[42:43] op_sel_hi:[1,1,0]
	v_mov_b32_dpp v3, v106 row_shr:1 row_mask:0xf bank_mask:0xf
	v_pk_fma_f32 v[94:95], v[94:95], v[96:97], s[44:45] op_sel_hi:[1,1,0]
	s_nop 0
	v_pk_mul_f32 v[90:91], v[90:91], v[94:95]
	s_nop 0
	v_pk_fma_f32 v[86:87], v[86:87], v[90:91], v[86:87]
	v_pk_fma_f32 v[90:91], v[150:151], v[92:93], v[162:163]
	v_pk_mul_f32 v[80:81], v[80:81], v[86:87]
	v_lshlrev_b32_e32 v86, 16, v105
	v_and_b32_e32 v87, 0xffff0000, v105
	v_pk_fma_f32 v[88:89], v[154:155], v[88:89], v[90:91]
	v_cvt_pk_bf16_f32 v80, v80, v81
	s_nop 0
	v_pk_fma_f32 v[86:87], v[158:159], v[86:87], v[88:89]
	s_nop 0
	v_pk_mul_f32 v[88:89], v[86:87], s[26:27] op_sel_hi:[1,0]
	v_pk_mul_f32 v[86:87], v[86:87], 0.5 op_sel_hi:[1,0]
	v_med3_f32 v88, v88, s71, v224
	v_med3_f32 v89, v89, s71, v224
	v_pk_mul_f32 v[90:91], v[88:89], v[88:89]
	s_nop 0
	v_pk_fma_f32 v[92:93], v[90:91], s[28:29], v[116:117] op_sel_hi:[1,0,0] neg_lo:[1,0,0] neg_hi:[1,0,0]
	s_nop 0
	v_pk_fma_f32 v[92:93], v[90:91], v[92:93], s[34:35] op_sel_hi:[1,1,0]
	s_nop 0
	v_pk_fma_f32 v[92:93], v[90:91], v[92:93], s[36:37] op_sel_hi:[1,1,0]
	s_nop 0
	v_pk_fma_f32 v[92:93], v[90:91], v[92:93], s[38:39] op_sel_hi:[1,1,0]
	s_nop 0
	v_pk_fma_f32 v[92:93], v[90:91], v[92:93], s[40:41] op_sel_hi:[1,1,0]
	s_nop 0
	v_pk_fma_f32 v[92:93], v[90:91], v[92:93], s[42:43] op_sel_hi:[1,1,0]
	s_nop 0
	v_pk_fma_f32 v[90:91], v[90:91], v[92:93], s[44:45] op_sel_hi:[1,1,0]
	v_lshlrev_b32_e32 v92, 16, v106
	v_pk_mul_f32 v[88:89], v[88:89], v[90:91]
	v_and_b32_e32 v93, 0xffff0000, v106
	v_pk_fma_f32 v[86:87], v[86:87], v[88:89], v[86:87]
	v_mov_b32_dpp v89, v110 row_ror:2 row_mask:0xf bank_mask:0xf bound_ctrl:1
	v_pk_mul_f32 v[82:83], v[82:83], v[86:87]
	v_mov_b32_dpp v91, v111 row_ror:2 row_mask:0xf bank_mask:0xf bound_ctrl:1
	v_mov_b32_dpp v89, v106 row_shr:2 row_mask:0xf bank_mask:0xf
	v_lshlrev_b32_e32 v88, 16, v89
	v_and_b32_e32 v89, 0xffff0000, v89
	v_cvt_pk_bf16_f32 v81, v82, v83
	v_lshlrev_b32_e32 v82, 16, v3
	v_and_b32_e32 v83, 0xffff0000, v3
	v_pk_fma_f32 v[88:89], v[132:133], v[88:89], v[144:145]
	v_mov_b32_dpp v87, v111 row_ror:1 row_mask:0xf bank_mask:0xf bound_ctrl:1
	v_pk_fma_f32 v[82:83], v[136:137], v[82:83], v[88:89]
	v_mov_b32_dpp v91, v107 row_shr:2 row_mask:0xf bank_mask:0xf
	v_pk_fma_f32 v[82:83], v[140:141], v[92:93], v[82:83]
	v_mov_b32_dpp v87, v107 row_shr:1 row_mask:0xf bank_mask:0xf
	v_pk_mul_f32 v[88:89], v[82:83], s[26:27] op_sel_hi:[1,0]
	v_lshlrev_b32_e32 v90, 16, v91
	v_med3_f32 v88, v88, s71, v224
	v_med3_f32 v89, v89, s71, v224
	v_pk_mul_f32 v[92:93], v[88:89], v[88:89]
	v_and_b32_e32 v91, 0xffff0000, v91
	v_pk_fma_f32 v[94:95], v[92:93], s[28:29], v[116:117] op_sel_hi:[1,0,0] neg_lo:[1,0,0] neg_hi:[1,0,0]
	v_pk_mul_f32 v[82:83], v[82:83], 0.5 op_sel_hi:[1,0]
	v_pk_fma_f32 v[94:95], v[92:93], v[94:95], s[34:35] op_sel_hi:[1,1,0]
	v_lshlrev_b32_e32 v86, 16, v87
	v_pk_fma_f32 v[94:95], v[92:93], v[94:95], s[36:37] op_sel_hi:[1,1,0]
	v_and_b32_e32 v87, 0xffff0000, v87
	v_pk_fma_f32 v[94:95], v[92:93], v[94:95], s[38:39] op_sel_hi:[1,1,0]
	v_add_u32_e32 v3, 32, v1
	v_pk_fma_f32 v[94:95], v[92:93], v[94:95], s[40:41] op_sel_hi:[1,1,0]
	v_mad_i64_i32 v[174:175], s[0:1], v3, s67, v[84:85]
	v_pk_fma_f32 v[94:95], v[92:93], v[94:95], s[42:43] op_sel_hi:[1,1,0]
	v_mov_b32_dpp v3, v104 row_ror:1 row_mask:0xf bank_mask:0xf bound_ctrl:1
	v_pk_fma_f32 v[92:93], v[92:93], v[94:95], s[44:45] op_sel_hi:[1,1,0]
	v_add_u32_e32 v1, 48, v1
	v_pk_mul_f32 v[88:89], v[88:89], v[92:93]
	v_mov_b32_dpp v3, v100 row_shr:1 row_mask:0xf bank_mask:0xf
	v_pk_fma_f32 v[82:83], v[82:83], v[88:89], v[82:83]
	v_pk_fma_f32 v[88:89], v[134:135], v[90:91], v[146:147]
	v_pk_mul_f32 v[76:77], v[76:77], v[82:83]
	v_lshlrev_b32_e32 v82, 16, v107
	v_and_b32_e32 v83, 0xffff0000, v107
	v_pk_fma_f32 v[86:87], v[138:139], v[86:87], v[88:89]
	s_nop 0
	v_pk_fma_f32 v[82:83], v[142:143], v[82:83], v[86:87]
	s_nop 0
	v_pk_mul_f32 v[86:87], v[82:83], s[26:27] op_sel_hi:[1,0]
	v_pk_mul_f32 v[82:83], v[82:83], 0.5 op_sel_hi:[1,0]
	v_med3_f32 v86, v86, s71, v224
	v_med3_f32 v87, v87, s71, v224
	v_pk_mul_f32 v[88:89], v[86:87], v[86:87]
	s_nop 0
	v_pk_fma_f32 v[90:91], v[88:89], s[28:29], v[116:117] op_sel_hi:[1,0,0] neg_lo:[1,0,0] neg_hi:[1,0,0]
	s_nop 0
	v_pk_fma_f32 v[90:91], v[88:89], v[90:91], s[34:35] op_sel_hi:[1,1,0]
	s_nop 0
	v_pk_fma_f32 v[90:91], v[88:89], v[90:91], s[36:37] op_sel_hi:[1,1,0]
	s_nop 0
	v_pk_fma_f32 v[90:91], v[88:89], v[90:91], s[38:39] op_sel_hi:[1,1,0]
	s_nop 0
	v_pk_fma_f32 v[90:91], v[88:89], v[90:91], s[40:41] op_sel_hi:[1,1,0]
	s_nop 0
	v_pk_fma_f32 v[90:91], v[88:89], v[90:91], s[42:43] op_sel_hi:[1,1,0]
	s_nop 0
	v_pk_fma_f32 v[88:89], v[88:89], v[90:91], s[44:45] op_sel_hi:[1,1,0]
	s_nop 0
	v_pk_mul_f32 v[86:87], v[86:87], v[88:89]
	s_nop 0
	v_pk_fma_f32 v[82:83], v[82:83], v[86:87], v[82:83]
	v_lshlrev_b32_e32 v86, 16, v100
	v_pk_mul_f32 v[78:79], v[78:79], v[82:83]
	v_cvt_pk_bf16_f32 v82, v76, v77
	v_lshl_add_u64 v[76:77], v[174:175], 0, v[180:181]
;     static __device__ __forceinline__ void unpk4(const u32x2 w, float (&o)[4]) { o[0] = bf_lo(w.x); o[1] = bf_hi(w.x); o[2] = bf_lo(w.y); o[3] = bf_hi(w.y); }
;     template <int N> static __device__ __forceinline__ u32x2 dpp_prev(const u32x2 pv, const u32x2 cur) { u32x2 r; r.x = dpp_prev1<N>(pv.x, cur.x); r.y = dpp_prev1<N>(pv.y, cur.y); return r; }
; __device__ __forceinline__ f32x2 gelu_pk(f32x2 v) {
;     f32x2 x = v * 0.70710678118f;
;     x.x = __builtin_amdgcn_fmed3f(x.x, -2.9f, 2.9f); x.y = __builtin_amdgcn_fmed3f(x.y, -2.9f, 2.9f);
;     const f32x2 t = x * x;
;     f32x2 p = t * (-4.953124630e-07f) + 1.987094038e-05f;
;     p = p * t + (-3.472001117e-04f); p = p * t + 3.517547622e-03f; p = p * t + (-2.333305031e-02f); p = p * t + 1.087993085e-01f; p = p * t + (-3.740358949e-01f); p = p * t + 1.128076553e+00f;
;     const f32x2 hv = v * 0.5f;
;     return hv * (x * p) + hv;
; }
;     __device__ __forceinline__ void operator()(const f32x4 (&acc)[2][2][4][2], const Unit& u, int wr, int wc, int fr, int fq) const {
;     ...
;                 for (int m = 0; m < 4; ++m) { const u32x4 cur = gq[m]; u32x4 hw;
; #pragma unroll
;                     for (int hv = 0; hv < 2; ++hv) { const u32x2 c2 = half2(cur, hv), p2 = half2(pv, hv);
;                         const u32x2 q1 = dpp_prev<1>(p2, c2), q2 = dpp_prev<2>(p2, c2);
;                         float g0[4], g1[4], g2[4]; unpk4(c2, g0); unpk4(q1, g1); unpk4(q2, g2);
;                         const u32x2 r = finish2(g0, g1, g2, w0[hv], w1[hv], w2[hv], bb[hv], acc[ai][bj][m][hv], rs8[ai][m]);
;                         if (hv == 0) { hw.x = r.x; hw.y = r.y; } else { hw.z = r.x; hw.w = r.y; } }
;                     *(u32x4*)(H + (size_t)(R0 + fr + 16 * m) * 2816 + col8) = hw;
;                     pv = cur; } }
	v_cvt_pk_bf16_f32 v83, v78, v79
	global_store_dwordx4 v[76:77], v[80:83], off
	v_lshlrev_b32_e32 v76, 16, v3
	v_and_b32_e32 v77, 0xffff0000, v3
	v_mov_b32_dpp v81, v104 row_ror:2 row_mask:0xf bank_mask:0xf bound_ctrl:1
	v_and_b32_e32 v87, 0xffff0000, v100
	v_mov_b32_dpp v83, v105 row_ror:2 row_mask:0xf bank_mask:0xf bound_ctrl:1
	v_mov_b32_dpp v81, v100 row_shr:2 row_mask:0xf bank_mask:0xf
	v_lshlrev_b32_e32 v80, 16, v81
	v_and_b32_e32 v81, 0xffff0000, v81
	v_pk_fma_f32 v[80:81], v[148:149], v[80:81], v[160:161]
	v_mov_b32_dpp v79, v105 row_ror:1 row_mask:0xf bank_mask:0xf bound_ctrl:1
	v_pk_fma_f32 v[76:77], v[152:153], v[76:77], v[80:81]
	v_mov_b32_dpp v83, v101 row_shr:2 row_mask:0xf bank_mask:0xf
	v_pk_fma_f32 v[76:77], v[156:157], v[86:87], v[76:77]
	v_mov_b32_dpp v79, v101 row_shr:1 row_mask:0xf bank_mask:0xf
	v_pk_mul_f32 v[80:81], v[76:77], s[26:27] op_sel_hi:[1,0]
	v_lshlrev_b32_e32 v82, 16, v83
	v_med3_f32 v80, v80, s71, v224
	v_med3_f32 v81, v81, s71, v224
	v_pk_mul_f32 v[86:87], v[80:81], v[80:81]
	v_and_b32_e32 v83, 0xffff0000, v83
	v_pk_fma_f32 v[88:89], v[86:87], s[28:29], v[116:117] op_sel_hi:[1,0,0] neg_lo:[1,0,0] neg_hi:[1,0,0]
	v_pk_mul_f32 v[76:77], v[76:77], 0.5 op_sel_hi:[1,0]
	v_pk_fma_f32 v[88:89], v[86:87], v[88:89], s[34:35] op_sel_hi:[1,1,0]
	v_lshlrev_b32_e32 v78, 16, v79
	v_pk_fma_f32 v[88:89], v[86:87], v[88:89], s[36:37] op_sel_hi:[1,1,0]
	v_and_b32_e32 v79, 0xffff0000, v79
	v_pk_fma_f32 v[88:89], v[86:87], v[88:89], s[38:39] op_sel_hi:[1,1,0]
	v_mov_b32_dpp v3, v106 row_ror:1 row_mask:0xf bank_mask:0xf bound_ctrl:1
	v_pk_fma_f32 v[88:89], v[86:87], v[88:89], s[40:41] op_sel_hi:[1,1,0]
	s_nop 0
	v_pk_fma_f32 v[88:89], v[86:87], v[88:89], s[42:43] op_sel_hi:[1,1,0]
	v_mov_b32_dpp v3, v102 row_shr:1 row_mask:0xf bank_mask:0xf
	v_pk_fma_f32 v[86:87], v[86:87], v[88:89], s[44:45] op_sel_hi:[1,1,0]
	s_nop 0
	v_pk_mul_f32 v[80:81], v[80:81], v[86:87]
	s_nop 0
	v_pk_fma_f32 v[76:77], v[76:77], v[80:81], v[76:77]
	v_pk_fma_f32 v[80:81], v[150:151], v[82:83], v[162:163]
	v_pk_mul_f32 v[72:73], v[72:73], v[76:77]
	v_lshlrev_b32_e32 v76, 16, v101
	v_and_b32_e32 v77, 0xffff0000, v101
	v_pk_fma_f32 v[78:79], v[154:155], v[78:79], v[80:81]
	v_cvt_pk_bf16_f32 v72, v72, v73
	s_nop 0
	v_pk_fma_f32 v[76:77], v[158:159], v[76:77], v[78:79]
	s_nop 0
	v_pk_mul_f32 v[78:79], v[76:77], s[26:27] op_sel_hi:[1,0]
	v_pk_mul_f32 v[76:77], v[76:77], 0.5 op_sel_hi:[1,0]
	v_med3_f32 v78, v78, s71, v224
	v_med3_f32 v79, v79, s71, v224
	v_pk_mul_f32 v[80:81], v[78:79], v[78:79]
	s_nop 0
	v_pk_fma_f32 v[82:83], v[80:81], s[28:29], v[116:117] op_sel_hi:[1,0,0] neg_lo:[1,0,0] neg_hi:[1,0,0]
	s_nop 0
	v_pk_fma_f32 v[82:83], v[80:81], v[82:83], s[34:35] op_sel_hi:[1,1,0]
	s_nop 0
	v_pk_fma_f32 v[82:83], v[80:81], v[82:83], s[36:37] op_sel_hi:[1,1,0]
	s_nop 0
	v_pk_fma_f32 v[82:83], v[80:81], v[82:83], s[38:39] op_sel_hi:[1,1,0]
	s_nop 0
	v_pk_fma_f32 v[82:83], v[80:81], v[82:83], s[40:41] op_sel_hi:[1,1,0]
	s_nop 0
	v_pk_fma_f32 v[82:83], v[80:81], v[82:83], s[42:43] op_sel_hi:[1,1,0]
	s_nop 0
	v_pk_fma_f32 v[80:81], v[80:81], v[82:83], s[44:45] op_sel_hi:[1,1,0]
	v_lshlrev_b32_e32 v82, 16, v102
	v_pk_mul_f32 v[78:79], v[78:79], v[80:81]
	v_and_b32_e32 v83, 0xffff0000, v102
	v_pk_fma_f32 v[76:77], v[76:77], v[78:79], v[76:77]
	v_mov_b32_dpp v79, v106 row_ror:2 row_mask:0xf bank_mask:0xf bound_ctrl:1
	v_pk_mul_f32 v[74:75], v[74:75], v[76:77]
	v_mov_b32_dpp v81, v107 row_ror:2 row_mask:0xf bank_mask:0xf bound_ctrl:1
	v_mov_b32_dpp v79, v102 row_shr:2 row_mask:0xf bank_mask:0xf
	v_lshlrev_b32_e32 v78, 16, v79
	v_and_b32_e32 v79, 0xffff0000, v79
	v_cvt_pk_bf16_f32 v73, v74, v75
	v_lshlrev_b32_e32 v74, 16, v3
	v_and_b32_e32 v75, 0xffff0000, v3
	v_pk_fma_f32 v[78:79], v[132:133], v[78:79], v[144:145]
	v_mov_b32_dpp v77, v107 row_ror:1 row_mask:0xf bank_mask:0xf bound_ctrl:1
	v_pk_fma_f32 v[74:75], v[136:137], v[74:75], v[78:79]
	v_mov_b32_dpp v81, v103 row_shr:2 row_mask:0xf bank_mask:0xf
	v_pk_fma_f32 v[74:75], v[140:141], v[82:83], v[74:75]
	v_mov_b32_dpp v77, v103 row_shr:1 row_mask:0xf bank_mask:0xf
	v_pk_mul_f32 v[78:79], v[74:75], s[26:27] op_sel_hi:[1,0]
	v_lshlrev_b32_e32 v80, 16, v81
	v_med3_f32 v78, v78, s71, v224
	v_med3_f32 v79, v79, s71, v224
	v_pk_mul_f32 v[82:83], v[78:79], v[78:79]
	v_and_b32_e32 v81, 0xffff0000, v81
	v_pk_fma_f32 v[86:87], v[82:83], s[28:29], v[116:117] op_sel_hi:[1,0,0] neg_lo:[1,0,0] neg_hi:[1,0,0]
	v_pk_mul_f32 v[74:75], v[74:75], 0.5 op_sel_hi:[1,0]
	v_pk_fma_f32 v[86:87], v[82:83], v[86:87], s[34:35] op_sel_hi:[1,1,0]
	v_lshlrev_b32_e32 v76, 16, v77
	v_pk_fma_f32 v[86:87], v[82:83], v[86:87], s[36:37] op_sel_hi:[1,1,0]
	v_and_b32_e32 v77, 0xffff0000, v77
	v_pk_fma_f32 v[86:87], v[82:83], v[86:87], s[38:39] op_sel_hi:[1,1,0]
	v_mad_i64_i32 v[132:133], s[0:1], v1, s67, v[84:85]
	v_pk_fma_f32 v[86:87], v[82:83], v[86:87], s[40:41] op_sel_hi:[1,1,0]
	s_nop 0
	v_pk_fma_f32 v[86:87], v[82:83], v[86:87], s[42:43] op_sel_hi:[1,1,0]
	s_nop 0
	v_pk_fma_f32 v[82:83], v[82:83], v[86:87], s[44:45] op_sel_hi:[1,1,0]
	s_nop 0
	v_pk_mul_f32 v[78:79], v[78:79], v[82:83]
	s_nop 0
	v_pk_fma_f32 v[74:75], v[74:75], v[78:79], v[74:75]
	v_pk_fma_f32 v[78:79], v[134:135], v[80:81], v[146:147]
	v_pk_mul_f32 v[64:65], v[64:65], v[74:75]
	v_lshlrev_b32_e32 v74, 16, v103
	v_and_b32_e32 v75, 0xffff0000, v103
	v_pk_fma_f32 v[76:77], v[138:139], v[76:77], v[78:79]
	v_add_u32_e32 v134, 0x80, v212
	v_pk_fma_f32 v[74:75], v[142:143], v[74:75], v[76:77]
	v_ashrrev_i32_e32 v135, 31, v134
	v_pk_mul_f32 v[76:77], v[74:75], s[26:27] op_sel_hi:[1,0]
	v_pk_mul_f32 v[74:75], v[74:75], 0.5 op_sel_hi:[1,0]
	v_med3_f32 v76, v76, s71, v224
;     __device__ __forceinline__ void operator()(const f32x4 (&acc)[2][2][4][2], const Unit& u, int wr, int wc, int fr, int fq) const {
;     ...
;           for (int bj = 0; bj < 2; ++bj) {
;             const int col8 = u.pn * BM + bj * HALF + wc * 32 + 8 * fq;
;             float w0[2][4], w1[2][4], w2[2][4], bb[2][4];
; #pragma unroll
;             for (int hv = 0; hv < 2; ++hv) { ld4f(cw + col8 + 4 * hv, w0[hv]); ld4f(cw + 2816 + col8 + 4 * hv, w1[hv]); ld4f(cw + 2 * 2816 + col8 + 4 * hv, w2[hv]); ld4f(cb + col8 + 4 * hv, bb[hv]); }
; #pragma unroll
;             for (int ai = 0; ai < 2; ++ai) { const int R0 = u.rb + ai * HALF + wr * 64; const bf16_t* gp = G + (size_t)(R0 + fr) * 2816 + col8;
;                 u32x4 gq[4], prv = (u32x4){0u, 0u, 0u, 0u};
; #pragma unroll
;                 for (int m = 0; m < 4; ++m) gq[m] = *(const u32x4*)(gp + (size_t)m * 16 * 2816);
;                 if ((R0 & 8191) != 0) prv = *(const u32x4*)(gp - (size_t)16 * 2816);
;                 u32x4 pv = prv;
	v_med3_f32 v77, v77, s71, v224
	v_pk_mul_f32 v[78:79], v[76:77], v[76:77]
	v_lshl_add_u64 v[136:137], v[134:135], 1, v[214:215]
	v_pk_fma_f32 v[80:81], v[78:79], s[28:29], v[116:117] op_sel_hi:[1,0,0] neg_lo:[1,0,0] neg_hi:[1,0,0]
	v_add_co_u32_e32 v100, vcc, s45, v136
	v_pk_fma_f32 v[80:81], v[78:79], v[80:81], s[34:35] op_sel_hi:[1,1,0]
	s_nop 0
	v_addc_co_u32_e32 v101, vcc, 0, v137, vcc
	v_pk_fma_f32 v[80:81], v[78:79], v[80:81], s[36:37] op_sel_hi:[1,1,0]
	v_add_co_u32_e32 v102, vcc, 0x2c000, v136
	v_pk_fma_f32 v[80:81], v[78:79], v[80:81], s[38:39] op_sel_hi:[1,1,0]
	s_nop 0
	v_addc_co_u32_e32 v103, vcc, 0, v137, vcc
	v_pk_fma_f32 v[80:81], v[78:79], v[80:81], s[40:41] op_sel_hi:[1,1,0]
	s_nop 0
	v_pk_fma_f32 v[80:81], v[78:79], v[80:81], s[42:43] op_sel_hi:[1,1,0]
	s_nop 0
	v_pk_fma_f32 v[78:79], v[78:79], v[80:81], s[44:45] op_sel_hi:[1,1,0]
	s_nop 0
	v_pk_mul_f32 v[76:77], v[76:77], v[78:79]
	s_nop 0
	v_pk_fma_f32 v[74:75], v[74:75], v[76:77], v[74:75]
	s_nop 0
	v_pk_mul_f32 v[66:67], v[66:67], v[74:75]
	v_cvt_pk_bf16_f32 v74, v64, v65
	v_lshl_add_u64 v[64:65], v[132:133], 0, v[180:181]
	v_cvt_pk_bf16_f32 v75, v66, v67
	global_store_dwordx4 v[64:65], v[72:75], off
	v_lshlrev_b64 v[64:65], 2, v[134:135]
	v_lshl_add_u64 v[76:77], s[18:19], 0, v[64:65]
	v_lshl_add_u64 v[72:73], s[12:13], 0, v[64:65]
	v_lshl_add_u64 v[80:81], s[20:21], 0, v[64:65]
	v_lshl_add_u64 v[96:97], s[14:15], 0, v[64:65]
	v_and_b32_e32 v241, 63, v216
	v_lshrrev_b32_e32 v242, 4, v241
	v_and_b32_e32 v243, 15, v241
	v_cmp_eq_u32_e64 s[98:99], 1, v242
	v_lshlrev_b32_e32 v246, 3, v243
	v_lshlrev_b32_e32 v247, 5, v242
	v_cndmask_b32_e64 v244, v72, v76, s[98:99]
	v_cndmask_b32_e64 v245, v73, v77, s[98:99]
	v_cmp_eq_u32_e64 s[98:99], 2, v242
	v_sub_u32_e32 v246, v246, v247
	v_ashrrev_i32_e32 v247, 31, v246
	v_cndmask_b32_e64 v244, v244, v80, s[98:99]
	v_cndmask_b32_e64 v245, v245, v81, s[98:99]
	v_cmp_eq_u32_e64 s[98:99], 3, v242
	s_nop 1
	v_cndmask_b32_e64 v244, v244, v96, s[98:99]
	v_cndmask_b32_e64 v245, v245, v97, s[98:99]
	v_lshl_add_u64 v[244:245], v[244:245], 0, v[246:247]
	global_load_dwordx2 v[250:251], v[244:245], off
	s_nop 0
	s_nop 0
	s_nop 0
	s_nop 0
	s_nop 0
	global_load_dwordx4 v[114:117], v[136:137], off
	global_load_dwordx4 v[110:113], v[100:101], off
	global_load_dwordx4 v[106:109], v[102:103], off
	v_add_co_u32_e32 v100, vcc, 0x42000, v136
	s_nop 1
	v_addc_co_u32_e32 v101, vcc, 0, v137, vcc
	global_load_dwordx4 v[102:105], v[100:101], off
	v_mov_b32_e32 v100, 0
	s_andn2_b64 vcc, exec, s[2:3]
	s_cbranch_vccnz .LBB0_3150
	v_add_co_u32_e32 v118, vcc, 0xfffea000, v136
	s_nop 1
	v_addc_co_u32_e32 v119, vcc, -1, v137, vcc
	global_load_dwordx4 v[118:121], v[118:119], off
.LBB0_3150:
	s_waitcnt vmcnt(0)
	v_lshrrev_b32_e32 v252, 6, v216
	v_lshlrev_b32_e32 v252, 10, v252
	v_add_u32_e32 v252, 0x20200, v252
	v_lshl_add_u32 v253, v241, 3, v252
	v_lshl_add_u32 v254, v242, 5, v252
	ds_write_b64 v253, v[250:251]
	s_waitcnt lgkmcnt(0)
	ds_read_b128 v[64:67], v254 offset:16
	ds_read_b128 v[84:87], v254
	ds_read_b128 v[72:75], v254 offset:144
	ds_read_b128 v[88:91], v254 offset:128
	ds_read_b128 v[76:79], v254 offset:272
	ds_read_b128 v[92:95], v254 offset:256
	ds_read_b128 v[80:83], v254 offset:400
	ds_read_b128 v[96:99], v254 offset:384
	s_waitcnt lgkmcnt(0)
	s_nop 0
	s_nop 0
	s_nop 0
	s_nop 0
	s_nop 0
	s_nop 0
	s_nop 0
	v_mov_b32_dpp v123, v118 row_ror:2 row_mask:0xf bank_mask:0xf bound_ctrl:1
	v_mov_b32_dpp v1, v118 row_ror:1 row_mask:0xf bank_mask:0xf bound_ctrl:1
	v_mov_b32_dpp v101, v119 row_ror:1 row_mask:0xf bank_mask:0xf bound_ctrl:1
	v_mov_b32_dpp v123, v114 row_shr:2 row_mask:0xf bank_mask:0xf
	v_mov_b32_dpp v1, v114 row_shr:1 row_mask:0xf bank_mask:0xf
	v_lshlrev_b32_e32 v138, 16, v123
	v_and_b32_e32 v139, 0xffff0000, v123
	v_mov_b32_dpp v125, v119 row_ror:2 row_mask:0xf bank_mask:0xf bound_ctrl:1
	v_lshlrev_b32_e32 v118, 16, v1
	v_and_b32_e32 v119, 0xffff0000, v1
	v_pk_fma_f32 v[138:139], v[84:85], v[138:139], v[96:97]
	v_lshlrev_b32_e32 v142, 16, v114
	v_and_b32_e32 v143, 0xffff0000, v114
	v_pk_fma_f32 v[118:119], v[88:89], v[118:119], v[138:139]
	v_mov_b32_dpp v125, v115 row_shr:2 row_mask:0xf bank_mask:0xf
	v_pk_fma_f32 v[138:139], v[92:93], v[142:143], v[118:119]
	v_mov_b32_e32 v189, v188
	v_pk_mul_f32 v[118:119], v[138:139], s[26:27] op_sel_hi:[1,0]
	v_mov_b32_dpp v101, v115 row_shr:1 row_mask:0xf bank_mask:0xf
	v_med3_f32 v142, v118, s71, v224
	v_med3_f32 v143, v119, s71, v224
	v_pk_mul_f32 v[144:145], v[142:143], v[142:143]
	v_mov_b64_e32 v[118:119], s[30:31]
	v_pk_fma_f32 v[146:147], v[144:145], s[28:29], v[118:119] op_sel_hi:[1,0,0] neg_lo:[1,0,0] neg_hi:[1,0,0]
	v_lshlrev_b32_e32 v140, 16, v125
	v_pk_fma_f32 v[146:147], v[144:145], v[146:147], s[34:35] op_sel_hi:[1,1,0]
	v_and_b32_e32 v141, 0xffff0000, v125
	v_pk_fma_f32 v[146:147], v[144:145], v[146:147], s[36:37] op_sel_hi:[1,1,0]
	v_pk_mul_f32 v[138:139], v[138:139], 0.5 op_sel_hi:[1,0]
	v_pk_fma_f32 v[146:147], v[144:145], v[146:147], s[38:39] op_sel_hi:[1,1,0]
	v_lshlrev_b32_e32 v136, 16, v101
	v_pk_fma_f32 v[146:147], v[144:145], v[146:147], s[40:41] op_sel_hi:[1,1,0]
	v_and_b32_e32 v137, 0xffff0000, v101
	v_pk_fma_f32 v[146:147], v[144:145], v[146:147], s[42:43] op_sel_hi:[1,1,0]
	v_pk_mul_f32 v[68:69], v[68:69], v[188:189]
	v_pk_fma_f32 v[144:145], v[144:145], v[146:147], s[44:45] op_sel_hi:[1,1,0]
	v_pk_fma_f32 v[140:141], v[86:87], v[140:141], v[98:99]
	v_pk_mul_f32 v[142:143], v[142:143], v[144:145]
	v_pk_fma_f32 v[136:137], v[90:91], v[136:137], v[140:141]
	v_pk_fma_f32 v[138:139], v[138:139], v[142:143], v[138:139]
	v_mov_b32_dpp v123, v120 row_ror:2 row_mask:0xf bank_mask:0xf bound_ctrl:1
;     static __device__ __forceinline__ void unpk4(const u32x2 w, float (&o)[4]) { o[0] = bf_lo(w.x); o[1] = bf_hi(w.x); o[2] = bf_lo(w.y); o[3] = bf_hi(w.y); }
;     template <int N> static __device__ __forceinline__ u32x2 dpp_prev(const u32x2 pv, const u32x2 cur) { u32x2 r; r.x = dpp_prev1<N>(pv.x, cur.x); r.y = dpp_prev1<N>(pv.y, cur.y); return r; }
; __device__ __forceinline__ f32x2 gelu_pk(f32x2 v) {
;     f32x2 x = v * 0.70710678118f;
;     x.x = __builtin_amdgcn_fmed3f(x.x, -2.9f, 2.9f); x.y = __builtin_amdgcn_fmed3f(x.y, -2.9f, 2.9f);
;     const f32x2 t = x * x;
;     f32x2 p = t * (-4.953124630e-07f) + 1.987094038e-05f;
;     p = p * t + (-3.472001117e-04f); p = p * t + 3.517547622e-03f; p = p * t + (-2.333305031e-02f); p = p * t + 1.087993085e-01f; p = p * t + (-3.740358949e-01f); p = p * t + 1.128076553e+00f;
;     const f32x2 hv = v * 0.5f;
;     return hv * (x * p) + hv;
; }
;     __device__ __forceinline__ void operator()(const f32x4 (&acc)[2][2][4][2], const Unit& u, int wr, int wc, int fr, int fq) const {
;     ...
;                 for (int m = 0; m < 4; ++m) { const u32x4 cur = gq[m]; u32x4 hw;
; #pragma unroll
;                     for (int hv = 0; hv < 2; ++hv) { const u32x2 c2 = half2(cur, hv), p2 = half2(pv, hv);
;                         const u32x2 q1 = dpp_prev<1>(p2, c2), q2 = dpp_prev<2>(p2, c2);
;                         float g0[4], g1[4], g2[4]; unpk4(c2, g0); unpk4(q1, g1); unpk4(q2, g2);
;                         const u32x2 r = finish2(g0, g1, g2, w0[hv], w1[hv], w2[hv], bb[hv], acc[ai][bj][m][hv], rs8[ai][m]);
;                         if (hv == 0) { hw.x = r.x; hw.y = r.y; } else { hw.z = r.x; hw.w = r.y; } }
;                     *(u32x4*)(H + (size_t)(R0 + fr + 16 * m) * 2816 + col8) = hw;
;                     pv = cur; } }
	v_pk_mul_f32 v[68:69], v[68:69], v[138:139]
	v_lshlrev_b32_e32 v138, 16, v115
	v_and_b32_e32 v139, 0xffff0000, v115
	v_pk_fma_f32 v[136:137], v[94:95], v[138:139], v[136:137]
	v_pk_mul_f32 v[70:71], v[70:71], v[188:189]
	v_pk_mul_f32 v[138:139], v[136:137], s[26:27] op_sel_hi:[1,0]
	v_pk_mul_f32 v[136:137], v[136:137], 0.5 op_sel_hi:[1,0]
	v_med3_f32 v138, v138, s71, v224
	v_med3_f32 v139, v139, s71, v224
	v_pk_mul_f32 v[140:141], v[138:139], v[138:139]
	v_mov_b32_dpp v1, v120 row_ror:1 row_mask:0xf bank_mask:0xf bound_ctrl:1
	v_pk_fma_f32 v[142:143], v[140:141], s[28:29], v[118:119] op_sel_hi:[1,0,0] neg_lo:[1,0,0] neg_hi:[1,0,0]
	v_mov_b32_dpp v123, v116 row_shr:2 row_mask:0xf bank_mask:0xf
	v_pk_fma_f32 v[142:143], v[140:141], v[142:143], s[34:35] op_sel_hi:[1,1,0]
	v_mov_b32_dpp v1, v116 row_shr:1 row_mask:0xf bank_mask:0xf
	v_pk_fma_f32 v[142:143], v[140:141], v[142:143], s[36:37] op_sel_hi:[1,1,0]
	v_cvt_pk_bf16_f32 v68, v68, v69
	v_mov_b32_dpp v125, v121 row_ror:2 row_mask:0xf bank_mask:0xf bound_ctrl:1
	v_pk_fma_f32 v[142:143], v[140:141], v[142:143], s[38:39] op_sel_hi:[1,1,0]
	v_mov_b32_dpp v101, v121 row_ror:1 row_mask:0xf bank_mask:0xf bound_ctrl:1
	v_pk_fma_f32 v[142:143], v[140:141], v[142:143], s[40:41] op_sel_hi:[1,1,0]
	v_mov_b32_dpp v125, v117 row_shr:2 row_mask:0xf bank_mask:0xf
	v_pk_fma_f32 v[142:143], v[140:141], v[142:143], s[42:43] op_sel_hi:[1,1,0]
	v_mov_b32_dpp v101, v117 row_shr:1 row_mask:0xf bank_mask:0xf
	v_pk_fma_f32 v[140:141], v[140:141], v[142:143], s[44:45] op_sel_hi:[1,1,0]
	v_lshlrev_b32_e32 v120, 16, v101
	v_pk_mul_f32 v[138:139], v[138:139], v[140:141]
	v_lshlrev_b32_e32 v140, 16, v116
	v_pk_fma_f32 v[136:137], v[136:137], v[138:139], v[136:137]
	v_and_b32_e32 v141, 0xffff0000, v116
	v_pk_mul_f32 v[70:71], v[70:71], v[136:137]
	v_lshlrev_b32_e32 v136, 16, v123
	v_and_b32_e32 v137, 0xffff0000, v123
	v_cvt_pk_bf16_f32 v69, v70, v71
	v_lshlrev_b32_e32 v70, 16, v1
	v_and_b32_e32 v71, 0xffff0000, v1
	v_pk_fma_f32 v[136:137], v[64:65], v[136:137], v[80:81]
	v_lshlrev_b32_e32 v138, 16, v125
	v_pk_fma_f32 v[70:71], v[72:73], v[70:71], v[136:137]
	v_and_b32_e32 v139, 0xffff0000, v125
	v_pk_fma_f32 v[70:71], v[76:77], v[140:141], v[70:71]
	v_and_b32_e32 v121, 0xffff0000, v101
	v_pk_mul_f32 v[136:137], v[70:71], s[26:27] op_sel_hi:[1,0]
	v_pk_mul_f32 v[70:71], v[70:71], 0.5 op_sel_hi:[1,0]
	v_med3_f32 v136, v136, s71, v224
	v_med3_f32 v137, v137, s71, v224
	v_pk_mul_f32 v[140:141], v[136:137], v[136:137]
	v_pk_mul_f32 v[60:61], v[60:61], v[188:189]
	v_pk_fma_f32 v[142:143], v[140:141], s[28:29], v[118:119] op_sel_hi:[1,0,0] neg_lo:[1,0,0] neg_hi:[1,0,0]
	v_pk_mul_f32 v[62:63], v[62:63], v[188:189]
	v_pk_fma_f32 v[142:143], v[140:141], v[142:143], s[34:35] op_sel_hi:[1,1,0]
	v_mov_b32_dpp v1, v114 row_ror:1 row_mask:0xf bank_mask:0xf bound_ctrl:1
	v_pk_fma_f32 v[142:143], v[140:141], v[142:143], s[36:37] op_sel_hi:[1,1,0]
	v_mov_b32_dpp v101, v115 row_ror:2 row_mask:0xf bank_mask:0xf bound_ctrl:1
	v_pk_fma_f32 v[142:143], v[140:141], v[142:143], s[38:39] op_sel_hi:[1,1,0]
	v_mov_b32_dpp v1, v110 row_shr:1 row_mask:0xf bank_mask:0xf
	v_pk_fma_f32 v[142:143], v[140:141], v[142:143], s[40:41] op_sel_hi:[1,1,0]
	v_mov_b32_dpp v101, v111 row_shr:2 row_mask:0xf bank_mask:0xf
	v_pk_fma_f32 v[142:143], v[140:141], v[142:143], s[42:43] op_sel_hi:[1,1,0]
	v_mov_b32_e32 v187, v186
	v_pk_fma_f32 v[140:141], v[140:141], v[142:143], s[44:45] op_sel_hi:[1,1,0]
	v_pk_mul_f32 v[56:57], v[56:57], v[186:187]
	v_pk_mul_f32 v[136:137], v[136:137], v[140:141]
	v_pk_mul_f32 v[58:59], v[58:59], v[186:187]
	v_pk_fma_f32 v[70:71], v[70:71], v[136:137], v[70:71]
	v_pk_fma_f32 v[136:137], v[66:67], v[138:139], v[82:83]
	v_pk_mul_f32 v[60:61], v[60:61], v[70:71]
	v_lshlrev_b32_e32 v70, 16, v117
	v_and_b32_e32 v71, 0xffff0000, v117
	v_pk_fma_f32 v[120:121], v[74:75], v[120:121], v[136:137]
	v_pk_mul_f32 v[52:53], v[52:53], v[186:187]
	v_pk_fma_f32 v[70:71], v[78:79], v[70:71], v[120:121]
	v_pk_mul_f32 v[54:55], v[54:55], v[186:187]
	v_pk_mul_f32 v[120:121], v[70:71], s[26:27] op_sel_hi:[1,0]
	v_pk_mul_f32 v[70:71], v[70:71], 0.5 op_sel_hi:[1,0]
	v_med3_f32 v120, v120, s71, v224
	v_med3_f32 v121, v121, s71, v224
	v_pk_mul_f32 v[136:137], v[120:121], v[120:121]
	v_mov_b32_e32 v185, v184
	v_pk_fma_f32 v[138:139], v[136:137], s[28:29], v[118:119] op_sel_hi:[1,0,0] neg_lo:[1,0,0] neg_hi:[1,0,0]
	v_pk_mul_f32 v[48:49], v[48:49], v[184:185]
	v_pk_fma_f32 v[138:139], v[136:137], v[138:139], s[34:35] op_sel_hi:[1,1,0]
	v_pk_mul_f32 v[50:51], v[50:51], v[184:185]
	v_pk_fma_f32 v[138:139], v[136:137], v[138:139], s[36:37] op_sel_hi:[1,1,0]
	v_pk_mul_f32 v[44:45], v[44:45], v[184:185]
	v_pk_fma_f32 v[138:139], v[136:137], v[138:139], s[38:39] op_sel_hi:[1,1,0]
	v_pk_mul_f32 v[46:47], v[46:47], v[184:185]
	v_pk_fma_f32 v[138:139], v[136:137], v[138:139], s[40:41] op_sel_hi:[1,1,0]
	v_mov_b32_e32 v3, v2
	v_pk_fma_f32 v[138:139], v[136:137], v[138:139], s[42:43] op_sel_hi:[1,1,0]
	v_pk_mul_f32 v[40:41], v[40:41], v[2:3]
	v_pk_fma_f32 v[136:137], v[136:137], v[138:139], s[44:45] op_sel_hi:[1,1,0]
	v_pk_mul_f32 v[42:43], v[42:43], v[2:3]
	v_pk_mul_f32 v[120:121], v[120:121], v[136:137]
	v_pk_mul_f32 v[36:37], v[36:37], v[2:3]
	v_pk_fma_f32 v[70:71], v[70:71], v[120:121], v[70:71]
	v_lshlrev_b32_e32 v120, 16, v110
	v_pk_mul_f32 v[62:63], v[62:63], v[70:71]
	v_cvt_pk_bf16_f32 v70, v60, v61
	v_lshlrev_b64 v[60:61], 1, v[134:135]
	v_cvt_pk_bf16_f32 v71, v62, v63
	v_lshl_add_u64 v[62:63], v[130:131], 0, v[60:61]
	global_store_dwordx4 v[62:63], v[68:71], off
	v_lshlrev_b32_e32 v62, 16, v1
	v_and_b32_e32 v63, 0xffff0000, v1
;     static __device__ __forceinline__ void unpk4(const u32x2 w, float (&o)[4]) { o[0] = bf_lo(w.x); o[1] = bf_hi(w.x); o[2] = bf_lo(w.y); o[3] = bf_hi(w.y); }
;     template <int N> static __device__ __forceinline__ u32x2 dpp_prev(const u32x2 pv, const u32x2 cur) { u32x2 r; r.x = dpp_prev1<N>(pv.x, cur.x); r.y = dpp_prev1<N>(pv.y, cur.y); return r; }
; __device__ __forceinline__ f32x2 gelu_pk(f32x2 v) {
;     f32x2 x = v * 0.70710678118f;
;     x.x = __builtin_amdgcn_fmed3f(x.x, -2.9f, 2.9f); x.y = __builtin_amdgcn_fmed3f(x.y, -2.9f, 2.9f);
;     const f32x2 t = x * x;
;     f32x2 p = t * (-4.953124630e-07f) + 1.987094038e-05f;
;     p = p * t + (-3.472001117e-04f); p = p * t + 3.517547622e-03f; p = p * t + (-2.333305031e-02f); p = p * t + 1.087993085e-01f; p = p * t + (-3.740358949e-01f); p = p * t + 1.128076553e+00f;
;     const f32x2 hv = v * 0.5f;
;     return hv * (x * p) + hv;
; }
;     __device__ __forceinline__ void operator()(const f32x4 (&acc)[2][2][4][2], const Unit& u, int wr, int wc, int fr, int fq) const {
;     ...
;                 for (int m = 0; m < 4; ++m) { const u32x4 cur = gq[m]; u32x4 hw;
; #pragma unroll
;                     for (int hv = 0; hv < 2; ++hv) { const u32x2 c2 = half2(cur, hv), p2 = half2(pv, hv);
;                         const u32x2 q1 = dpp_prev<1>(p2, c2), q2 = dpp_prev<2>(p2, c2);
;                         float g0[4], g1[4], g2[4]; unpk4(c2, g0); unpk4(q1, g1); unpk4(q2, g2);
;                         const u32x2 r = finish2(g0, g1, g2, w0[hv], w1[hv], w2[hv], bb[hv], acc[ai][bj][m][hv], rs8[ai][m]);
;                         if (hv == 0) { hw.x = r.x; hw.y = r.y; } else { hw.z = r.x; hw.w = r.y; } }
;                     *(u32x4*)(H + (size_t)(R0 + fr + 16 * m) * 2816 + col8) = hw;
;                     pv = cur; } }
	v_mov_b32_dpp v71, v114 row_ror:2 row_mask:0xf bank_mask:0xf bound_ctrl:1
	v_and_b32_e32 v121, 0xffff0000, v110
	v_mov_b32_dpp v69, v115 row_ror:1 row_mask:0xf bank_mask:0xf bound_ctrl:1
	v_mov_b32_dpp v71, v110 row_shr:2 row_mask:0xf bank_mask:0xf
	v_lshlrev_b32_e32 v70, 16, v71
	v_and_b32_e32 v71, 0xffff0000, v71
	v_pk_fma_f32 v[70:71], v[84:85], v[70:71], v[96:97]
	v_mov_b32_dpp v69, v111 row_shr:1 row_mask:0xf bank_mask:0xf
	v_pk_fma_f32 v[62:63], v[88:89], v[62:63], v[70:71]
	v_lshlrev_b32_e32 v114, 16, v101
	v_pk_fma_f32 v[62:63], v[92:93], v[120:121], v[62:63]
	v_and_b32_e32 v115, 0xffff0000, v101
	v_pk_mul_f32 v[70:71], v[62:63], s[26:27] op_sel_hi:[1,0]
	v_pk_mul_f32 v[62:63], v[62:63], 0.5 op_sel_hi:[1,0]
	v_med3_f32 v70, v70, s71, v224
	v_med3_f32 v71, v71, s71, v224
	v_pk_mul_f32 v[120:121], v[70:71], v[70:71]
	v_lshlrev_b32_e32 v68, 16, v69
	v_pk_fma_f32 v[130:131], v[120:121], s[28:29], v[118:119] op_sel_hi:[1,0,0] neg_lo:[1,0,0] neg_hi:[1,0,0]
	v_and_b32_e32 v69, 0xffff0000, v69
	v_pk_fma_f32 v[130:131], v[120:121], v[130:131], s[34:35] op_sel_hi:[1,1,0]
	v_mov_b32_dpp v1, v116 row_ror:1 row_mask:0xf bank_mask:0xf bound_ctrl:1
	v_pk_fma_f32 v[130:131], v[120:121], v[130:131], s[36:37] op_sel_hi:[1,1,0]
	v_pk_mul_f32 v[2:3], v[38:39], v[2:3]
	v_pk_fma_f32 v[130:131], v[120:121], v[130:131], s[38:39] op_sel_hi:[1,1,0]
	v_mov_b32_dpp v1, v112 row_shr:1 row_mask:0xf bank_mask:0xf
	v_pk_fma_f32 v[130:131], v[120:121], v[130:131], s[40:41] op_sel_hi:[1,1,0]
	v_mov_b32_e32 v101, 0
	v_pk_fma_f32 v[130:131], v[120:121], v[130:131], s[42:43] op_sel_hi:[1,1,0]
	s_nop 0
	v_pk_fma_f32 v[120:121], v[120:121], v[130:131], s[44:45] op_sel_hi:[1,1,0]
	s_nop 0
	v_pk_mul_f32 v[70:71], v[70:71], v[120:121]
	s_nop 0
	v_pk_fma_f32 v[62:63], v[62:63], v[70:71], v[62:63]
	v_pk_fma_f32 v[70:71], v[86:87], v[114:115], v[98:99]
	v_pk_mul_f32 v[56:57], v[56:57], v[62:63]
	v_lshlrev_b32_e32 v62, 16, v111
	v_and_b32_e32 v63, 0xffff0000, v111
	v_pk_fma_f32 v[68:69], v[90:91], v[68:69], v[70:71]
	v_cvt_pk_bf16_f32 v56, v56, v57
	s_nop 0
	v_pk_fma_f32 v[62:63], v[94:95], v[62:63], v[68:69]
	s_nop 0
	v_pk_mul_f32 v[68:69], v[62:63], s[26:27] op_sel_hi:[1,0]
	v_pk_mul_f32 v[62:63], v[62:63], 0.5 op_sel_hi:[1,0]
	v_med3_f32 v68, v68, s71, v224
	v_med3_f32 v69, v69, s71, v224
	v_pk_mul_f32 v[70:71], v[68:69], v[68:69]
	s_nop 0
	v_pk_fma_f32 v[114:115], v[70:71], s[28:29], v[118:119] op_sel_hi:[1,0,0] neg_lo:[1,0,0] neg_hi:[1,0,0]
	s_nop 0
	v_pk_fma_f32 v[114:115], v[70:71], v[114:115], s[34:35] op_sel_hi:[1,1,0]
	s_nop 0
	v_pk_fma_f32 v[114:115], v[70:71], v[114:115], s[36:37] op_sel_hi:[1,1,0]
	s_nop 0
	v_pk_fma_f32 v[114:115], v[70:71], v[114:115], s[38:39] op_sel_hi:[1,1,0]
	s_nop 0
	v_pk_fma_f32 v[114:115], v[70:71], v[114:115], s[40:41] op_sel_hi:[1,1,0]
	s_nop 0
	v_pk_fma_f32 v[114:115], v[70:71], v[114:115], s[42:43] op_sel_hi:[1,1,0]
	s_nop 0
	v_pk_fma_f32 v[70:71], v[70:71], v[114:115], s[44:45] op_sel_hi:[1,1,0]
	v_lshlrev_b32_e32 v114, 16, v112
	v_pk_mul_f32 v[68:69], v[68:69], v[70:71]
	v_and_b32_e32 v115, 0xffff0000, v112
	v_pk_fma_f32 v[62:63], v[62:63], v[68:69], v[62:63]
	v_mov_b32_dpp v69, v116 row_ror:2 row_mask:0xf bank_mask:0xf bound_ctrl:1
	v_pk_mul_f32 v[58:59], v[58:59], v[62:63]
	v_mov_b32_dpp v63, v117 row_ror:1 row_mask:0xf bank_mask:0xf bound_ctrl:1
	v_mov_b32_dpp v69, v112 row_shr:2 row_mask:0xf bank_mask:0xf
	v_lshlrev_b32_e32 v68, 16, v69
	v_and_b32_e32 v69, 0xffff0000, v69
	v_cvt_pk_bf16_f32 v57, v58, v59
	v_lshlrev_b32_e32 v58, 16, v1
	v_and_b32_e32 v59, 0xffff0000, v1
	v_pk_fma_f32 v[68:69], v[64:65], v[68:69], v[80:81]
	v_mov_b32_dpp v71, v117 row_ror:2 row_mask:0xf bank_mask:0xf bound_ctrl:1
	v_pk_fma_f32 v[58:59], v[72:73], v[58:59], v[68:69]
	v_mov_b32_dpp v63, v113 row_shr:1 row_mask:0xf bank_mask:0xf
	v_pk_fma_f32 v[58:59], v[76:77], v[114:115], v[58:59]
	v_mov_b32_dpp v71, v113 row_shr:2 row_mask:0xf bank_mask:0xf
	v_pk_mul_f32 v[68:69], v[58:59], s[26:27] op_sel_hi:[1,0]
	v_lshlrev_b32_e32 v70, 16, v71
	v_med3_f32 v68, v68, s71, v224
	v_med3_f32 v69, v69, s71, v224
	v_pk_mul_f32 v[114:115], v[68:69], v[68:69]
	v_and_b32_e32 v71, 0xffff0000, v71
	v_pk_fma_f32 v[116:117], v[114:115], s[28:29], v[118:119] op_sel_hi:[1,0,0] neg_lo:[1,0,0] neg_hi:[1,0,0]
	v_pk_mul_f32 v[58:59], v[58:59], 0.5 op_sel_hi:[1,0]
	v_pk_fma_f32 v[116:117], v[114:115], v[116:117], s[34:35] op_sel_hi:[1,1,0]
	v_lshlrev_b32_e32 v62, 16, v63
	v_pk_fma_f32 v[116:117], v[114:115], v[116:117], s[36:37] op_sel_hi:[1,1,0]
	v_and_b32_e32 v63, 0xffff0000, v63
	v_pk_fma_f32 v[116:117], v[114:115], v[116:117], s[38:39] op_sel_hi:[1,1,0]
	v_mov_b32_dpp v1, v110 row_ror:1 row_mask:0xf bank_mask:0xf bound_ctrl:1
	v_pk_fma_f32 v[116:117], v[114:115], v[116:117], s[40:41] op_sel_hi:[1,1,0]
	s_nop 0
	v_pk_fma_f32 v[116:117], v[114:115], v[116:117], s[42:43] op_sel_hi:[1,1,0]
	v_mov_b32_dpp v1, v106 row_shr:1 row_mask:0xf bank_mask:0xf
	v_pk_fma_f32 v[114:115], v[114:115], v[116:117], s[44:45] op_sel_hi:[1,1,0]
	s_nop 0
	v_pk_mul_f32 v[68:69], v[68:69], v[114:115]
	s_nop 0
	v_pk_fma_f32 v[58:59], v[58:59], v[68:69], v[58:59]
	v_pk_fma_f32 v[68:69], v[66:67], v[70:71], v[82:83]
	v_pk_mul_f32 v[52:53], v[52:53], v[58:59]
	v_lshlrev_b32_e32 v58, 16, v113
	v_and_b32_e32 v59, 0xffff0000, v113
	v_pk_fma_f32 v[62:63], v[74:75], v[62:63], v[68:69]
	s_nop 0
	v_pk_fma_f32 v[58:59], v[78:79], v[58:59], v[62:63]
	s_nop 0
	v_pk_mul_f32 v[62:63], v[58:59], s[26:27] op_sel_hi:[1,0]
	v_pk_mul_f32 v[58:59], v[58:59], 0.5 op_sel_hi:[1,0]
	v_med3_f32 v62, v62, s71, v224
	v_med3_f32 v63, v63, s71, v224
	v_pk_mul_f32 v[68:69], v[62:63], v[62:63]
	s_nop 0
;     static __device__ __forceinline__ void unpk4(const u32x2 w, float (&o)[4]) { o[0] = bf_lo(w.x); o[1] = bf_hi(w.x); o[2] = bf_lo(w.y); o[3] = bf_hi(w.y); }
;     template <int N> static __device__ __forceinline__ u32x2 dpp_prev(const u32x2 pv, const u32x2 cur) { u32x2 r; r.x = dpp_prev1<N>(pv.x, cur.x); r.y = dpp_prev1<N>(pv.y, cur.y); return r; }
; __device__ __forceinline__ f32x2 gelu_pk(f32x2 v) {
;     f32x2 x = v * 0.70710678118f;
;     x.x = __builtin_amdgcn_fmed3f(x.x, -2.9f, 2.9f); x.y = __builtin_amdgcn_fmed3f(x.y, -2.9f, 2.9f);
;     const f32x2 t = x * x;
;     f32x2 p = t * (-4.953124630e-07f) + 1.987094038e-05f;
;     p = p * t + (-3.472001117e-04f); p = p * t + 3.517547622e-03f; p = p * t + (-2.333305031e-02f); p = p * t + 1.087993085e-01f; p = p * t + (-3.740358949e-01f); p = p * t + 1.128076553e+00f;
;     const f32x2 hv = v * 0.5f;
;     return hv * (x * p) + hv;
; }
;     __device__ __forceinline__ void operator()(const f32x4 (&acc)[2][2][4][2], const Unit& u, int wr, int wc, int fr, int fq) const {
;     ...
;                 for (int m = 0; m < 4; ++m) { const u32x4 cur = gq[m]; u32x4 hw;
; #pragma unroll
;                     for (int hv = 0; hv < 2; ++hv) { const u32x2 c2 = half2(cur, hv), p2 = half2(pv, hv);
;                         const u32x2 q1 = dpp_prev<1>(p2, c2), q2 = dpp_prev<2>(p2, c2);
;                         float g0[4], g1[4], g2[4]; unpk4(c2, g0); unpk4(q1, g1); unpk4(q2, g2);
;                         const u32x2 r = finish2(g0, g1, g2, w0[hv], w1[hv], w2[hv], bb[hv], acc[ai][bj][m][hv], rs8[ai][m]);
;                         if (hv == 0) { hw.x = r.x; hw.y = r.y; } else { hw.z = r.x; hw.w = r.y; } }
;                     *(u32x4*)(H + (size_t)(R0 + fr + 16 * m) * 2816 + col8) = hw;
;                     pv = cur; } }
	v_pk_fma_f32 v[70:71], v[68:69], s[28:29], v[118:119] op_sel_hi:[1,0,0] neg_lo:[1,0,0] neg_hi:[1,0,0]
	s_nop 0
	v_pk_fma_f32 v[70:71], v[68:69], v[70:71], s[34:35] op_sel_hi:[1,1,0]
	s_nop 0
	v_pk_fma_f32 v[70:71], v[68:69], v[70:71], s[36:37] op_sel_hi:[1,1,0]
	s_nop 0
	v_pk_fma_f32 v[70:71], v[68:69], v[70:71], s[38:39] op_sel_hi:[1,1,0]
	s_nop 0
	v_pk_fma_f32 v[70:71], v[68:69], v[70:71], s[40:41] op_sel_hi:[1,1,0]
	s_nop 0
	v_pk_fma_f32 v[70:71], v[68:69], v[70:71], s[42:43] op_sel_hi:[1,1,0]
	s_nop 0
	v_pk_fma_f32 v[68:69], v[68:69], v[70:71], s[44:45] op_sel_hi:[1,1,0]
	s_nop 0
	v_pk_mul_f32 v[62:63], v[62:63], v[68:69]
	s_nop 0
	v_pk_fma_f32 v[58:59], v[58:59], v[62:63], v[58:59]
	v_lshlrev_b32_e32 v62, 16, v106
	v_pk_mul_f32 v[54:55], v[54:55], v[58:59]
	v_cvt_pk_bf16_f32 v58, v52, v53
	v_lshl_add_u64 v[52:53], v[176:177], 0, v[60:61]
	v_cvt_pk_bf16_f32 v59, v54, v55
	global_store_dwordx4 v[52:53], v[56:59], off
	v_lshlrev_b32_e32 v52, 16, v1
	v_and_b32_e32 v53, 0xffff0000, v1
	v_mov_b32_dpp v57, v110 row_ror:2 row_mask:0xf bank_mask:0xf bound_ctrl:1
	v_and_b32_e32 v63, 0xffff0000, v106
	v_mov_b32_dpp v59, v111 row_ror:2 row_mask:0xf bank_mask:0xf bound_ctrl:1
	v_mov_b32_dpp v57, v106 row_shr:2 row_mask:0xf bank_mask:0xf
	v_lshlrev_b32_e32 v56, 16, v57
	v_and_b32_e32 v57, 0xffff0000, v57
	v_pk_fma_f32 v[56:57], v[84:85], v[56:57], v[96:97]
	v_mov_b32_dpp v55, v111 row_ror:1 row_mask:0xf bank_mask:0xf bound_ctrl:1
	v_pk_fma_f32 v[52:53], v[88:89], v[52:53], v[56:57]
	v_mov_b32_dpp v59, v107 row_shr:2 row_mask:0xf bank_mask:0xf
	v_pk_fma_f32 v[52:53], v[92:93], v[62:63], v[52:53]
	v_mov_b32_dpp v55, v107 row_shr:1 row_mask:0xf bank_mask:0xf
	v_pk_mul_f32 v[56:57], v[52:53], s[26:27] op_sel_hi:[1,0]
	v_lshlrev_b32_e32 v58, 16, v59
	v_med3_f32 v56, v56, s71, v224
	v_med3_f32 v57, v57, s71, v224
	v_pk_mul_f32 v[62:63], v[56:57], v[56:57]
	v_and_b32_e32 v59, 0xffff0000, v59
	v_pk_fma_f32 v[68:69], v[62:63], s[28:29], v[118:119] op_sel_hi:[1,0,0] neg_lo:[1,0,0] neg_hi:[1,0,0]
	v_pk_mul_f32 v[52:53], v[52:53], 0.5 op_sel_hi:[1,0]
	v_pk_fma_f32 v[68:69], v[62:63], v[68:69], s[34:35] op_sel_hi:[1,1,0]
	v_lshlrev_b32_e32 v54, 16, v55
	v_pk_fma_f32 v[68:69], v[62:63], v[68:69], s[36:37] op_sel_hi:[1,1,0]
	v_and_b32_e32 v55, 0xffff0000, v55
	v_pk_fma_f32 v[68:69], v[62:63], v[68:69], s[38:39] op_sel_hi:[1,1,0]
	v_mov_b32_dpp v1, v112 row_ror:1 row_mask:0xf bank_mask:0xf bound_ctrl:1
	v_pk_fma_f32 v[68:69], v[62:63], v[68:69], s[40:41] op_sel_hi:[1,1,0]
	s_nop 0
	v_pk_fma_f32 v[68:69], v[62:63], v[68:69], s[42:43] op_sel_hi:[1,1,0]
	v_mov_b32_dpp v1, v108 row_shr:1 row_mask:0xf bank_mask:0xf
	v_pk_fma_f32 v[62:63], v[62:63], v[68:69], s[44:45] op_sel_hi:[1,1,0]
	s_nop 0
	v_pk_mul_f32 v[56:57], v[56:57], v[62:63]
	s_nop 0
	v_pk_fma_f32 v[52:53], v[52:53], v[56:57], v[52:53]
	v_pk_fma_f32 v[56:57], v[86:87], v[58:59], v[98:99]
	v_pk_mul_f32 v[48:49], v[48:49], v[52:53]
	v_lshlrev_b32_e32 v52, 16, v107
	v_and_b32_e32 v53, 0xffff0000, v107
	v_pk_fma_f32 v[54:55], v[90:91], v[54:55], v[56:57]
	v_cvt_pk_bf16_f32 v48, v48, v49
	s_nop 0
	v_pk_fma_f32 v[52:53], v[94:95], v[52:53], v[54:55]
	s_nop 0
	v_pk_mul_f32 v[54:55], v[52:53], s[26:27] op_sel_hi:[1,0]
	v_pk_mul_f32 v[52:53], v[52:53], 0.5 op_sel_hi:[1,0]
	v_med3_f32 v54, v54, s71, v224
	v_med3_f32 v55, v55, s71, v224
	v_pk_mul_f32 v[56:57], v[54:55], v[54:55]
	s_nop 0
	v_pk_fma_f32 v[58:59], v[56:57], s[28:29], v[118:119] op_sel_hi:[1,0,0] neg_lo:[1,0,0] neg_hi:[1,0,0]
	s_nop 0
	v_pk_fma_f32 v[58:59], v[56:57], v[58:59], s[34:35] op_sel_hi:[1,1,0]
	s_nop 0
	v_pk_fma_f32 v[58:59], v[56:57], v[58:59], s[36:37] op_sel_hi:[1,1,0]
	s_nop 0
	v_pk_fma_f32 v[58:59], v[56:57], v[58:59], s[38:39] op_sel_hi:[1,1,0]
	s_nop 0
	v_pk_fma_f32 v[58:59], v[56:57], v[58:59], s[40:41] op_sel_hi:[1,1,0]
	s_nop 0
	v_pk_fma_f32 v[58:59], v[56:57], v[58:59], s[42:43] op_sel_hi:[1,1,0]
	s_nop 0
	v_pk_fma_f32 v[56:57], v[56:57], v[58:59], s[44:45] op_sel_hi:[1,1,0]
	v_lshlrev_b32_e32 v58, 16, v108
	v_pk_mul_f32 v[54:55], v[54:55], v[56:57]
	v_and_b32_e32 v59, 0xffff0000, v108
	v_pk_fma_f32 v[52:53], v[52:53], v[54:55], v[52:53]
	v_mov_b32_dpp v55, v112 row_ror:2 row_mask:0xf bank_mask:0xf bound_ctrl:1
	v_pk_mul_f32 v[50:51], v[50:51], v[52:53]
	v_mov_b32_dpp v57, v113 row_ror:2 row_mask:0xf bank_mask:0xf bound_ctrl:1
	v_mov_b32_dpp v55, v108 row_shr:2 row_mask:0xf bank_mask:0xf
	v_lshlrev_b32_e32 v54, 16, v55
	v_and_b32_e32 v55, 0xffff0000, v55
	v_cvt_pk_bf16_f32 v49, v50, v51
	v_lshlrev_b32_e32 v50, 16, v1
	v_and_b32_e32 v51, 0xffff0000, v1
	v_pk_fma_f32 v[54:55], v[64:65], v[54:55], v[80:81]
	v_mov_b32_dpp v53, v113 row_ror:1 row_mask:0xf bank_mask:0xf bound_ctrl:1
	v_pk_fma_f32 v[50:51], v[72:73], v[50:51], v[54:55]
	v_mov_b32_dpp v57, v109 row_shr:2 row_mask:0xf bank_mask:0xf
	v_pk_fma_f32 v[50:51], v[76:77], v[58:59], v[50:51]
	v_mov_b32_dpp v53, v109 row_shr:1 row_mask:0xf bank_mask:0xf
	v_pk_mul_f32 v[54:55], v[50:51], s[26:27] op_sel_hi:[1,0]
	v_lshlrev_b32_e32 v56, 16, v57
	v_med3_f32 v54, v54, s71, v224
	v_med3_f32 v55, v55, s71, v224
	v_pk_mul_f32 v[58:59], v[54:55], v[54:55]
	v_and_b32_e32 v57, 0xffff0000, v57
	v_pk_fma_f32 v[62:63], v[58:59], s[28:29], v[118:119] op_sel_hi:[1,0,0] neg_lo:[1,0,0] neg_hi:[1,0,0]
	v_pk_mul_f32 v[50:51], v[50:51], 0.5 op_sel_hi:[1,0]
	v_pk_fma_f32 v[62:63], v[58:59], v[62:63], s[34:35] op_sel_hi:[1,1,0]
	v_lshlrev_b32_e32 v52, 16, v53
	v_pk_fma_f32 v[62:63], v[58:59], v[62:63], s[36:37] op_sel_hi:[1,1,0]
	v_and_b32_e32 v53, 0xffff0000, v53
	v_pk_fma_f32 v[62:63], v[58:59], v[62:63], s[38:39] op_sel_hi:[1,1,0]
	v_mov_b32_dpp v1, v106 row_ror:1 row_mask:0xf bank_mask:0xf bound_ctrl:1
;     static __device__ __forceinline__ void unpk4(const u32x2 w, float (&o)[4]) { o[0] = bf_lo(w.x); o[1] = bf_hi(w.x); o[2] = bf_lo(w.y); o[3] = bf_hi(w.y); }
;     template <int N> static __device__ __forceinline__ u32x2 dpp_prev(const u32x2 pv, const u32x2 cur) { u32x2 r; r.x = dpp_prev1<N>(pv.x, cur.x); r.y = dpp_prev1<N>(pv.y, cur.y); return r; }
; __device__ __forceinline__ f32x2 gelu_pk(f32x2 v) {
;     f32x2 x = v * 0.70710678118f;
;     x.x = __builtin_amdgcn_fmed3f(x.x, -2.9f, 2.9f); x.y = __builtin_amdgcn_fmed3f(x.y, -2.9f, 2.9f);
;     const f32x2 t = x * x;
;     f32x2 p = t * (-4.953124630e-07f) + 1.987094038e-05f;
;     p = p * t + (-3.472001117e-04f); p = p * t + 3.517547622e-03f; p = p * t + (-2.333305031e-02f); p = p * t + 1.087993085e-01f; p = p * t + (-3.740358949e-01f); p = p * t + 1.128076553e+00f;
;     const f32x2 hv = v * 0.5f;
;     return hv * (x * p) + hv;
; }
;     __device__ __forceinline__ void operator()(const f32x4 (&acc)[2][2][4][2], const Unit& u, int wr, int wc, int fr, int fq) const {
;     ...
;                 for (int m = 0; m < 4; ++m) { const u32x4 cur = gq[m]; u32x4 hw;
; #pragma unroll
;                     for (int hv = 0; hv < 2; ++hv) { const u32x2 c2 = half2(cur, hv), p2 = half2(pv, hv);
;                         const u32x2 q1 = dpp_prev<1>(p2, c2), q2 = dpp_prev<2>(p2, c2);
;                         float g0[4], g1[4], g2[4]; unpk4(c2, g0); unpk4(q1, g1); unpk4(q2, g2);
;                         const u32x2 r = finish2(g0, g1, g2, w0[hv], w1[hv], w2[hv], bb[hv], acc[ai][bj][m][hv], rs8[ai][m]);
;                         if (hv == 0) { hw.x = r.x; hw.y = r.y; } else { hw.z = r.x; hw.w = r.y; } }
;                     *(u32x4*)(H + (size_t)(R0 + fr + 16 * m) * 2816 + col8) = hw;
;                     pv = cur; } }
	v_pk_fma_f32 v[62:63], v[58:59], v[62:63], s[40:41] op_sel_hi:[1,1,0]
	s_nop 0
	v_pk_fma_f32 v[62:63], v[58:59], v[62:63], s[42:43] op_sel_hi:[1,1,0]
	v_mov_b32_dpp v1, v102 row_shr:1 row_mask:0xf bank_mask:0xf
	v_pk_fma_f32 v[58:59], v[58:59], v[62:63], s[44:45] op_sel_hi:[1,1,0]
	s_nop 0
	v_pk_mul_f32 v[54:55], v[54:55], v[58:59]
	s_nop 0
	v_pk_fma_f32 v[50:51], v[50:51], v[54:55], v[50:51]
	v_pk_fma_f32 v[54:55], v[66:67], v[56:57], v[82:83]
	v_pk_mul_f32 v[44:45], v[44:45], v[50:51]
	v_lshlrev_b32_e32 v50, 16, v109
	v_and_b32_e32 v51, 0xffff0000, v109
	v_pk_fma_f32 v[52:53], v[74:75], v[52:53], v[54:55]
	s_nop 0
	v_pk_fma_f32 v[50:51], v[78:79], v[50:51], v[52:53]
	s_nop 0
	v_pk_mul_f32 v[52:53], v[50:51], s[26:27] op_sel_hi:[1,0]
	v_pk_mul_f32 v[50:51], v[50:51], 0.5 op_sel_hi:[1,0]
	v_med3_f32 v52, v52, s71, v224
	v_med3_f32 v53, v53, s71, v224
	v_pk_mul_f32 v[54:55], v[52:53], v[52:53]
	s_nop 0
	v_pk_fma_f32 v[56:57], v[54:55], s[28:29], v[118:119] op_sel_hi:[1,0,0] neg_lo:[1,0,0] neg_hi:[1,0,0]
	s_nop 0
	v_pk_fma_f32 v[56:57], v[54:55], v[56:57], s[34:35] op_sel_hi:[1,1,0]
	s_nop 0
	v_pk_fma_f32 v[56:57], v[54:55], v[56:57], s[36:37] op_sel_hi:[1,1,0]
	s_nop 0
	v_pk_fma_f32 v[56:57], v[54:55], v[56:57], s[38:39] op_sel_hi:[1,1,0]
	s_nop 0
	v_pk_fma_f32 v[56:57], v[54:55], v[56:57], s[40:41] op_sel_hi:[1,1,0]
	s_nop 0
	v_pk_fma_f32 v[56:57], v[54:55], v[56:57], s[42:43] op_sel_hi:[1,1,0]
	s_nop 0
	v_pk_fma_f32 v[54:55], v[54:55], v[56:57], s[44:45] op_sel_hi:[1,1,0]
	v_lshl_add_u64 v[56:57], v[166:167], 0, v[60:61]
	v_pk_mul_f32 v[52:53], v[52:53], v[54:55]
	s_nop 0
	v_pk_fma_f32 v[50:51], v[50:51], v[52:53], v[50:51]
	v_lshlrev_b32_e32 v52, 16, v102
	v_pk_mul_f32 v[46:47], v[46:47], v[50:51]
	v_cvt_pk_bf16_f32 v50, v44, v45
	v_lshl_add_u64 v[44:45], v[172:173], 0, v[60:61]
	v_cvt_pk_bf16_f32 v51, v46, v47
	global_store_dwordx4 v[44:45], v[48:51], off
	v_lshlrev_b32_e32 v44, 16, v1
	v_and_b32_e32 v45, 0xffff0000, v1
	v_mov_b32_dpp v49, v106 row_ror:2 row_mask:0xf bank_mask:0xf bound_ctrl:1
	v_and_b32_e32 v53, 0xffff0000, v102
	v_mov_b32_dpp v51, v107 row_ror:2 row_mask:0xf bank_mask:0xf bound_ctrl:1
	v_mov_b32_dpp v49, v102 row_shr:2 row_mask:0xf bank_mask:0xf
	v_lshlrev_b32_e32 v48, 16, v49
	v_and_b32_e32 v49, 0xffff0000, v49
	v_pk_fma_f32 v[48:49], v[84:85], v[48:49], v[96:97]
	v_mov_b32_dpp v47, v107 row_ror:1 row_mask:0xf bank_mask:0xf bound_ctrl:1
	v_pk_fma_f32 v[44:45], v[88:89], v[44:45], v[48:49]
	v_mov_b32_dpp v51, v103 row_shr:2 row_mask:0xf bank_mask:0xf
	v_pk_fma_f32 v[44:45], v[92:93], v[52:53], v[44:45]
	v_mov_b32_dpp v47, v103 row_shr:1 row_mask:0xf bank_mask:0xf
	v_pk_mul_f32 v[48:49], v[44:45], s[26:27] op_sel_hi:[1,0]
	v_lshlrev_b32_e32 v50, 16, v51
	v_med3_f32 v48, v48, s71, v224
	v_med3_f32 v49, v49, s71, v224
	v_pk_mul_f32 v[52:53], v[48:49], v[48:49]
	v_and_b32_e32 v51, 0xffff0000, v51
	v_pk_fma_f32 v[54:55], v[52:53], s[28:29], v[118:119] op_sel_hi:[1,0,0] neg_lo:[1,0,0] neg_hi:[1,0,0]
	v_pk_mul_f32 v[44:45], v[44:45], 0.5 op_sel_hi:[1,0]
	v_pk_fma_f32 v[54:55], v[52:53], v[54:55], s[34:35] op_sel_hi:[1,1,0]
	v_lshlrev_b32_e32 v46, 16, v47
	v_pk_fma_f32 v[54:55], v[52:53], v[54:55], s[36:37] op_sel_hi:[1,1,0]
	v_and_b32_e32 v47, 0xffff0000, v47
	v_pk_fma_f32 v[54:55], v[52:53], v[54:55], s[38:39] op_sel_hi:[1,1,0]
	v_mov_b32_dpp v1, v108 row_ror:1 row_mask:0xf bank_mask:0xf bound_ctrl:1
	v_pk_fma_f32 v[54:55], v[52:53], v[54:55], s[40:41] op_sel_hi:[1,1,0]
	v_mov_b32_e32 v102, 0
	v_pk_fma_f32 v[54:55], v[52:53], v[54:55], s[42:43] op_sel_hi:[1,1,0]
	v_mov_b32_dpp v1, v104 row_shr:1 row_mask:0xf bank_mask:0xf
	v_pk_fma_f32 v[52:53], v[52:53], v[54:55], s[44:45] op_sel_hi:[1,1,0]
	s_nop 0
	v_pk_mul_f32 v[48:49], v[48:49], v[52:53]
	s_nop 0
	v_pk_fma_f32 v[44:45], v[44:45], v[48:49], v[44:45]
	v_pk_fma_f32 v[48:49], v[86:87], v[50:51], v[98:99]
	v_pk_mul_f32 v[40:41], v[40:41], v[44:45]
	v_lshlrev_b32_e32 v44, 16, v103
	v_and_b32_e32 v45, 0xffff0000, v103
	v_pk_fma_f32 v[46:47], v[90:91], v[46:47], v[48:49]
	v_cvt_pk_bf16_f32 v52, v40, v41
	v_lshlrev_b32_e32 v40, 16, v1
	v_pk_fma_f32 v[44:45], v[94:95], v[44:45], v[46:47]
	v_and_b32_e32 v41, 0xffff0000, v1
	v_pk_mul_f32 v[46:47], v[44:45], s[26:27] op_sel_hi:[1,0]
	v_pk_mul_f32 v[44:45], v[44:45], 0.5 op_sel_hi:[1,0]
	v_med3_f32 v46, v46, s71, v224
	v_med3_f32 v47, v47, s71, v224
	v_pk_mul_f32 v[48:49], v[46:47], v[46:47]
	v_mov_b32_e32 v103, 0
	v_pk_fma_f32 v[50:51], v[48:49], s[28:29], v[118:119] op_sel_hi:[1,0,0] neg_lo:[1,0,0] neg_hi:[1,0,0]
;     static __device__ __forceinline__ void unpk4(const u32x2 w, float (&o)[4]) { o[0] = bf_lo(w.x); o[1] = bf_hi(w.x); o[2] = bf_lo(w.y); o[3] = bf_hi(w.y); }
;     template <int N> static __device__ __forceinline__ u32x2 dpp_prev(const u32x2 pv, const u32x2 cur) { u32x2 r; r.x = dpp_prev1<N>(pv.x, cur.x); r.y = dpp_prev1<N>(pv.y, cur.y); return r; }
; __device__ __forceinline__ f32x2 gelu_pk(f32x2 v) {
;     f32x2 x = v * 0.70710678118f;
;     x.x = __builtin_amdgcn_fmed3f(x.x, -2.9f, 2.9f); x.y = __builtin_amdgcn_fmed3f(x.y, -2.9f, 2.9f);
;     const f32x2 t = x * x;
;     f32x2 p = t * (-4.953124630e-07f) + 1.987094038e-05f;
;     p = p * t + (-3.472001117e-04f); p = p * t + 3.517547622e-03f; p = p * t + (-2.333305031e-02f); p = p * t + 1.087993085e-01f; p = p * t + (-3.740358949e-01f); p = p * t + 1.128076553e+00f;
;     const f32x2 hv = v * 0.5f;
;     return hv * (x * p) + hv;
; }
;     __device__ __forceinline__ void operator()(const f32x4 (&acc)[2][2][4][2], const Unit& u, int wr, int wc, int fr, int fq) const {
;     ...
;             for (int ai = 0; ai < 2; ++ai) { const int R0 = u.rb + ai * HALF + wr * 64; const bf16_t* gp = G + (size_t)(R0 + fr) * 2816 + col8;
;                 u32x4 gq[4], prv = (u32x4){0u, 0u, 0u, 0u};
; #pragma unroll
;                 for (int m = 0; m < 4; ++m) gq[m] = *(const u32x4*)(gp + (size_t)m * 16 * 2816);
;                 if ((R0 & 8191) != 0) prv = *(const u32x4*)(gp - (size_t)16 * 2816);
;                 u32x4 pv = prv;
; #pragma unroll
;                 for (int m = 0; m < 4; ++m) { const u32x4 cur = gq[m]; u32x4 hw;
; #pragma unroll
;                     for (int hv = 0; hv < 2; ++hv) { const u32x2 c2 = half2(cur, hv), p2 = half2(pv, hv);
;                         const u32x2 q1 = dpp_prev<1>(p2, c2), q2 = dpp_prev<2>(p2, c2);
;                         float g0[4], g1[4], g2[4]; unpk4(c2, g0); unpk4(q1, g1); unpk4(q2, g2);
;                         const u32x2 r = finish2(g0, g1, g2, w0[hv], w1[hv], w2[hv], bb[hv], acc[ai][bj][m][hv], rs8[ai][m]);
;                         if (hv == 0) { hw.x = r.x; hw.y = r.y; } else { hw.z = r.x; hw.w = r.y; } }
;                     *(u32x4*)(H + (size_t)(R0 + fr + 16 * m) * 2816 + col8) = hw;
;                     pv = cur; } }
	s_nop 0
	v_pk_fma_f32 v[50:51], v[48:49], v[50:51], s[34:35] op_sel_hi:[1,1,0]
	s_nop 0
	v_pk_fma_f32 v[50:51], v[48:49], v[50:51], s[36:37] op_sel_hi:[1,1,0]
	s_nop 0
	v_pk_fma_f32 v[50:51], v[48:49], v[50:51], s[38:39] op_sel_hi:[1,1,0]
	s_nop 0
	v_pk_fma_f32 v[50:51], v[48:49], v[50:51], s[40:41] op_sel_hi:[1,1,0]
	s_nop 0
	v_pk_fma_f32 v[50:51], v[48:49], v[50:51], s[42:43] op_sel_hi:[1,1,0]
	s_nop 0
	v_pk_fma_f32 v[48:49], v[48:49], v[50:51], s[44:45] op_sel_hi:[1,1,0]
	s_nop 0
	v_pk_mul_f32 v[46:47], v[46:47], v[48:49]
	v_lshlrev_b32_e32 v48, 16, v104
	v_pk_fma_f32 v[44:45], v[44:45], v[46:47], v[44:45]
	v_and_b32_e32 v49, 0xffff0000, v104
	v_pk_mul_f32 v[42:43], v[42:43], v[44:45]
	v_mov_b32_dpp v45, v108 row_ror:2 row_mask:0xf bank_mask:0xf bound_ctrl:1
	v_mov_b32_dpp v47, v109 row_ror:2 row_mask:0xf bank_mask:0xf bound_ctrl:1
	v_cvt_pk_bf16_f32 v53, v42, v43
	v_mov_b32_dpp v43, v109 row_ror:1 row_mask:0xf bank_mask:0xf bound_ctrl:1
	v_mov_b32_dpp v45, v104 row_shr:2 row_mask:0xf bank_mask:0xf
	v_lshlrev_b32_e32 v44, 16, v45
	v_and_b32_e32 v45, 0xffff0000, v45
	v_pk_fma_f32 v[44:45], v[64:65], v[44:45], v[80:81]
	v_mov_b32_dpp v47, v105 row_shr:2 row_mask:0xf bank_mask:0xf
	v_pk_fma_f32 v[40:41], v[72:73], v[40:41], v[44:45]
	v_mov_b32_dpp v43, v105 row_shr:1 row_mask:0xf bank_mask:0xf
	v_pk_fma_f32 v[40:41], v[76:77], v[48:49], v[40:41]
	v_lshlrev_b32_e32 v46, 16, v47
	v_pk_mul_f32 v[44:45], v[40:41], s[26:27] op_sel_hi:[1,0]
	v_and_b32_e32 v47, 0xffff0000, v47
	v_med3_f32 v44, v44, s71, v224
	v_med3_f32 v45, v45, s71, v224
	v_pk_mul_f32 v[48:49], v[44:45], v[44:45]
	v_pk_mul_f32 v[40:41], v[40:41], 0.5 op_sel_hi:[1,0]
	v_pk_fma_f32 v[50:51], v[48:49], s[28:29], v[118:119] op_sel_hi:[1,0,0] neg_lo:[1,0,0] neg_hi:[1,0,0]
	v_lshlrev_b32_e32 v42, 16, v43
	v_pk_fma_f32 v[50:51], v[48:49], v[50:51], s[34:35] op_sel_hi:[1,1,0]
	v_and_b32_e32 v43, 0xffff0000, v43
	v_pk_fma_f32 v[50:51], v[48:49], v[50:51], s[36:37] op_sel_hi:[1,1,0]
	s_nop 0
	v_pk_fma_f32 v[50:51], v[48:49], v[50:51], s[38:39] op_sel_hi:[1,1,0]
	s_nop 0
	v_pk_fma_f32 v[50:51], v[48:49], v[50:51], s[40:41] op_sel_hi:[1,1,0]
	s_nop 0
	v_pk_fma_f32 v[50:51], v[48:49], v[50:51], s[42:43] op_sel_hi:[1,1,0]
	s_nop 0
	v_pk_fma_f32 v[48:49], v[48:49], v[50:51], s[44:45] op_sel_hi:[1,1,0]
	s_nop 0
	v_pk_mul_f32 v[44:45], v[44:45], v[48:49]
	s_nop 0
	v_pk_fma_f32 v[40:41], v[40:41], v[44:45], v[40:41]
	v_pk_fma_f32 v[44:45], v[66:67], v[46:47], v[82:83]
	v_pk_mul_f32 v[36:37], v[36:37], v[40:41]
	v_lshlrev_b32_e32 v40, 16, v105
	v_and_b32_e32 v41, 0xffff0000, v105
	v_pk_fma_f32 v[42:43], v[74:75], v[42:43], v[44:45]
	v_cvt_pk_bf16_f32 v54, v36, v37
	s_nop 0
	v_pk_fma_f32 v[40:41], v[78:79], v[40:41], v[42:43]
	s_nop 0
	v_pk_mul_f32 v[42:43], v[40:41], s[26:27] op_sel_hi:[1,0]
	v_pk_mul_f32 v[40:41], v[40:41], 0.5 op_sel_hi:[1,0]
	v_med3_f32 v42, v42, s71, v224
	v_med3_f32 v43, v43, s71, v224
	v_pk_mul_f32 v[44:45], v[42:43], v[42:43]
	s_nop 0
	v_pk_fma_f32 v[46:47], v[44:45], s[28:29], v[118:119] op_sel_hi:[1,0,0] neg_lo:[1,0,0] neg_hi:[1,0,0]
	s_nop 0
	v_pk_fma_f32 v[46:47], v[44:45], v[46:47], s[34:35] op_sel_hi:[1,1,0]
	s_nop 0
	v_pk_fma_f32 v[46:47], v[44:45], v[46:47], s[36:37] op_sel_hi:[1,1,0]
	s_nop 0
	v_pk_fma_f32 v[46:47], v[44:45], v[46:47], s[38:39] op_sel_hi:[1,1,0]
	s_nop 0
	v_pk_fma_f32 v[46:47], v[44:45], v[46:47], s[40:41] op_sel_hi:[1,1,0]
	s_nop 0
	v_pk_fma_f32 v[46:47], v[44:45], v[46:47], s[42:43] op_sel_hi:[1,1,0]
	s_nop 0
	v_pk_fma_f32 v[44:45], v[44:45], v[46:47], s[44:45] op_sel_hi:[1,1,0]
	s_nop 0
	v_pk_mul_f32 v[42:43], v[42:43], v[44:45]
	s_nop 0
	v_pk_fma_f32 v[40:41], v[40:41], v[42:43], v[40:41]
	s_nop 0
	v_pk_mul_f32 v[2:3], v[2:3], v[40:41]
	s_nop 0
	v_cvt_pk_bf16_f32 v55, v2, v3
	v_lshl_add_u64 v[2:3], v[164:165], 0, v[60:61]
	v_add_co_u32_e32 v36, vcc, s45, v2
	s_nop 1
	v_addc_co_u32_e32 v37, vcc, 0, v3, vcc
	global_load_dwordx4 v[48:51], v[2:3], off
	global_load_dwordx4 v[44:47], v[36:37], off
	v_add_co_u32_e32 v36, vcc, 0x2c000, v2
	s_nop 1
	v_addc_co_u32_e32 v37, vcc, 0, v3, vcc
	v_add_co_u32_e32 v38, vcc, 0x42000, v2
	s_nop 1
	v_addc_co_u32_e32 v39, vcc, 0, v3, vcc
	global_load_dwordx4 v[40:43], v[36:37], off
	s_nop 0
	global_load_dwordx4 v[36:39], v[38:39], off
	s_andn2_b64 vcc, exec, s[8:9]
	global_store_dwordx4 v[56:57], v[52:55], off
	s_cbranch_vccnz .LBB0_3152
	v_add_co_u32_e32 v2, vcc, 0xfffea000, v2
	s_nop 1
	v_addc_co_u32_e32 v3, vcc, -1, v3, vcc
	global_load_dwordx4 v[100:103], v[2:3], off

; #define LAS __attribute__((address_space(3)))
; __global__ void __launch_bounds__(NTHR, 2) fwd_megakernel(Params p) {
;     extern __shared__ __attribute__((aligned(16))) unsigned char lds_raw[];
;     LAS unsigned char* lds = (LAS unsigned char*)lds_raw;
;     cg::grid_group grid = cg::this_grid();
;     const int G = gridDim.x, bx = blockIdx.x;
;     const int wave0 = __builtin_amdgcn_readfirstlane((int)threadIdx.x >> 6);
;     const int ngw = G * NWAVES;
	.amdhsa_kernel _Z14fwd_megakernel6Params
		.amdhsa_group_segment_fixed_size 0
		.amdhsa_private_segment_fixed_size 0
		.amdhsa_kernarg_size 544
		.amdhsa_user_sgpr_count 2
		.amdhsa_user_sgpr_dispatch_ptr 0
		.amdhsa_user_sgpr_queue_ptr 0
		.amdhsa_user_sgpr_kernarg_segment_ptr 1
		.amdhsa_user_sgpr_dispatch_id 0
		.amdhsa_user_sgpr_kernarg_preload_length 0
		.amdhsa_user_sgpr_kernarg_preload_offset 0
		.amdhsa_user_sgpr_private_segment_size 0
		.amdhsa_uses_dynamic_stack 0
		.amdhsa_enable_private_segment 0
		.amdhsa_system_sgpr_workgroup_id_x 1
		.amdhsa_system_sgpr_workgroup_id_y 0
		.amdhsa_system_sgpr_workgroup_id_z 0
		.amdhsa_system_sgpr_workgroup_info 0
		.amdhsa_system_vgpr_workitem_id 2
		.amdhsa_next_free_vgpr 256
		.amdhsa_next_free_sgpr 102
		.amdhsa_accum_offset 256
		.amdhsa_reserve_vcc 1
		.amdhsa_float_round_mode_32 0
		.amdhsa_float_round_mode_16_64 0
		.amdhsa_float_denorm_mode_32 3
		.amdhsa_float_denorm_mode_16_64 3
		.amdhsa_dx10_clamp 1
		.amdhsa_ieee_mode 1
		.amdhsa_fp16_overflow 0
		.amdhsa_tg_split 0
		.amdhsa_exception_fp_ieee_invalid_op 0
		.amdhsa_exception_fp_denorm_src 0
		.amdhsa_exception_fp_ieee_div_zero 0
		.amdhsa_exception_fp_ieee_overflow 0
		.amdhsa_exception_fp_ieee_underflow 0
		.amdhsa_exception_fp_ieee_inexact 0
		.amdhsa_exception_int_div_zero 0
	.end_amdhsa_kernel

; #define LAS __attribute__((address_space(3)))
; __global__ void __launch_bounds__(NTHR, 2) fwd_megakernel(Params p) {
;     extern __shared__ __attribute__((aligned(16))) unsigned char lds_raw[];
;     LAS unsigned char* lds = (LAS unsigned char*)lds_raw;
;     cg::grid_group grid = cg::this_grid();
;     const int G = gridDim.x, bx = blockIdx.x;
;     const int wave0 = __builtin_amdgcn_readfirstlane((int)threadIdx.x >> 6);
;     const int ngw = G * NWAVES;
amdhsa.kernels:
  - .agpr_count:     0
    .args:
      - .offset:         0
        .size:           288
        .value_kind:     by_value
      - .offset:         288
        .size:           4
        .value_kind:     hidden_block_count_x
      - .offset:         292
        .size:           4
        .value_kind:     hidden_block_count_y
      - .offset:         296
        .size:           4
        .value_kind:     hidden_block_count_z
      - .offset:         300
        .size:           2
        .value_kind:     hidden_group_size_x
      - .offset:         302
        .size:           2
        .value_kind:     hidden_group_size_y
      - .offset:         304
        .size:           2
        .value_kind:     hidden_group_size_z
      - .offset:         306
        .size:           2
        .value_kind:     hidden_remainder_x
      - .offset:         308
        .size:           2
        .value_kind:     hidden_remainder_y
      - .offset:         310
        .size:           2
        .value_kind:     hidden_remainder_z
      - .offset:         328
        .size:           8
        .value_kind:     hidden_global_offset_x
      - .offset:         336
        .size:           8
        .value_kind:     hidden_global_offset_y
      - .offset:         344
        .size:           8
        .value_kind:     hidden_global_offset_z
      - .offset:         352
        .size:           2
        .value_kind:     hidden_grid_dims
      - .offset:         376
        .size:           8
        .value_kind:     hidden_multigrid_sync_arg
      - .offset:         408
        .size:           4
        .value_kind:     hidden_dynamic_lds_size
    .group_segment_fixed_size: 0
    .kernarg_segment_align: 8
    .kernarg_segment_size: 544
    .language:       OpenCL C
    .language_version:
      - 2
      - 0
    .max_flat_workgroup_size: 512
    .name:           _Z14fwd_megakernel6Params
    .private_segment_fixed_size: 0
    .sgpr_count:     108
    .sgpr_spill_count: 199
    .symbol:         _Z14fwd_megakernel6Params.kd
    .uniform_work_group_size: 1
    .uses_dynamic_stack: false
    .vgpr_count:     256
    .vgpr_spill_count: 0
    .wavefront_size: 64
